# prep_gdn: the 128 per-thread 2-byte stores of the solved u/w columns become 64 dword stores (lane pairs exchange packed bf16 by DPP + v_perm; even lanes store row t, odd lanes row t+1), same bytes wri
# baseline (speedup 1.0000x reference)
.LBB0_257:
	s_or_b64 exec, exec, s[0:1]
	v_mad_u64_u32 v[124:125], s[0:1], v22, s29, 0
	s_waitcnt lgkmcnt(0)
	v_mul_f32_e32 v0, v9, v0
	v_cmp_gt_u32_e32 vcc, v14, v10
	v_cvt_pk_bf16_f32 v0, v0, s0
	v_lshlrev_b32_e32 v20, 1, v8
	v_cndmask_b32_e64 v0, v0, 0, vcc
	v_lshl_add_u64 v[4:5], v[4:5], 0, v[20:21]
	global_store_short v[4:5], v0, off
	v_mul_f32_e32 v0, v9, v1
	v_cvt_pk_bf16_f32 v0, v0, s0
	v_cndmask_b32_e64 v4, v0, 0, vcc
	v_lshl_add_u64 v[0:1], v[2:3], 0, v[20:21]
	global_store_short v[0:1], v4, off
	v_lshlrev_b32_e32 v0, 8, v136
	ds_write2st64_b32 v11, v6, v7 offset0:152 offset1:216
	v_add_u32_e32 v140, v13, v0
	v_lshlrev_b32_e32 v126, 1, v32
	v_mad_i32_i24 v125, v37, s29, v125
	v_add_u32_e32 v25, v12, v0
	v_add_u32_e32 v20, v196, v126
	ds_read_b128 v[4:7], v140
	ds_read_b128 v[8:11], v140 offset:16
	ds_read_b128 v[36:39], v140 offset:32
	ds_read_b128 v[42:45], v140 offset:48
	ds_read_u16 v0, v20 offset:21504
	s_waitcnt lgkmcnt(4)
	v_mov_b32_e32 v112, v4
	v_lshlrev_b32_e32 v120, 16, v84
	v_pk_mul_f32 v[16:17], v[34:35], v[28:29]
	v_lshlrev_b32_e32 v121, 16, v85
	s_waitcnt lgkmcnt(0)
	v_lshlrev_b32_e32 v19, 16, v0
	ds_read_b128 v[12:15], v25
	ds_read_b128 v[46:49], v25 offset:16
	ds_read_b128 v[108:111], v25 offset:32
	ds_read_b128 v[0:3], v25 offset:48
	ds_read_u16 v4, v20 offset:21776
	v_mov_b32_e32 v84, v33
	v_mov_b32_e32 v85, v120
	s_waitcnt lgkmcnt(4)
	v_mov_b32_e32 v113, v12
	v_mov_b32_e32 v12, v5
	s_waitcnt lgkmcnt(0)
	v_lshlrev_b32_e32 v115, 16, v4
	ds_read_u16 v4, v20 offset:22048
	v_pk_mul_f32 v[84:85], v[84:85], v[30:31]
	v_mov_b32_e32 v118, v6
	v_mov_b32_e32 v32, v35
	v_pk_mul_f32 v[34:35], v[32:33], v[28:29]
	s_waitcnt lgkmcnt(0)
	v_lshlrev_b32_e32 v5, 16, v4
	v_add_f32_e32 v4, v16, v17
	v_add_f32_e32 v4, v4, v84
	v_add_f32_e32 v4, v4, v85
	v_mul_f32_e32 v6, 0xbfb8aa3b, v4
	v_exp_f32_e32 v6, v6
	v_pk_mul_f32 v[16:17], v[30:31], v[120:121]
	v_mov_b32_e32 v119, v14
	v_mov_b32_e32 v14, v7
	v_add_f32_e32 v6, 1.0, v6
	v_rcp_f32_e32 v6, v6
	v_lshlrev_b32_e32 v7, 16, v104
	v_mov_b32_e32 v84, v8
	v_mov_b32_e32 v85, v46
	v_mul_f32_e32 v18, v4, v6
	v_add_f32_e32 v4, v34, v35
	v_add_f32_e32 v4, v4, v16
	v_add_f32_e32 v4, v4, v17
	v_mul_f32_e32 v6, 0xbfb8aa3b, v4
	v_exp_f32_e32 v6, v6
	v_mov_b32_e32 v16, v28
	v_mov_b32_e32 v17, v120
	v_pk_mul_f32 v[128:129], v[18:19], v[112:113]
	v_add_f32_e32 v6, 1.0, v6
	v_rcp_f32_e32 v6, v6
	v_pk_mul_f32 v[18:19], v[28:29], v[120:121]
	v_mov_b32_e32 v46, v9
	v_lshlrev_b32_e32 v71, 16, v71
	v_mul_f32_e32 v114, v4, v6
	ds_read_u16 v4, v20 offset:22320
	v_pk_mul_f32 v[130:131], v[114:115], v[12:13]
	v_mov_b32_e32 v12, v33
	v_mov_b32_e32 v13, v29
	v_lshlrev_b32_e32 v6, 16, v99
	s_waitcnt lgkmcnt(0)
	v_lshlrev_b32_e32 v33, 16, v4
	ds_read_u16 v4, v20 offset:22592
	v_pk_mul_f32 v[12:13], v[12:13], v[16:17]
	v_pk_mov_b32 v[34:35], v[120:121], v[6:7] op_sel:[1,0]
	v_lshlrev_b32_e32 v51, 16, v51
	v_pk_mul_f32 v[104:105], v[30:31], v[34:35]
	s_waitcnt lgkmcnt(0)
	v_lshlrev_b32_e32 v17, 16, v4
	v_add_f32_e32 v4, v12, v13
	v_add_f32_e32 v4, v4, v104
	v_add_f32_e32 v4, v4, v105
	v_mul_f32_e32 v8, 0xbfb8aa3b, v4
	v_exp_f32_e32 v8, v8
	v_pk_mul_f32 v[12:13], v[28:29], v[6:7]
	v_lshlrev_b32_e32 v105, 16, v58
	v_lshlrev_b32_e32 v104, 16, v55
	v_add_f32_e32 v8, 1.0, v8
	v_rcp_f32_e32 v8, v8
	v_lshlrev_b32_e32 v113, 16, v69
	v_lshlrev_b32_e32 v112, 16, v68
	v_lshlrev_b32_e32 v115, 16, v77
	v_mul_f32_e32 v4, v4, v8
	v_pk_mul_f32 v[132:133], v[4:5], v[118:119]
	v_pk_mul_f32 v[4:5], v[30:31], v[6:7]
	v_add_f32_e32 v8, v18, v19
	v_add_f32_e32 v4, v8, v4
	v_add_f32_e32 v4, v4, v5
	v_mul_f32_e32 v5, 0xbfb8aa3b, v4
	v_exp_f32_e32 v5, v5
	ds_read_u16 v8, v20 offset:22864
	v_mov_b32_e32 v19, v48
	v_mov_b32_e32 v48, v11
	v_add_f32_e32 v5, 1.0, v5
	v_rcp_f32_e32 v5, v5
	v_mov_b32_e32 v18, v10
	v_lshlrev_b32_e32 v114, 16, v76
	v_lshlrev_b32_e32 v145, 16, v100
	v_mul_f32_e32 v32, v4, v5
	v_pk_mul_f32 v[134:135], v[32:33], v[14:15]
	v_lshlrev_b32_e32 v33, 16, v101
	v_lshlrev_b32_e32 v32, 16, v91
	v_pk_mul_f32 v[4:5], v[28:29], v[34:35]
	v_pk_mov_b32 v[6:7], v[6:7], v[32:33] op_sel:[1,0]
	v_add_f32_e32 v4, v4, v5
	v_pk_mul_f32 v[34:35], v[30:31], v[6:7]
	s_waitcnt lgkmcnt(0)
	v_lshlrev_b32_e32 v15, 16, v8
	v_add_f32_e32 v4, v4, v34
	v_add_f32_e32 v4, v4, v35
	v_mul_f32_e32 v5, 0xbfb8aa3b, v4
	v_exp_f32_e32 v5, v5
	ds_read_u16 v8, v20 offset:23136
	v_lshlrev_b32_e32 v35, 16, v93
	v_lshlrev_b32_e32 v34, 16, v88
	v_add_f32_e32 v5, 1.0, v5
	v_rcp_f32_e32 v5, v5
	s_waitcnt lgkmcnt(0)
	v_lshlrev_b32_e32 v9, 16, v8
	v_add_f32_e32 v8, v12, v13
	v_lshlrev_b32_e32 v144, 16, v98
	v_mul_f32_e32 v16, v4, v5
	v_pk_mul_f32 v[4:5], v[30:31], v[32:33]
	v_pk_mul_f32 v[148:149], v[28:29], v[144:145]
	v_add_f32_e32 v4, v8, v4
	v_add_f32_e32 v4, v4, v5
	v_mul_f32_e32 v5, 0xbfb8aa3b, v4
	v_exp_f32_e32 v5, v5
	ds_read_u16 v8, v20 offset:23408
	v_lshlrev_b32_e32 v215, 16, v143
	v_lshlrev_b32_e32 v214, 16, v142
	v_add_f32_e32 v5, 1.0, v5
	v_rcp_f32_e32 v5, v5
	s_waitcnt lgkmcnt(0)
	v_lshlrev_b32_e32 v13, 16, v8
	ds_read_u16 v8, v20 offset:23680
	v_lshlrev_b32_e32 v139, 16, v139
	v_mul_f32_e32 v14, v4, v5
	v_pk_mul_f32 v[4:5], v[28:29], v[6:7]
	v_pk_mul_f32 v[6:7], v[28:29], v[32:33]
	v_pk_mov_b32 v[32:33], v[32:33], v[34:35] op_sel:[1,0]
	v_pk_mul_f32 v[122:123], v[14:15], v[46:47]
	v_pk_mul_f32 v[46:47], v[30:31], v[32:33]
	v_add_f32_e32 v4, v4, v5
	v_add_f32_e32 v4, v4, v46
	v_add_f32_e32 v4, v4, v47
	v_mul_f32_e32 v5, 0xbfb8aa3b, v4
	v_exp_f32_e32 v5, v5
	s_waitcnt lgkmcnt(0)
	v_lshlrev_b32_e32 v11, 16, v8
	v_add_f32_e32 v6, v6, v7
	v_mov_b32_e32 v14, v36
	v_add_f32_e32 v5, 1.0, v5
	v_rcp_f32_e32 v5, v5
	v_mov_b32_e32 v15, v108
	v_mov_b32_e32 v108, v37
	v_lshlrev_b32_e32 v37, 16, v97
	v_mul_f32_e32 v8, v4, v5
	v_pk_mul_f32 v[4:5], v[30:31], v[34:35]
	v_lshlrev_b32_e32 v36, 16, v96
	v_add_f32_e32 v4, v6, v4
	v_add_f32_e32 v4, v4, v5
	v_mul_f32_e32 v5, 0xbfb8aa3b, v4
	v_exp_f32_e32 v5, v5
	v_pk_mul_f32 v[6:7], v[28:29], v[34:35]
	v_pk_mul_f32 v[186:187], v[8:9], v[18:19]
	v_add_f32_e32 v6, v6, v7
	v_add_f32_e32 v5, 1.0, v5
	v_rcp_f32_e32 v5, v5
	ds_read_u16 v8, v20 offset:23952
	v_lshlrev_b32_e32 v138, 16, v138
	v_lshl_add_u64 v[124:125], s[68:69], 0, v[124:125]
	v_mul_f32_e32 v12, v4, v5
	v_pk_mul_f32 v[184:185], v[12:13], v[48:49]
	v_pk_mul_f32 v[4:5], v[28:29], v[32:33]
	v_pk_mov_b32 v[12:13], v[34:35], v[36:37] op_sel:[1,0]
	v_add_f32_e32 v4, v4, v5
	v_pk_mul_f32 v[34:35], v[30:31], v[12:13]
	s_waitcnt lgkmcnt(0)
	v_lshlrev_b32_e32 v9, 16, v8
	v_add_f32_e32 v4, v4, v34
	v_add_f32_e32 v4, v4, v35
	v_mul_f32_e32 v5, 0xbfb8aa3b, v4
	v_exp_f32_e32 v5, v5
	ds_read_u16 v8, v20 offset:24224
	v_mov_b32_e32 v32, v38
	v_mov_b32_e32 v33, v110
	v_add_f32_e32 v5, 1.0, v5
	v_rcp_f32_e32 v5, v5
	v_mov_b32_e32 v110, v39
	v_lshlrev_b32_e32 v39, 16, v89
	v_lshlrev_b32_e32 v38, 16, v83
	v_mul_f32_e32 v10, v4, v5
	v_pk_mul_f32 v[4:5], v[30:31], v[36:37]
	s_waitcnt lgkmcnt(0)
	v_lshlrev_b32_e32 v19, 16, v8
	v_add_f32_e32 v4, v6, v4
	v_add_f32_e32 v4, v4, v5
	v_mul_f32_e32 v5, 0xbfb8aa3b, v4
	v_exp_f32_e32 v5, v5
	v_pk_mul_f32 v[6:7], v[28:29], v[36:37]
	v_pk_mov_b32 v[36:37], v[36:37], v[38:39] op_sel:[1,0]
	v_lshlrev_b32_e32 v49, 16, v81
	v_add_f32_e32 v5, 1.0, v5
	v_rcp_f32_e32 v5, v5
	v_pk_mul_f32 v[46:47], v[30:31], v[36:37]
	v_lshlrev_b32_e32 v48, 16, v78
	s_add_i32 s33, s33, s26
	v_mul_f32_e32 v8, v4, v5
	v_pk_mul_f32 v[4:5], v[28:29], v[12:13]
	v_mov_b32_e32 v13, v0
	v_add_f32_e32 v0, v4, v5
	v_add_f32_e32 v0, v0, v46
	v_add_f32_e32 v0, v0, v47
	v_mul_f32_e32 v4, 0xbfb8aa3b, v0
	v_exp_f32_e32 v4, v4
	v_pk_mul_f32 v[182:183], v[8:9], v[108:109]
	ds_read_u16 v8, v20 offset:24496
	v_mov_b32_e32 v47, v2
	v_add_f32_e32 v4, 1.0, v4
	v_rcp_f32_e32 v4, v4
	v_mov_b32_e32 v46, v44
	v_lshlrev_b32_e32 v44, 16, v70
	v_mov_b32_e32 v12, v42
	v_mul_f32_e32 v18, v0, v4
	v_pk_mul_f32 v[4:5], v[30:31], v[38:39]
	v_add_f32_e32 v0, v6, v7
	v_add_f32_e32 v0, v0, v4
	v_add_f32_e32 v0, v0, v5
	v_mul_f32_e32 v4, 0xbfb8aa3b, v0
	v_exp_f32_e32 v4, v4
	v_pk_mul_f32 v[180:181], v[18:19], v[32:33]
	v_pk_mul_f32 v[6:7], v[28:29], v[38:39]
	v_lshlrev_b32_e32 v70, 16, v67
	v_add_f32_e32 v4, 1.0, v4
	v_rcp_f32_e32 v4, v4
	s_cmpk_gt_i32 s33, 0xfff
	v_mul_f32_e32 v34, v0, v4
	ds_read_u16 v0, v20 offset:25040
	s_waitcnt lgkmcnt(1)
	v_lshlrev_b32_e32 v35, 16, v8
	v_pk_mul_f32 v[18:19], v[34:35], v[110:111]
	v_pk_mul_f32 v[4:5], v[28:29], v[36:37]
	v_pk_mov_b32 v[34:35], v[38:39], v[48:49] op_sel:[1,0]
	v_add_f32_e32 v2, v4, v5
	v_pk_mul_f32 v[36:37], v[30:31], v[34:35]
	ds_read_u16 v8, v20 offset:24768
	v_add_f32_e32 v2, v2, v36
	v_add_f32_e32 v2, v2, v37
	v_mul_f32_e32 v4, 0xbfb8aa3b, v2
	v_exp_f32_e32 v4, v4
	s_waitcnt lgkmcnt(0)
	v_lshlrev_b32_e32 v9, 16, v8
	ds_read_u16 v8, v20 offset:25312
	v_lshlrev_b32_e32 v33, 16, v0
	v_add_f32_e32 v4, 1.0, v4
	v_rcp_f32_e32 v4, v4
	v_mov_b32_e32 v0, v43
	s_waitcnt lgkmcnt(0)
	v_lshlrev_b32_e32 v43, 16, v8
	v_mul_f32_e32 v8, v2, v4
	v_pk_mul_f32 v[4:5], v[30:31], v[48:49]
	v_add_f32_e32 v2, v6, v7
	v_add_f32_e32 v2, v2, v4
	v_add_f32_e32 v2, v2, v5
	v_mul_f32_e32 v4, 0xbfb8aa3b, v2
	v_exp_f32_e32 v4, v4
	s_nop 0
	v_add_f32_e32 v4, 1.0, v4
	v_rcp_f32_e32 v4, v4
	s_nop 0
	v_mul_f32_e32 v32, v2, v4
	ds_read_u16 v2, v20 offset:25584
	v_pk_mul_f32 v[178:179], v[32:33], v[0:1]
	v_pk_mul_f32 v[0:1], v[28:29], v[34:35]
	v_pk_mul_f32 v[32:33], v[28:29], v[48:49]
	v_add_f32_e32 v0, v0, v1
	s_waitcnt lgkmcnt(0)
	v_lshlrev_b32_e32 v39, 16, v2
	v_mov_b32_e32 v2, v45
	v_lshlrev_b32_e32 v45, 16, v73
	v_pk_mov_b32 v[48:49], v[48:49], v[44:45] op_sel:[1,0]
	ds_read_b128 v[4:7], v140 offset:64
	ds_read_u16 v34, v20 offset:25856
	v_pk_mul_f32 v[88:89], v[30:31], v[48:49]
	s_waitcnt lgkmcnt(1)
	v_mov_b32_e32 v170, v4
	v_add_f32_e32 v0, v0, v88
	v_add_f32_e32 v0, v0, v89
	v_mul_f32_e32 v1, 0xbfb8aa3b, v0
	v_exp_f32_e32 v1, v1
	v_add_f32_e32 v4, v32, v33
	s_waitcnt lgkmcnt(0)
	v_lshlrev_b32_e32 v169, 16, v34
	ds_read_b128 v[34:37], v25 offset:64
	v_add_f32_e32 v1, 1.0, v1
	v_rcp_f32_e32 v1, v1
	s_nop 0
	v_mul_f32_e32 v42, v0, v1
	v_pk_mul_f32 v[0:1], v[30:31], v[44:45]
	v_pk_mul_f32 v[176:177], v[42:43], v[46:47]
	v_add_f32_e32 v0, v4, v0
	v_add_f32_e32 v0, v0, v1
	v_mul_f32_e32 v1, 0xbfb8aa3b, v0
	v_exp_f32_e32 v1, v1
	ds_read_u16 v4, v20 offset:26128
	v_lshlrev_b32_e32 v47, 16, v79
	v_lshlrev_b32_e32 v46, 16, v75
	v_add_f32_e32 v1, 1.0, v1
	v_rcp_f32_e32 v1, v1
	s_waitcnt lgkmcnt(0)
	v_lshlrev_b32_e32 v33, 16, v4
	ds_read_u16 v4, v20 offset:26400
	v_mov_b32_e32 v171, v34
	v_mul_f32_e32 v38, v0, v1
	v_pk_mul_f32 v[174:175], v[38:39], v[2:3]
	v_pk_mul_f32 v[0:1], v[28:29], v[48:49]
	v_mov_b32_e32 v34, v5
	s_waitcnt lgkmcnt(0)
	v_lshlrev_b32_e32 v39, 16, v4
	v_pk_mov_b32 v[4:5], v[44:45], v[46:47] op_sel:[1,0]
	v_pk_mul_f32 v[2:3], v[28:29], v[44:45]
	v_pk_mul_f32 v[44:45], v[30:31], v[4:5]
	v_add_f32_e32 v0, v0, v1
	v_add_f32_e32 v0, v0, v44
	v_add_f32_e32 v0, v0, v45
	v_mul_f32_e32 v1, 0xbfb8aa3b, v0
	v_exp_f32_e32 v1, v1
	v_add_f32_e32 v2, v2, v3
	v_pk_mul_f32 v[44:45], v[28:29], v[4:5]
	v_mov_b32_e32 v42, v6
	v_add_f32_e32 v1, 1.0, v1
	v_rcp_f32_e32 v1, v1
	v_mov_b32_e32 v43, v36
	v_mov_b32_e32 v36, v7
	v_pk_mul_f32 v[48:49], v[28:29], v[46:47]
	v_mul_f32_e32 v168, v0, v1
	v_pk_mul_f32 v[0:1], v[30:31], v[46:47]
	v_pk_mov_b32 v[46:47], v[46:47], v[70:71] op_sel:[1,0]
	v_add_f32_e32 v0, v2, v0
	v_add_f32_e32 v0, v0, v1
	v_mul_f32_e32 v1, 0xbfb8aa3b, v0
	v_exp_f32_e32 v1, v1
	v_pk_mul_f32 v[88:89], v[30:31], v[46:47]
	v_add_f32_e32 v1, 1.0, v1
	v_rcp_f32_e32 v1, v1
	s_nop 0
	v_mul_f32_e32 v32, v0, v1
	ds_read_u16 v0, v20 offset:26672
	v_pk_mul_f32 v[172:173], v[32:33], v[34:35]
	s_waitcnt lgkmcnt(0)
	v_lshlrev_b32_e32 v79, 16, v0
	ds_read_b128 v[0:3], v140 offset:80
	ds_read_u16 v4, v20 offset:26944
	s_waitcnt lgkmcnt(1)
	v_mov_b32_e32 v34, v0
	s_waitcnt lgkmcnt(0)
	v_lshlrev_b32_e32 v33, 16, v4
	ds_read_b128 v[4:7], v25 offset:80
	v_add_f32_e32 v0, v44, v45
	v_add_f32_e32 v0, v0, v88
	v_add_f32_e32 v0, v0, v89
	v_lshlrev_b32_e32 v89, 16, v65
	s_waitcnt lgkmcnt(0)
	v_mov_b32_e32 v35, v4
	v_mul_f32_e32 v4, 0xbfb8aa3b, v0
	v_exp_f32_e32 v4, v4
	v_lshlrev_b32_e32 v88, 16, v50
	v_lshlrev_b32_e32 v50, 16, v41
	v_add_f32_e32 v4, 1.0, v4
	v_rcp_f32_e32 v4, v4
	s_nop 0
	v_mul_f32_e32 v38, v0, v4
	v_pk_mul_f32 v[166:167], v[38:39], v[42:43]
	v_pk_mul_f32 v[38:39], v[30:31], v[70:71]
	v_add_f32_e32 v0, v48, v49
	v_add_f32_e32 v0, v0, v38
	v_add_f32_e32 v0, v0, v39
	v_mul_f32_e32 v4, 0xbfb8aa3b, v0
	v_exp_f32_e32 v4, v4
	v_pk_mul_f32 v[38:39], v[28:29], v[70:71]
	v_add_f32_e32 v4, 1.0, v4
	v_rcp_f32_e32 v4, v4
	s_nop 0
	v_mul_f32_e32 v78, v0, v4
	ds_read_u16 v0, v20 offset:27216
	v_pk_mul_f32 v[162:163], v[78:79], v[36:37]
	v_pk_mul_f32 v[36:37], v[28:29], v[46:47]
	v_mov_b32_e32 v4, v1
	v_mov_b32_e32 v78, v2
	s_waitcnt lgkmcnt(0)
	v_lshlrev_b32_e32 v43, 16, v0
	ds_read_u16 v0, v20 offset:27488
	v_add_f32_e32 v2, v36, v37
	v_mov_b32_e32 v79, v6
	v_pk_mul_f32 v[36:37], v[30:31], v[88:89]
	s_waitcnt lgkmcnt(0)
	v_lshlrev_b32_e32 v49, 16, v0
	v_pk_mov_b32 v[0:1], v[70:71], v[88:89] op_sel:[1,0]
	v_pk_mul_f32 v[70:71], v[28:29], v[88:89]
	v_pk_mul_f32 v[44:45], v[30:31], v[0:1]
	v_pk_mov_b32 v[88:89], v[88:89], v[50:51] op_sel:[1,0]
	v_add_f32_e32 v2, v2, v44
	v_add_f32_e32 v2, v2, v45
	v_mul_f32_e32 v6, 0xbfb8aa3b, v2
	v_exp_f32_e32 v6, v6
	s_nop 0
	v_add_f32_e32 v6, 1.0, v6
	v_rcp_f32_e32 v6, v6
	s_nop 0
	v_mul_f32_e32 v32, v2, v6
	v_add_f32_e32 v2, v38, v39
	v_add_f32_e32 v2, v2, v36
	v_add_f32_e32 v2, v2, v37
	v_mul_f32_e32 v6, 0xbfb8aa3b, v2
	v_exp_f32_e32 v6, v6
	s_nop 0
	v_add_f32_e32 v6, 1.0, v6
	v_rcp_f32_e32 v6, v6
	s_nop 0
	v_mul_f32_e32 v42, v2, v6
	v_pk_mul_f32 v[160:161], v[42:43], v[4:5]
	v_pk_mul_f32 v[4:5], v[28:29], v[0:1]
	ds_read_u16 v0, v20 offset:27760
	v_mov_b32_e32 v6, v3
	s_waitcnt lgkmcnt(0)
	v_lshlrev_b32_e32 v97, 16, v0
	ds_read_b128 v[0:3], v140 offset:96
	ds_read_u16 v36, v20 offset:28032
	ds_read_b128 v[44:47], v25 offset:96
	s_waitcnt lgkmcnt(2)
	v_mov_b32_e32 v42, v0
	s_waitcnt lgkmcnt(1)
	v_lshlrev_b32_e32 v39, 16, v36
	v_pk_mul_f32 v[36:37], v[30:31], v[88:89]
	v_add_f32_e32 v0, v4, v5
	v_add_f32_e32 v0, v0, v36
	v_add_f32_e32 v0, v0, v37
	v_mul_f32_e32 v4, 0xbfb8aa3b, v0
	v_exp_f32_e32 v4, v4
	s_nop 0
	v_add_f32_e32 v4, 1.0, v4
	v_rcp_f32_e32 v4, v4
	s_nop 0
	v_mul_f32_e32 v48, v0, v4
	v_pk_mul_f32 v[4:5], v[30:31], v[50:51]
	v_add_f32_e32 v0, v70, v71
	v_add_f32_e32 v0, v0, v4
	v_add_f32_e32 v0, v0, v5
	v_mul_f32_e32 v4, 0xbfb8aa3b, v0
	v_exp_f32_e32 v4, v4
	v_pk_mul_f32 v[36:37], v[48:49], v[78:79]
	v_mov_b32_e32 v78, v2
	v_add_f32_e32 v4, 1.0, v4
	v_rcp_f32_e32 v4, v4
	s_nop 0
	v_mul_f32_e32 v96, v0, v4
	ds_read_u16 v0, v20 offset:28304
	v_pk_mul_f32 v[4:5], v[28:29], v[88:89]
	v_lshlrev_b32_e32 v89, 16, v63
	v_lshlrev_b32_e32 v88, 16, v59
	s_waitcnt lgkmcnt(1)
	v_mov_b32_e32 v43, v44
	s_waitcnt lgkmcnt(0)
	v_lshlrev_b32_e32 v49, 16, v0
	ds_read_u16 v0, v20 offset:28576
	v_mov_b32_e32 v44, v1
	v_pk_mul_f32 v[40:41], v[96:97], v[6:7]
	v_pk_mul_f32 v[6:7], v[28:29], v[50:51]
	v_add_f32_e32 v2, v4, v5
	s_waitcnt lgkmcnt(0)
	v_lshlrev_b32_e32 v71, 16, v0
	v_pk_mov_b32 v[0:1], v[50:51], v[88:89] op_sel:[1,0]
	v_mov_b32_e32 v79, v46
	v_pk_mul_f32 v[50:51], v[30:31], v[0:1]
	v_mov_b32_e32 v46, v3
	v_add_f32_e32 v2, v2, v50
	v_add_f32_e32 v2, v2, v51
	v_mul_f32_e32 v4, 0xbfb8aa3b, v2
	v_exp_f32_e32 v4, v4
	v_pk_mul_f32 v[96:97], v[28:29], v[88:89]
	v_add_f32_e32 v4, 1.0, v4
	v_rcp_f32_e32 v4, v4
	s_nop 0
	v_mul_f32_e32 v38, v2, v4
	v_pk_mul_f32 v[4:5], v[30:31], v[88:89]
	v_add_f32_e32 v2, v6, v7
	v_add_f32_e32 v2, v2, v4
	v_add_f32_e32 v2, v2, v5
	v_mul_f32_e32 v4, 0xbfb8aa3b, v2
	v_exp_f32_e32 v4, v4
	v_pk_mov_b32 v[88:89], v[88:89], v[104:105] op_sel:[1,0]
	v_add_f32_e32 v4, 1.0, v4
	v_rcp_f32_e32 v4, v4
	v_pk_mul_f32 v[108:109], v[30:31], v[88:89]
	v_mul_f32_e32 v48, v2, v4
	v_pk_mul_f32 v[158:159], v[48:49], v[44:45]
	v_pk_mul_f32 v[44:45], v[28:29], v[0:1]
	ds_read_u16 v0, v20 offset:28848
	s_waitcnt lgkmcnt(0)
	v_lshlrev_b32_e32 v59, 16, v0
	ds_read_b128 v[0:3], v140 offset:112
	ds_read_u16 v4, v20 offset:29120
	s_waitcnt lgkmcnt(1)
	v_mov_b32_e32 v50, v0
	s_waitcnt lgkmcnt(0)
	v_lshlrev_b32_e32 v49, 16, v4
	ds_read_b128 v[4:7], v25 offset:112
	v_add_f32_e32 v0, v44, v45
	v_add_f32_e32 v0, v0, v108
	v_add_f32_e32 v0, v0, v109
	s_waitcnt lgkmcnt(0)
	v_mov_b32_e32 v51, v4
	v_mul_f32_e32 v4, 0xbfb8aa3b, v0
	v_exp_f32_e32 v4, v4
	s_nop 0
	v_add_f32_e32 v4, 1.0, v4
	v_rcp_f32_e32 v4, v4
	s_nop 0
	v_mul_f32_e32 v70, v0, v4
	v_pk_mul_f32 v[44:45], v[70:71], v[78:79]
	v_pk_mul_f32 v[70:71], v[30:31], v[104:105]
	v_add_f32_e32 v0, v96, v97
	v_add_f32_e32 v0, v0, v70
	v_add_f32_e32 v0, v0, v71
	v_mul_f32_e32 v4, 0xbfb8aa3b, v0
	v_exp_f32_e32 v4, v4
	v_lshlrev_b32_e32 v97, 16, v57
	v_lshlrev_b32_e32 v96, 16, v53
	v_pk_mul_f32 v[70:71], v[28:29], v[104:105]
	v_add_f32_e32 v4, 1.0, v4
	v_rcp_f32_e32 v4, v4
	s_nop 0
	v_mul_f32_e32 v58, v0, v4
	ds_read_u16 v0, v20 offset:29392
	v_pk_mul_f32 v[46:47], v[58:59], v[46:47]
	v_pk_mul_f32 v[58:59], v[28:29], v[88:89]
	v_mov_b32_e32 v4, v1
	v_mov_b32_e32 v88, v2
	s_waitcnt lgkmcnt(0)
	v_lshlrev_b32_e32 v79, 16, v0
	ds_read_u16 v0, v20 offset:29664
	v_add_f32_e32 v2, v58, v59
	v_mov_b32_e32 v89, v6
	v_pk_mul_f32 v[58:59], v[30:31], v[96:97]
	s_waitcnt lgkmcnt(0)
	v_lshlrev_b32_e32 v55, 16, v0
	v_pk_mov_b32 v[0:1], v[104:105], v[96:97] op_sel:[1,0]
	s_nop 0
	v_pk_mul_f32 v[104:105], v[30:31], v[0:1]
	s_nop 0
	v_add_f32_e32 v2, v2, v104
	v_add_f32_e32 v2, v2, v105
	v_mul_f32_e32 v6, 0xbfb8aa3b, v2
	v_exp_f32_e32 v6, v6
	v_lshlrev_b32_e32 v105, 16, v54
	v_lshlrev_b32_e32 v104, 16, v52
	v_add_f32_e32 v6, 1.0, v6
	v_rcp_f32_e32 v6, v6
	s_nop 0
	v_mul_f32_e32 v48, v2, v6
	v_add_f32_e32 v2, v70, v71
	v_add_f32_e32 v2, v2, v58
	v_add_f32_e32 v2, v2, v59
	v_mul_f32_e32 v6, 0xbfb8aa3b, v2
	v_exp_f32_e32 v6, v6
	v_pk_mul_f32 v[70:71], v[28:29], v[96:97]
	v_pk_mov_b32 v[96:97], v[96:97], v[104:105] op_sel:[1,0]
	v_add_f32_e32 v6, 1.0, v6
	v_rcp_f32_e32 v6, v6
	s_nop 0
	v_mul_f32_e32 v78, v2, v6
	v_pk_mul_f32 v[156:157], v[78:79], v[4:5]
	v_pk_mul_f32 v[4:5], v[28:29], v[0:1]
	ds_read_u16 v0, v20 offset:29936
	v_mov_b32_e32 v6, v3
	s_waitcnt lgkmcnt(0)
	v_lshlrev_b32_e32 v79, 16, v0
	ds_read_b128 v[0:3], v140 offset:128
	ds_read_u16 v53, v20 offset:30208
	ds_read_b128 v[108:111], v25 offset:128
	s_waitcnt lgkmcnt(2)
	v_mov_b32_e32 v58, v0
	s_waitcnt lgkmcnt(1)
	v_lshlrev_b32_e32 v57, 16, v53
	v_pk_mul_f32 v[52:53], v[30:31], v[96:97]
	v_add_f32_e32 v0, v4, v5
	v_add_f32_e32 v0, v0, v52
	v_add_f32_e32 v0, v0, v53
	v_mul_f32_e32 v4, 0xbfb8aa3b, v0
	v_exp_f32_e32 v4, v4
	s_nop 0
	v_add_f32_e32 v4, 1.0, v4
	v_rcp_f32_e32 v4, v4
	s_nop 0
	v_mul_f32_e32 v54, v0, v4
	v_pk_mul_f32 v[4:5], v[30:31], v[104:105]
	v_add_f32_e32 v0, v70, v71
	v_add_f32_e32 v0, v0, v4
	v_add_f32_e32 v0, v0, v5
	v_mul_f32_e32 v4, 0xbfb8aa3b, v0
	v_exp_f32_e32 v4, v4
	v_pk_mul_f32 v[52:53], v[54:55], v[88:89]
	v_lshlrev_b32_e32 v89, 16, v62
	v_lshlrev_b32_e32 v88, 16, v56
	v_add_f32_e32 v4, 1.0, v4
	v_rcp_f32_e32 v4, v4
	s_nop 0
	v_mul_f32_e32 v78, v0, v4
	ds_read_u16 v0, v20 offset:30480
	s_waitcnt lgkmcnt(1)
	v_mov_b32_e32 v59, v108
	v_pk_mul_f32 v[4:5], v[28:29], v[96:97]
	v_mov_b32_e32 v108, v1
	v_pk_mul_f32 v[54:55], v[78:79], v[6:7]
	s_waitcnt lgkmcnt(0)
	v_lshlrev_b32_e32 v63, 16, v0
	ds_read_u16 v0, v20 offset:30752
	v_mov_b32_e32 v78, v2
	v_add_f32_e32 v2, v4, v5
	v_pk_mul_f32 v[6:7], v[28:29], v[104:105]
	v_mov_b32_e32 v79, v110
	s_waitcnt lgkmcnt(0)
	v_lshlrev_b32_e32 v71, 16, v0
	v_pk_mov_b32 v[0:1], v[104:105], v[88:89] op_sel:[1,0]
	v_mov_b32_e32 v110, v3
	v_pk_mul_f32 v[96:97], v[30:31], v[0:1]
	s_nop 0
	v_add_f32_e32 v2, v2, v96
	v_add_f32_e32 v2, v2, v97
	v_mul_f32_e32 v4, 0xbfb8aa3b, v2
	v_exp_f32_e32 v4, v4
	v_pk_mul_f32 v[96:97], v[28:29], v[88:89]
	v_add_f32_e32 v4, 1.0, v4
	v_rcp_f32_e32 v4, v4
	s_nop 0
	v_mul_f32_e32 v56, v2, v4
	v_pk_mul_f32 v[4:5], v[30:31], v[88:89]
	v_add_f32_e32 v2, v6, v7
	v_add_f32_e32 v2, v2, v4
	v_add_f32_e32 v2, v2, v5
	v_mul_f32_e32 v4, 0xbfb8aa3b, v2
	v_exp_f32_e32 v4, v4
	s_nop 0
	v_add_f32_e32 v4, 1.0, v4
	v_rcp_f32_e32 v4, v4
	s_nop 0
	v_mul_f32_e32 v62, v2, v4
	v_pk_mul_f32 v[154:155], v[62:63], v[108:109]
	v_pk_mul_f32 v[62:63], v[28:29], v[0:1]
	ds_read_u16 v0, v20 offset:31024
	v_lshlrev_b32_e32 v109, 16, v61
	v_lshlrev_b32_e32 v108, 16, v60
	v_pk_mov_b32 v[88:89], v[88:89], v[108:109] op_sel:[1,0]
	s_waitcnt lgkmcnt(0)
	v_lshlrev_b32_e32 v105, 16, v0
	ds_read_b128 v[0:3], v140 offset:144
	ds_read_u16 v4, v20 offset:31296
	v_pk_mul_f32 v[60:61], v[30:31], v[88:89]
	s_waitcnt lgkmcnt(1)
	v_mov_b32_e32 v152, v0
	s_waitcnt lgkmcnt(0)
	v_lshlrev_b32_e32 v65, 16, v4
	ds_read_b128 v[4:7], v25 offset:144
	v_add_f32_e32 v0, v62, v63
	v_add_f32_e32 v0, v0, v60
	v_add_f32_e32 v0, v0, v61
	v_pk_mul_f32 v[62:63], v[30:31], v[108:109]
	s_waitcnt lgkmcnt(0)
	v_mov_b32_e32 v153, v4
	v_mul_f32_e32 v4, 0xbfb8aa3b, v0
	v_exp_f32_e32 v4, v4
	s_nop 0
	v_add_f32_e32 v4, 1.0, v4
	v_rcp_f32_e32 v4, v4
	s_nop 0
	v_mul_f32_e32 v70, v0, v4
	v_add_f32_e32 v0, v96, v97
	v_add_f32_e32 v0, v0, v62
	v_add_f32_e32 v0, v0, v63
	v_mul_f32_e32 v4, 0xbfb8aa3b, v0
	v_exp_f32_e32 v4, v4
	v_pk_mul_f32 v[60:61], v[70:71], v[78:79]
	v_pk_mul_f32 v[70:71], v[28:29], v[88:89]
	v_pk_mul_f32 v[78:79], v[28:29], v[108:109]
	v_add_f32_e32 v4, 1.0, v4
	v_rcp_f32_e32 v4, v4
	v_mov_b32_e32 v96, v2
	v_add_f32_e32 v2, v70, v71
	v_mov_b32_e32 v97, v6
	v_mul_f32_e32 v104, v0, v4
	ds_read_u16 v0, v20 offset:31568
	v_pk_mul_f32 v[62:63], v[104:105], v[110:111]
	v_lshlrev_b32_e32 v105, 16, v66
	v_lshlrev_b32_e32 v104, 16, v64
	v_mov_b32_e32 v4, v1
	s_waitcnt lgkmcnt(0)
	v_lshlrev_b32_e32 v67, 16, v0
	ds_read_u16 v0, v20 offset:31840
	v_pk_mul_f32 v[70:71], v[30:31], v[104:105]
	s_waitcnt lgkmcnt(0)
	v_lshlrev_b32_e32 v89, 16, v0
	v_pk_mov_b32 v[0:1], v[108:109], v[104:105] op_sel:[1,0]
	s_nop 0
	v_pk_mul_f32 v[108:109], v[30:31], v[0:1]
	s_nop 0
	v_add_f32_e32 v2, v2, v108
	v_add_f32_e32 v2, v2, v109
	v_mul_f32_e32 v6, 0xbfb8aa3b, v2
	v_exp_f32_e32 v6, v6
	s_nop 0
	v_add_f32_e32 v6, 1.0, v6
	v_rcp_f32_e32 v6, v6
	s_nop 0
	v_mul_f32_e32 v64, v2, v6
	v_add_f32_e32 v2, v78, v79
	v_add_f32_e32 v2, v2, v70
	v_add_f32_e32 v2, v2, v71
	v_mul_f32_e32 v6, 0xbfb8aa3b, v2
	v_exp_f32_e32 v6, v6
	v_pk_mul_f32 v[70:71], v[28:29], v[104:105]
	v_pk_mov_b32 v[104:105], v[104:105], v[112:113] op_sel:[1,0]
	v_add_f32_e32 v6, 1.0, v6
	v_rcp_f32_e32 v6, v6
	v_pk_mul_f32 v[68:69], v[30:31], v[104:105]
	v_mul_f32_e32 v66, v2, v6
	v_pk_mul_f32 v[66:67], v[66:67], v[4:5]
	v_pk_mul_f32 v[4:5], v[28:29], v[0:1]
	ds_read_u16 v0, v20 offset:32112
	v_mov_b32_e32 v6, v3
	s_waitcnt lgkmcnt(0)
	v_lshlrev_b32_e32 v79, 16, v0
	ds_read_b128 v[0:3], v140 offset:160
	ds_read_u16 v73, v20 offset:32384
	ds_read_b128 v[108:111], v25 offset:160
	s_waitcnt lgkmcnt(2)
	v_mov_b32_e32 v150, v0
	v_add_f32_e32 v0, v4, v5
	v_add_f32_e32 v0, v0, v68
	v_add_f32_e32 v0, v0, v69
	v_mul_f32_e32 v4, 0xbfb8aa3b, v0
	v_exp_f32_e32 v4, v4
	s_waitcnt lgkmcnt(1)
	v_lshlrev_b32_e32 v73, 16, v73
	v_add_f32_e32 v4, 1.0, v4
	v_rcp_f32_e32 v4, v4
	s_nop 0
	v_mul_f32_e32 v88, v0, v4
	v_pk_mul_f32 v[4:5], v[30:31], v[112:113]
	v_add_f32_e32 v0, v70, v71
	v_add_f32_e32 v0, v0, v4
	v_add_f32_e32 v0, v0, v5
	v_mul_f32_e32 v4, 0xbfb8aa3b, v0
	v_exp_f32_e32 v4, v4
	v_pk_mul_f32 v[68:69], v[88:89], v[96:97]
	v_lshlrev_b32_e32 v97, 16, v74
	v_lshlrev_b32_e32 v96, 16, v72
	v_add_f32_e32 v4, 1.0, v4
	v_rcp_f32_e32 v4, v4
	v_mov_b32_e32 v88, v2
	v_mul_f32_e32 v78, v0, v4
	ds_read_u16 v0, v20 offset:32656
	v_pk_mul_f32 v[70:71], v[78:79], v[6:7]
	v_pk_mul_f32 v[4:5], v[28:29], v[104:105]
	v_pk_mul_f32 v[6:7], v[28:29], v[112:113]
	v_add_f32_e32 v2, v4, v5
	s_waitcnt lgkmcnt(0)
	v_lshlrev_b32_e32 v75, 16, v0
	ds_read_u16 v0, v20 offset:32928
	v_mov_b32_e32 v151, v108
	v_mov_b32_e32 v108, v1
	v_mov_b32_e32 v89, v110
	v_mov_b32_e32 v110, v3
	s_waitcnt lgkmcnt(0)
	v_lshlrev_b32_e32 v79, 16, v0
	v_pk_mov_b32 v[0:1], v[112:113], v[96:97] op_sel:[1,0]
	s_nop 0
	v_pk_mul_f32 v[104:105], v[30:31], v[0:1]
	s_nop 0
	v_add_f32_e32 v2, v2, v104
	v_add_f32_e32 v2, v2, v105
	v_mul_f32_e32 v4, 0xbfb8aa3b, v2
	v_exp_f32_e32 v4, v4
	v_pk_mul_f32 v[104:105], v[28:29], v[0:1]
	ds_read_u16 v0, v20 offset:33200
	v_add_f32_e32 v4, 1.0, v4
	v_rcp_f32_e32 v4, v4
	s_waitcnt lgkmcnt(0)
	v_lshlrev_b32_e32 v113, 16, v0
	v_mul_f32_e32 v72, v2, v4
	v_pk_mul_f32 v[4:5], v[30:31], v[96:97]
	v_add_f32_e32 v2, v6, v7
	v_add_f32_e32 v2, v2, v4
	v_add_f32_e32 v2, v2, v5
	v_mul_f32_e32 v4, 0xbfb8aa3b, v2
	v_exp_f32_e32 v4, v4
	s_nop 0
	v_add_f32_e32 v4, 1.0, v4
	v_rcp_f32_e32 v4, v4
	s_nop 0
	v_mul_f32_e32 v74, v2, v4
	ds_read_b128 v[0:3], v140 offset:176
	ds_read_u16 v4, v20 offset:33472
	v_pk_mul_f32 v[74:75], v[74:75], v[108:109]
	v_pk_mul_f32 v[108:109], v[28:29], v[96:97]
	v_pk_mov_b32 v[96:97], v[96:97], v[114:115] op_sel:[1,0]
	s_waitcnt lgkmcnt(1)
	v_mov_b32_e32 v146, v0
	s_waitcnt lgkmcnt(0)
	v_lshlrev_b32_e32 v81, 16, v4
	ds_read_b128 v[4:7], v25 offset:176
	v_pk_mul_f32 v[76:77], v[30:31], v[96:97]
	v_add_f32_e32 v0, v104, v105
	v_add_f32_e32 v0, v0, v76
	v_add_f32_e32 v0, v0, v77
	s_waitcnt lgkmcnt(0)
	v_mov_b32_e32 v147, v4
	v_mul_f32_e32 v4, 0xbfb8aa3b, v0
	v_exp_f32_e32 v4, v4
	s_nop 0
	v_add_f32_e32 v4, 1.0, v4
	v_rcp_f32_e32 v4, v4
	s_nop 0
	v_mul_f32_e32 v78, v0, v4
	v_pk_mul_f32 v[76:77], v[78:79], v[88:89]
	v_pk_mul_f32 v[78:79], v[30:31], v[114:115]
	v_add_f32_e32 v0, v108, v109
	v_add_f32_e32 v0, v0, v78
	v_add_f32_e32 v0, v0, v79
	v_mul_f32_e32 v4, 0xbfb8aa3b, v0
	v_exp_f32_e32 v4, v4
	v_pk_mul_f32 v[88:89], v[28:29], v[96:97]
	v_mov_b32_e32 v108, v2
	v_add_f32_e32 v2, v88, v89
	v_add_f32_e32 v4, 1.0, v4
	v_rcp_f32_e32 v4, v4
	v_mov_b32_e32 v109, v6
	v_pk_mul_f32 v[96:97], v[28:29], v[114:115]
	v_mul_f32_e32 v112, v0, v4
	ds_read_u16 v0, v20 offset:33744
	v_pk_mul_f32 v[78:79], v[112:113], v[110:111]
	v_lshlrev_b32_e32 v111, 16, v82
	v_lshlrev_b32_e32 v110, 16, v80
	v_mov_b32_e32 v4, v1
	s_waitcnt lgkmcnt(0)
	v_lshlrev_b32_e32 v83, 16, v0
	ds_read_u16 v0, v20 offset:34016
	v_pk_mul_f32 v[88:89], v[30:31], v[110:111]
	s_waitcnt lgkmcnt(0)
	v_lshlrev_b32_e32 v105, 16, v0
	v_pk_mov_b32 v[0:1], v[114:115], v[110:111] op_sel:[1,0]
	v_lshlrev_b32_e32 v115, 16, v87
	v_pk_mul_f32 v[112:113], v[30:31], v[0:1]
	v_lshlrev_b32_e32 v114, 16, v86
	v_add_f32_e32 v2, v2, v112
	v_add_f32_e32 v2, v2, v113
	v_mul_f32_e32 v6, 0xbfb8aa3b, v2
	v_exp_f32_e32 v6, v6
	s_nop 0
	v_add_f32_e32 v6, 1.0, v6
	v_rcp_f32_e32 v6, v6
	s_nop 0
	v_mul_f32_e32 v80, v2, v6
	v_add_f32_e32 v2, v96, v97
	v_add_f32_e32 v2, v2, v88
	v_add_f32_e32 v2, v2, v89
	v_mul_f32_e32 v6, 0xbfb8aa3b, v2
	v_exp_f32_e32 v6, v6
	v_pk_mul_f32 v[88:89], v[28:29], v[110:111]
	v_pk_mov_b32 v[110:111], v[110:111], v[114:115] op_sel:[1,0]
	v_add_f32_e32 v6, 1.0, v6
	v_rcp_f32_e32 v6, v6
	v_pk_mul_f32 v[86:87], v[30:31], v[110:111]
	v_mul_f32_e32 v82, v2, v6
	v_pk_mul_f32 v[82:83], v[82:83], v[4:5]
	v_pk_mul_f32 v[4:5], v[28:29], v[0:1]
	ds_read_u16 v0, v20 offset:34288
	v_mov_b32_e32 v6, v3
	s_waitcnt lgkmcnt(0)
	v_lshlrev_b32_e32 v97, 16, v0
	ds_read_b128 v[0:3], v140 offset:192
	ds_read_u16 v91, v20 offset:34560
	ds_read_b128 v[118:121], v25 offset:192
	s_waitcnt lgkmcnt(2)
	v_mov_b32_e32 v112, v0
	v_add_f32_e32 v0, v4, v5
	v_add_f32_e32 v0, v0, v86
	v_add_f32_e32 v0, v0, v87
	v_mul_f32_e32 v4, 0xbfb8aa3b, v0
	v_exp_f32_e32 v4, v4
	s_waitcnt lgkmcnt(1)
	v_lshlrev_b32_e32 v91, 16, v91
	v_add_f32_e32 v4, 1.0, v4
	v_rcp_f32_e32 v4, v4
	s_nop 0
	v_mul_f32_e32 v104, v0, v4
	v_pk_mul_f32 v[4:5], v[30:31], v[114:115]
	v_add_f32_e32 v0, v88, v89
	v_add_f32_e32 v0, v0, v4
	v_add_f32_e32 v0, v0, v5
	v_mul_f32_e32 v4, 0xbfb8aa3b, v0
	v_exp_f32_e32 v4, v4
	v_pk_mul_f32 v[86:87], v[104:105], v[108:109]
	v_lshlrev_b32_e32 v109, 16, v92
	v_lshlrev_b32_e32 v108, 16, v90
	v_add_f32_e32 v4, 1.0, v4
	v_rcp_f32_e32 v4, v4
	v_mov_b32_e32 v104, v2
	v_mul_f32_e32 v96, v0, v4
	ds_read_u16 v0, v20 offset:34832
	s_waitcnt lgkmcnt(1)
	v_mov_b32_e32 v113, v118
	v_pk_mul_f32 v[88:89], v[96:97], v[6:7]
	v_pk_mul_f32 v[4:5], v[28:29], v[110:111]
	v_mov_b32_e32 v118, v1
	s_waitcnt lgkmcnt(0)
	v_lshlrev_b32_e32 v93, 16, v0
	ds_read_u16 v0, v20 offset:35104
	v_add_f32_e32 v2, v4, v5
	v_pk_mul_f32 v[6:7], v[28:29], v[114:115]
	v_mov_b32_e32 v105, v120
	v_mov_b32_e32 v120, v3
	s_waitcnt lgkmcnt(0)
	v_lshlrev_b32_e32 v97, 16, v0
	v_pk_mov_b32 v[0:1], v[114:115], v[108:109] op_sel:[1,0]
	s_nop 0
	v_pk_mul_f32 v[110:111], v[30:31], v[0:1]
	s_nop 0
	v_add_f32_e32 v2, v2, v110
	v_add_f32_e32 v2, v2, v111
	v_mul_f32_e32 v4, 0xbfb8aa3b, v2
	v_exp_f32_e32 v4, v4
	s_nop 0
	v_add_f32_e32 v4, 1.0, v4
	v_rcp_f32_e32 v4, v4
	s_nop 0
	v_mul_f32_e32 v90, v2, v4
	v_pk_mul_f32 v[4:5], v[30:31], v[108:109]
	v_add_f32_e32 v2, v6, v7
	v_add_f32_e32 v2, v2, v4
	v_add_f32_e32 v2, v2, v5
	v_mul_f32_e32 v4, 0xbfb8aa3b, v2
	v_exp_f32_e32 v4, v4
	v_pk_mul_f32 v[6:7], v[28:29], v[108:109]
	v_add_f32_e32 v4, 1.0, v4
	v_rcp_f32_e32 v4, v4
	s_nop 0
	v_mul_f32_e32 v92, v2, v4
	v_pk_mul_f32 v[4:5], v[28:29], v[0:1]
	ds_read_u16 v0, v20 offset:35376
	v_pk_mul_f32 v[92:93], v[92:93], v[118:119]
	v_lshlrev_b32_e32 v119, 16, v95
	v_lshlrev_b32_e32 v118, 16, v94
	v_pk_mov_b32 v[108:109], v[108:109], v[118:119] op_sel:[1,0]
	s_waitcnt lgkmcnt(0)
	v_lshlrev_b32_e32 v115, 16, v0
	ds_read_b128 v[0:3], v140 offset:208
	ds_read_u16 v96, v20 offset:35648
	v_pk_mul_f32 v[94:95], v[30:31], v[108:109]
	ds_read_b128 v[208:211], v25 offset:208
	s_waitcnt lgkmcnt(2)
	v_mov_b32_e32 v110, v0
	v_add_f32_e32 v0, v4, v5
	v_add_f32_e32 v0, v0, v94
	v_add_f32_e32 v0, v0, v95
	v_mul_f32_e32 v4, 0xbfb8aa3b, v0
	v_exp_f32_e32 v4, v4
	s_waitcnt lgkmcnt(1)
	v_lshlrev_b32_e32 v99, 16, v96
	v_add_f32_e32 v4, 1.0, v4
	v_rcp_f32_e32 v4, v4
	s_nop 0
	v_mul_f32_e32 v96, v0, v4
	v_pk_mul_f32 v[4:5], v[30:31], v[118:119]
	v_add_f32_e32 v0, v6, v7
	v_add_f32_e32 v0, v0, v4
	v_add_f32_e32 v0, v0, v5
	v_mul_f32_e32 v4, 0xbfb8aa3b, v0
	v_exp_f32_e32 v4, v4
	v_pk_mul_f32 v[94:95], v[96:97], v[104:105]
	v_pk_mul_f32 v[6:7], v[28:29], v[118:119]
	v_add_f32_e32 v4, 1.0, v4
	v_rcp_f32_e32 v4, v4
	s_nop 0
	v_mul_f32_e32 v114, v0, v4
	ds_read_u16 v0, v20 offset:35920
	s_waitcnt lgkmcnt(1)
	v_mov_b32_e32 v111, v208
	v_pk_mul_f32 v[4:5], v[28:29], v[108:109]
	v_mov_b32_e32 v208, v1
	v_pk_mul_f32 v[96:97], v[114:115], v[120:121]
	s_waitcnt lgkmcnt(0)
	v_lshlrev_b32_e32 v101, 16, v0
	ds_read_u16 v0, v20 offset:36192
	v_mov_b32_e32 v120, v2
	v_add_f32_e32 v2, v4, v5
	v_mov_b32_e32 v121, v210
	v_mov_b32_e32 v210, v3
	s_waitcnt lgkmcnt(0)
	v_lshlrev_b32_e32 v105, 16, v0
	v_pk_mov_b32 v[0:1], v[118:119], v[144:145] op_sel:[1,0]
	v_lshlrev_b32_e32 v115, 16, v103
	v_pk_mul_f32 v[108:109], v[30:31], v[0:1]
	v_pk_mul_f32 v[118:119], v[28:29], v[0:1]
	v_add_f32_e32 v2, v2, v108
	v_add_f32_e32 v2, v2, v109
	v_mul_f32_e32 v4, 0xbfb8aa3b, v2
	v_exp_f32_e32 v4, v4
	ds_read_u16 v0, v20 offset:36464
	v_lshlrev_b32_e32 v114, 16, v102
	v_add_f32_e32 v4, 1.0, v4
	v_rcp_f32_e32 v4, v4
	s_nop 0
	v_mul_f32_e32 v98, v2, v4
	v_pk_mul_f32 v[4:5], v[30:31], v[144:145]
	v_add_f32_e32 v2, v6, v7
	v_add_f32_e32 v2, v2, v4
	v_add_f32_e32 v2, v2, v5
	v_mul_f32_e32 v4, 0xbfb8aa3b, v2
	v_exp_f32_e32 v4, v4
	v_pk_mov_b32 v[144:145], v[144:145], v[114:115] op_sel:[1,0]
	v_add_f32_e32 v4, 1.0, v4
	v_rcp_f32_e32 v4, v4
	v_pk_mul_f32 v[102:103], v[30:31], v[144:145]
	v_mul_f32_e32 v100, v2, v4
	v_pk_mul_f32 v[100:101], v[100:101], v[208:209]
	s_waitcnt lgkmcnt(0)
	v_lshlrev_b32_e32 v209, 16, v0
	ds_read_b128 v[4:7], v140 offset:224
	ds_read_u16 v0, v20 offset:36736
	s_waitcnt lgkmcnt(1)
	v_mov_b32_e32 v108, v4
	s_waitcnt lgkmcnt(0)
	v_lshlrev_b32_e32 v107, 16, v0
	ds_read_b128 v[0:3], v25 offset:224
	s_waitcnt lgkmcnt(0)
	v_mov_b32_e32 v109, v0
	v_add_f32_e32 v0, v118, v119
	v_add_f32_e32 v0, v0, v102
	v_add_f32_e32 v0, v0, v103
	v_mul_f32_e32 v4, 0xbfb8aa3b, v0
	v_exp_f32_e32 v4, v4
	v_pk_mul_f32 v[118:119], v[28:29], v[114:115]
	v_add_f32_e32 v4, 1.0, v4
	v_rcp_f32_e32 v4, v4
	s_nop 0
	v_mul_f32_e32 v104, v0, v4
	v_pk_mul_f32 v[102:103], v[104:105], v[120:121]
	v_pk_mul_f32 v[104:105], v[30:31], v[114:115]
	v_add_f32_e32 v0, v148, v149
	v_add_f32_e32 v0, v0, v104
	v_add_f32_e32 v0, v0, v105
	v_mul_f32_e32 v4, 0xbfb8aa3b, v0
	v_exp_f32_e32 v4, v4
	v_pk_mul_f32 v[120:121], v[28:29], v[144:145]
	v_add_f32_e32 v4, 1.0, v4
	v_rcp_f32_e32 v4, v4
	s_nop 0
	v_mul_f32_e32 v208, v0, v4
	ds_read_u16 v0, v20 offset:37008
	ds_read_u16 v4, v20 offset:37280
	v_pk_mul_f32 v[104:105], v[208:209], v[210:211]
	v_lshlrev_b32_e32 v211, 16, v116
	v_lshlrev_b32_e32 v210, 16, v106
	s_waitcnt lgkmcnt(1)
	v_lshlrev_b32_e32 v117, 16, v0
	v_mov_b32_e32 v0, v5
	s_waitcnt lgkmcnt(0)
	v_lshlrev_b32_e32 v145, 16, v4
	v_pk_mov_b32 v[4:5], v[114:115], v[210:211] op_sel:[1,0]
	v_mov_b32_e32 v209, v2
	v_pk_mul_f32 v[114:115], v[30:31], v[4:5]
	v_add_f32_e32 v2, v120, v121
	v_add_f32_e32 v2, v2, v114
	v_add_f32_e32 v2, v2, v115
	v_mov_b32_e32 v208, v6
	v_mul_f32_e32 v6, 0xbfb8aa3b, v2
	v_exp_f32_e32 v6, v6
	v_pk_mul_f32 v[114:115], v[30:31], v[210:211]
	v_add_f32_e32 v6, 1.0, v6
	v_rcp_f32_e32 v6, v6
	s_nop 0
	v_mul_f32_e32 v106, v2, v6
	v_add_f32_e32 v2, v118, v119
	v_add_f32_e32 v2, v2, v114
	v_add_f32_e32 v2, v2, v115
	v_mul_f32_e32 v6, 0xbfb8aa3b, v2
	v_exp_f32_e32 v6, v6
	s_nop 0
	v_add_f32_e32 v6, 1.0, v6
	v_rcp_f32_e32 v6, v6
	s_nop 0
	v_mul_f32_e32 v116, v2, v6
	v_pk_mul_f32 v[148:149], v[116:117], v[0:1]
	v_pk_mul_f32 v[0:1], v[28:29], v[4:5]
	v_pk_mul_f32 v[116:117], v[28:29], v[210:211]
	v_pk_mov_b32 v[210:211], v[210:211], v[214:215] op_sel:[1,0]
	v_add_f32_e32 v0, v0, v1
	v_pk_mul_f32 v[142:143], v[30:31], v[210:211]
	ds_read_u16 v2, v20 offset:37552
	v_add_f32_e32 v0, v0, v142
	v_add_f32_e32 v0, v0, v143
	v_mul_f32_e32 v1, 0xbfb8aa3b, v0
	v_exp_f32_e32 v1, v1
	s_waitcnt lgkmcnt(0)
	v_lshlrev_b32_e32 v213, 16, v2
	v_mov_b32_e32 v2, v7
	ds_read_b128 v[4:7], v140 offset:240
	ds_read_u16 v114, v20 offset:37824
	v_add_f32_e32 v1, 1.0, v1
	v_rcp_f32_e32 v1, v1
	ds_read_b128 v[118:121], v25 offset:240
	s_waitcnt lgkmcnt(2)
	v_mov_b32_e32 v140, v4
	v_add_f32_e32 v4, v116, v117
	v_mul_f32_e32 v144, v0, v1
	v_pk_mul_f32 v[0:1], v[30:31], v[214:215]
	s_waitcnt lgkmcnt(1)
	v_lshlrev_b32_e32 v115, 16, v114
	v_add_f32_e32 v0, v4, v0
	v_add_f32_e32 v0, v0, v1
	v_mul_f32_e32 v1, 0xbfb8aa3b, v0
	v_exp_f32_e32 v1, v1
	ds_read_u16 v4, v20 offset:38096
	s_waitcnt lgkmcnt(1)
	v_mov_b32_e32 v141, v118
	v_mov_b32_e32 v118, v5
	v_add_f32_e32 v1, 1.0, v1
	v_rcp_f32_e32 v1, v1
	s_waitcnt lgkmcnt(0)
	v_lshlrev_b32_e32 v117, 16, v4
	ds_read_u16 v4, v20 offset:38368
	v_pk_mul_f32 v[144:145], v[144:145], v[208:209]
	v_mul_f32_e32 v212, v0, v1
	v_pk_mul_f32 v[0:1], v[28:29], v[210:211]
	v_pk_mov_b32 v[210:211], v[214:215], v[138:139] op_sel:[1,0]
	v_pk_mul_f32 v[142:143], v[212:213], v[2:3]
	v_pk_mul_f32 v[212:213], v[30:31], v[210:211]
	v_add_f32_e32 v0, v0, v1
	v_add_f32_e32 v0, v0, v212
	v_add_f32_e32 v0, v0, v213
	v_mul_f32_e32 v1, 0xbfb8aa3b, v0
	v_exp_f32_e32 v1, v1
	v_pk_mul_f32 v[2:3], v[28:29], v[214:215]
	s_waitcnt lgkmcnt(0)
	v_lshlrev_b32_e32 v5, 16, v4
	v_add_f32_e32 v2, v2, v3
	v_add_f32_e32 v1, 1.0, v1
	v_rcp_f32_e32 v1, v1
	v_mov_b32_e32 v209, v120
	v_mov_b32_e32 v120, v7
	v_mov_b32_e32 v208, v6
	v_mul_f32_e32 v114, v0, v1
	v_pk_mul_f32 v[0:1], v[30:31], v[138:139]
	s_nop 0
	v_add_f32_e32 v0, v2, v0
	v_add_f32_e32 v0, v0, v1
	v_mul_f32_e32 v1, 0xbfb8aa3b, v0
	v_exp_f32_e32 v1, v1
	v_pk_mul_f32 v[2:3], v[28:29], v[138:139]
	v_add_f32_e32 v1, 1.0, v1
	v_rcp_f32_e32 v1, v1
	v_add_f32_e32 v2, v2, v3
	v_mul_f32_e32 v116, v0, v1
	v_pk_mul_f32 v[0:1], v[28:29], v[210:211]
	v_lshlrev_b32_e32 v28, 16, v137
	v_lshlrev_b32_e32 v29, 16, v207
	v_pk_mul_f32 v[116:117], v[116:117], v[118:119]
	v_pk_mov_b32 v[118:119], v[138:139], v[28:29] op_sel:[1,0]
	v_add_f32_e32 v0, v0, v1
	v_pk_mul_f32 v[118:119], v[30:31], v[118:119]
	s_nop 0
	v_add_f32_e32 v0, v0, v118
	v_add_f32_e32 v0, v0, v119
	v_mul_f32_e32 v1, 0xbfb8aa3b, v0
	v_exp_f32_e32 v1, v1
	s_nop 0
	v_add_f32_e32 v1, 1.0, v1
	v_rcp_f32_e32 v1, v1
	s_nop 0
	v_mul_f32_e32 v4, v0, v1
	v_pk_mul_f32 v[0:1], v[30:31], v[28:29]
	v_pk_mul_f32 v[118:119], v[4:5], v[208:209]
	v_add_f32_e32 v0, v2, v0
	v_add_f32_e32 v0, v0, v1
	v_mul_f32_e32 v1, 0xbfb8aa3b, v0
	v_exp_f32_e32 v1, v1
	s_nop 0
	v_add_f32_e32 v1, 1.0, v1
	v_rcp_f32_e32 v1, v1
	s_nop 0
	v_mul_f32_e32 v0, v0, v1
	ds_read_u16 v1, v20 offset:38640
	v_lshl_add_u32 v20, v136, 14, v196
	s_waitcnt lgkmcnt(0)
	s_barrier
	v_lshlrev_b32_e32 v1, 16, v1
	v_pk_mul_f32 v[120:121], v[0:1], v[120:121]
	ds_read_b128 v[0:3], v20 offset:39168
	s_waitcnt lgkmcnt(0)
	v_pk_fma_f32 v[4:5], v[130:131], v[0:1], 0 op_sel:[0,1,0] op_sel_hi:[1,1,0] neg_lo:[1,0,0] neg_hi:[1,0,0]
	v_pk_fma_f32 v[0:1], v[128:129], v[0:1], v[130:131] op_sel_hi:[1,0,1] neg_lo:[1,0,0] neg_hi:[1,0,0]
	v_pk_fma_f32 v[4:5], v[134:135], v[2:3], v[4:5] op_sel:[0,1,0] neg_lo:[1,0,0] neg_hi:[1,0,0]
	v_pk_fma_f32 v[0:1], v[132:133], v[2:3], v[0:1] op_sel_hi:[1,0,1] neg_lo:[1,0,0] neg_hi:[1,0,0]
	ds_read_b128 v[28:31], v20 offset:41248
	v_pk_add_f32 v[138:139], v[0:1], v[4:5]
	ds_read_b128 v[0:3], v20 offset:39424
	s_waitcnt lgkmcnt(0)
	v_pk_fma_f32 v[4:5], v[0:1], v[138:139], 0 op_sel:[1,0,0] op_sel_hi:[1,1,0] neg_lo:[1,0,0] neg_hi:[1,0,0]
	v_pk_fma_f32 v[0:1], v[128:129], v[0:1], v[132:133] op_sel_hi:[1,0,1] neg_lo:[1,0,0] neg_hi:[1,0,0]
	v_pk_fma_f32 v[4:5], v[134:135], v[2:3], v[4:5] op_sel:[0,1,0] neg_lo:[1,0,0] neg_hi:[1,0,0]
	v_pk_fma_f32 v[0:1], v[132:133], v[2:3], v[0:1] op_sel_hi:[1,0,1] neg_lo:[1,0,0] neg_hi:[1,0,0]
	ds_read_b128 v[208:211], v20 offset:44368
	v_pk_add_f32 v[136:137], v[0:1], v[4:5]
	ds_read_b128 v[0:3], v20 offset:39680
	s_waitcnt lgkmcnt(0)
	v_pk_fma_f32 v[4:5], v[0:1], v[138:139], 0 op_sel:[1,0,0] op_sel_hi:[1,1,0] neg_lo:[1,0,0] neg_hi:[1,0,0]
	v_pk_fma_f32 v[0:1], v[128:129], v[0:1], v[134:135] op_sel_hi:[1,0,1] neg_lo:[1,0,0] neg_hi:[1,0,0]
	v_pk_fma_f32 v[4:5], v[134:135], v[2:3], v[4:5] op_sel:[0,1,0] neg_lo:[1,0,0] neg_hi:[1,0,0]
	v_pk_fma_f32 v[0:1], v[2:3], v[136:137], v[0:1] op_sel_hi:[0,1,1] neg_lo:[1,0,0] neg_hi:[1,0,0]
	ds_read_b128 v[212:215], v20 offset:46448
	v_pk_add_f32 v[134:135], v[4:5], v[0:1]
	ds_read_b128 v[0:3], v20 offset:39936
	s_waitcnt lgkmcnt(0)
	v_pk_fma_f32 v[4:5], v[0:1], v[138:139], 0 op_sel:[1,0,0] op_sel_hi:[1,1,0] neg_lo:[1,0,0] neg_hi:[1,0,0]
	v_pk_mul_f32 v[0:1], v[128:129], v[0:1] op_sel_hi:[1,0]
	v_pk_fma_f32 v[4:5], v[2:3], v[134:135], v[4:5] op_sel:[1,0,0] neg_lo:[1,0,0] neg_hi:[1,0,0]
	v_pk_fma_f32 v[0:1], v[16:17], v[84:85], v[0:1] neg_lo:[0,0,1] neg_hi:[0,0,1]
	ds_read_b128 v[216:219], v20 offset:49568
	v_pk_fma_f32 v[0:1], v[2:3], v[136:137], v[0:1] op_sel_hi:[0,1,1] neg_lo:[1,0,0] neg_hi:[1,0,0]
	ds_read_b128 v[220:223], v20 offset:50608
	v_pk_add_f32 v[132:133], v[0:1], v[4:5]
	ds_read_b128 v[0:3], v20 offset:40192
	ds_read_b128 v[4:7], v20 offset:40208
	s_waitcnt lgkmcnt(1)
	v_pk_fma_f32 v[16:17], v[0:1], v[138:139], 0 op_sel:[1,0,0] op_sel_hi:[1,1,0] neg_lo:[1,0,0] neg_hi:[1,0,0]
	v_pk_fma_f32 v[0:1], v[128:129], v[0:1], v[122:123] op_sel_hi:[1,0,1] neg_lo:[1,0,0] neg_hi:[1,0,0]
	v_pk_fma_f32 v[16:17], v[2:3], v[134:135], v[16:17] op_sel:[1,0,0] neg_lo:[1,0,0] neg_hi:[1,0,0]
	v_pk_fma_f32 v[0:1], v[2:3], v[136:137], v[0:1] op_sel_hi:[0,1,1] neg_lo:[1,0,0] neg_hi:[1,0,0]
	s_waitcnt lgkmcnt(0)
	v_pk_fma_f32 v[16:17], v[122:123], v[4:5], v[16:17] op_sel:[0,1,0] neg_lo:[1,0,0] neg_hi:[1,0,0]
	v_pk_fma_f32 v[0:1], v[4:5], v[132:133], v[0:1] op_sel_hi:[0,1,1] neg_lo:[1,0,0] neg_hi:[1,0,0]
	v_pk_fma_f32 v[16:17], v[184:185], v[6:7], v[16:17] op_sel:[0,1,0] neg_lo:[1,0,0] neg_hi:[1,0,0]
	v_pk_fma_f32 v[0:1], v[186:187], v[6:7], v[0:1] op_sel_hi:[1,0,1] neg_lo:[1,0,0] neg_hi:[1,0,0]
	ds_read_b128 v[4:7], v20 offset:40464
	v_pk_add_f32 v[130:131], v[16:17], v[0:1]
	ds_read_b128 v[0:3], v20 offset:40448
	s_waitcnt lgkmcnt(0)
	v_pk_fma_f32 v[16:17], v[138:139], v[0:1], 0 op_sel:[0,1,0] op_sel_hi:[1,1,0] neg_lo:[1,0,0] neg_hi:[1,0,0]
	v_pk_fma_f32 v[0:1], v[128:129], v[0:1], v[186:187] op_sel_hi:[1,0,1] neg_lo:[1,0,0] neg_hi:[1,0,0]
	v_pk_fma_f32 v[16:17], v[2:3], v[134:135], v[16:17] op_sel:[1,0,0] neg_lo:[1,0,0] neg_hi:[1,0,0]
	v_pk_fma_f32 v[0:1], v[2:3], v[136:137], v[0:1] op_sel_hi:[0,1,1] neg_lo:[1,0,0] neg_hi:[1,0,0]
	v_pk_fma_f32 v[16:17], v[4:5], v[130:131], v[16:17] op_sel:[1,0,0] neg_lo:[1,0,0] neg_hi:[1,0,0]
	v_pk_fma_f32 v[0:1], v[4:5], v[132:133], v[0:1] op_sel_hi:[0,1,1] neg_lo:[1,0,0] neg_hi:[1,0,0]
	v_pk_fma_f32 v[16:17], v[184:185], v[6:7], v[16:17] op_sel:[0,1,0] neg_lo:[1,0,0] neg_hi:[1,0,0]
	v_pk_fma_f32 v[0:1], v[186:187], v[6:7], v[0:1] op_sel_hi:[1,0,1] neg_lo:[1,0,0] neg_hi:[1,0,0]
	ds_read_b128 v[4:7], v20 offset:40720
	v_pk_add_f32 v[122:123], v[0:1], v[16:17]
	ds_read_b128 v[0:3], v20 offset:40704
	s_waitcnt lgkmcnt(0)
	v_pk_fma_f32 v[16:17], v[138:139], v[0:1], 0 op_sel:[0,1,0] op_sel_hi:[1,1,0] neg_lo:[1,0,0] neg_hi:[1,0,0]
	v_pk_fma_f32 v[0:1], v[128:129], v[0:1], v[184:185] op_sel_hi:[1,0,1] neg_lo:[1,0,0] neg_hi:[1,0,0]
	v_pk_fma_f32 v[16:17], v[2:3], v[134:135], v[16:17] op_sel:[1,0,0] neg_lo:[1,0,0] neg_hi:[1,0,0]
	v_pk_fma_f32 v[0:1], v[2:3], v[136:137], v[0:1] op_sel_hi:[0,1,1] neg_lo:[1,0,0] neg_hi:[1,0,0]
	v_pk_fma_f32 v[16:17], v[4:5], v[130:131], v[16:17] op_sel:[1,0,0] neg_lo:[1,0,0] neg_hi:[1,0,0]
	v_pk_fma_f32 v[0:1], v[4:5], v[132:133], v[0:1] op_sel_hi:[0,1,1] neg_lo:[1,0,0] neg_hi:[1,0,0]
	v_pk_fma_f32 v[16:17], v[184:185], v[6:7], v[16:17] op_sel:[0,1,0] neg_lo:[1,0,0] neg_hi:[1,0,0]
	v_pk_fma_f32 v[0:1], v[6:7], v[122:123], v[0:1] op_sel_hi:[0,1,1] neg_lo:[1,0,0] neg_hi:[1,0,0]
	ds_read_b128 v[4:7], v20 offset:40976
	v_pk_add_f32 v[84:85], v[16:17], v[0:1]
	ds_read_b128 v[0:3], v20 offset:40960
	s_waitcnt lgkmcnt(0)
	v_pk_fma_f32 v[16:17], v[138:139], v[0:1], 0 op_sel:[0,1,0] op_sel_hi:[1,1,0] neg_lo:[1,0,0] neg_hi:[1,0,0]
	v_pk_mul_f32 v[0:1], v[128:129], v[0:1] op_sel_hi:[1,0]
	v_pk_fma_f32 v[16:17], v[2:3], v[134:135], v[16:17] op_sel:[1,0,0] neg_lo:[1,0,0] neg_hi:[1,0,0]
	v_pk_fma_f32 v[0:1], v[10:11], v[14:15], v[0:1] neg_lo:[0,0,1] neg_hi:[0,0,1]
	v_pk_fma_f32 v[16:17], v[4:5], v[130:131], v[16:17] op_sel:[1,0,0] neg_lo:[1,0,0] neg_hi:[1,0,0]
	v_pk_fma_f32 v[0:1], v[136:137], v[2:3], v[0:1] op_sel_hi:[1,0,1] neg_lo:[1,0,0] neg_hi:[1,0,0]
	v_pk_fma_f32 v[16:17], v[6:7], v[84:85], v[16:17] op_sel:[1,0,0] neg_lo:[1,0,0] neg_hi:[1,0,0]
	v_pk_fma_f32 v[0:1], v[4:5], v[132:133], v[0:1] op_sel_hi:[0,1,1] neg_lo:[1,0,0] neg_hi:[1,0,0]
	ds_read_b128 v[184:187], v20 offset:42288
	v_pk_fma_f32 v[0:1], v[6:7], v[122:123], v[0:1] op_sel_hi:[0,1,1] neg_lo:[1,0,0] neg_hi:[1,0,0]
	ds_read_b128 v[4:7], v20 offset:41232
	v_pk_add_f32 v[14:15], v[0:1], v[16:17]
	ds_read_b128 v[0:3], v20 offset:41216
	s_waitcnt lgkmcnt(0)
	v_pk_fma_f32 v[10:11], v[138:139], v[0:1], 0 op_sel:[0,1,0] op_sel_hi:[1,1,0] neg_lo:[1,0,0] neg_hi:[1,0,0]
	v_pk_fma_f32 v[0:1], v[128:129], v[0:1], v[182:183] op_sel_hi:[1,0,1] neg_lo:[1,0,0] neg_hi:[1,0,0]
	v_pk_fma_f32 v[10:11], v[134:135], v[2:3], v[10:11] op_sel:[0,1,0] neg_lo:[1,0,0] neg_hi:[1,0,0]
	v_pk_fma_f32 v[0:1], v[136:137], v[2:3], v[0:1] op_sel_hi:[1,0,1] neg_lo:[1,0,0] neg_hi:[1,0,0]
	v_pk_fma_f32 v[10:11], v[4:5], v[130:131], v[10:11] op_sel:[1,0,0] neg_lo:[1,0,0] neg_hi:[1,0,0]
	v_pk_fma_f32 v[0:1], v[4:5], v[132:133], v[0:1] op_sel_hi:[0,1,1] neg_lo:[1,0,0] neg_hi:[1,0,0]
	v_pk_fma_f32 v[10:11], v[6:7], v[84:85], v[10:11] op_sel:[1,0,0] neg_lo:[1,0,0] neg_hi:[1,0,0]
	v_pk_fma_f32 v[0:1], v[6:7], v[122:123], v[0:1] op_sel_hi:[0,1,1] neg_lo:[1,0,0] neg_hi:[1,0,0]
	ds_read_b128 v[4:7], v20 offset:41488
	v_pk_fma_f32 v[10:11], v[182:183], v[28:29], v[10:11] op_sel:[0,1,0] neg_lo:[1,0,0] neg_hi:[1,0,0]
	v_pk_fma_f32 v[0:1], v[28:29], v[14:15], v[0:1] op_sel_hi:[0,1,1] neg_lo:[1,0,0] neg_hi:[1,0,0]
	v_pk_fma_f32 v[10:11], v[18:19], v[30:31], v[10:11] op_sel:[0,1,0] neg_lo:[1,0,0] neg_hi:[1,0,0]
	v_pk_fma_f32 v[0:1], v[180:181], v[30:31], v[0:1] op_sel_hi:[1,0,1] neg_lo:[1,0,0] neg_hi:[1,0,0]
	ds_read_b128 v[28:31], v20 offset:41504
	v_pk_add_f32 v[10:11], v[10:11], v[0:1]
	ds_read_b128 v[0:3], v20 offset:41472
	s_waitcnt lgkmcnt(0)
	v_pk_fma_f32 v[16:17], v[138:139], v[0:1], 0 op_sel:[0,1,0] op_sel_hi:[1,1,0] neg_lo:[1,0,0] neg_hi:[1,0,0]
	v_pk_fma_f32 v[0:1], v[128:129], v[0:1], v[180:181] op_sel_hi:[1,0,1] neg_lo:[1,0,0] neg_hi:[1,0,0]
	v_pk_fma_f32 v[16:17], v[134:135], v[2:3], v[16:17] op_sel:[0,1,0] neg_lo:[1,0,0] neg_hi:[1,0,0]
	v_pk_fma_f32 v[0:1], v[136:137], v[2:3], v[0:1] op_sel_hi:[1,0,1] neg_lo:[1,0,0] neg_hi:[1,0,0]
	v_pk_fma_f32 v[16:17], v[4:5], v[130:131], v[16:17] op_sel:[1,0,0] neg_lo:[1,0,0] neg_hi:[1,0,0]
	v_pk_fma_f32 v[0:1], v[132:133], v[4:5], v[0:1] op_sel_hi:[1,0,1] neg_lo:[1,0,0] neg_hi:[1,0,0]
	v_pk_fma_f32 v[16:17], v[6:7], v[84:85], v[16:17] op_sel:[1,0,0] neg_lo:[1,0,0] neg_hi:[1,0,0]
	v_pk_fma_f32 v[0:1], v[6:7], v[122:123], v[0:1] op_sel_hi:[0,1,1] neg_lo:[1,0,0] neg_hi:[1,0,0]
	ds_read_b128 v[4:7], v20 offset:41744
	v_pk_fma_f32 v[16:17], v[28:29], v[10:11], v[16:17] op_sel:[1,0,0] neg_lo:[1,0,0] neg_hi:[1,0,0]
	v_pk_fma_f32 v[0:1], v[28:29], v[14:15], v[0:1] op_sel_hi:[0,1,1] neg_lo:[1,0,0] neg_hi:[1,0,0]
	v_pk_fma_f32 v[16:17], v[18:19], v[30:31], v[16:17] op_sel:[0,1,0] neg_lo:[1,0,0] neg_hi:[1,0,0]
	v_pk_fma_f32 v[0:1], v[180:181], v[30:31], v[0:1] op_sel_hi:[1,0,1] neg_lo:[1,0,0] neg_hi:[1,0,0]
	ds_read_b128 v[28:31], v20 offset:41760
	v_pk_add_f32 v[16:17], v[0:1], v[16:17]
	ds_read_b128 v[0:3], v20 offset:41728
	s_waitcnt lgkmcnt(0)
	v_pk_fma_f32 v[180:181], v[138:139], v[0:1], 0 op_sel:[0,1,0] op_sel_hi:[1,1,0] neg_lo:[1,0,0] neg_hi:[1,0,0]
	v_pk_fma_f32 v[0:1], v[128:129], v[0:1], v[18:19] op_sel_hi:[1,0,1] neg_lo:[1,0,0] neg_hi:[1,0,0]
	v_pk_fma_f32 v[180:181], v[134:135], v[2:3], v[180:181] op_sel:[0,1,0] neg_lo:[1,0,0] neg_hi:[1,0,0]
	v_pk_fma_f32 v[0:1], v[136:137], v[2:3], v[0:1] op_sel_hi:[1,0,1] neg_lo:[1,0,0] neg_hi:[1,0,0]
	v_pk_fma_f32 v[180:181], v[130:131], v[4:5], v[180:181] op_sel:[0,1,0] neg_lo:[1,0,0] neg_hi:[1,0,0]
	v_pk_fma_f32 v[0:1], v[132:133], v[4:5], v[0:1] op_sel_hi:[1,0,1] neg_lo:[1,0,0] neg_hi:[1,0,0]
	v_pk_fma_f32 v[180:181], v[6:7], v[84:85], v[180:181] op_sel:[1,0,0] neg_lo:[1,0,0] neg_hi:[1,0,0]
	v_pk_fma_f32 v[0:1], v[6:7], v[122:123], v[0:1] op_sel_hi:[0,1,1] neg_lo:[1,0,0] neg_hi:[1,0,0]
	v_pk_fma_f32 v[180:181], v[28:29], v[10:11], v[180:181] op_sel:[1,0,0] neg_lo:[1,0,0] neg_hi:[1,0,0]
	v_pk_fma_f32 v[0:1], v[28:29], v[14:15], v[0:1] op_sel_hi:[0,1,1] neg_lo:[1,0,0] neg_hi:[1,0,0]
	v_pk_fma_f32 v[180:181], v[18:19], v[30:31], v[180:181] op_sel:[0,1,0] neg_lo:[1,0,0] neg_hi:[1,0,0]
	v_pk_fma_f32 v[0:1], v[30:31], v[16:17], v[0:1] op_sel_hi:[0,1,1] neg_lo:[1,0,0] neg_hi:[1,0,0]
	ds_read_b128 v[28:31], v20 offset:42000
	v_pk_add_f32 v[6:7], v[180:181], v[0:1]
	ds_read_b128 v[0:3], v20 offset:41984
	ds_read_b128 v[180:183], v20 offset:42016
	s_waitcnt lgkmcnt(1)
	v_pk_fma_f32 v[4:5], v[138:139], v[0:1], 0 op_sel:[0,1,0] op_sel_hi:[1,1,0] neg_lo:[1,0,0] neg_hi:[1,0,0]
	v_pk_mul_f32 v[0:1], v[128:129], v[0:1] op_sel_hi:[1,0]
	v_pk_fma_f32 v[4:5], v[134:135], v[2:3], v[4:5] op_sel:[0,1,0] neg_lo:[1,0,0] neg_hi:[1,0,0]
	v_pk_fma_f32 v[0:1], v[8:9], v[12:13], v[0:1] neg_lo:[0,0,1] neg_hi:[0,0,1]
	v_pk_fma_f32 v[4:5], v[130:131], v[28:29], v[4:5] op_sel:[0,1,0] neg_lo:[1,0,0] neg_hi:[1,0,0]
	v_pk_fma_f32 v[0:1], v[136:137], v[2:3], v[0:1] op_sel_hi:[1,0,1] neg_lo:[1,0,0] neg_hi:[1,0,0]
	v_pk_fma_f32 v[4:5], v[30:31], v[84:85], v[4:5] op_sel:[1,0,0] neg_lo:[1,0,0] neg_hi:[1,0,0]
	v_pk_fma_f32 v[0:1], v[132:133], v[28:29], v[0:1] op_sel_hi:[1,0,1] neg_lo:[1,0,0] neg_hi:[1,0,0]
	s_waitcnt lgkmcnt(0)
	v_pk_fma_f32 v[4:5], v[180:181], v[10:11], v[4:5] op_sel:[1,0,0] neg_lo:[1,0,0] neg_hi:[1,0,0]
	v_pk_fma_f32 v[0:1], v[30:31], v[122:123], v[0:1] op_sel_hi:[0,1,1] neg_lo:[1,0,0] neg_hi:[1,0,0]
	ds_read_b128 v[28:31], v20 offset:42256
	v_pk_fma_f32 v[0:1], v[180:181], v[14:15], v[0:1] op_sel_hi:[0,1,1] neg_lo:[1,0,0] neg_hi:[1,0,0]
	v_pk_fma_f32 v[4:5], v[182:183], v[6:7], v[4:5] op_sel:[1,0,0] neg_lo:[1,0,0] neg_hi:[1,0,0]
	v_pk_fma_f32 v[0:1], v[182:183], v[16:17], v[0:1] op_sel_hi:[0,1,1] neg_lo:[1,0,0] neg_hi:[1,0,0]
	ds_read_b128 v[180:183], v20 offset:42272
	v_pk_add_f32 v[18:19], v[0:1], v[4:5]
	ds_read_b128 v[0:3], v20 offset:42240
	s_waitcnt lgkmcnt(0)
	v_pk_fma_f32 v[4:5], v[138:139], v[0:1], 0 op_sel:[0,1,0] op_sel_hi:[1,1,0] neg_lo:[1,0,0] neg_hi:[1,0,0]
	v_pk_fma_f32 v[0:1], v[128:129], v[0:1], v[178:179] op_sel_hi:[1,0,1] neg_lo:[1,0,0] neg_hi:[1,0,0]
	v_pk_fma_f32 v[4:5], v[134:135], v[2:3], v[4:5] op_sel:[0,1,0] neg_lo:[1,0,0] neg_hi:[1,0,0]
	v_pk_fma_f32 v[0:1], v[136:137], v[2:3], v[0:1] op_sel_hi:[1,0,1] neg_lo:[1,0,0] neg_hi:[1,0,0]
	v_pk_fma_f32 v[4:5], v[130:131], v[28:29], v[4:5] op_sel:[0,1,0] neg_lo:[1,0,0] neg_hi:[1,0,0]
	v_pk_fma_f32 v[0:1], v[132:133], v[28:29], v[0:1] op_sel_hi:[1,0,1] neg_lo:[1,0,0] neg_hi:[1,0,0]
	v_pk_fma_f32 v[4:5], v[30:31], v[84:85], v[4:5] op_sel:[1,0,0] neg_lo:[1,0,0] neg_hi:[1,0,0]
	v_pk_fma_f32 v[0:1], v[122:123], v[30:31], v[0:1] op_sel_hi:[1,0,1] neg_lo:[1,0,0] neg_hi:[1,0,0]
	ds_read_b128 v[28:31], v20 offset:42512
	v_pk_fma_f32 v[4:5], v[180:181], v[10:11], v[4:5] op_sel:[1,0,0] neg_lo:[1,0,0] neg_hi:[1,0,0]
	v_pk_fma_f32 v[0:1], v[180:181], v[14:15], v[0:1] op_sel_hi:[0,1,1] neg_lo:[1,0,0] neg_hi:[1,0,0]
	v_pk_fma_f32 v[4:5], v[182:183], v[6:7], v[4:5] op_sel:[1,0,0] neg_lo:[1,0,0] neg_hi:[1,0,0]
	v_pk_fma_f32 v[0:1], v[182:183], v[16:17], v[0:1] op_sel_hi:[0,1,1] neg_lo:[1,0,0] neg_hi:[1,0,0]
	v_pk_fma_f32 v[4:5], v[178:179], v[184:185], v[4:5] op_sel:[0,1,0] neg_lo:[1,0,0] neg_hi:[1,0,0]
	ds_read_b128 v[178:181], v20 offset:42528
	v_pk_fma_f32 v[0:1], v[184:185], v[18:19], v[0:1] op_sel_hi:[0,1,1] neg_lo:[1,0,0] neg_hi:[1,0,0]
	ds_read_b128 v[182:185], v20 offset:42544
	v_pk_fma_f32 v[4:5], v[174:175], v[186:187], v[4:5] op_sel:[0,1,0] neg_lo:[1,0,0] neg_hi:[1,0,0]
	v_pk_fma_f32 v[0:1], v[176:177], v[186:187], v[0:1] op_sel_hi:[1,0,1] neg_lo:[1,0,0] neg_hi:[1,0,0]
	ds_read_b128 v[224:227], v20 offset:51648
	v_pk_add_f32 v[12:13], v[4:5], v[0:1]
	ds_read_b128 v[0:3], v20 offset:42496
	s_waitcnt lgkmcnt(0)
	v_pk_fma_f32 v[4:5], v[138:139], v[0:1], 0 op_sel:[0,1,0] op_sel_hi:[1,1,0] neg_lo:[1,0,0] neg_hi:[1,0,0]
	v_pk_fma_f32 v[0:1], v[128:129], v[0:1], v[176:177] op_sel_hi:[1,0,1] neg_lo:[1,0,0] neg_hi:[1,0,0]
	v_pk_fma_f32 v[4:5], v[134:135], v[2:3], v[4:5] op_sel:[0,1,0] neg_lo:[1,0,0] neg_hi:[1,0,0]
	v_pk_fma_f32 v[0:1], v[136:137], v[2:3], v[0:1] op_sel_hi:[1,0,1] neg_lo:[1,0,0] neg_hi:[1,0,0]
	v_pk_fma_f32 v[4:5], v[130:131], v[28:29], v[4:5] op_sel:[0,1,0] neg_lo:[1,0,0] neg_hi:[1,0,0]
	v_pk_fma_f32 v[0:1], v[132:133], v[28:29], v[0:1] op_sel_hi:[1,0,1] neg_lo:[1,0,0] neg_hi:[1,0,0]
	v_pk_fma_f32 v[4:5], v[84:85], v[30:31], v[4:5] op_sel:[0,1,0] neg_lo:[1,0,0] neg_hi:[1,0,0]
	v_pk_fma_f32 v[0:1], v[122:123], v[30:31], v[0:1] op_sel_hi:[1,0,1] neg_lo:[1,0,0] neg_hi:[1,0,0]
	ds_read_b128 v[28:31], v20 offset:42768
	v_pk_fma_f32 v[4:5], v[178:179], v[10:11], v[4:5] op_sel:[1,0,0] neg_lo:[1,0,0] neg_hi:[1,0,0]
	v_pk_fma_f32 v[0:1], v[14:15], v[178:179], v[0:1] op_sel_hi:[1,0,1] neg_lo:[1,0,0] neg_hi:[1,0,0]
	v_pk_fma_f32 v[4:5], v[180:181], v[6:7], v[4:5] op_sel:[1,0,0] neg_lo:[1,0,0] neg_hi:[1,0,0]
	v_pk_fma_f32 v[0:1], v[180:181], v[16:17], v[0:1] op_sel_hi:[0,1,1] neg_lo:[1,0,0] neg_hi:[1,0,0]
	v_pk_fma_f32 v[4:5], v[182:183], v[12:13], v[4:5] op_sel:[1,0,0] neg_lo:[1,0,0] neg_hi:[1,0,0]
	v_pk_fma_f32 v[0:1], v[182:183], v[18:19], v[0:1] op_sel_hi:[0,1,1] neg_lo:[1,0,0] neg_hi:[1,0,0]
	ds_read_b128 v[180:183], v20 offset:42800
	v_pk_fma_f32 v[4:5], v[174:175], v[184:185], v[4:5] op_sel:[0,1,0] neg_lo:[1,0,0] neg_hi:[1,0,0]
	v_pk_fma_f32 v[0:1], v[176:177], v[184:185], v[0:1] op_sel_hi:[1,0,1] neg_lo:[1,0,0] neg_hi:[1,0,0]
	ds_read_b128 v[176:179], v20 offset:42784
	v_pk_add_f32 v[8:9], v[0:1], v[4:5]
	ds_read_b128 v[0:3], v20 offset:42752
	s_waitcnt lgkmcnt(0)
	v_pk_fma_f32 v[4:5], v[138:139], v[0:1], 0 op_sel:[0,1,0] op_sel_hi:[1,1,0] neg_lo:[1,0,0] neg_hi:[1,0,0]
	v_pk_fma_f32 v[0:1], v[128:129], v[0:1], v[174:175] op_sel_hi:[1,0,1] neg_lo:[1,0,0] neg_hi:[1,0,0]
	v_pk_fma_f32 v[4:5], v[134:135], v[2:3], v[4:5] op_sel:[0,1,0] neg_lo:[1,0,0] neg_hi:[1,0,0]
	v_pk_fma_f32 v[0:1], v[136:137], v[2:3], v[0:1] op_sel_hi:[1,0,1] neg_lo:[1,0,0] neg_hi:[1,0,0]
	v_pk_fma_f32 v[4:5], v[130:131], v[28:29], v[4:5] op_sel:[0,1,0] neg_lo:[1,0,0] neg_hi:[1,0,0]
	v_pk_fma_f32 v[0:1], v[132:133], v[28:29], v[0:1] op_sel_hi:[1,0,1] neg_lo:[1,0,0] neg_hi:[1,0,0]
	v_pk_fma_f32 v[4:5], v[84:85], v[30:31], v[4:5] op_sel:[0,1,0] neg_lo:[1,0,0] neg_hi:[1,0,0]
	v_pk_fma_f32 v[0:1], v[122:123], v[30:31], v[0:1] op_sel_hi:[1,0,1] neg_lo:[1,0,0] neg_hi:[1,0,0]
	ds_read_b128 v[28:31], v20 offset:43024
	v_pk_fma_f32 v[4:5], v[10:11], v[176:177], v[4:5] op_sel:[0,1,0] neg_lo:[1,0,0] neg_hi:[1,0,0]
	v_pk_fma_f32 v[0:1], v[14:15], v[176:177], v[0:1] op_sel_hi:[1,0,1] neg_lo:[1,0,0] neg_hi:[1,0,0]
	v_pk_fma_f32 v[4:5], v[178:179], v[6:7], v[4:5] op_sel:[1,0,0] neg_lo:[1,0,0] neg_hi:[1,0,0]
	v_pk_fma_f32 v[0:1], v[178:179], v[16:17], v[0:1] op_sel_hi:[0,1,1] neg_lo:[1,0,0] neg_hi:[1,0,0]
	v_pk_fma_f32 v[4:5], v[180:181], v[12:13], v[4:5] op_sel:[1,0,0] neg_lo:[1,0,0] neg_hi:[1,0,0]
	v_pk_fma_f32 v[0:1], v[180:181], v[18:19], v[0:1] op_sel_hi:[0,1,1] neg_lo:[1,0,0] neg_hi:[1,0,0]
	ds_read_b128 v[178:181], v20 offset:43056
	v_pk_fma_f32 v[4:5], v[174:175], v[182:183], v[4:5] op_sel:[0,1,0] neg_lo:[1,0,0] neg_hi:[1,0,0]
	ds_read_b128 v[174:177], v20 offset:43040
	v_pk_fma_f32 v[0:1], v[182:183], v[8:9], v[0:1] op_sel_hi:[0,1,1] neg_lo:[1,0,0] neg_hi:[1,0,0]
	ds_read_b128 v[228:231], v20 offset:53728
	v_pk_add_f32 v[4:5], v[4:5], v[0:1]
	ds_read_b128 v[0:3], v20 offset:43008
	s_waitcnt lgkmcnt(0)
	v_pk_fma_f32 v[182:183], v[138:139], v[0:1], 0 op_sel:[0,1,0] op_sel_hi:[1,1,0] neg_lo:[1,0,0] neg_hi:[1,0,0]
	v_pk_mul_f32 v[0:1], v[128:129], v[0:1] op_sel_hi:[1,0]
	v_pk_fma_f32 v[182:183], v[134:135], v[2:3], v[182:183] op_sel:[0,1,0] neg_lo:[1,0,0] neg_hi:[1,0,0]
	v_pk_fma_f32 v[0:1], v[168:169], v[170:171], v[0:1] neg_lo:[0,0,1] neg_hi:[0,0,1]
	ds_read_b128 v[168:171], v20 offset:43280
	v_pk_fma_f32 v[0:1], v[136:137], v[2:3], v[0:1] op_sel_hi:[1,0,1] neg_lo:[1,0,0] neg_hi:[1,0,0]
	v_pk_fma_f32 v[182:183], v[130:131], v[28:29], v[182:183] op_sel:[0,1,0] neg_lo:[1,0,0] neg_hi:[1,0,0]
	v_pk_fma_f32 v[0:1], v[132:133], v[28:29], v[0:1] op_sel_hi:[1,0,1] neg_lo:[1,0,0] neg_hi:[1,0,0]
	v_pk_fma_f32 v[182:183], v[84:85], v[30:31], v[182:183] op_sel:[0,1,0] neg_lo:[1,0,0] neg_hi:[1,0,0]
	v_pk_fma_f32 v[0:1], v[122:123], v[30:31], v[0:1] op_sel_hi:[1,0,1] neg_lo:[1,0,0] neg_hi:[1,0,0]
	ds_read_b128 v[28:31], v20 offset:43264
	v_pk_fma_f32 v[182:183], v[10:11], v[174:175], v[182:183] op_sel:[0,1,0] neg_lo:[1,0,0] neg_hi:[1,0,0]
	v_pk_fma_f32 v[0:1], v[14:15], v[174:175], v[0:1] op_sel_hi:[1,0,1] neg_lo:[1,0,0] neg_hi:[1,0,0]
	v_pk_fma_f32 v[182:183], v[176:177], v[6:7], v[182:183] op_sel:[1,0,0] neg_lo:[1,0,0] neg_hi:[1,0,0]
	v_pk_fma_f32 v[0:1], v[16:17], v[176:177], v[0:1] op_sel_hi:[1,0,1] neg_lo:[1,0,0] neg_hi:[1,0,0]
	ds_read_b128 v[174:177], v20 offset:43296
	v_pk_fma_f32 v[182:183], v[178:179], v[12:13], v[182:183] op_sel:[1,0,0] neg_lo:[1,0,0] neg_hi:[1,0,0]
	v_pk_fma_f32 v[0:1], v[178:179], v[18:19], v[0:1] op_sel_hi:[0,1,1] neg_lo:[1,0,0] neg_hi:[1,0,0]
	v_pk_fma_f32 v[182:183], v[180:181], v[4:5], v[182:183] op_sel:[1,0,0] neg_lo:[1,0,0] neg_hi:[1,0,0]
	v_pk_fma_f32 v[0:1], v[180:181], v[8:9], v[0:1] op_sel_hi:[0,1,1] neg_lo:[1,0,0] neg_hi:[1,0,0]
	ds_read_b128 v[178:181], v20 offset:43312
	v_pk_add_f32 v[2:3], v[0:1], v[182:183]
	ds_read_b128 v[182:185], v20 offset:43328
	s_waitcnt lgkmcnt(3)
	v_pk_fma_f32 v[0:1], v[138:139], v[28:29], 0 op_sel:[0,1,0] op_sel_hi:[1,1,0] neg_lo:[1,0,0] neg_hi:[1,0,0]
	v_pk_fma_f32 v[28:29], v[128:129], v[28:29], v[172:173] op_sel_hi:[1,0,1] neg_lo:[1,0,0] neg_hi:[1,0,0]
	v_pk_fma_f32 v[0:1], v[134:135], v[30:31], v[0:1] op_sel:[0,1,0] neg_lo:[1,0,0] neg_hi:[1,0,0]
	v_pk_fma_f32 v[28:29], v[136:137], v[30:31], v[28:29] op_sel_hi:[1,0,1] neg_lo:[1,0,0] neg_hi:[1,0,0]
	v_pk_fma_f32 v[0:1], v[130:131], v[168:169], v[0:1] op_sel:[0,1,0] neg_lo:[1,0,0] neg_hi:[1,0,0]
	v_pk_fma_f32 v[28:29], v[132:133], v[168:169], v[28:29] op_sel_hi:[1,0,1] neg_lo:[1,0,0] neg_hi:[1,0,0]
	v_pk_fma_f32 v[0:1], v[84:85], v[170:171], v[0:1] op_sel:[0,1,0] neg_lo:[1,0,0] neg_hi:[1,0,0]
	v_pk_fma_f32 v[28:29], v[122:123], v[170:171], v[28:29] op_sel_hi:[1,0,1] neg_lo:[1,0,0] neg_hi:[1,0,0]
	ds_read_b128 v[168:171], v20 offset:43536
	s_waitcnt lgkmcnt(3)
	v_pk_fma_f32 v[0:1], v[10:11], v[174:175], v[0:1] op_sel:[0,1,0] neg_lo:[1,0,0] neg_hi:[1,0,0]
	v_pk_fma_f32 v[28:29], v[14:15], v[174:175], v[28:29] op_sel_hi:[1,0,1] neg_lo:[1,0,0] neg_hi:[1,0,0]
	v_pk_fma_f32 v[0:1], v[6:7], v[176:177], v[0:1] op_sel:[0,1,0] neg_lo:[1,0,0] neg_hi:[1,0,0]
	v_pk_fma_f32 v[28:29], v[16:17], v[176:177], v[28:29] op_sel_hi:[1,0,1] neg_lo:[1,0,0] neg_hi:[1,0,0]
	s_waitcnt lgkmcnt(2)
	v_pk_fma_f32 v[0:1], v[178:179], v[12:13], v[0:1] op_sel:[1,0,0] neg_lo:[1,0,0] neg_hi:[1,0,0]
	v_pk_fma_f32 v[28:29], v[18:19], v[178:179], v[28:29] op_sel_hi:[1,0,1] neg_lo:[1,0,0] neg_hi:[1,0,0]
	ds_read_b128 v[176:179], v20 offset:43568
	v_pk_fma_f32 v[0:1], v[180:181], v[4:5], v[0:1] op_sel:[1,0,0] neg_lo:[1,0,0] neg_hi:[1,0,0]
	v_pk_fma_f32 v[28:29], v[180:181], v[8:9], v[28:29] op_sel_hi:[0,1,1] neg_lo:[1,0,0] neg_hi:[1,0,0]
	s_waitcnt lgkmcnt(2)
	v_pk_fma_f32 v[0:1], v[172:173], v[182:183], v[0:1] op_sel:[0,1,0] neg_lo:[1,0,0] neg_hi:[1,0,0]
	ds_read_b128 v[172:175], v20 offset:43552
	v_pk_fma_f32 v[28:29], v[182:183], v[2:3], v[28:29] op_sel_hi:[0,1,1] neg_lo:[1,0,0] neg_hi:[1,0,0]
	ds_read_b128 v[180:183], v20 offset:43584
	v_pk_fma_f32 v[0:1], v[162:163], v[184:185], v[0:1] op_sel:[0,1,0] neg_lo:[1,0,0] neg_hi:[1,0,0]
	v_pk_fma_f32 v[28:29], v[166:167], v[184:185], v[28:29] op_sel_hi:[1,0,1] neg_lo:[1,0,0] neg_hi:[1,0,0]
	s_nop 0
	v_pk_add_f32 v[0:1], v[0:1], v[28:29]
	ds_read_b128 v[28:31], v20 offset:43520
	s_waitcnt lgkmcnt(0)
	v_pk_fma_f32 v[184:185], v[138:139], v[28:29], 0 op_sel:[0,1,0] op_sel_hi:[1,1,0] neg_lo:[1,0,0] neg_hi:[1,0,0]
	v_pk_fma_f32 v[28:29], v[128:129], v[28:29], v[166:167] op_sel_hi:[1,0,1] neg_lo:[1,0,0] neg_hi:[1,0,0]
	v_pk_fma_f32 v[184:185], v[134:135], v[30:31], v[184:185] op_sel:[0,1,0] neg_lo:[1,0,0] neg_hi:[1,0,0]
	v_pk_fma_f32 v[28:29], v[136:137], v[30:31], v[28:29] op_sel_hi:[1,0,1] neg_lo:[1,0,0] neg_hi:[1,0,0]
	v_pk_fma_f32 v[184:185], v[130:131], v[168:169], v[184:185] op_sel:[0,1,0] neg_lo:[1,0,0] neg_hi:[1,0,0]
	v_pk_fma_f32 v[28:29], v[132:133], v[168:169], v[28:29] op_sel_hi:[1,0,1] neg_lo:[1,0,0] neg_hi:[1,0,0]
	v_pk_fma_f32 v[184:185], v[84:85], v[170:171], v[184:185] op_sel:[0,1,0] neg_lo:[1,0,0] neg_hi:[1,0,0]
	v_pk_fma_f32 v[28:29], v[122:123], v[170:171], v[28:29] op_sel_hi:[1,0,1] neg_lo:[1,0,0] neg_hi:[1,0,0]
	v_pk_fma_f32 v[184:185], v[10:11], v[172:173], v[184:185] op_sel:[0,1,0] neg_lo:[1,0,0] neg_hi:[1,0,0]
	v_pk_fma_f32 v[28:29], v[14:15], v[172:173], v[28:29] op_sel_hi:[1,0,1] neg_lo:[1,0,0] neg_hi:[1,0,0]
	ds_read_b128 v[170:173], v20 offset:43792
	v_pk_fma_f32 v[184:185], v[6:7], v[174:175], v[184:185] op_sel:[0,1,0] neg_lo:[1,0,0] neg_hi:[1,0,0]
	v_pk_fma_f32 v[28:29], v[16:17], v[174:175], v[28:29] op_sel_hi:[1,0,1] neg_lo:[1,0,0] neg_hi:[1,0,0]
	v_pk_fma_f32 v[184:185], v[12:13], v[176:177], v[184:185] op_sel:[0,1,0] neg_lo:[1,0,0] neg_hi:[1,0,0]
	v_pk_fma_f32 v[28:29], v[18:19], v[176:177], v[28:29] op_sel_hi:[1,0,1] neg_lo:[1,0,0] neg_hi:[1,0,0]
	ds_read_b128 v[174:177], v20 offset:43808
	v_pk_fma_f32 v[184:185], v[178:179], v[4:5], v[184:185] op_sel:[1,0,0] neg_lo:[1,0,0] neg_hi:[1,0,0]
	v_pk_fma_f32 v[28:29], v[178:179], v[8:9], v[28:29] op_sel_hi:[0,1,1] neg_lo:[1,0,0] neg_hi:[1,0,0]
	v_pk_fma_f32 v[184:185], v[180:181], v[0:1], v[184:185] op_sel:[1,0,0] neg_lo:[1,0,0] neg_hi:[1,0,0]
	v_pk_fma_f32 v[28:29], v[180:181], v[2:3], v[28:29] op_sel_hi:[0,1,1] neg_lo:[1,0,0] neg_hi:[1,0,0]
	ds_read_b128 v[178:181], v20 offset:43824
	v_pk_fma_f32 v[184:185], v[162:163], v[182:183], v[184:185] op_sel:[0,1,0] neg_lo:[1,0,0] neg_hi:[1,0,0]
	v_pk_fma_f32 v[28:29], v[166:167], v[182:183], v[28:29] op_sel_hi:[1,0,1] neg_lo:[1,0,0] neg_hi:[1,0,0]
	ds_read_b128 v[166:169], v20 offset:43776
	v_pk_add_f32 v[30:31], v[28:29], v[184:185]
	ds_read_b128 v[182:185], v20 offset:43840
	s_waitcnt lgkmcnt(1)
	v_pk_fma_f32 v[28:29], v[138:139], v[166:167], 0 op_sel:[0,1,0] op_sel_hi:[1,1,0] neg_lo:[1,0,0] neg_hi:[1,0,0]
	v_pk_fma_f32 v[252:253], v[128:129], v[166:167], v[162:163] op_sel_hi:[1,0,1] neg_lo:[1,0,0] neg_hi:[1,0,0]
	v_pk_fma_f32 v[28:29], v[134:135], v[168:169], v[28:29] op_sel:[0,1,0] neg_lo:[1,0,0] neg_hi:[1,0,0]
	v_pk_fma_f32 v[252:253], v[136:137], v[168:169], v[252:253] op_sel_hi:[1,0,1] neg_lo:[1,0,0] neg_hi:[1,0,0]
	ds_read_b128 v[166:169], v20 offset:44032
	v_pk_fma_f32 v[28:29], v[130:131], v[170:171], v[28:29] op_sel:[0,1,0] neg_lo:[1,0,0] neg_hi:[1,0,0]
	v_pk_fma_f32 v[252:253], v[132:133], v[170:171], v[252:253] op_sel_hi:[1,0,1] neg_lo:[1,0,0] neg_hi:[1,0,0]
	v_pk_fma_f32 v[28:29], v[84:85], v[172:173], v[28:29] op_sel:[0,1,0] neg_lo:[1,0,0] neg_hi:[1,0,0]
	v_pk_fma_f32 v[252:253], v[122:123], v[172:173], v[252:253] op_sel_hi:[1,0,1] neg_lo:[1,0,0] neg_hi:[1,0,0]
	ds_read_b128 v[170:173], v20 offset:44048
	v_pk_fma_f32 v[28:29], v[10:11], v[174:175], v[28:29] op_sel:[0,1,0] neg_lo:[1,0,0] neg_hi:[1,0,0]
	v_pk_fma_f32 v[252:253], v[14:15], v[174:175], v[252:253] op_sel_hi:[1,0,1] neg_lo:[1,0,0] neg_hi:[1,0,0]
	v_pk_fma_f32 v[28:29], v[6:7], v[176:177], v[28:29] op_sel:[0,1,0] neg_lo:[1,0,0] neg_hi:[1,0,0]
	v_pk_fma_f32 v[252:253], v[16:17], v[176:177], v[252:253] op_sel_hi:[1,0,1] neg_lo:[1,0,0] neg_hi:[1,0,0]
	ds_read_b128 v[174:177], v20 offset:44064
	v_pk_fma_f32 v[28:29], v[12:13], v[178:179], v[28:29] op_sel:[0,1,0] neg_lo:[1,0,0] neg_hi:[1,0,0]
	v_pk_fma_f32 v[252:253], v[18:19], v[178:179], v[252:253] op_sel_hi:[1,0,1] neg_lo:[1,0,0] neg_hi:[1,0,0]
	v_pk_fma_f32 v[28:29], v[180:181], v[4:5], v[28:29] op_sel:[1,0,0] neg_lo:[1,0,0] neg_hi:[1,0,0]
	v_pk_fma_f32 v[252:253], v[8:9], v[180:181], v[252:253] op_sel_hi:[1,0,1] neg_lo:[1,0,0] neg_hi:[1,0,0]
	ds_read_b128 v[178:181], v20 offset:44080
	s_waitcnt lgkmcnt(4)
	v_pk_fma_f32 v[28:29], v[182:183], v[0:1], v[28:29] op_sel:[1,0,0] neg_lo:[1,0,0] neg_hi:[1,0,0]
	v_pk_fma_f32 v[252:253], v[182:183], v[2:3], v[252:253] op_sel_hi:[0,1,1] neg_lo:[1,0,0] neg_hi:[1,0,0]
	v_pk_fma_f32 v[28:29], v[162:163], v[184:185], v[28:29] op_sel:[0,1,0] neg_lo:[1,0,0] neg_hi:[1,0,0]
	v_pk_fma_f32 v[252:253], v[184:185], v[30:31], v[252:253] op_sel_hi:[0,1,1] neg_lo:[1,0,0] neg_hi:[1,0,0]
	ds_read_b128 v[182:185], v20 offset:44096
	v_pk_add_f32 v[28:29], v[28:29], v[252:253]
	s_waitcnt lgkmcnt(4)
	v_pk_fma_f32 v[162:163], v[138:139], v[166:167], 0 op_sel:[0,1,0] op_sel_hi:[1,1,0] neg_lo:[1,0,0] neg_hi:[1,0,0]
	v_pk_mul_f32 v[166:167], v[128:129], v[166:167] op_sel_hi:[1,0]
	v_pk_fma_f32 v[162:163], v[134:135], v[168:169], v[162:163] op_sel:[0,1,0] neg_lo:[1,0,0] neg_hi:[1,0,0]
	v_pk_fma_f32 v[32:33], v[32:33], v[34:35], v[166:167] neg_lo:[0,0,1] neg_hi:[0,0,1]
	s_waitcnt lgkmcnt(3)
	v_pk_fma_f32 v[162:163], v[130:131], v[170:171], v[162:163] op_sel:[0,1,0] neg_lo:[1,0,0] neg_hi:[1,0,0]
	v_pk_fma_f32 v[32:33], v[136:137], v[168:169], v[32:33] op_sel_hi:[1,0,1] neg_lo:[1,0,0] neg_hi:[1,0,0]
	ds_read_b128 v[166:169], v20 offset:44288
	v_pk_fma_f32 v[32:33], v[132:133], v[170:171], v[32:33] op_sel_hi:[1,0,1] neg_lo:[1,0,0] neg_hi:[1,0,0]
	v_pk_fma_f32 v[162:163], v[84:85], v[172:173], v[162:163] op_sel:[0,1,0] neg_lo:[1,0,0] neg_hi:[1,0,0]
	v_pk_fma_f32 v[32:33], v[122:123], v[172:173], v[32:33] op_sel_hi:[1,0,1] neg_lo:[1,0,0] neg_hi:[1,0,0]
	ds_read_b128 v[170:173], v20 offset:44304
	s_waitcnt lgkmcnt(4)
	v_pk_fma_f32 v[162:163], v[10:11], v[174:175], v[162:163] op_sel:[0,1,0] neg_lo:[1,0,0] neg_hi:[1,0,0]
	v_pk_fma_f32 v[32:33], v[14:15], v[174:175], v[32:33] op_sel_hi:[1,0,1] neg_lo:[1,0,0] neg_hi:[1,0,0]
	v_pk_fma_f32 v[162:163], v[6:7], v[176:177], v[162:163] op_sel:[0,1,0] neg_lo:[1,0,0] neg_hi:[1,0,0]
	v_pk_fma_f32 v[32:33], v[16:17], v[176:177], v[32:33] op_sel_hi:[1,0,1] neg_lo:[1,0,0] neg_hi:[1,0,0]
	ds_read_b128 v[174:177], v20 offset:44320
	s_waitcnt lgkmcnt(4)
	v_pk_fma_f32 v[162:163], v[12:13], v[178:179], v[162:163] op_sel:[0,1,0] neg_lo:[1,0,0] neg_hi:[1,0,0]
	v_pk_fma_f32 v[32:33], v[18:19], v[178:179], v[32:33] op_sel_hi:[1,0,1] neg_lo:[1,0,0] neg_hi:[1,0,0]
	v_pk_fma_f32 v[162:163], v[4:5], v[180:181], v[162:163] op_sel:[0,1,0] neg_lo:[1,0,0] neg_hi:[1,0,0]
	v_pk_fma_f32 v[32:33], v[8:9], v[180:181], v[32:33] op_sel_hi:[1,0,1] neg_lo:[1,0,0] neg_hi:[1,0,0]
	ds_read_b128 v[178:181], v20 offset:44336
	s_waitcnt lgkmcnt(4)
	v_pk_fma_f32 v[162:163], v[182:183], v[0:1], v[162:163] op_sel:[1,0,0] neg_lo:[1,0,0] neg_hi:[1,0,0]
	v_pk_fma_f32 v[32:33], v[2:3], v[182:183], v[32:33] op_sel_hi:[1,0,1] neg_lo:[1,0,0] neg_hi:[1,0,0]
	v_pk_fma_f32 v[162:163], v[184:185], v[28:29], v[162:163] op_sel:[1,0,0] neg_lo:[1,0,0] neg_hi:[1,0,0]
	v_pk_fma_f32 v[32:33], v[184:185], v[30:31], v[32:33] op_sel_hi:[0,1,1] neg_lo:[1,0,0] neg_hi:[1,0,0]
	ds_read_b128 v[182:185], v20 offset:44352
	v_pk_add_f32 v[32:33], v[32:33], v[162:163]
	s_waitcnt lgkmcnt(4)
	v_pk_fma_f32 v[34:35], v[138:139], v[166:167], 0 op_sel:[0,1,0] op_sel_hi:[1,1,0] neg_lo:[1,0,0] neg_hi:[1,0,0]
	v_pk_fma_f32 v[252:253], v[128:129], v[166:167], v[160:161] op_sel_hi:[1,0,1] neg_lo:[1,0,0] neg_hi:[1,0,0]
	v_pk_fma_f32 v[34:35], v[134:135], v[168:169], v[34:35] op_sel:[0,1,0] neg_lo:[1,0,0] neg_hi:[1,0,0]
	v_pk_fma_f32 v[252:253], v[136:137], v[168:169], v[252:253] op_sel_hi:[1,0,1] neg_lo:[1,0,0] neg_hi:[1,0,0]
	ds_read_b128 v[166:169], v20 offset:44560
	s_waitcnt lgkmcnt(4)
	v_pk_fma_f32 v[34:35], v[130:131], v[170:171], v[34:35] op_sel:[0,1,0] neg_lo:[1,0,0] neg_hi:[1,0,0]
	v_pk_fma_f32 v[252:253], v[132:133], v[170:171], v[252:253] op_sel_hi:[1,0,1] neg_lo:[1,0,0] neg_hi:[1,0,0]
	v_pk_fma_f32 v[34:35], v[84:85], v[172:173], v[34:35] op_sel:[0,1,0] neg_lo:[1,0,0] neg_hi:[1,0,0]
	v_pk_fma_f32 v[252:253], v[122:123], v[172:173], v[252:253] op_sel_hi:[1,0,1] neg_lo:[1,0,0] neg_hi:[1,0,0]
	ds_read_b128 v[170:173], v20 offset:44576
	s_waitcnt lgkmcnt(4)
	v_pk_fma_f32 v[34:35], v[10:11], v[174:175], v[34:35] op_sel:[0,1,0] neg_lo:[1,0,0] neg_hi:[1,0,0]
	v_pk_fma_f32 v[252:253], v[14:15], v[174:175], v[252:253] op_sel_hi:[1,0,1] neg_lo:[1,0,0] neg_hi:[1,0,0]
	v_pk_fma_f32 v[34:35], v[6:7], v[176:177], v[34:35] op_sel:[0,1,0] neg_lo:[1,0,0] neg_hi:[1,0,0]
	v_pk_fma_f32 v[252:253], v[16:17], v[176:177], v[252:253] op_sel_hi:[1,0,1] neg_lo:[1,0,0] neg_hi:[1,0,0]
	ds_read_b128 v[174:177], v20 offset:44592
	s_waitcnt lgkmcnt(4)
	v_pk_fma_f32 v[34:35], v[12:13], v[178:179], v[34:35] op_sel:[0,1,0] neg_lo:[1,0,0] neg_hi:[1,0,0]
	v_pk_fma_f32 v[252:253], v[18:19], v[178:179], v[252:253] op_sel_hi:[1,0,1] neg_lo:[1,0,0] neg_hi:[1,0,0]
	v_pk_fma_f32 v[34:35], v[4:5], v[180:181], v[34:35] op_sel:[0,1,0] neg_lo:[1,0,0] neg_hi:[1,0,0]
	v_pk_fma_f32 v[252:253], v[8:9], v[180:181], v[252:253] op_sel_hi:[1,0,1] neg_lo:[1,0,0] neg_hi:[1,0,0]
	ds_read_b128 v[178:181], v20 offset:44608
	s_waitcnt lgkmcnt(4)
	v_pk_fma_f32 v[34:35], v[0:1], v[182:183], v[34:35] op_sel:[0,1,0] neg_lo:[1,0,0] neg_hi:[1,0,0]
	v_pk_fma_f32 v[252:253], v[2:3], v[182:183], v[252:253] op_sel_hi:[1,0,1] neg_lo:[1,0,0] neg_hi:[1,0,0]
	v_pk_fma_f32 v[34:35], v[184:185], v[28:29], v[34:35] op_sel:[1,0,0] neg_lo:[1,0,0] neg_hi:[1,0,0]
	v_pk_fma_f32 v[252:253], v[184:185], v[30:31], v[252:253] op_sel_hi:[0,1,1] neg_lo:[1,0,0] neg_hi:[1,0,0]
	ds_read_b128 v[182:185], v20 offset:44624
	v_pk_fma_f32 v[34:35], v[160:161], v[208:209], v[34:35] op_sel:[0,1,0] neg_lo:[1,0,0] neg_hi:[1,0,0]
	ds_read_b128 v[160:163], v20 offset:44544
	v_pk_fma_f32 v[34:35], v[40:41], v[210:211], v[34:35] op_sel:[0,1,0] neg_lo:[1,0,0] neg_hi:[1,0,0]
	v_pk_fma_f32 v[252:253], v[208:209], v[32:33], v[252:253] op_sel_hi:[0,1,1] neg_lo:[1,0,0] neg_hi:[1,0,0]
	s_waitcnt lgkmcnt(0)
	v_pk_fma_f32 v[186:187], v[138:139], v[160:161], 0 op_sel:[0,1,0] op_sel_hi:[1,1,0] neg_lo:[1,0,0] neg_hi:[1,0,0]
	v_pk_fma_f32 v[252:253], v[36:37], v[210:211], v[252:253] op_sel_hi:[1,0,1] neg_lo:[1,0,0] neg_hi:[1,0,0]
	v_pk_fma_f32 v[160:161], v[128:129], v[160:161], v[36:37] op_sel_hi:[1,0,1] neg_lo:[1,0,0] neg_hi:[1,0,0]
	v_pk_add_f32 v[34:35], v[252:253], v[34:35]
	v_pk_fma_f32 v[186:187], v[134:135], v[162:163], v[186:187] op_sel:[0,1,0] neg_lo:[1,0,0] neg_hi:[1,0,0]
	v_pk_fma_f32 v[160:161], v[136:137], v[162:163], v[160:161] op_sel_hi:[1,0,1] neg_lo:[1,0,0] neg_hi:[1,0,0]
	v_pk_fma_f32 v[186:187], v[130:131], v[166:167], v[186:187] op_sel:[0,1,0] neg_lo:[1,0,0] neg_hi:[1,0,0]
	v_pk_fma_f32 v[160:161], v[132:133], v[166:167], v[160:161] op_sel_hi:[1,0,1] neg_lo:[1,0,0] neg_hi:[1,0,0]
	v_pk_fma_f32 v[186:187], v[84:85], v[168:169], v[186:187] op_sel:[0,1,0] neg_lo:[1,0,0] neg_hi:[1,0,0]
	v_pk_fma_f32 v[160:161], v[122:123], v[168:169], v[160:161] op_sel_hi:[1,0,1] neg_lo:[1,0,0] neg_hi:[1,0,0]
	ds_read_b128 v[166:169], v20 offset:44816
	v_pk_fma_f32 v[186:187], v[10:11], v[170:171], v[186:187] op_sel:[0,1,0] neg_lo:[1,0,0] neg_hi:[1,0,0]
	v_pk_fma_f32 v[160:161], v[14:15], v[170:171], v[160:161] op_sel_hi:[1,0,1] neg_lo:[1,0,0] neg_hi:[1,0,0]
	v_pk_fma_f32 v[186:187], v[6:7], v[172:173], v[186:187] op_sel:[0,1,0] neg_lo:[1,0,0] neg_hi:[1,0,0]
	v_pk_fma_f32 v[160:161], v[16:17], v[172:173], v[160:161] op_sel_hi:[1,0,1] neg_lo:[1,0,0] neg_hi:[1,0,0]
	ds_read_b128 v[170:173], v20 offset:44832
	v_pk_fma_f32 v[186:187], v[12:13], v[174:175], v[186:187] op_sel:[0,1,0] neg_lo:[1,0,0] neg_hi:[1,0,0]
	v_pk_fma_f32 v[160:161], v[18:19], v[174:175], v[160:161] op_sel_hi:[1,0,1] neg_lo:[1,0,0] neg_hi:[1,0,0]
	v_pk_fma_f32 v[186:187], v[4:5], v[176:177], v[186:187] op_sel:[0,1,0] neg_lo:[1,0,0] neg_hi:[1,0,0]
	v_pk_fma_f32 v[160:161], v[8:9], v[176:177], v[160:161] op_sel_hi:[1,0,1] neg_lo:[1,0,0] neg_hi:[1,0,0]
	ds_read_b128 v[174:177], v20 offset:44848
	v_pk_fma_f32 v[186:187], v[0:1], v[178:179], v[186:187] op_sel:[0,1,0] neg_lo:[1,0,0] neg_hi:[1,0,0]
	v_pk_fma_f32 v[160:161], v[2:3], v[178:179], v[160:161] op_sel_hi:[1,0,1] neg_lo:[1,0,0] neg_hi:[1,0,0]
	v_pk_fma_f32 v[186:187], v[28:29], v[180:181], v[186:187] op_sel:[0,1,0] neg_lo:[1,0,0] neg_hi:[1,0,0]
	v_pk_fma_f32 v[160:161], v[30:31], v[180:181], v[160:161] op_sel_hi:[1,0,1] neg_lo:[1,0,0] neg_hi:[1,0,0]
	ds_read_b128 v[178:181], v20 offset:44864
	v_pk_fma_f32 v[186:187], v[182:183], v[34:35], v[186:187] op_sel:[1,0,0] neg_lo:[1,0,0] neg_hi:[1,0,0]
	v_pk_fma_f32 v[160:161], v[32:33], v[182:183], v[160:161] op_sel_hi:[1,0,1] neg_lo:[1,0,0] neg_hi:[1,0,0]
	v_pk_fma_f32 v[186:187], v[40:41], v[184:185], v[186:187] op_sel:[0,1,0] neg_lo:[1,0,0] neg_hi:[1,0,0]
	v_pk_fma_f32 v[36:37], v[36:37], v[184:185], v[160:161] op_sel_hi:[1,0,1] neg_lo:[1,0,0] neg_hi:[1,0,0]
	ds_read_b128 v[160:163], v20 offset:44800
	ds_read_b128 v[182:185], v20 offset:44880
	v_pk_add_f32 v[36:37], v[36:37], v[186:187]
	s_waitcnt lgkmcnt(1)
	v_pk_fma_f32 v[186:187], v[138:139], v[160:161], 0 op_sel:[0,1,0] op_sel_hi:[1,1,0] neg_lo:[1,0,0] neg_hi:[1,0,0]
	ds_read_b128 v[208:211], v20 offset:45408
	v_pk_fma_f32 v[186:187], v[134:135], v[162:163], v[186:187] op_sel:[0,1,0] neg_lo:[1,0,0] neg_hi:[1,0,0]
	v_pk_fma_f32 v[252:253], v[128:129], v[160:161], v[40:41] op_sel_hi:[1,0,1] neg_lo:[1,0,0] neg_hi:[1,0,0]
	v_pk_fma_f32 v[186:187], v[130:131], v[166:167], v[186:187] op_sel:[0,1,0] neg_lo:[1,0,0] neg_hi:[1,0,0]
	v_pk_fma_f32 v[252:253], v[136:137], v[162:163], v[252:253] op_sel_hi:[1,0,1] neg_lo:[1,0,0] neg_hi:[1,0,0]
	ds_read_b128 v[160:163], v20 offset:45056
	v_pk_fma_f32 v[186:187], v[84:85], v[168:169], v[186:187] op_sel:[0,1,0] neg_lo:[1,0,0] neg_hi:[1,0,0]
	v_pk_fma_f32 v[252:253], v[132:133], v[166:167], v[252:253] op_sel_hi:[1,0,1] neg_lo:[1,0,0] neg_hi:[1,0,0]
	v_pk_fma_f32 v[186:187], v[10:11], v[170:171], v[186:187] op_sel:[0,1,0] neg_lo:[1,0,0] neg_hi:[1,0,0]
	v_pk_fma_f32 v[252:253], v[122:123], v[168:169], v[252:253] op_sel_hi:[1,0,1] neg_lo:[1,0,0] neg_hi:[1,0,0]
	ds_read_b128 v[166:169], v20 offset:45072
	v_pk_fma_f32 v[186:187], v[6:7], v[172:173], v[186:187] op_sel:[0,1,0] neg_lo:[1,0,0] neg_hi:[1,0,0]
	v_pk_fma_f32 v[252:253], v[14:15], v[170:171], v[252:253] op_sel_hi:[1,0,1] neg_lo:[1,0,0] neg_hi:[1,0,0]
	v_pk_fma_f32 v[186:187], v[12:13], v[174:175], v[186:187] op_sel:[0,1,0] neg_lo:[1,0,0] neg_hi:[1,0,0]
	v_pk_fma_f32 v[252:253], v[16:17], v[172:173], v[252:253] op_sel_hi:[1,0,1] neg_lo:[1,0,0] neg_hi:[1,0,0]
	ds_read_b128 v[170:173], v20 offset:45088
	v_pk_fma_f32 v[186:187], v[4:5], v[176:177], v[186:187] op_sel:[0,1,0] neg_lo:[1,0,0] neg_hi:[1,0,0]
	v_pk_fma_f32 v[252:253], v[18:19], v[174:175], v[252:253] op_sel_hi:[1,0,1] neg_lo:[1,0,0] neg_hi:[1,0,0]
	v_pk_fma_f32 v[186:187], v[0:1], v[178:179], v[186:187] op_sel:[0,1,0] neg_lo:[1,0,0] neg_hi:[1,0,0]
	v_pk_fma_f32 v[252:253], v[8:9], v[176:177], v[252:253] op_sel_hi:[1,0,1] neg_lo:[1,0,0] neg_hi:[1,0,0]
	ds_read_b128 v[174:177], v20 offset:45104
	v_pk_fma_f32 v[186:187], v[28:29], v[180:181], v[186:187] op_sel:[0,1,0] neg_lo:[1,0,0] neg_hi:[1,0,0]
	v_pk_fma_f32 v[252:253], v[2:3], v[178:179], v[252:253] op_sel_hi:[1,0,1] neg_lo:[1,0,0] neg_hi:[1,0,0]
	s_waitcnt lgkmcnt(5)
	v_pk_fma_f32 v[186:187], v[34:35], v[182:183], v[186:187] op_sel:[0,1,0] neg_lo:[1,0,0] neg_hi:[1,0,0]
	v_pk_fma_f32 v[252:253], v[30:31], v[180:181], v[252:253] op_sel_hi:[1,0,1] neg_lo:[1,0,0] neg_hi:[1,0,0]
	ds_read_b128 v[178:181], v20 offset:45120
	v_pk_fma_f32 v[186:187], v[40:41], v[184:185], v[186:187] op_sel:[0,1,0] neg_lo:[1,0,0] neg_hi:[1,0,0]
	v_pk_fma_f32 v[252:253], v[32:33], v[182:183], v[252:253] op_sel_hi:[1,0,1] neg_lo:[1,0,0] neg_hi:[1,0,0]
	s_nop 0
	v_pk_fma_f32 v[252:253], v[184:185], v[36:37], v[252:253] op_sel_hi:[0,1,1] neg_lo:[1,0,0] neg_hi:[1,0,0]
	ds_read_b128 v[182:185], v20 offset:45136
	v_pk_add_f32 v[40:41], v[252:253], v[186:187]
	s_waitcnt lgkmcnt(5)
	v_pk_fma_f32 v[186:187], v[138:139], v[160:161], 0 op_sel:[0,1,0] op_sel_hi:[1,1,0] neg_lo:[1,0,0] neg_hi:[1,0,0]
	v_pk_mul_f32 v[160:161], v[128:129], v[160:161] op_sel_hi:[1,0]
	v_pk_fma_f32 v[186:187], v[134:135], v[162:163], v[186:187] op_sel:[0,1,0] neg_lo:[1,0,0] neg_hi:[1,0,0]
	v_pk_fma_f32 v[38:39], v[38:39], v[42:43], v[160:161] neg_lo:[0,0,1] neg_hi:[0,0,1]
	s_waitcnt lgkmcnt(4)
	v_pk_fma_f32 v[186:187], v[130:131], v[166:167], v[186:187] op_sel:[0,1,0] neg_lo:[1,0,0] neg_hi:[1,0,0]
	v_pk_fma_f32 v[38:39], v[136:137], v[162:163], v[38:39] op_sel_hi:[1,0,1] neg_lo:[1,0,0] neg_hi:[1,0,0]
	ds_read_b128 v[160:163], v20 offset:45312
	v_pk_fma_f32 v[38:39], v[132:133], v[166:167], v[38:39] op_sel_hi:[1,0,1] neg_lo:[1,0,0] neg_hi:[1,0,0]
	v_pk_fma_f32 v[186:187], v[84:85], v[168:169], v[186:187] op_sel:[0,1,0] neg_lo:[1,0,0] neg_hi:[1,0,0]
	v_pk_fma_f32 v[38:39], v[122:123], v[168:169], v[38:39] op_sel_hi:[1,0,1] neg_lo:[1,0,0] neg_hi:[1,0,0]
	ds_read_b128 v[166:169], v20 offset:45328
	s_waitcnt lgkmcnt(5)
	v_pk_fma_f32 v[186:187], v[10:11], v[170:171], v[186:187] op_sel:[0,1,0] neg_lo:[1,0,0] neg_hi:[1,0,0]
	v_pk_fma_f32 v[38:39], v[14:15], v[170:171], v[38:39] op_sel_hi:[1,0,1] neg_lo:[1,0,0] neg_hi:[1,0,0]
	v_pk_fma_f32 v[186:187], v[6:7], v[172:173], v[186:187] op_sel:[0,1,0] neg_lo:[1,0,0] neg_hi:[1,0,0]
	v_pk_fma_f32 v[38:39], v[16:17], v[172:173], v[38:39] op_sel_hi:[1,0,1] neg_lo:[1,0,0] neg_hi:[1,0,0]
	ds_read_b128 v[170:173], v20 offset:45344
	s_waitcnt lgkmcnt(5)
	v_pk_fma_f32 v[186:187], v[12:13], v[174:175], v[186:187] op_sel:[0,1,0] neg_lo:[1,0,0] neg_hi:[1,0,0]
	v_pk_fma_f32 v[38:39], v[18:19], v[174:175], v[38:39] op_sel_hi:[1,0,1] neg_lo:[1,0,0] neg_hi:[1,0,0]
	v_pk_fma_f32 v[186:187], v[4:5], v[176:177], v[186:187] op_sel:[0,1,0] neg_lo:[1,0,0] neg_hi:[1,0,0]
	v_pk_fma_f32 v[38:39], v[8:9], v[176:177], v[38:39] op_sel_hi:[1,0,1] neg_lo:[1,0,0] neg_hi:[1,0,0]
	ds_read_b128 v[174:177], v20 offset:45360
	s_waitcnt lgkmcnt(5)
	v_pk_fma_f32 v[186:187], v[0:1], v[178:179], v[186:187] op_sel:[0,1,0] neg_lo:[1,0,0] neg_hi:[1,0,0]
	v_pk_fma_f32 v[38:39], v[2:3], v[178:179], v[38:39] op_sel_hi:[1,0,1] neg_lo:[1,0,0] neg_hi:[1,0,0]
	v_pk_fma_f32 v[186:187], v[28:29], v[180:181], v[186:187] op_sel:[0,1,0] neg_lo:[1,0,0] neg_hi:[1,0,0]
	v_pk_fma_f32 v[38:39], v[30:31], v[180:181], v[38:39] op_sel_hi:[1,0,1] neg_lo:[1,0,0] neg_hi:[1,0,0]
	ds_read_b128 v[178:181], v20 offset:45376
	s_waitcnt lgkmcnt(5)
	v_pk_fma_f32 v[186:187], v[34:35], v[182:183], v[186:187] op_sel:[0,1,0] neg_lo:[1,0,0] neg_hi:[1,0,0]
	v_pk_fma_f32 v[38:39], v[32:33], v[182:183], v[38:39] op_sel_hi:[1,0,1] neg_lo:[1,0,0] neg_hi:[1,0,0]
	v_pk_fma_f32 v[186:187], v[184:185], v[40:41], v[186:187] op_sel:[1,0,0] neg_lo:[1,0,0] neg_hi:[1,0,0]
	v_pk_fma_f32 v[38:39], v[36:37], v[184:185], v[38:39] op_sel_hi:[1,0,1] neg_lo:[1,0,0] neg_hi:[1,0,0]
	ds_read_b128 v[182:185], v20 offset:45392
	v_pk_add_f32 v[38:39], v[38:39], v[186:187]
	s_waitcnt lgkmcnt(5)
	v_pk_fma_f32 v[42:43], v[138:139], v[160:161], 0 op_sel:[0,1,0] op_sel_hi:[1,1,0] neg_lo:[1,0,0] neg_hi:[1,0,0]
	v_pk_fma_f32 v[252:253], v[128:129], v[160:161], v[158:159] op_sel_hi:[1,0,1] neg_lo:[1,0,0] neg_hi:[1,0,0]
	v_pk_fma_f32 v[42:43], v[134:135], v[162:163], v[42:43] op_sel:[0,1,0] neg_lo:[1,0,0] neg_hi:[1,0,0]
	v_pk_fma_f32 v[252:253], v[136:137], v[162:163], v[252:253] op_sel_hi:[1,0,1] neg_lo:[1,0,0] neg_hi:[1,0,0]
	s_waitcnt lgkmcnt(4)
	v_pk_fma_f32 v[42:43], v[130:131], v[166:167], v[42:43] op_sel:[0,1,0] neg_lo:[1,0,0] neg_hi:[1,0,0]
	v_pk_fma_f32 v[252:253], v[132:133], v[166:167], v[252:253] op_sel_hi:[1,0,1] neg_lo:[1,0,0] neg_hi:[1,0,0]
	v_pk_fma_f32 v[42:43], v[84:85], v[168:169], v[42:43] op_sel:[0,1,0] neg_lo:[1,0,0] neg_hi:[1,0,0]
	v_pk_fma_f32 v[252:253], v[122:123], v[168:169], v[252:253] op_sel_hi:[1,0,1] neg_lo:[1,0,0] neg_hi:[1,0,0]
	ds_read_b128 v[166:169], v20 offset:45584
	s_waitcnt lgkmcnt(4)
	v_pk_fma_f32 v[42:43], v[10:11], v[170:171], v[42:43] op_sel:[0,1,0] neg_lo:[1,0,0] neg_hi:[1,0,0]
	v_pk_fma_f32 v[252:253], v[14:15], v[170:171], v[252:253] op_sel_hi:[1,0,1] neg_lo:[1,0,0] neg_hi:[1,0,0]
	v_pk_fma_f32 v[42:43], v[6:7], v[172:173], v[42:43] op_sel:[0,1,0] neg_lo:[1,0,0] neg_hi:[1,0,0]
	v_pk_fma_f32 v[252:253], v[16:17], v[172:173], v[252:253] op_sel_hi:[1,0,1] neg_lo:[1,0,0] neg_hi:[1,0,0]
	ds_read_b128 v[170:173], v20 offset:45600
	s_waitcnt lgkmcnt(4)
	v_pk_fma_f32 v[42:43], v[12:13], v[174:175], v[42:43] op_sel:[0,1,0] neg_lo:[1,0,0] neg_hi:[1,0,0]
	v_pk_fma_f32 v[252:253], v[18:19], v[174:175], v[252:253] op_sel_hi:[1,0,1] neg_lo:[1,0,0] neg_hi:[1,0,0]
	v_pk_fma_f32 v[42:43], v[4:5], v[176:177], v[42:43] op_sel:[0,1,0] neg_lo:[1,0,0] neg_hi:[1,0,0]
	v_pk_fma_f32 v[252:253], v[8:9], v[176:177], v[252:253] op_sel_hi:[1,0,1] neg_lo:[1,0,0] neg_hi:[1,0,0]
	ds_read_b128 v[174:177], v20 offset:45616
	s_waitcnt lgkmcnt(4)
	v_pk_fma_f32 v[42:43], v[0:1], v[178:179], v[42:43] op_sel:[0,1,0] neg_lo:[1,0,0] neg_hi:[1,0,0]
	v_pk_fma_f32 v[252:253], v[2:3], v[178:179], v[252:253] op_sel_hi:[1,0,1] neg_lo:[1,0,0] neg_hi:[1,0,0]
	v_pk_fma_f32 v[42:43], v[28:29], v[180:181], v[42:43] op_sel:[0,1,0] neg_lo:[1,0,0] neg_hi:[1,0,0]
	v_pk_fma_f32 v[252:253], v[30:31], v[180:181], v[252:253] op_sel_hi:[1,0,1] neg_lo:[1,0,0] neg_hi:[1,0,0]
	ds_read_b128 v[178:181], v20 offset:45632
	s_waitcnt lgkmcnt(4)
	v_pk_fma_f32 v[42:43], v[34:35], v[182:183], v[42:43] op_sel:[0,1,0] neg_lo:[1,0,0] neg_hi:[1,0,0]
	v_pk_fma_f32 v[252:253], v[32:33], v[182:183], v[252:253] op_sel_hi:[1,0,1] neg_lo:[1,0,0] neg_hi:[1,0,0]
	v_pk_fma_f32 v[42:43], v[40:41], v[184:185], v[42:43] op_sel:[0,1,0] neg_lo:[1,0,0] neg_hi:[1,0,0]
	v_pk_fma_f32 v[252:253], v[36:37], v[184:185], v[252:253] op_sel_hi:[1,0,1] neg_lo:[1,0,0] neg_hi:[1,0,0]
	ds_read_b128 v[182:185], v20 offset:45648
	v_pk_fma_f32 v[42:43], v[158:159], v[208:209], v[42:43] op_sel:[0,1,0] neg_lo:[1,0,0] neg_hi:[1,0,0]
	ds_read_b128 v[158:161], v20 offset:45568
	v_pk_fma_f32 v[42:43], v[46:47], v[210:211], v[42:43] op_sel:[0,1,0] neg_lo:[1,0,0] neg_hi:[1,0,0]
	v_pk_fma_f32 v[252:253], v[208:209], v[38:39], v[252:253] op_sel_hi:[0,1,1] neg_lo:[1,0,0] neg_hi:[1,0,0]
	s_waitcnt lgkmcnt(0)
	v_pk_fma_f32 v[162:163], v[138:139], v[158:159], 0 op_sel:[0,1,0] op_sel_hi:[1,1,0] neg_lo:[1,0,0] neg_hi:[1,0,0]
	v_pk_fma_f32 v[252:253], v[44:45], v[210:211], v[252:253] op_sel_hi:[1,0,1] neg_lo:[1,0,0] neg_hi:[1,0,0]
	ds_read_b128 v[208:211], v20 offset:45664
	v_pk_add_f32 v[42:43], v[252:253], v[42:43]
	v_pk_fma_f32 v[158:159], v[128:129], v[158:159], v[44:45] op_sel_hi:[1,0,1] neg_lo:[1,0,0] neg_hi:[1,0,0]
	v_pk_fma_f32 v[162:163], v[134:135], v[160:161], v[162:163] op_sel:[0,1,0] neg_lo:[1,0,0] neg_hi:[1,0,0]
	v_pk_fma_f32 v[158:159], v[136:137], v[160:161], v[158:159] op_sel_hi:[1,0,1] neg_lo:[1,0,0] neg_hi:[1,0,0]
	v_pk_fma_f32 v[162:163], v[130:131], v[166:167], v[162:163] op_sel:[0,1,0] neg_lo:[1,0,0] neg_hi:[1,0,0]
	v_pk_fma_f32 v[158:159], v[132:133], v[166:167], v[158:159] op_sel_hi:[1,0,1] neg_lo:[1,0,0] neg_hi:[1,0,0]
	v_pk_fma_f32 v[162:163], v[84:85], v[168:169], v[162:163] op_sel:[0,1,0] neg_lo:[1,0,0] neg_hi:[1,0,0]
	v_pk_fma_f32 v[158:159], v[122:123], v[168:169], v[158:159] op_sel_hi:[1,0,1] neg_lo:[1,0,0] neg_hi:[1,0,0]
	ds_read_b128 v[166:169], v20 offset:45840
	v_pk_fma_f32 v[162:163], v[10:11], v[170:171], v[162:163] op_sel:[0,1,0] neg_lo:[1,0,0] neg_hi:[1,0,0]
	v_pk_fma_f32 v[158:159], v[14:15], v[170:171], v[158:159] op_sel_hi:[1,0,1] neg_lo:[1,0,0] neg_hi:[1,0,0]
	v_pk_fma_f32 v[162:163], v[6:7], v[172:173], v[162:163] op_sel:[0,1,0] neg_lo:[1,0,0] neg_hi:[1,0,0]
	v_pk_fma_f32 v[158:159], v[16:17], v[172:173], v[158:159] op_sel_hi:[1,0,1] neg_lo:[1,0,0] neg_hi:[1,0,0]
	ds_read_b128 v[170:173], v20 offset:45856
	v_pk_fma_f32 v[162:163], v[12:13], v[174:175], v[162:163] op_sel:[0,1,0] neg_lo:[1,0,0] neg_hi:[1,0,0]
	v_pk_fma_f32 v[158:159], v[18:19], v[174:175], v[158:159] op_sel_hi:[1,0,1] neg_lo:[1,0,0] neg_hi:[1,0,0]
	v_pk_fma_f32 v[162:163], v[4:5], v[176:177], v[162:163] op_sel:[0,1,0] neg_lo:[1,0,0] neg_hi:[1,0,0]
	v_pk_fma_f32 v[158:159], v[8:9], v[176:177], v[158:159] op_sel_hi:[1,0,1] neg_lo:[1,0,0] neg_hi:[1,0,0]
	ds_read_b128 v[174:177], v20 offset:45872
	v_pk_fma_f32 v[162:163], v[0:1], v[178:179], v[162:163] op_sel:[0,1,0] neg_lo:[1,0,0] neg_hi:[1,0,0]
	v_pk_fma_f32 v[158:159], v[2:3], v[178:179], v[158:159] op_sel_hi:[1,0,1] neg_lo:[1,0,0] neg_hi:[1,0,0]
	v_pk_fma_f32 v[162:163], v[28:29], v[180:181], v[162:163] op_sel:[0,1,0] neg_lo:[1,0,0] neg_hi:[1,0,0]
	v_pk_fma_f32 v[158:159], v[30:31], v[180:181], v[158:159] op_sel_hi:[1,0,1] neg_lo:[1,0,0] neg_hi:[1,0,0]
	ds_read_b128 v[178:181], v20 offset:45888
	v_pk_fma_f32 v[162:163], v[34:35], v[182:183], v[162:163] op_sel:[0,1,0] neg_lo:[1,0,0] neg_hi:[1,0,0]
	v_pk_fma_f32 v[158:159], v[32:33], v[182:183], v[158:159] op_sel_hi:[1,0,1] neg_lo:[1,0,0] neg_hi:[1,0,0]
	v_pk_fma_f32 v[162:163], v[40:41], v[184:185], v[162:163] op_sel:[0,1,0] neg_lo:[1,0,0] neg_hi:[1,0,0]
	v_pk_fma_f32 v[158:159], v[36:37], v[184:185], v[158:159] op_sel_hi:[1,0,1] neg_lo:[1,0,0] neg_hi:[1,0,0]
	ds_read_b128 v[182:185], v20 offset:45904
	s_waitcnt lgkmcnt(5)
	v_pk_fma_f32 v[162:163], v[208:209], v[42:43], v[162:163] op_sel:[1,0,0] neg_lo:[1,0,0] neg_hi:[1,0,0]
	v_pk_fma_f32 v[158:159], v[38:39], v[208:209], v[158:159] op_sel_hi:[1,0,1] neg_lo:[1,0,0] neg_hi:[1,0,0]
	v_pk_fma_f32 v[162:163], v[46:47], v[210:211], v[162:163] op_sel:[0,1,0] neg_lo:[1,0,0] neg_hi:[1,0,0]
	v_pk_fma_f32 v[44:45], v[44:45], v[210:211], v[158:159] op_sel_hi:[1,0,1] neg_lo:[1,0,0] neg_hi:[1,0,0]
	ds_read_b128 v[158:161], v20 offset:45824
	ds_read_b128 v[208:211], v20 offset:45920
	v_pk_add_f32 v[44:45], v[44:45], v[162:163]
	s_waitcnt lgkmcnt(1)
	v_pk_fma_f32 v[162:163], v[138:139], v[158:159], 0 op_sel:[0,1,0] op_sel_hi:[1,1,0] neg_lo:[1,0,0] neg_hi:[1,0,0]
	v_pk_fma_f32 v[252:253], v[128:129], v[158:159], v[46:47] op_sel_hi:[1,0,1] neg_lo:[1,0,0] neg_hi:[1,0,0]
	v_pk_fma_f32 v[162:163], v[134:135], v[160:161], v[162:163] op_sel:[0,1,0] neg_lo:[1,0,0] neg_hi:[1,0,0]
	v_pk_fma_f32 v[252:253], v[136:137], v[160:161], v[252:253] op_sel_hi:[1,0,1] neg_lo:[1,0,0] neg_hi:[1,0,0]
	ds_read_b128 v[158:161], v20 offset:46080
	v_pk_fma_f32 v[162:163], v[130:131], v[166:167], v[162:163] op_sel:[0,1,0] neg_lo:[1,0,0] neg_hi:[1,0,0]
	v_pk_fma_f32 v[252:253], v[132:133], v[166:167], v[252:253] op_sel_hi:[1,0,1] neg_lo:[1,0,0] neg_hi:[1,0,0]
	v_pk_fma_f32 v[162:163], v[84:85], v[168:169], v[162:163] op_sel:[0,1,0] neg_lo:[1,0,0] neg_hi:[1,0,0]
	v_pk_fma_f32 v[252:253], v[122:123], v[168:169], v[252:253] op_sel_hi:[1,0,1] neg_lo:[1,0,0] neg_hi:[1,0,0]
	ds_read_b128 v[166:169], v20 offset:46096
	v_pk_fma_f32 v[162:163], v[10:11], v[170:171], v[162:163] op_sel:[0,1,0] neg_lo:[1,0,0] neg_hi:[1,0,0]
	v_pk_fma_f32 v[252:253], v[14:15], v[170:171], v[252:253] op_sel_hi:[1,0,1] neg_lo:[1,0,0] neg_hi:[1,0,0]
	v_pk_fma_f32 v[162:163], v[6:7], v[172:173], v[162:163] op_sel:[0,1,0] neg_lo:[1,0,0] neg_hi:[1,0,0]
	v_pk_fma_f32 v[252:253], v[16:17], v[172:173], v[252:253] op_sel_hi:[1,0,1] neg_lo:[1,0,0] neg_hi:[1,0,0]
	ds_read_b128 v[170:173], v20 offset:46112
	v_pk_fma_f32 v[162:163], v[12:13], v[174:175], v[162:163] op_sel:[0,1,0] neg_lo:[1,0,0] neg_hi:[1,0,0]
	v_pk_fma_f32 v[252:253], v[18:19], v[174:175], v[252:253] op_sel_hi:[1,0,1] neg_lo:[1,0,0] neg_hi:[1,0,0]
	v_pk_fma_f32 v[162:163], v[4:5], v[176:177], v[162:163] op_sel:[0,1,0] neg_lo:[1,0,0] neg_hi:[1,0,0]
	v_pk_fma_f32 v[252:253], v[8:9], v[176:177], v[252:253] op_sel_hi:[1,0,1] neg_lo:[1,0,0] neg_hi:[1,0,0]
	ds_read_b128 v[174:177], v20 offset:46128
	v_pk_fma_f32 v[162:163], v[0:1], v[178:179], v[162:163] op_sel:[0,1,0] neg_lo:[1,0,0] neg_hi:[1,0,0]
	v_pk_fma_f32 v[252:253], v[2:3], v[178:179], v[252:253] op_sel_hi:[1,0,1] neg_lo:[1,0,0] neg_hi:[1,0,0]
	v_pk_fma_f32 v[162:163], v[28:29], v[180:181], v[162:163] op_sel:[0,1,0] neg_lo:[1,0,0] neg_hi:[1,0,0]
	v_pk_fma_f32 v[252:253], v[30:31], v[180:181], v[252:253] op_sel_hi:[1,0,1] neg_lo:[1,0,0] neg_hi:[1,0,0]
	ds_read_b128 v[178:181], v20 offset:46144
	v_pk_fma_f32 v[162:163], v[34:35], v[182:183], v[162:163] op_sel:[0,1,0] neg_lo:[1,0,0] neg_hi:[1,0,0]
	v_pk_fma_f32 v[252:253], v[32:33], v[182:183], v[252:253] op_sel_hi:[1,0,1] neg_lo:[1,0,0] neg_hi:[1,0,0]
	v_pk_fma_f32 v[162:163], v[40:41], v[184:185], v[162:163] op_sel:[0,1,0] neg_lo:[1,0,0] neg_hi:[1,0,0]
	v_pk_fma_f32 v[252:253], v[36:37], v[184:185], v[252:253] op_sel_hi:[1,0,1] neg_lo:[1,0,0] neg_hi:[1,0,0]
	ds_read_b128 v[182:185], v20 offset:46160
	s_waitcnt lgkmcnt(6)
	v_pk_fma_f32 v[162:163], v[42:43], v[208:209], v[162:163] op_sel:[0,1,0] neg_lo:[1,0,0] neg_hi:[1,0,0]
	v_pk_fma_f32 v[252:253], v[38:39], v[208:209], v[252:253] op_sel_hi:[1,0,1] neg_lo:[1,0,0] neg_hi:[1,0,0]
	v_pk_fma_f32 v[162:163], v[46:47], v[210:211], v[162:163] op_sel:[0,1,0] neg_lo:[1,0,0] neg_hi:[1,0,0]
	v_pk_fma_f32 v[252:253], v[210:211], v[44:45], v[252:253] op_sel_hi:[0,1,1] neg_lo:[1,0,0] neg_hi:[1,0,0]
	ds_read_b128 v[208:211], v20 offset:46176
	v_pk_add_f32 v[46:47], v[252:253], v[162:163]
	s_waitcnt lgkmcnt(6)
	v_pk_fma_f32 v[162:163], v[138:139], v[158:159], 0 op_sel:[0,1,0] op_sel_hi:[1,1,0] neg_lo:[1,0,0] neg_hi:[1,0,0]
	v_pk_mul_f32 v[158:159], v[128:129], v[158:159] op_sel_hi:[1,0]
	v_pk_fma_f32 v[162:163], v[134:135], v[160:161], v[162:163] op_sel:[0,1,0] neg_lo:[1,0,0] neg_hi:[1,0,0]
	v_pk_fma_f32 v[48:49], v[48:49], v[50:51], v[158:159] neg_lo:[0,0,1] neg_hi:[0,0,1]
	s_waitcnt lgkmcnt(5)
	v_pk_fma_f32 v[162:163], v[130:131], v[166:167], v[162:163] op_sel:[0,1,0] neg_lo:[1,0,0] neg_hi:[1,0,0]
	v_pk_fma_f32 v[48:49], v[136:137], v[160:161], v[48:49] op_sel_hi:[1,0,1] neg_lo:[1,0,0] neg_hi:[1,0,0]
	ds_read_b128 v[158:161], v20 offset:46336
	v_pk_fma_f32 v[48:49], v[132:133], v[166:167], v[48:49] op_sel_hi:[1,0,1] neg_lo:[1,0,0] neg_hi:[1,0,0]
	v_pk_fma_f32 v[162:163], v[84:85], v[168:169], v[162:163] op_sel:[0,1,0] neg_lo:[1,0,0] neg_hi:[1,0,0]
	v_pk_fma_f32 v[48:49], v[122:123], v[168:169], v[48:49] op_sel_hi:[1,0,1] neg_lo:[1,0,0] neg_hi:[1,0,0]
	ds_read_b128 v[166:169], v20 offset:46352
	s_waitcnt lgkmcnt(6)
	v_pk_fma_f32 v[162:163], v[10:11], v[170:171], v[162:163] op_sel:[0,1,0] neg_lo:[1,0,0] neg_hi:[1,0,0]
	v_pk_fma_f32 v[48:49], v[14:15], v[170:171], v[48:49] op_sel_hi:[1,0,1] neg_lo:[1,0,0] neg_hi:[1,0,0]
	v_pk_fma_f32 v[162:163], v[6:7], v[172:173], v[162:163] op_sel:[0,1,0] neg_lo:[1,0,0] neg_hi:[1,0,0]
	v_pk_fma_f32 v[48:49], v[16:17], v[172:173], v[48:49] op_sel_hi:[1,0,1] neg_lo:[1,0,0] neg_hi:[1,0,0]
	ds_read_b128 v[170:173], v20 offset:46368
	s_waitcnt lgkmcnt(6)
	v_pk_fma_f32 v[162:163], v[12:13], v[174:175], v[162:163] op_sel:[0,1,0] neg_lo:[1,0,0] neg_hi:[1,0,0]
	v_pk_fma_f32 v[48:49], v[18:19], v[174:175], v[48:49] op_sel_hi:[1,0,1] neg_lo:[1,0,0] neg_hi:[1,0,0]
	v_pk_fma_f32 v[162:163], v[4:5], v[176:177], v[162:163] op_sel:[0,1,0] neg_lo:[1,0,0] neg_hi:[1,0,0]
	v_pk_fma_f32 v[48:49], v[8:9], v[176:177], v[48:49] op_sel_hi:[1,0,1] neg_lo:[1,0,0] neg_hi:[1,0,0]
	ds_read_b128 v[174:177], v20 offset:46384
	s_waitcnt lgkmcnt(6)
	v_pk_fma_f32 v[162:163], v[0:1], v[178:179], v[162:163] op_sel:[0,1,0] neg_lo:[1,0,0] neg_hi:[1,0,0]
	v_pk_fma_f32 v[48:49], v[2:3], v[178:179], v[48:49] op_sel_hi:[1,0,1] neg_lo:[1,0,0] neg_hi:[1,0,0]
	v_pk_fma_f32 v[162:163], v[28:29], v[180:181], v[162:163] op_sel:[0,1,0] neg_lo:[1,0,0] neg_hi:[1,0,0]
	v_pk_fma_f32 v[48:49], v[30:31], v[180:181], v[48:49] op_sel_hi:[1,0,1] neg_lo:[1,0,0] neg_hi:[1,0,0]
	ds_read_b128 v[178:181], v20 offset:46400
	s_waitcnt lgkmcnt(6)
	v_pk_fma_f32 v[162:163], v[34:35], v[182:183], v[162:163] op_sel:[0,1,0] neg_lo:[1,0,0] neg_hi:[1,0,0]
	v_pk_fma_f32 v[48:49], v[32:33], v[182:183], v[48:49] op_sel_hi:[1,0,1] neg_lo:[1,0,0] neg_hi:[1,0,0]
	v_pk_fma_f32 v[162:163], v[40:41], v[184:185], v[162:163] op_sel:[0,1,0] neg_lo:[1,0,0] neg_hi:[1,0,0]
	v_pk_fma_f32 v[48:49], v[36:37], v[184:185], v[48:49] op_sel_hi:[1,0,1] neg_lo:[1,0,0] neg_hi:[1,0,0]
	ds_read_b128 v[182:185], v20 offset:46416
	s_waitcnt lgkmcnt(6)
	v_pk_fma_f32 v[162:163], v[42:43], v[208:209], v[162:163] op_sel:[0,1,0] neg_lo:[1,0,0] neg_hi:[1,0,0]
	v_pk_fma_f32 v[48:49], v[38:39], v[208:209], v[48:49] op_sel_hi:[1,0,1] neg_lo:[1,0,0] neg_hi:[1,0,0]
	v_pk_fma_f32 v[162:163], v[210:211], v[46:47], v[162:163] op_sel:[1,0,0] neg_lo:[1,0,0] neg_hi:[1,0,0]
	v_pk_fma_f32 v[48:49], v[44:45], v[210:211], v[48:49] op_sel_hi:[1,0,1] neg_lo:[1,0,0] neg_hi:[1,0,0]
	ds_read_b128 v[208:211], v20 offset:46432
	v_pk_add_f32 v[48:49], v[48:49], v[162:163]
	s_waitcnt lgkmcnt(6)
	v_pk_fma_f32 v[50:51], v[138:139], v[158:159], 0 op_sel:[0,1,0] op_sel_hi:[1,1,0] neg_lo:[1,0,0] neg_hi:[1,0,0]
	v_pk_fma_f32 v[252:253], v[128:129], v[158:159], v[156:157] op_sel_hi:[1,0,1] neg_lo:[1,0,0] neg_hi:[1,0,0]
	v_pk_fma_f32 v[50:51], v[134:135], v[160:161], v[50:51] op_sel:[0,1,0] neg_lo:[1,0,0] neg_hi:[1,0,0]
	v_pk_fma_f32 v[252:253], v[136:137], v[160:161], v[252:253] op_sel_hi:[1,0,1] neg_lo:[1,0,0] neg_hi:[1,0,0]
	ds_read_b128 v[160:163], v20 offset:46608
	s_waitcnt lgkmcnt(6)
	v_pk_fma_f32 v[50:51], v[130:131], v[166:167], v[50:51] op_sel:[0,1,0] neg_lo:[1,0,0] neg_hi:[1,0,0]
	v_pk_fma_f32 v[252:253], v[132:133], v[166:167], v[252:253] op_sel_hi:[1,0,1] neg_lo:[1,0,0] neg_hi:[1,0,0]
	v_pk_fma_f32 v[50:51], v[84:85], v[168:169], v[50:51] op_sel:[0,1,0] neg_lo:[1,0,0] neg_hi:[1,0,0]
	v_pk_fma_f32 v[252:253], v[122:123], v[168:169], v[252:253] op_sel_hi:[1,0,1] neg_lo:[1,0,0] neg_hi:[1,0,0]
	ds_read_b128 v[166:169], v20 offset:46624
	s_waitcnt lgkmcnt(6)
	v_pk_fma_f32 v[50:51], v[10:11], v[170:171], v[50:51] op_sel:[0,1,0] neg_lo:[1,0,0] neg_hi:[1,0,0]
	v_pk_fma_f32 v[252:253], v[14:15], v[170:171], v[252:253] op_sel_hi:[1,0,1] neg_lo:[1,0,0] neg_hi:[1,0,0]
	v_pk_fma_f32 v[50:51], v[6:7], v[172:173], v[50:51] op_sel:[0,1,0] neg_lo:[1,0,0] neg_hi:[1,0,0]
	v_pk_fma_f32 v[252:253], v[16:17], v[172:173], v[252:253] op_sel_hi:[1,0,1] neg_lo:[1,0,0] neg_hi:[1,0,0]
	ds_read_b128 v[170:173], v20 offset:46640
	s_waitcnt lgkmcnt(6)
	v_pk_fma_f32 v[50:51], v[12:13], v[174:175], v[50:51] op_sel:[0,1,0] neg_lo:[1,0,0] neg_hi:[1,0,0]
	v_pk_fma_f32 v[252:253], v[18:19], v[174:175], v[252:253] op_sel_hi:[1,0,1] neg_lo:[1,0,0] neg_hi:[1,0,0]
	v_pk_fma_f32 v[50:51], v[4:5], v[176:177], v[50:51] op_sel:[0,1,0] neg_lo:[1,0,0] neg_hi:[1,0,0]
	v_pk_fma_f32 v[252:253], v[8:9], v[176:177], v[252:253] op_sel_hi:[1,0,1] neg_lo:[1,0,0] neg_hi:[1,0,0]
	ds_read_b128 v[174:177], v20 offset:46656
	s_waitcnt lgkmcnt(6)
	v_pk_fma_f32 v[50:51], v[0:1], v[178:179], v[50:51] op_sel:[0,1,0] neg_lo:[1,0,0] neg_hi:[1,0,0]
	v_pk_fma_f32 v[252:253], v[2:3], v[178:179], v[252:253] op_sel_hi:[1,0,1] neg_lo:[1,0,0] neg_hi:[1,0,0]
	v_pk_fma_f32 v[50:51], v[28:29], v[180:181], v[50:51] op_sel:[0,1,0] neg_lo:[1,0,0] neg_hi:[1,0,0]
	v_pk_fma_f32 v[252:253], v[30:31], v[180:181], v[252:253] op_sel_hi:[1,0,1] neg_lo:[1,0,0] neg_hi:[1,0,0]
	ds_read_b128 v[178:181], v20 offset:46672
	s_waitcnt lgkmcnt(6)
	v_pk_fma_f32 v[50:51], v[34:35], v[182:183], v[50:51] op_sel:[0,1,0] neg_lo:[1,0,0] neg_hi:[1,0,0]
	v_pk_fma_f32 v[252:253], v[32:33], v[182:183], v[252:253] op_sel_hi:[1,0,1] neg_lo:[1,0,0] neg_hi:[1,0,0]
	v_pk_fma_f32 v[50:51], v[40:41], v[184:185], v[50:51] op_sel:[0,1,0] neg_lo:[1,0,0] neg_hi:[1,0,0]
	v_pk_fma_f32 v[252:253], v[36:37], v[184:185], v[252:253] op_sel_hi:[1,0,1] neg_lo:[1,0,0] neg_hi:[1,0,0]
	ds_read_b128 v[182:185], v20 offset:46688
	s_waitcnt lgkmcnt(6)
	v_pk_fma_f32 v[50:51], v[42:43], v[208:209], v[50:51] op_sel:[0,1,0] neg_lo:[1,0,0] neg_hi:[1,0,0]
	v_pk_fma_f32 v[252:253], v[38:39], v[208:209], v[252:253] op_sel_hi:[1,0,1] neg_lo:[1,0,0] neg_hi:[1,0,0]
	v_pk_fma_f32 v[50:51], v[46:47], v[210:211], v[50:51] op_sel:[0,1,0] neg_lo:[1,0,0] neg_hi:[1,0,0]
	v_pk_fma_f32 v[252:253], v[44:45], v[210:211], v[252:253] op_sel_hi:[1,0,1] neg_lo:[1,0,0] neg_hi:[1,0,0]
	ds_read_b128 v[208:211], v20 offset:46704
	v_pk_fma_f32 v[50:51], v[156:157], v[212:213], v[50:51] op_sel:[0,1,0] neg_lo:[1,0,0] neg_hi:[1,0,0]
	ds_read_b128 v[156:159], v20 offset:46592
	v_pk_fma_f32 v[50:51], v[54:55], v[214:215], v[50:51] op_sel:[0,1,0] neg_lo:[1,0,0] neg_hi:[1,0,0]
	v_pk_fma_f32 v[252:253], v[212:213], v[48:49], v[252:253] op_sel_hi:[0,1,1] neg_lo:[1,0,0] neg_hi:[1,0,0]
	s_waitcnt lgkmcnt(0)
	v_pk_fma_f32 v[186:187], v[138:139], v[156:157], 0 op_sel:[0,1,0] op_sel_hi:[1,1,0] neg_lo:[1,0,0] neg_hi:[1,0,0]
	v_pk_fma_f32 v[252:253], v[52:53], v[214:215], v[252:253] op_sel_hi:[1,0,1] neg_lo:[1,0,0] neg_hi:[1,0,0]
	v_pk_fma_f32 v[156:157], v[128:129], v[156:157], v[52:53] op_sel_hi:[1,0,1] neg_lo:[1,0,0] neg_hi:[1,0,0]
	v_pk_add_f32 v[50:51], v[252:253], v[50:51]
	v_pk_fma_f32 v[186:187], v[134:135], v[158:159], v[186:187] op_sel:[0,1,0] neg_lo:[1,0,0] neg_hi:[1,0,0]
	v_pk_fma_f32 v[156:157], v[136:137], v[158:159], v[156:157] op_sel_hi:[1,0,1] neg_lo:[1,0,0] neg_hi:[1,0,0]
	v_pk_fma_f32 v[186:187], v[130:131], v[160:161], v[186:187] op_sel:[0,1,0] neg_lo:[1,0,0] neg_hi:[1,0,0]
	v_pk_fma_f32 v[156:157], v[132:133], v[160:161], v[156:157] op_sel_hi:[1,0,1] neg_lo:[1,0,0] neg_hi:[1,0,0]
	v_pk_fma_f32 v[186:187], v[84:85], v[162:163], v[186:187] op_sel:[0,1,0] neg_lo:[1,0,0] neg_hi:[1,0,0]
	v_pk_fma_f32 v[156:157], v[122:123], v[162:163], v[156:157] op_sel_hi:[1,0,1] neg_lo:[1,0,0] neg_hi:[1,0,0]
	ds_read_b128 v[160:163], v20 offset:46864
	v_pk_fma_f32 v[186:187], v[10:11], v[166:167], v[186:187] op_sel:[0,1,0] neg_lo:[1,0,0] neg_hi:[1,0,0]
	v_pk_fma_f32 v[156:157], v[14:15], v[166:167], v[156:157] op_sel_hi:[1,0,1] neg_lo:[1,0,0] neg_hi:[1,0,0]
	v_pk_fma_f32 v[186:187], v[6:7], v[168:169], v[186:187] op_sel:[0,1,0] neg_lo:[1,0,0] neg_hi:[1,0,0]
	v_pk_fma_f32 v[156:157], v[16:17], v[168:169], v[156:157] op_sel_hi:[1,0,1] neg_lo:[1,0,0] neg_hi:[1,0,0]
	ds_read_b128 v[166:169], v20 offset:46880
	v_pk_fma_f32 v[186:187], v[12:13], v[170:171], v[186:187] op_sel:[0,1,0] neg_lo:[1,0,0] neg_hi:[1,0,0]
	v_pk_fma_f32 v[156:157], v[18:19], v[170:171], v[156:157] op_sel_hi:[1,0,1] neg_lo:[1,0,0] neg_hi:[1,0,0]
	v_pk_fma_f32 v[186:187], v[4:5], v[172:173], v[186:187] op_sel:[0,1,0] neg_lo:[1,0,0] neg_hi:[1,0,0]
	v_pk_fma_f32 v[156:157], v[8:9], v[172:173], v[156:157] op_sel_hi:[1,0,1] neg_lo:[1,0,0] neg_hi:[1,0,0]
	ds_read_b128 v[170:173], v20 offset:46896
	v_pk_fma_f32 v[186:187], v[0:1], v[174:175], v[186:187] op_sel:[0,1,0] neg_lo:[1,0,0] neg_hi:[1,0,0]
	v_pk_fma_f32 v[156:157], v[2:3], v[174:175], v[156:157] op_sel_hi:[1,0,1] neg_lo:[1,0,0] neg_hi:[1,0,0]
	v_pk_fma_f32 v[186:187], v[28:29], v[176:177], v[186:187] op_sel:[0,1,0] neg_lo:[1,0,0] neg_hi:[1,0,0]
	v_pk_fma_f32 v[156:157], v[30:31], v[176:177], v[156:157] op_sel_hi:[1,0,1] neg_lo:[1,0,0] neg_hi:[1,0,0]
	ds_read_b128 v[174:177], v20 offset:46912
	v_pk_fma_f32 v[186:187], v[34:35], v[178:179], v[186:187] op_sel:[0,1,0] neg_lo:[1,0,0] neg_hi:[1,0,0]
	v_pk_fma_f32 v[156:157], v[32:33], v[178:179], v[156:157] op_sel_hi:[1,0,1] neg_lo:[1,0,0] neg_hi:[1,0,0]
	v_pk_fma_f32 v[186:187], v[40:41], v[180:181], v[186:187] op_sel:[0,1,0] neg_lo:[1,0,0] neg_hi:[1,0,0]
	v_pk_fma_f32 v[156:157], v[36:37], v[180:181], v[156:157] op_sel_hi:[1,0,1] neg_lo:[1,0,0] neg_hi:[1,0,0]
	ds_read_b128 v[178:181], v20 offset:46928
	v_pk_fma_f32 v[186:187], v[42:43], v[182:183], v[186:187] op_sel:[0,1,0] neg_lo:[1,0,0] neg_hi:[1,0,0]
	v_pk_fma_f32 v[156:157], v[38:39], v[182:183], v[156:157] op_sel_hi:[1,0,1] neg_lo:[1,0,0] neg_hi:[1,0,0]
	v_pk_fma_f32 v[186:187], v[46:47], v[184:185], v[186:187] op_sel:[0,1,0] neg_lo:[1,0,0] neg_hi:[1,0,0]
	v_pk_fma_f32 v[156:157], v[44:45], v[184:185], v[156:157] op_sel_hi:[1,0,1] neg_lo:[1,0,0] neg_hi:[1,0,0]
	ds_read_b128 v[182:185], v20 offset:46944
	v_pk_fma_f32 v[186:187], v[208:209], v[50:51], v[186:187] op_sel:[1,0,0] neg_lo:[1,0,0] neg_hi:[1,0,0]
	v_pk_fma_f32 v[156:157], v[48:49], v[208:209], v[156:157] op_sel_hi:[1,0,1] neg_lo:[1,0,0] neg_hi:[1,0,0]
	v_pk_fma_f32 v[186:187], v[54:55], v[210:211], v[186:187] op_sel:[0,1,0] neg_lo:[1,0,0] neg_hi:[1,0,0]
	v_pk_fma_f32 v[52:53], v[52:53], v[210:211], v[156:157] op_sel_hi:[1,0,1] neg_lo:[1,0,0] neg_hi:[1,0,0]
	ds_read_b128 v[156:159], v20 offset:46848
	ds_read_b128 v[208:211], v20 offset:46960
	v_pk_add_f32 v[52:53], v[52:53], v[186:187]
	s_waitcnt lgkmcnt(1)
	v_pk_fma_f32 v[186:187], v[138:139], v[156:157], 0 op_sel:[0,1,0] op_sel_hi:[1,1,0] neg_lo:[1,0,0] neg_hi:[1,0,0]
	v_pk_fma_f32 v[252:253], v[128:129], v[156:157], v[54:55] op_sel_hi:[1,0,1] neg_lo:[1,0,0] neg_hi:[1,0,0]
	v_pk_fma_f32 v[186:187], v[134:135], v[158:159], v[186:187] op_sel:[0,1,0] neg_lo:[1,0,0] neg_hi:[1,0,0]
	v_pk_fma_f32 v[252:253], v[136:137], v[158:159], v[252:253] op_sel_hi:[1,0,1] neg_lo:[1,0,0] neg_hi:[1,0,0]
	ds_read_b128 v[156:159], v20 offset:47104
	v_pk_fma_f32 v[186:187], v[130:131], v[160:161], v[186:187] op_sel:[0,1,0] neg_lo:[1,0,0] neg_hi:[1,0,0]
	v_pk_fma_f32 v[252:253], v[132:133], v[160:161], v[252:253] op_sel_hi:[1,0,1] neg_lo:[1,0,0] neg_hi:[1,0,0]
	v_pk_fma_f32 v[186:187], v[84:85], v[162:163], v[186:187] op_sel:[0,1,0] neg_lo:[1,0,0] neg_hi:[1,0,0]
	v_pk_fma_f32 v[252:253], v[122:123], v[162:163], v[252:253] op_sel_hi:[1,0,1] neg_lo:[1,0,0] neg_hi:[1,0,0]
	ds_read_b128 v[160:163], v20 offset:47120
	v_pk_fma_f32 v[186:187], v[10:11], v[166:167], v[186:187] op_sel:[0,1,0] neg_lo:[1,0,0] neg_hi:[1,0,0]
	v_pk_fma_f32 v[252:253], v[14:15], v[166:167], v[252:253] op_sel_hi:[1,0,1] neg_lo:[1,0,0] neg_hi:[1,0,0]
	v_pk_fma_f32 v[186:187], v[6:7], v[168:169], v[186:187] op_sel:[0,1,0] neg_lo:[1,0,0] neg_hi:[1,0,0]
	v_pk_fma_f32 v[252:253], v[16:17], v[168:169], v[252:253] op_sel_hi:[1,0,1] neg_lo:[1,0,0] neg_hi:[1,0,0]
	ds_read_b128 v[166:169], v20 offset:47136
	v_pk_fma_f32 v[186:187], v[12:13], v[170:171], v[186:187] op_sel:[0,1,0] neg_lo:[1,0,0] neg_hi:[1,0,0]
	v_pk_fma_f32 v[252:253], v[18:19], v[170:171], v[252:253] op_sel_hi:[1,0,1] neg_lo:[1,0,0] neg_hi:[1,0,0]
	v_pk_fma_f32 v[186:187], v[4:5], v[172:173], v[186:187] op_sel:[0,1,0] neg_lo:[1,0,0] neg_hi:[1,0,0]
	v_pk_fma_f32 v[252:253], v[8:9], v[172:173], v[252:253] op_sel_hi:[1,0,1] neg_lo:[1,0,0] neg_hi:[1,0,0]
	ds_read_b128 v[170:173], v20 offset:47152
	v_pk_fma_f32 v[186:187], v[0:1], v[174:175], v[186:187] op_sel:[0,1,0] neg_lo:[1,0,0] neg_hi:[1,0,0]
	v_pk_fma_f32 v[252:253], v[2:3], v[174:175], v[252:253] op_sel_hi:[1,0,1] neg_lo:[1,0,0] neg_hi:[1,0,0]
	v_pk_fma_f32 v[186:187], v[28:29], v[176:177], v[186:187] op_sel:[0,1,0] neg_lo:[1,0,0] neg_hi:[1,0,0]
	ds_read_b128 v[212:215], v20 offset:47488
	v_pk_fma_f32 v[186:187], v[34:35], v[178:179], v[186:187] op_sel:[0,1,0] neg_lo:[1,0,0] neg_hi:[1,0,0]
	v_pk_fma_f32 v[252:253], v[30:31], v[176:177], v[252:253] op_sel_hi:[1,0,1] neg_lo:[1,0,0] neg_hi:[1,0,0]
	ds_read_b128 v[174:177], v20 offset:47168
	v_pk_fma_f32 v[186:187], v[40:41], v[180:181], v[186:187] op_sel:[0,1,0] neg_lo:[1,0,0] neg_hi:[1,0,0]
	v_pk_fma_f32 v[252:253], v[32:33], v[178:179], v[252:253] op_sel_hi:[1,0,1] neg_lo:[1,0,0] neg_hi:[1,0,0]
	v_pk_fma_f32 v[186:187], v[42:43], v[182:183], v[186:187] op_sel:[0,1,0] neg_lo:[1,0,0] neg_hi:[1,0,0]
	v_pk_fma_f32 v[252:253], v[36:37], v[180:181], v[252:253] op_sel_hi:[1,0,1] neg_lo:[1,0,0] neg_hi:[1,0,0]
	ds_read_b128 v[178:181], v20 offset:47184
	v_pk_fma_f32 v[186:187], v[46:47], v[184:185], v[186:187] op_sel:[0,1,0] neg_lo:[1,0,0] neg_hi:[1,0,0]
	v_pk_fma_f32 v[252:253], v[38:39], v[182:183], v[252:253] op_sel_hi:[1,0,1] neg_lo:[1,0,0] neg_hi:[1,0,0]
	s_waitcnt lgkmcnt(7)
	v_pk_fma_f32 v[186:187], v[50:51], v[208:209], v[186:187] op_sel:[0,1,0] neg_lo:[1,0,0] neg_hi:[1,0,0]
	v_pk_fma_f32 v[252:253], v[44:45], v[184:185], v[252:253] op_sel_hi:[1,0,1] neg_lo:[1,0,0] neg_hi:[1,0,0]
	ds_read_b128 v[182:185], v20 offset:47200
	v_pk_fma_f32 v[186:187], v[54:55], v[210:211], v[186:187] op_sel:[0,1,0] neg_lo:[1,0,0] neg_hi:[1,0,0]
	v_pk_fma_f32 v[252:253], v[48:49], v[208:209], v[252:253] op_sel_hi:[1,0,1] neg_lo:[1,0,0] neg_hi:[1,0,0]
	s_nop 0
	v_pk_fma_f32 v[252:253], v[210:211], v[52:53], v[252:253] op_sel_hi:[0,1,1] neg_lo:[1,0,0] neg_hi:[1,0,0]
	ds_read_b128 v[208:211], v20 offset:47216
	v_pk_add_f32 v[54:55], v[252:253], v[186:187]
	s_waitcnt lgkmcnt(8)
	v_pk_fma_f32 v[186:187], v[138:139], v[156:157], 0 op_sel:[0,1,0] op_sel_hi:[1,1,0] neg_lo:[1,0,0] neg_hi:[1,0,0]
	v_pk_mul_f32 v[156:157], v[128:129], v[156:157] op_sel_hi:[1,0]
	v_pk_fma_f32 v[186:187], v[134:135], v[158:159], v[186:187] op_sel:[0,1,0] neg_lo:[1,0,0] neg_hi:[1,0,0]
	v_pk_fma_f32 v[56:57], v[56:57], v[58:59], v[156:157] neg_lo:[0,0,1] neg_hi:[0,0,1]
	s_waitcnt lgkmcnt(7)
	v_pk_fma_f32 v[186:187], v[130:131], v[160:161], v[186:187] op_sel:[0,1,0] neg_lo:[1,0,0] neg_hi:[1,0,0]
	v_pk_fma_f32 v[56:57], v[136:137], v[158:159], v[56:57] op_sel_hi:[1,0,1] neg_lo:[1,0,0] neg_hi:[1,0,0]
	ds_read_b128 v[156:159], v20 offset:47360
	v_pk_fma_f32 v[56:57], v[132:133], v[160:161], v[56:57] op_sel_hi:[1,0,1] neg_lo:[1,0,0] neg_hi:[1,0,0]
	v_pk_fma_f32 v[186:187], v[84:85], v[162:163], v[186:187] op_sel:[0,1,0] neg_lo:[1,0,0] neg_hi:[1,0,0]
	v_pk_fma_f32 v[56:57], v[122:123], v[162:163], v[56:57] op_sel_hi:[1,0,1] neg_lo:[1,0,0] neg_hi:[1,0,0]
	ds_read_b128 v[160:163], v20 offset:47376
	s_waitcnt lgkmcnt(8)
	v_pk_fma_f32 v[186:187], v[10:11], v[166:167], v[186:187] op_sel:[0,1,0] neg_lo:[1,0,0] neg_hi:[1,0,0]
	v_pk_fma_f32 v[56:57], v[14:15], v[166:167], v[56:57] op_sel_hi:[1,0,1] neg_lo:[1,0,0] neg_hi:[1,0,0]
	v_pk_fma_f32 v[186:187], v[6:7], v[168:169], v[186:187] op_sel:[0,1,0] neg_lo:[1,0,0] neg_hi:[1,0,0]
	v_pk_fma_f32 v[56:57], v[16:17], v[168:169], v[56:57] op_sel_hi:[1,0,1] neg_lo:[1,0,0] neg_hi:[1,0,0]
	ds_read_b128 v[166:169], v20 offset:47392
	s_waitcnt lgkmcnt(8)
	v_pk_fma_f32 v[186:187], v[12:13], v[170:171], v[186:187] op_sel:[0,1,0] neg_lo:[1,0,0] neg_hi:[1,0,0]
	v_pk_fma_f32 v[56:57], v[18:19], v[170:171], v[56:57] op_sel_hi:[1,0,1] neg_lo:[1,0,0] neg_hi:[1,0,0]
	v_pk_fma_f32 v[186:187], v[4:5], v[172:173], v[186:187] op_sel:[0,1,0] neg_lo:[1,0,0] neg_hi:[1,0,0]
	v_pk_fma_f32 v[56:57], v[8:9], v[172:173], v[56:57] op_sel_hi:[1,0,1] neg_lo:[1,0,0] neg_hi:[1,0,0]
	ds_read_b128 v[170:173], v20 offset:47408
	s_waitcnt lgkmcnt(7)
	v_pk_fma_f32 v[186:187], v[0:1], v[174:175], v[186:187] op_sel:[0,1,0] neg_lo:[1,0,0] neg_hi:[1,0,0]
	v_pk_fma_f32 v[56:57], v[2:3], v[174:175], v[56:57] op_sel_hi:[1,0,1] neg_lo:[1,0,0] neg_hi:[1,0,0]
	v_pk_fma_f32 v[186:187], v[28:29], v[176:177], v[186:187] op_sel:[0,1,0] neg_lo:[1,0,0] neg_hi:[1,0,0]
	v_pk_fma_f32 v[56:57], v[30:31], v[176:177], v[56:57] op_sel_hi:[1,0,1] neg_lo:[1,0,0] neg_hi:[1,0,0]
	ds_read_b128 v[174:177], v20 offset:47424
	s_waitcnt lgkmcnt(7)
	v_pk_fma_f32 v[186:187], v[34:35], v[178:179], v[186:187] op_sel:[0,1,0] neg_lo:[1,0,0] neg_hi:[1,0,0]
	v_pk_fma_f32 v[56:57], v[32:33], v[178:179], v[56:57] op_sel_hi:[1,0,1] neg_lo:[1,0,0] neg_hi:[1,0,0]
	v_pk_fma_f32 v[186:187], v[40:41], v[180:181], v[186:187] op_sel:[0,1,0] neg_lo:[1,0,0] neg_hi:[1,0,0]
	v_pk_fma_f32 v[56:57], v[36:37], v[180:181], v[56:57] op_sel_hi:[1,0,1] neg_lo:[1,0,0] neg_hi:[1,0,0]
	ds_read_b128 v[178:181], v20 offset:47440
	s_waitcnt lgkmcnt(7)
	v_pk_fma_f32 v[186:187], v[42:43], v[182:183], v[186:187] op_sel:[0,1,0] neg_lo:[1,0,0] neg_hi:[1,0,0]
	v_pk_fma_f32 v[56:57], v[38:39], v[182:183], v[56:57] op_sel_hi:[1,0,1] neg_lo:[1,0,0] neg_hi:[1,0,0]
	v_pk_fma_f32 v[186:187], v[46:47], v[184:185], v[186:187] op_sel:[0,1,0] neg_lo:[1,0,0] neg_hi:[1,0,0]
	v_pk_fma_f32 v[56:57], v[44:45], v[184:185], v[56:57] op_sel_hi:[1,0,1] neg_lo:[1,0,0] neg_hi:[1,0,0]
	ds_read_b128 v[182:185], v20 offset:47456
	s_waitcnt lgkmcnt(7)
	v_pk_fma_f32 v[186:187], v[50:51], v[208:209], v[186:187] op_sel:[0,1,0] neg_lo:[1,0,0] neg_hi:[1,0,0]
	v_pk_fma_f32 v[56:57], v[48:49], v[208:209], v[56:57] op_sel_hi:[1,0,1] neg_lo:[1,0,0] neg_hi:[1,0,0]
	v_pk_fma_f32 v[186:187], v[210:211], v[54:55], v[186:187] op_sel:[1,0,0] neg_lo:[1,0,0] neg_hi:[1,0,0]
	v_pk_fma_f32 v[56:57], v[52:53], v[210:211], v[56:57] op_sel_hi:[1,0,1] neg_lo:[1,0,0] neg_hi:[1,0,0]
	ds_read_b128 v[208:211], v20 offset:47472
	v_pk_add_f32 v[56:57], v[56:57], v[186:187]
	s_waitcnt lgkmcnt(7)
	v_pk_fma_f32 v[58:59], v[138:139], v[156:157], 0 op_sel:[0,1,0] op_sel_hi:[1,1,0] neg_lo:[1,0,0] neg_hi:[1,0,0]
	v_pk_fma_f32 v[252:253], v[128:129], v[156:157], v[154:155] op_sel_hi:[1,0,1] neg_lo:[1,0,0] neg_hi:[1,0,0]
	v_pk_fma_f32 v[58:59], v[134:135], v[158:159], v[58:59] op_sel:[0,1,0] neg_lo:[1,0,0] neg_hi:[1,0,0]
	v_pk_fma_f32 v[252:253], v[136:137], v[158:159], v[252:253] op_sel_hi:[1,0,1] neg_lo:[1,0,0] neg_hi:[1,0,0]
	s_waitcnt lgkmcnt(6)
	v_pk_fma_f32 v[58:59], v[130:131], v[160:161], v[58:59] op_sel:[0,1,0] neg_lo:[1,0,0] neg_hi:[1,0,0]
	v_pk_fma_f32 v[252:253], v[132:133], v[160:161], v[252:253] op_sel_hi:[1,0,1] neg_lo:[1,0,0] neg_hi:[1,0,0]
	ds_read_b128 v[158:161], v20 offset:47632
	v_pk_fma_f32 v[58:59], v[84:85], v[162:163], v[58:59] op_sel:[0,1,0] neg_lo:[1,0,0] neg_hi:[1,0,0]
	v_pk_fma_f32 v[252:253], v[122:123], v[162:163], v[252:253] op_sel_hi:[1,0,1] neg_lo:[1,0,0] neg_hi:[1,0,0]
	s_waitcnt lgkmcnt(6)
	v_pk_fma_f32 v[58:59], v[10:11], v[166:167], v[58:59] op_sel:[0,1,0] neg_lo:[1,0,0] neg_hi:[1,0,0]
	v_pk_fma_f32 v[252:253], v[14:15], v[166:167], v[252:253] op_sel_hi:[1,0,1] neg_lo:[1,0,0] neg_hi:[1,0,0]
	v_pk_fma_f32 v[58:59], v[6:7], v[168:169], v[58:59] op_sel:[0,1,0] neg_lo:[1,0,0] neg_hi:[1,0,0]
	v_pk_fma_f32 v[252:253], v[16:17], v[168:169], v[252:253] op_sel_hi:[1,0,1] neg_lo:[1,0,0] neg_hi:[1,0,0]
	ds_read_b128 v[166:169], v20 offset:47648
	s_waitcnt lgkmcnt(6)
	v_pk_fma_f32 v[58:59], v[12:13], v[170:171], v[58:59] op_sel:[0,1,0] neg_lo:[1,0,0] neg_hi:[1,0,0]
	v_pk_fma_f32 v[252:253], v[18:19], v[170:171], v[252:253] op_sel_hi:[1,0,1] neg_lo:[1,0,0] neg_hi:[1,0,0]
	v_pk_fma_f32 v[58:59], v[4:5], v[172:173], v[58:59] op_sel:[0,1,0] neg_lo:[1,0,0] neg_hi:[1,0,0]
	v_pk_fma_f32 v[252:253], v[8:9], v[172:173], v[252:253] op_sel_hi:[1,0,1] neg_lo:[1,0,0] neg_hi:[1,0,0]
	ds_read_b128 v[170:173], v20 offset:47664
	s_waitcnt lgkmcnt(6)
	v_pk_fma_f32 v[58:59], v[0:1], v[174:175], v[58:59] op_sel:[0,1,0] neg_lo:[1,0,0] neg_hi:[1,0,0]
	v_pk_fma_f32 v[252:253], v[2:3], v[174:175], v[252:253] op_sel_hi:[1,0,1] neg_lo:[1,0,0] neg_hi:[1,0,0]
	v_pk_fma_f32 v[58:59], v[28:29], v[176:177], v[58:59] op_sel:[0,1,0] neg_lo:[1,0,0] neg_hi:[1,0,0]
	v_pk_fma_f32 v[252:253], v[30:31], v[176:177], v[252:253] op_sel_hi:[1,0,1] neg_lo:[1,0,0] neg_hi:[1,0,0]
	ds_read_b128 v[174:177], v20 offset:47680
	s_waitcnt lgkmcnt(6)
	v_pk_fma_f32 v[58:59], v[34:35], v[178:179], v[58:59] op_sel:[0,1,0] neg_lo:[1,0,0] neg_hi:[1,0,0]
	v_pk_fma_f32 v[252:253], v[32:33], v[178:179], v[252:253] op_sel_hi:[1,0,1] neg_lo:[1,0,0] neg_hi:[1,0,0]
	v_pk_fma_f32 v[58:59], v[40:41], v[180:181], v[58:59] op_sel:[0,1,0] neg_lo:[1,0,0] neg_hi:[1,0,0]
	v_pk_fma_f32 v[252:253], v[36:37], v[180:181], v[252:253] op_sel_hi:[1,0,1] neg_lo:[1,0,0] neg_hi:[1,0,0]
	ds_read_b128 v[178:181], v20 offset:47696
	s_waitcnt lgkmcnt(6)
	v_pk_fma_f32 v[58:59], v[42:43], v[182:183], v[58:59] op_sel:[0,1,0] neg_lo:[1,0,0] neg_hi:[1,0,0]
	v_pk_fma_f32 v[252:253], v[38:39], v[182:183], v[252:253] op_sel_hi:[1,0,1] neg_lo:[1,0,0] neg_hi:[1,0,0]
	v_pk_fma_f32 v[58:59], v[46:47], v[184:185], v[58:59] op_sel:[0,1,0] neg_lo:[1,0,0] neg_hi:[1,0,0]
	v_pk_fma_f32 v[252:253], v[44:45], v[184:185], v[252:253] op_sel_hi:[1,0,1] neg_lo:[1,0,0] neg_hi:[1,0,0]
	ds_read_b128 v[182:185], v20 offset:47712
	s_waitcnt lgkmcnt(6)
	v_pk_fma_f32 v[58:59], v[50:51], v[208:209], v[58:59] op_sel:[0,1,0] neg_lo:[1,0,0] neg_hi:[1,0,0]
	v_pk_fma_f32 v[252:253], v[48:49], v[208:209], v[252:253] op_sel_hi:[1,0,1] neg_lo:[1,0,0] neg_hi:[1,0,0]
	v_pk_fma_f32 v[58:59], v[54:55], v[210:211], v[58:59] op_sel:[0,1,0] neg_lo:[1,0,0] neg_hi:[1,0,0]
	v_pk_fma_f32 v[252:253], v[52:53], v[210:211], v[252:253] op_sel_hi:[1,0,1] neg_lo:[1,0,0] neg_hi:[1,0,0]
	ds_read_b128 v[208:211], v20 offset:47728
	v_pk_fma_f32 v[58:59], v[154:155], v[212:213], v[58:59] op_sel:[0,1,0] neg_lo:[1,0,0] neg_hi:[1,0,0]
	ds_read_b128 v[154:157], v20 offset:47616
	v_pk_fma_f32 v[58:59], v[62:63], v[214:215], v[58:59] op_sel:[0,1,0] neg_lo:[1,0,0] neg_hi:[1,0,0]
	v_pk_fma_f32 v[252:253], v[212:213], v[56:57], v[252:253] op_sel_hi:[0,1,1] neg_lo:[1,0,0] neg_hi:[1,0,0]
	s_waitcnt lgkmcnt(0)
	v_pk_fma_f32 v[162:163], v[138:139], v[154:155], 0 op_sel:[0,1,0] op_sel_hi:[1,1,0] neg_lo:[1,0,0] neg_hi:[1,0,0]
	v_pk_fma_f32 v[252:253], v[60:61], v[214:215], v[252:253] op_sel_hi:[1,0,1] neg_lo:[1,0,0] neg_hi:[1,0,0]
	ds_read_b128 v[212:215], v20 offset:47744
	v_pk_add_f32 v[58:59], v[252:253], v[58:59]
	v_pk_fma_f32 v[154:155], v[128:129], v[154:155], v[60:61] op_sel_hi:[1,0,1] neg_lo:[1,0,0] neg_hi:[1,0,0]
	v_pk_fma_f32 v[162:163], v[134:135], v[156:157], v[162:163] op_sel:[0,1,0] neg_lo:[1,0,0] neg_hi:[1,0,0]
	v_pk_fma_f32 v[154:155], v[136:137], v[156:157], v[154:155] op_sel_hi:[1,0,1] neg_lo:[1,0,0] neg_hi:[1,0,0]
	v_pk_fma_f32 v[162:163], v[130:131], v[158:159], v[162:163] op_sel:[0,1,0] neg_lo:[1,0,0] neg_hi:[1,0,0]
	v_pk_fma_f32 v[154:155], v[132:133], v[158:159], v[154:155] op_sel_hi:[1,0,1] neg_lo:[1,0,0] neg_hi:[1,0,0]
	v_pk_fma_f32 v[162:163], v[84:85], v[160:161], v[162:163] op_sel:[0,1,0] neg_lo:[1,0,0] neg_hi:[1,0,0]
	v_pk_fma_f32 v[154:155], v[122:123], v[160:161], v[154:155] op_sel_hi:[1,0,1] neg_lo:[1,0,0] neg_hi:[1,0,0]
	ds_read_b128 v[158:161], v20 offset:47888
	v_pk_fma_f32 v[162:163], v[10:11], v[166:167], v[162:163] op_sel:[0,1,0] neg_lo:[1,0,0] neg_hi:[1,0,0]
	v_pk_fma_f32 v[154:155], v[14:15], v[166:167], v[154:155] op_sel_hi:[1,0,1] neg_lo:[1,0,0] neg_hi:[1,0,0]
	v_pk_fma_f32 v[162:163], v[6:7], v[168:169], v[162:163] op_sel:[0,1,0] neg_lo:[1,0,0] neg_hi:[1,0,0]
	v_pk_fma_f32 v[154:155], v[16:17], v[168:169], v[154:155] op_sel_hi:[1,0,1] neg_lo:[1,0,0] neg_hi:[1,0,0]
	ds_read_b128 v[166:169], v20 offset:47904
	v_pk_fma_f32 v[162:163], v[12:13], v[170:171], v[162:163] op_sel:[0,1,0] neg_lo:[1,0,0] neg_hi:[1,0,0]
	v_pk_fma_f32 v[154:155], v[18:19], v[170:171], v[154:155] op_sel_hi:[1,0,1] neg_lo:[1,0,0] neg_hi:[1,0,0]
	v_pk_fma_f32 v[162:163], v[4:5], v[172:173], v[162:163] op_sel:[0,1,0] neg_lo:[1,0,0] neg_hi:[1,0,0]
	v_pk_fma_f32 v[154:155], v[8:9], v[172:173], v[154:155] op_sel_hi:[1,0,1] neg_lo:[1,0,0] neg_hi:[1,0,0]
	ds_read_b128 v[170:173], v20 offset:47920
	v_pk_fma_f32 v[162:163], v[0:1], v[174:175], v[162:163] op_sel:[0,1,0] neg_lo:[1,0,0] neg_hi:[1,0,0]
	v_pk_fma_f32 v[154:155], v[2:3], v[174:175], v[154:155] op_sel_hi:[1,0,1] neg_lo:[1,0,0] neg_hi:[1,0,0]
	v_pk_fma_f32 v[162:163], v[28:29], v[176:177], v[162:163] op_sel:[0,1,0] neg_lo:[1,0,0] neg_hi:[1,0,0]
	v_pk_fma_f32 v[154:155], v[30:31], v[176:177], v[154:155] op_sel_hi:[1,0,1] neg_lo:[1,0,0] neg_hi:[1,0,0]
	ds_read_b128 v[174:177], v20 offset:47936
	v_pk_fma_f32 v[162:163], v[34:35], v[178:179], v[162:163] op_sel:[0,1,0] neg_lo:[1,0,0] neg_hi:[1,0,0]
	v_pk_fma_f32 v[154:155], v[32:33], v[178:179], v[154:155] op_sel_hi:[1,0,1] neg_lo:[1,0,0] neg_hi:[1,0,0]
	v_pk_fma_f32 v[162:163], v[40:41], v[180:181], v[162:163] op_sel:[0,1,0] neg_lo:[1,0,0] neg_hi:[1,0,0]
	v_pk_fma_f32 v[154:155], v[36:37], v[180:181], v[154:155] op_sel_hi:[1,0,1] neg_lo:[1,0,0] neg_hi:[1,0,0]
	ds_read_b128 v[178:181], v20 offset:47952
	v_pk_fma_f32 v[162:163], v[42:43], v[182:183], v[162:163] op_sel:[0,1,0] neg_lo:[1,0,0] neg_hi:[1,0,0]
	v_pk_fma_f32 v[154:155], v[38:39], v[182:183], v[154:155] op_sel_hi:[1,0,1] neg_lo:[1,0,0] neg_hi:[1,0,0]
	v_pk_fma_f32 v[162:163], v[46:47], v[184:185], v[162:163] op_sel:[0,1,0] neg_lo:[1,0,0] neg_hi:[1,0,0]
	v_pk_fma_f32 v[154:155], v[44:45], v[184:185], v[154:155] op_sel_hi:[1,0,1] neg_lo:[1,0,0] neg_hi:[1,0,0]
	ds_read_b128 v[182:185], v20 offset:47968
	v_pk_fma_f32 v[162:163], v[50:51], v[208:209], v[162:163] op_sel:[0,1,0] neg_lo:[1,0,0] neg_hi:[1,0,0]
	v_pk_fma_f32 v[154:155], v[48:49], v[208:209], v[154:155] op_sel_hi:[1,0,1] neg_lo:[1,0,0] neg_hi:[1,0,0]
	v_pk_fma_f32 v[162:163], v[54:55], v[210:211], v[162:163] op_sel:[0,1,0] neg_lo:[1,0,0] neg_hi:[1,0,0]
	v_pk_fma_f32 v[154:155], v[52:53], v[210:211], v[154:155] op_sel_hi:[1,0,1] neg_lo:[1,0,0] neg_hi:[1,0,0]
	ds_read_b128 v[208:211], v20 offset:47984
	s_waitcnt lgkmcnt(7)
	v_pk_fma_f32 v[162:163], v[212:213], v[58:59], v[162:163] op_sel:[1,0,0] neg_lo:[1,0,0] neg_hi:[1,0,0]
	v_pk_fma_f32 v[154:155], v[56:57], v[212:213], v[154:155] op_sel_hi:[1,0,1] neg_lo:[1,0,0] neg_hi:[1,0,0]
	v_pk_fma_f32 v[162:163], v[62:63], v[214:215], v[162:163] op_sel:[0,1,0] neg_lo:[1,0,0] neg_hi:[1,0,0]
	v_pk_fma_f32 v[60:61], v[60:61], v[214:215], v[154:155] op_sel_hi:[1,0,1] neg_lo:[1,0,0] neg_hi:[1,0,0]
	ds_read_b128 v[154:157], v20 offset:47872
	ds_read_b128 v[212:215], v20 offset:48000
	v_pk_add_f32 v[60:61], v[60:61], v[162:163]
	s_waitcnt lgkmcnt(1)
	v_pk_fma_f32 v[162:163], v[138:139], v[154:155], 0 op_sel:[0,1,0] op_sel_hi:[1,1,0] neg_lo:[1,0,0] neg_hi:[1,0,0]
	v_pk_fma_f32 v[252:253], v[128:129], v[154:155], v[62:63] op_sel_hi:[1,0,1] neg_lo:[1,0,0] neg_hi:[1,0,0]
	v_pk_fma_f32 v[162:163], v[134:135], v[156:157], v[162:163] op_sel:[0,1,0] neg_lo:[1,0,0] neg_hi:[1,0,0]
	v_pk_fma_f32 v[252:253], v[136:137], v[156:157], v[252:253] op_sel_hi:[1,0,1] neg_lo:[1,0,0] neg_hi:[1,0,0]
	ds_read_b128 v[154:157], v20 offset:48128
	v_pk_fma_f32 v[162:163], v[130:131], v[158:159], v[162:163] op_sel:[0,1,0] neg_lo:[1,0,0] neg_hi:[1,0,0]
	v_pk_fma_f32 v[252:253], v[132:133], v[158:159], v[252:253] op_sel_hi:[1,0,1] neg_lo:[1,0,0] neg_hi:[1,0,0]
	v_pk_fma_f32 v[162:163], v[84:85], v[160:161], v[162:163] op_sel:[0,1,0] neg_lo:[1,0,0] neg_hi:[1,0,0]
	v_pk_fma_f32 v[252:253], v[122:123], v[160:161], v[252:253] op_sel_hi:[1,0,1] neg_lo:[1,0,0] neg_hi:[1,0,0]
	ds_read_b128 v[158:161], v20 offset:48144
	v_pk_fma_f32 v[162:163], v[10:11], v[166:167], v[162:163] op_sel:[0,1,0] neg_lo:[1,0,0] neg_hi:[1,0,0]
	v_pk_fma_f32 v[252:253], v[14:15], v[166:167], v[252:253] op_sel_hi:[1,0,1] neg_lo:[1,0,0] neg_hi:[1,0,0]
	v_pk_fma_f32 v[162:163], v[6:7], v[168:169], v[162:163] op_sel:[0,1,0] neg_lo:[1,0,0] neg_hi:[1,0,0]
	v_pk_fma_f32 v[252:253], v[16:17], v[168:169], v[252:253] op_sel_hi:[1,0,1] neg_lo:[1,0,0] neg_hi:[1,0,0]
	ds_read_b128 v[166:169], v20 offset:48160
	v_pk_fma_f32 v[162:163], v[12:13], v[170:171], v[162:163] op_sel:[0,1,0] neg_lo:[1,0,0] neg_hi:[1,0,0]
	v_pk_fma_f32 v[252:253], v[18:19], v[170:171], v[252:253] op_sel_hi:[1,0,1] neg_lo:[1,0,0] neg_hi:[1,0,0]
	v_pk_fma_f32 v[162:163], v[4:5], v[172:173], v[162:163] op_sel:[0,1,0] neg_lo:[1,0,0] neg_hi:[1,0,0]
	v_pk_fma_f32 v[252:253], v[8:9], v[172:173], v[252:253] op_sel_hi:[1,0,1] neg_lo:[1,0,0] neg_hi:[1,0,0]
	ds_read_b128 v[170:173], v20 offset:48176
	v_pk_fma_f32 v[162:163], v[0:1], v[174:175], v[162:163] op_sel:[0,1,0] neg_lo:[1,0,0] neg_hi:[1,0,0]
	v_pk_fma_f32 v[252:253], v[2:3], v[174:175], v[252:253] op_sel_hi:[1,0,1] neg_lo:[1,0,0] neg_hi:[1,0,0]
	v_pk_fma_f32 v[162:163], v[28:29], v[176:177], v[162:163] op_sel:[0,1,0] neg_lo:[1,0,0] neg_hi:[1,0,0]
	v_pk_fma_f32 v[252:253], v[30:31], v[176:177], v[252:253] op_sel_hi:[1,0,1] neg_lo:[1,0,0] neg_hi:[1,0,0]
	ds_read_b128 v[174:177], v20 offset:48192
	v_pk_fma_f32 v[162:163], v[34:35], v[178:179], v[162:163] op_sel:[0,1,0] neg_lo:[1,0,0] neg_hi:[1,0,0]
	v_pk_fma_f32 v[252:253], v[32:33], v[178:179], v[252:253] op_sel_hi:[1,0,1] neg_lo:[1,0,0] neg_hi:[1,0,0]
	v_pk_fma_f32 v[162:163], v[40:41], v[180:181], v[162:163] op_sel:[0,1,0] neg_lo:[1,0,0] neg_hi:[1,0,0]
	v_pk_fma_f32 v[252:253], v[36:37], v[180:181], v[252:253] op_sel_hi:[1,0,1] neg_lo:[1,0,0] neg_hi:[1,0,0]
	ds_read_b128 v[178:181], v20 offset:48208
	v_pk_fma_f32 v[162:163], v[42:43], v[182:183], v[162:163] op_sel:[0,1,0] neg_lo:[1,0,0] neg_hi:[1,0,0]
	v_pk_fma_f32 v[252:253], v[38:39], v[182:183], v[252:253] op_sel_hi:[1,0,1] neg_lo:[1,0,0] neg_hi:[1,0,0]
	v_pk_fma_f32 v[162:163], v[46:47], v[184:185], v[162:163] op_sel:[0,1,0] neg_lo:[1,0,0] neg_hi:[1,0,0]
	v_pk_fma_f32 v[252:253], v[44:45], v[184:185], v[252:253] op_sel_hi:[1,0,1] neg_lo:[1,0,0] neg_hi:[1,0,0]
	ds_read_b128 v[182:185], v20 offset:48224
	v_pk_fma_f32 v[162:163], v[50:51], v[208:209], v[162:163] op_sel:[0,1,0] neg_lo:[1,0,0] neg_hi:[1,0,0]
	v_pk_fma_f32 v[252:253], v[48:49], v[208:209], v[252:253] op_sel_hi:[1,0,1] neg_lo:[1,0,0] neg_hi:[1,0,0]
	v_pk_fma_f32 v[162:163], v[54:55], v[210:211], v[162:163] op_sel:[0,1,0] neg_lo:[1,0,0] neg_hi:[1,0,0]
	v_pk_fma_f32 v[252:253], v[52:53], v[210:211], v[252:253] op_sel_hi:[1,0,1] neg_lo:[1,0,0] neg_hi:[1,0,0]
	ds_read_b128 v[208:211], v20 offset:48240
	s_waitcnt lgkmcnt(8)
	v_pk_fma_f32 v[162:163], v[58:59], v[212:213], v[162:163] op_sel:[0,1,0] neg_lo:[1,0,0] neg_hi:[1,0,0]
	v_pk_fma_f32 v[252:253], v[56:57], v[212:213], v[252:253] op_sel_hi:[1,0,1] neg_lo:[1,0,0] neg_hi:[1,0,0]
	v_pk_fma_f32 v[162:163], v[62:63], v[214:215], v[162:163] op_sel:[0,1,0] neg_lo:[1,0,0] neg_hi:[1,0,0]
	v_pk_fma_f32 v[252:253], v[214:215], v[60:61], v[252:253] op_sel_hi:[0,1,1] neg_lo:[1,0,0] neg_hi:[1,0,0]
	ds_read_b128 v[212:215], v20 offset:48256
	v_pk_add_f32 v[62:63], v[252:253], v[162:163]
	s_waitcnt lgkmcnt(8)
	v_pk_fma_f32 v[162:163], v[138:139], v[154:155], 0 op_sel:[0,1,0] op_sel_hi:[1,1,0] neg_lo:[1,0,0] neg_hi:[1,0,0]
	v_pk_mul_f32 v[154:155], v[128:129], v[154:155] op_sel_hi:[1,0]
	v_pk_fma_f32 v[162:163], v[134:135], v[156:157], v[162:163] op_sel:[0,1,0] neg_lo:[1,0,0] neg_hi:[1,0,0]
	v_pk_fma_f32 v[64:65], v[64:65], v[152:153], v[154:155] neg_lo:[0,0,1] neg_hi:[0,0,1]
	ds_read_b128 v[152:155], v20 offset:48384
	v_pk_fma_f32 v[64:65], v[136:137], v[156:157], v[64:65] op_sel_hi:[1,0,1] neg_lo:[1,0,0] neg_hi:[1,0,0]
	s_waitcnt lgkmcnt(8)
	v_pk_fma_f32 v[162:163], v[130:131], v[158:159], v[162:163] op_sel:[0,1,0] neg_lo:[1,0,0] neg_hi:[1,0,0]
	v_pk_fma_f32 v[64:65], v[132:133], v[158:159], v[64:65] op_sel_hi:[1,0,1] neg_lo:[1,0,0] neg_hi:[1,0,0]
	ds_read_b128 v[156:159], v20 offset:48400
	v_pk_fma_f32 v[162:163], v[84:85], v[160:161], v[162:163] op_sel:[0,1,0] neg_lo:[1,0,0] neg_hi:[1,0,0]
	v_pk_fma_f32 v[64:65], v[122:123], v[160:161], v[64:65] op_sel_hi:[1,0,1] neg_lo:[1,0,0] neg_hi:[1,0,0]
	s_waitcnt lgkmcnt(8)
	v_pk_fma_f32 v[162:163], v[10:11], v[166:167], v[162:163] op_sel:[0,1,0] neg_lo:[1,0,0] neg_hi:[1,0,0]
	v_pk_fma_f32 v[64:65], v[14:15], v[166:167], v[64:65] op_sel_hi:[1,0,1] neg_lo:[1,0,0] neg_hi:[1,0,0]
	v_pk_fma_f32 v[162:163], v[6:7], v[168:169], v[162:163] op_sel:[0,1,0] neg_lo:[1,0,0] neg_hi:[1,0,0]
	v_pk_fma_f32 v[64:65], v[16:17], v[168:169], v[64:65] op_sel_hi:[1,0,1] neg_lo:[1,0,0] neg_hi:[1,0,0]
	ds_read_b128 v[166:169], v20 offset:48432
	s_waitcnt lgkmcnt(8)
	v_pk_fma_f32 v[162:163], v[12:13], v[170:171], v[162:163] op_sel:[0,1,0] neg_lo:[1,0,0] neg_hi:[1,0,0]
	v_pk_fma_f32 v[64:65], v[18:19], v[170:171], v[64:65] op_sel_hi:[1,0,1] neg_lo:[1,0,0] neg_hi:[1,0,0]
	v_pk_fma_f32 v[162:163], v[4:5], v[172:173], v[162:163] op_sel:[0,1,0] neg_lo:[1,0,0] neg_hi:[1,0,0]
	v_pk_fma_f32 v[64:65], v[8:9], v[172:173], v[64:65] op_sel_hi:[1,0,1] neg_lo:[1,0,0] neg_hi:[1,0,0]
	ds_read_b128 v[170:173], v20 offset:48448
	s_waitcnt lgkmcnt(8)
	v_pk_fma_f32 v[162:163], v[0:1], v[174:175], v[162:163] op_sel:[0,1,0] neg_lo:[1,0,0] neg_hi:[1,0,0]
	v_pk_fma_f32 v[64:65], v[2:3], v[174:175], v[64:65] op_sel_hi:[1,0,1] neg_lo:[1,0,0] neg_hi:[1,0,0]
	v_pk_fma_f32 v[162:163], v[28:29], v[176:177], v[162:163] op_sel:[0,1,0] neg_lo:[1,0,0] neg_hi:[1,0,0]
	v_pk_fma_f32 v[64:65], v[30:31], v[176:177], v[64:65] op_sel_hi:[1,0,1] neg_lo:[1,0,0] neg_hi:[1,0,0]
	ds_read_b128 v[174:177], v20 offset:48464
	s_waitcnt lgkmcnt(8)
	v_pk_fma_f32 v[162:163], v[34:35], v[178:179], v[162:163] op_sel:[0,1,0] neg_lo:[1,0,0] neg_hi:[1,0,0]
	v_pk_fma_f32 v[64:65], v[32:33], v[178:179], v[64:65] op_sel_hi:[1,0,1] neg_lo:[1,0,0] neg_hi:[1,0,0]
	v_pk_fma_f32 v[162:163], v[40:41], v[180:181], v[162:163] op_sel:[0,1,0] neg_lo:[1,0,0] neg_hi:[1,0,0]
	v_pk_fma_f32 v[64:65], v[36:37], v[180:181], v[64:65] op_sel_hi:[1,0,1] neg_lo:[1,0,0] neg_hi:[1,0,0]
	ds_read_b128 v[178:181], v20 offset:48480
	s_waitcnt lgkmcnt(8)
	v_pk_fma_f32 v[162:163], v[42:43], v[182:183], v[162:163] op_sel:[0,1,0] neg_lo:[1,0,0] neg_hi:[1,0,0]
	v_pk_fma_f32 v[64:65], v[38:39], v[182:183], v[64:65] op_sel_hi:[1,0,1] neg_lo:[1,0,0] neg_hi:[1,0,0]
	v_pk_fma_f32 v[162:163], v[46:47], v[184:185], v[162:163] op_sel:[0,1,0] neg_lo:[1,0,0] neg_hi:[1,0,0]
	v_pk_fma_f32 v[64:65], v[44:45], v[184:185], v[64:65] op_sel_hi:[1,0,1] neg_lo:[1,0,0] neg_hi:[1,0,0]
	ds_read_b128 v[182:185], v20 offset:48496
	s_waitcnt lgkmcnt(8)
	v_pk_fma_f32 v[162:163], v[50:51], v[208:209], v[162:163] op_sel:[0,1,0] neg_lo:[1,0,0] neg_hi:[1,0,0]
	v_pk_fma_f32 v[64:65], v[48:49], v[208:209], v[64:65] op_sel_hi:[1,0,1] neg_lo:[1,0,0] neg_hi:[1,0,0]
	v_pk_fma_f32 v[162:163], v[54:55], v[210:211], v[162:163] op_sel:[0,1,0] neg_lo:[1,0,0] neg_hi:[1,0,0]
	v_pk_fma_f32 v[64:65], v[52:53], v[210:211], v[64:65] op_sel_hi:[1,0,1] neg_lo:[1,0,0] neg_hi:[1,0,0]
	ds_read_b128 v[208:211], v20 offset:48512
	s_waitcnt lgkmcnt(8)
	v_pk_fma_f32 v[162:163], v[58:59], v[212:213], v[162:163] op_sel:[0,1,0] neg_lo:[1,0,0] neg_hi:[1,0,0]
	v_pk_fma_f32 v[64:65], v[56:57], v[212:213], v[64:65] op_sel_hi:[1,0,1] neg_lo:[1,0,0] neg_hi:[1,0,0]
	v_pk_fma_f32 v[162:163], v[214:215], v[62:63], v[162:163] op_sel:[1,0,0] neg_lo:[1,0,0] neg_hi:[1,0,0]
	v_pk_fma_f32 v[64:65], v[60:61], v[214:215], v[64:65] op_sel_hi:[1,0,1] neg_lo:[1,0,0] neg_hi:[1,0,0]
	ds_read_b128 v[212:215], v20 offset:48528
	v_pk_add_f32 v[64:65], v[64:65], v[162:163]
	ds_read_b128 v[160:163], v20 offset:48416
	s_waitcnt lgkmcnt(9)
	v_pk_fma_f32 v[186:187], v[138:139], v[152:153], 0 op_sel:[0,1,0] op_sel_hi:[1,1,0] neg_lo:[1,0,0] neg_hi:[1,0,0]
	v_pk_fma_f32 v[252:253], v[128:129], v[152:153], v[66:67] op_sel_hi:[1,0,1] neg_lo:[1,0,0] neg_hi:[1,0,0]
	v_pk_fma_f32 v[186:187], v[134:135], v[154:155], v[186:187] op_sel:[0,1,0] neg_lo:[1,0,0] neg_hi:[1,0,0]
	v_pk_fma_f32 v[252:253], v[136:137], v[154:155], v[252:253] op_sel_hi:[1,0,1] neg_lo:[1,0,0] neg_hi:[1,0,0]
	ds_read_b128 v[152:155], v20 offset:48640
	s_waitcnt lgkmcnt(9)
	v_pk_fma_f32 v[186:187], v[130:131], v[156:157], v[186:187] op_sel:[0,1,0] neg_lo:[1,0,0] neg_hi:[1,0,0]
	v_pk_fma_f32 v[252:253], v[132:133], v[156:157], v[252:253] op_sel_hi:[1,0,1] neg_lo:[1,0,0] neg_hi:[1,0,0]
	v_pk_fma_f32 v[186:187], v[84:85], v[158:159], v[186:187] op_sel:[0,1,0] neg_lo:[1,0,0] neg_hi:[1,0,0]
	v_pk_fma_f32 v[252:253], v[122:123], v[158:159], v[252:253] op_sel_hi:[1,0,1] neg_lo:[1,0,0] neg_hi:[1,0,0]
	ds_read_b128 v[156:159], v20 offset:48656
	s_waitcnt lgkmcnt(2)
	v_pk_fma_f32 v[186:187], v[10:11], v[160:161], v[186:187] op_sel:[0,1,0] neg_lo:[1,0,0] neg_hi:[1,0,0]
	v_pk_fma_f32 v[252:253], v[14:15], v[160:161], v[252:253] op_sel_hi:[1,0,1] neg_lo:[1,0,0] neg_hi:[1,0,0]
	v_pk_fma_f32 v[186:187], v[6:7], v[162:163], v[186:187] op_sel:[0,1,0] neg_lo:[1,0,0] neg_hi:[1,0,0]
	v_pk_fma_f32 v[252:253], v[16:17], v[162:163], v[252:253] op_sel_hi:[1,0,1] neg_lo:[1,0,0] neg_hi:[1,0,0]
	ds_read_b128 v[160:163], v20 offset:48672
	v_pk_fma_f32 v[186:187], v[12:13], v[166:167], v[186:187] op_sel:[0,1,0] neg_lo:[1,0,0] neg_hi:[1,0,0]
	v_pk_fma_f32 v[252:253], v[18:19], v[166:167], v[252:253] op_sel_hi:[1,0,1] neg_lo:[1,0,0] neg_hi:[1,0,0]
	v_pk_fma_f32 v[186:187], v[4:5], v[168:169], v[186:187] op_sel:[0,1,0] neg_lo:[1,0,0] neg_hi:[1,0,0]
	v_pk_fma_f32 v[252:253], v[8:9], v[168:169], v[252:253] op_sel_hi:[1,0,1] neg_lo:[1,0,0] neg_hi:[1,0,0]
	ds_read_b128 v[166:169], v20 offset:48688
	v_pk_fma_f32 v[186:187], v[0:1], v[170:171], v[186:187] op_sel:[0,1,0] neg_lo:[1,0,0] neg_hi:[1,0,0]
	v_pk_fma_f32 v[252:253], v[2:3], v[170:171], v[252:253] op_sel_hi:[1,0,1] neg_lo:[1,0,0] neg_hi:[1,0,0]
	v_pk_fma_f32 v[186:187], v[28:29], v[172:173], v[186:187] op_sel:[0,1,0] neg_lo:[1,0,0] neg_hi:[1,0,0]
	v_pk_fma_f32 v[252:253], v[30:31], v[172:173], v[252:253] op_sel_hi:[1,0,1] neg_lo:[1,0,0] neg_hi:[1,0,0]
	ds_read_b128 v[170:173], v20 offset:48704
	v_pk_fma_f32 v[186:187], v[34:35], v[174:175], v[186:187] op_sel:[0,1,0] neg_lo:[1,0,0] neg_hi:[1,0,0]
	v_pk_fma_f32 v[252:253], v[32:33], v[174:175], v[252:253] op_sel_hi:[1,0,1] neg_lo:[1,0,0] neg_hi:[1,0,0]
	v_pk_fma_f32 v[186:187], v[40:41], v[176:177], v[186:187] op_sel:[0,1,0] neg_lo:[1,0,0] neg_hi:[1,0,0]
	v_pk_fma_f32 v[252:253], v[36:37], v[176:177], v[252:253] op_sel_hi:[1,0,1] neg_lo:[1,0,0] neg_hi:[1,0,0]
	ds_read_b128 v[174:177], v20 offset:48720
	v_pk_fma_f32 v[186:187], v[42:43], v[178:179], v[186:187] op_sel:[0,1,0] neg_lo:[1,0,0] neg_hi:[1,0,0]
	v_pk_fma_f32 v[252:253], v[38:39], v[178:179], v[252:253] op_sel_hi:[1,0,1] neg_lo:[1,0,0] neg_hi:[1,0,0]
	v_pk_fma_f32 v[186:187], v[46:47], v[180:181], v[186:187] op_sel:[0,1,0] neg_lo:[1,0,0] neg_hi:[1,0,0]
	v_pk_fma_f32 v[252:253], v[44:45], v[180:181], v[252:253] op_sel_hi:[1,0,1] neg_lo:[1,0,0] neg_hi:[1,0,0]
	ds_read_b128 v[178:181], v20 offset:48736
	v_pk_fma_f32 v[186:187], v[50:51], v[182:183], v[186:187] op_sel:[0,1,0] neg_lo:[1,0,0] neg_hi:[1,0,0]
	v_pk_fma_f32 v[252:253], v[48:49], v[182:183], v[252:253] op_sel_hi:[1,0,1] neg_lo:[1,0,0] neg_hi:[1,0,0]
	v_pk_fma_f32 v[186:187], v[54:55], v[184:185], v[186:187] op_sel:[0,1,0] neg_lo:[1,0,0] neg_hi:[1,0,0]
	v_pk_fma_f32 v[252:253], v[52:53], v[184:185], v[252:253] op_sel_hi:[1,0,1] neg_lo:[1,0,0] neg_hi:[1,0,0]
	ds_read_b128 v[182:185], v20 offset:48752
	v_pk_fma_f32 v[186:187], v[58:59], v[208:209], v[186:187] op_sel:[0,1,0] neg_lo:[1,0,0] neg_hi:[1,0,0]
	v_pk_fma_f32 v[252:253], v[56:57], v[208:209], v[252:253] op_sel_hi:[1,0,1] neg_lo:[1,0,0] neg_hi:[1,0,0]
	v_pk_fma_f32 v[186:187], v[62:63], v[210:211], v[186:187] op_sel:[0,1,0] neg_lo:[1,0,0] neg_hi:[1,0,0]
	v_pk_fma_f32 v[252:253], v[60:61], v[210:211], v[252:253] op_sel_hi:[1,0,1] neg_lo:[1,0,0] neg_hi:[1,0,0]
	ds_read_b128 v[208:211], v20 offset:48768
	v_pk_fma_f32 v[186:187], v[66:67], v[212:213], v[186:187] op_sel:[0,1,0] neg_lo:[1,0,0] neg_hi:[1,0,0]
	v_pk_fma_f32 v[252:253], v[212:213], v[64:65], v[252:253] op_sel_hi:[0,1,1] neg_lo:[1,0,0] neg_hi:[1,0,0]
	v_pk_fma_f32 v[186:187], v[70:71], v[214:215], v[186:187] op_sel:[0,1,0] neg_lo:[1,0,0] neg_hi:[1,0,0]
	v_pk_fma_f32 v[252:253], v[68:69], v[214:215], v[252:253] op_sel_hi:[1,0,1] neg_lo:[1,0,0] neg_hi:[1,0,0]
	ds_read_b128 v[212:215], v20 offset:48784
	v_pk_add_f32 v[66:67], v[252:253], v[186:187]
	s_waitcnt lgkmcnt(9)
	v_pk_fma_f32 v[186:187], v[138:139], v[152:153], 0 op_sel:[0,1,0] op_sel_hi:[1,1,0] neg_lo:[1,0,0] neg_hi:[1,0,0]
	v_pk_fma_f32 v[152:153], v[128:129], v[152:153], v[68:69] op_sel_hi:[1,0,1] neg_lo:[1,0,0] neg_hi:[1,0,0]
	v_pk_fma_f32 v[186:187], v[134:135], v[154:155], v[186:187] op_sel:[0,1,0] neg_lo:[1,0,0] neg_hi:[1,0,0]
	v_pk_fma_f32 v[152:153], v[136:137], v[154:155], v[152:153] op_sel_hi:[1,0,1] neg_lo:[1,0,0] neg_hi:[1,0,0]
	s_waitcnt lgkmcnt(8)
	v_pk_fma_f32 v[186:187], v[130:131], v[156:157], v[186:187] op_sel:[0,1,0] neg_lo:[1,0,0] neg_hi:[1,0,0]
	v_pk_fma_f32 v[152:153], v[132:133], v[156:157], v[152:153] op_sel_hi:[1,0,1] neg_lo:[1,0,0] neg_hi:[1,0,0]
	v_pk_fma_f32 v[186:187], v[84:85], v[158:159], v[186:187] op_sel:[0,1,0] neg_lo:[1,0,0] neg_hi:[1,0,0]
	v_pk_fma_f32 v[152:153], v[122:123], v[158:159], v[152:153] op_sel_hi:[1,0,1] neg_lo:[1,0,0] neg_hi:[1,0,0]
	ds_read_b128 v[156:159], v20 offset:48912
	s_waitcnt lgkmcnt(8)
	v_pk_fma_f32 v[186:187], v[10:11], v[160:161], v[186:187] op_sel:[0,1,0] neg_lo:[1,0,0] neg_hi:[1,0,0]
	v_pk_fma_f32 v[152:153], v[14:15], v[160:161], v[152:153] op_sel_hi:[1,0,1] neg_lo:[1,0,0] neg_hi:[1,0,0]
	v_pk_fma_f32 v[186:187], v[6:7], v[162:163], v[186:187] op_sel:[0,1,0] neg_lo:[1,0,0] neg_hi:[1,0,0]
	v_pk_fma_f32 v[152:153], v[16:17], v[162:163], v[152:153] op_sel_hi:[1,0,1] neg_lo:[1,0,0] neg_hi:[1,0,0]
	ds_read_b128 v[160:163], v20 offset:48928
	s_waitcnt lgkmcnt(8)
	v_pk_fma_f32 v[186:187], v[12:13], v[166:167], v[186:187] op_sel:[0,1,0] neg_lo:[1,0,0] neg_hi:[1,0,0]
	v_pk_fma_f32 v[152:153], v[18:19], v[166:167], v[152:153] op_sel_hi:[1,0,1] neg_lo:[1,0,0] neg_hi:[1,0,0]
	v_pk_fma_f32 v[186:187], v[4:5], v[168:169], v[186:187] op_sel:[0,1,0] neg_lo:[1,0,0] neg_hi:[1,0,0]
	v_pk_fma_f32 v[152:153], v[8:9], v[168:169], v[152:153] op_sel_hi:[1,0,1] neg_lo:[1,0,0] neg_hi:[1,0,0]
	ds_read_b128 v[166:169], v20 offset:48944
	s_waitcnt lgkmcnt(8)
	v_pk_fma_f32 v[186:187], v[0:1], v[170:171], v[186:187] op_sel:[0,1,0] neg_lo:[1,0,0] neg_hi:[1,0,0]
	v_pk_fma_f32 v[152:153], v[2:3], v[170:171], v[152:153] op_sel_hi:[1,0,1] neg_lo:[1,0,0] neg_hi:[1,0,0]
	v_pk_fma_f32 v[186:187], v[28:29], v[172:173], v[186:187] op_sel:[0,1,0] neg_lo:[1,0,0] neg_hi:[1,0,0]
	v_pk_fma_f32 v[152:153], v[30:31], v[172:173], v[152:153] op_sel_hi:[1,0,1] neg_lo:[1,0,0] neg_hi:[1,0,0]
	ds_read_b128 v[170:173], v20 offset:48960
	s_waitcnt lgkmcnt(8)
	v_pk_fma_f32 v[186:187], v[34:35], v[174:175], v[186:187] op_sel:[0,1,0] neg_lo:[1,0,0] neg_hi:[1,0,0]
	v_pk_fma_f32 v[152:153], v[32:33], v[174:175], v[152:153] op_sel_hi:[1,0,1] neg_lo:[1,0,0] neg_hi:[1,0,0]
	v_pk_fma_f32 v[186:187], v[40:41], v[176:177], v[186:187] op_sel:[0,1,0] neg_lo:[1,0,0] neg_hi:[1,0,0]
	v_pk_fma_f32 v[152:153], v[36:37], v[176:177], v[152:153] op_sel_hi:[1,0,1] neg_lo:[1,0,0] neg_hi:[1,0,0]
	ds_read_b128 v[174:177], v20 offset:48976
	s_waitcnt lgkmcnt(8)
	v_pk_fma_f32 v[186:187], v[42:43], v[178:179], v[186:187] op_sel:[0,1,0] neg_lo:[1,0,0] neg_hi:[1,0,0]
	v_pk_fma_f32 v[152:153], v[38:39], v[178:179], v[152:153] op_sel_hi:[1,0,1] neg_lo:[1,0,0] neg_hi:[1,0,0]
	v_pk_fma_f32 v[186:187], v[46:47], v[180:181], v[186:187] op_sel:[0,1,0] neg_lo:[1,0,0] neg_hi:[1,0,0]
	v_pk_fma_f32 v[152:153], v[44:45], v[180:181], v[152:153] op_sel_hi:[1,0,1] neg_lo:[1,0,0] neg_hi:[1,0,0]
	ds_read_b128 v[178:181], v20 offset:48992
	s_waitcnt lgkmcnt(8)
	v_pk_fma_f32 v[186:187], v[50:51], v[182:183], v[186:187] op_sel:[0,1,0] neg_lo:[1,0,0] neg_hi:[1,0,0]
	v_pk_fma_f32 v[152:153], v[48:49], v[182:183], v[152:153] op_sel_hi:[1,0,1] neg_lo:[1,0,0] neg_hi:[1,0,0]
	v_pk_fma_f32 v[186:187], v[54:55], v[184:185], v[186:187] op_sel:[0,1,0] neg_lo:[1,0,0] neg_hi:[1,0,0]
	v_pk_fma_f32 v[152:153], v[52:53], v[184:185], v[152:153] op_sel_hi:[1,0,1] neg_lo:[1,0,0] neg_hi:[1,0,0]
	ds_read_b128 v[182:185], v20 offset:49008
	s_waitcnt lgkmcnt(8)
	v_pk_fma_f32 v[186:187], v[58:59], v[208:209], v[186:187] op_sel:[0,1,0] neg_lo:[1,0,0] neg_hi:[1,0,0]
	v_pk_fma_f32 v[152:153], v[56:57], v[208:209], v[152:153] op_sel_hi:[1,0,1] neg_lo:[1,0,0] neg_hi:[1,0,0]
	v_pk_fma_f32 v[186:187], v[62:63], v[210:211], v[186:187] op_sel:[0,1,0] neg_lo:[1,0,0] neg_hi:[1,0,0]
	v_pk_fma_f32 v[152:153], v[60:61], v[210:211], v[152:153] op_sel_hi:[1,0,1] neg_lo:[1,0,0] neg_hi:[1,0,0]
	ds_read_b128 v[208:211], v20 offset:49024
	s_waitcnt lgkmcnt(8)
	v_pk_fma_f32 v[186:187], v[212:213], v[66:67], v[186:187] op_sel:[1,0,0] neg_lo:[1,0,0] neg_hi:[1,0,0]
	v_pk_fma_f32 v[152:153], v[64:65], v[212:213], v[152:153] op_sel_hi:[1,0,1] neg_lo:[1,0,0] neg_hi:[1,0,0]
	v_pk_fma_f32 v[186:187], v[70:71], v[214:215], v[186:187] op_sel:[0,1,0] neg_lo:[1,0,0] neg_hi:[1,0,0]
	v_pk_fma_f32 v[68:69], v[68:69], v[214:215], v[152:153] op_sel_hi:[1,0,1] neg_lo:[1,0,0] neg_hi:[1,0,0]
	ds_read_b128 v[152:155], v20 offset:48896
	ds_read_b128 v[212:215], v20 offset:49040
	v_pk_add_f32 v[68:69], v[68:69], v[186:187]
	s_waitcnt lgkmcnt(1)
	v_pk_fma_f32 v[186:187], v[138:139], v[152:153], 0 op_sel:[0,1,0] op_sel_hi:[1,1,0] neg_lo:[1,0,0] neg_hi:[1,0,0]
	v_pk_fma_f32 v[252:253], v[128:129], v[152:153], v[70:71] op_sel_hi:[1,0,1] neg_lo:[1,0,0] neg_hi:[1,0,0]
	v_pk_fma_f32 v[186:187], v[134:135], v[154:155], v[186:187] op_sel:[0,1,0] neg_lo:[1,0,0] neg_hi:[1,0,0]
	v_pk_fma_f32 v[252:253], v[136:137], v[154:155], v[252:253] op_sel_hi:[1,0,1] neg_lo:[1,0,0] neg_hi:[1,0,0]
	v_pk_fma_f32 v[186:187], v[130:131], v[156:157], v[186:187] op_sel:[0,1,0] neg_lo:[1,0,0] neg_hi:[1,0,0]
	ds_read_b128 v[152:155], v20 offset:49152
	v_pk_fma_f32 v[186:187], v[84:85], v[158:159], v[186:187] op_sel:[0,1,0] neg_lo:[1,0,0] neg_hi:[1,0,0]
	v_pk_fma_f32 v[252:253], v[132:133], v[156:157], v[252:253] op_sel_hi:[1,0,1] neg_lo:[1,0,0] neg_hi:[1,0,0]
	v_pk_fma_f32 v[186:187], v[10:11], v[160:161], v[186:187] op_sel:[0,1,0] neg_lo:[1,0,0] neg_hi:[1,0,0]
	v_pk_fma_f32 v[252:253], v[122:123], v[158:159], v[252:253] op_sel_hi:[1,0,1] neg_lo:[1,0,0] neg_hi:[1,0,0]
	ds_read_b128 v[156:159], v20 offset:49168
	v_pk_fma_f32 v[186:187], v[6:7], v[162:163], v[186:187] op_sel:[0,1,0] neg_lo:[1,0,0] neg_hi:[1,0,0]
	v_pk_fma_f32 v[252:253], v[14:15], v[160:161], v[252:253] op_sel_hi:[1,0,1] neg_lo:[1,0,0] neg_hi:[1,0,0]
	v_pk_fma_f32 v[186:187], v[12:13], v[166:167], v[186:187] op_sel:[0,1,0] neg_lo:[1,0,0] neg_hi:[1,0,0]
	v_pk_fma_f32 v[252:253], v[16:17], v[162:163], v[252:253] op_sel_hi:[1,0,1] neg_lo:[1,0,0] neg_hi:[1,0,0]
	ds_read_b128 v[160:163], v20 offset:49184
	v_pk_fma_f32 v[186:187], v[4:5], v[168:169], v[186:187] op_sel:[0,1,0] neg_lo:[1,0,0] neg_hi:[1,0,0]
	v_pk_fma_f32 v[252:253], v[18:19], v[166:167], v[252:253] op_sel_hi:[1,0,1] neg_lo:[1,0,0] neg_hi:[1,0,0]
	v_pk_fma_f32 v[186:187], v[0:1], v[170:171], v[186:187] op_sel:[0,1,0] neg_lo:[1,0,0] neg_hi:[1,0,0]
	v_pk_fma_f32 v[252:253], v[8:9], v[168:169], v[252:253] op_sel_hi:[1,0,1] neg_lo:[1,0,0] neg_hi:[1,0,0]
	ds_read_b128 v[166:169], v20 offset:49200
	v_pk_fma_f32 v[186:187], v[28:29], v[172:173], v[186:187] op_sel:[0,1,0] neg_lo:[1,0,0] neg_hi:[1,0,0]
	v_pk_fma_f32 v[252:253], v[2:3], v[170:171], v[252:253] op_sel_hi:[1,0,1] neg_lo:[1,0,0] neg_hi:[1,0,0]
	v_pk_fma_f32 v[186:187], v[34:35], v[174:175], v[186:187] op_sel:[0,1,0] neg_lo:[1,0,0] neg_hi:[1,0,0]
	v_pk_fma_f32 v[252:253], v[30:31], v[172:173], v[252:253] op_sel_hi:[1,0,1] neg_lo:[1,0,0] neg_hi:[1,0,0]
	ds_read_b128 v[170:173], v20 offset:49216
	v_pk_fma_f32 v[186:187], v[40:41], v[176:177], v[186:187] op_sel:[0,1,0] neg_lo:[1,0,0] neg_hi:[1,0,0]
	v_pk_fma_f32 v[252:253], v[32:33], v[174:175], v[252:253] op_sel_hi:[1,0,1] neg_lo:[1,0,0] neg_hi:[1,0,0]
	v_pk_fma_f32 v[186:187], v[42:43], v[178:179], v[186:187] op_sel:[0,1,0] neg_lo:[1,0,0] neg_hi:[1,0,0]
	v_pk_fma_f32 v[252:253], v[36:37], v[176:177], v[252:253] op_sel_hi:[1,0,1] neg_lo:[1,0,0] neg_hi:[1,0,0]
	ds_read_b128 v[174:177], v20 offset:49232
	v_pk_fma_f32 v[186:187], v[46:47], v[180:181], v[186:187] op_sel:[0,1,0] neg_lo:[1,0,0] neg_hi:[1,0,0]
	v_pk_fma_f32 v[252:253], v[38:39], v[178:179], v[252:253] op_sel_hi:[1,0,1] neg_lo:[1,0,0] neg_hi:[1,0,0]
	v_pk_fma_f32 v[186:187], v[50:51], v[182:183], v[186:187] op_sel:[0,1,0] neg_lo:[1,0,0] neg_hi:[1,0,0]
	v_pk_fma_f32 v[252:253], v[44:45], v[180:181], v[252:253] op_sel_hi:[1,0,1] neg_lo:[1,0,0] neg_hi:[1,0,0]
	ds_read_b128 v[178:181], v20 offset:49248
	v_pk_fma_f32 v[186:187], v[54:55], v[184:185], v[186:187] op_sel:[0,1,0] neg_lo:[1,0,0] neg_hi:[1,0,0]
	v_pk_fma_f32 v[252:253], v[48:49], v[182:183], v[252:253] op_sel_hi:[1,0,1] neg_lo:[1,0,0] neg_hi:[1,0,0]
	v_pk_fma_f32 v[186:187], v[58:59], v[208:209], v[186:187] op_sel:[0,1,0] neg_lo:[1,0,0] neg_hi:[1,0,0]
	v_pk_fma_f32 v[252:253], v[52:53], v[184:185], v[252:253] op_sel_hi:[1,0,1] neg_lo:[1,0,0] neg_hi:[1,0,0]
	ds_read_b128 v[182:185], v20 offset:49264
	v_pk_fma_f32 v[186:187], v[62:63], v[210:211], v[186:187] op_sel:[0,1,0] neg_lo:[1,0,0] neg_hi:[1,0,0]
	v_pk_fma_f32 v[252:253], v[56:57], v[208:209], v[252:253] op_sel_hi:[1,0,1] neg_lo:[1,0,0] neg_hi:[1,0,0]
	s_waitcnt lgkmcnt(8)
	v_pk_fma_f32 v[186:187], v[66:67], v[212:213], v[186:187] op_sel:[0,1,0] neg_lo:[1,0,0] neg_hi:[1,0,0]
	v_pk_fma_f32 v[252:253], v[60:61], v[210:211], v[252:253] op_sel_hi:[1,0,1] neg_lo:[1,0,0] neg_hi:[1,0,0]
	ds_read_b128 v[208:211], v20 offset:49280
	v_pk_fma_f32 v[186:187], v[70:71], v[214:215], v[186:187] op_sel:[0,1,0] neg_lo:[1,0,0] neg_hi:[1,0,0]
	v_pk_fma_f32 v[252:253], v[64:65], v[212:213], v[252:253] op_sel_hi:[1,0,1] neg_lo:[1,0,0] neg_hi:[1,0,0]
	s_nop 0
	v_pk_fma_f32 v[252:253], v[214:215], v[68:69], v[252:253] op_sel_hi:[0,1,1] neg_lo:[1,0,0] neg_hi:[1,0,0]
	ds_read_b128 v[212:215], v20 offset:49296
	v_pk_add_f32 v[70:71], v[252:253], v[186:187]
	s_waitcnt lgkmcnt(9)
	v_pk_fma_f32 v[186:187], v[138:139], v[152:153], 0 op_sel:[0,1,0] op_sel_hi:[1,1,0] neg_lo:[1,0,0] neg_hi:[1,0,0]
	v_pk_mul_f32 v[152:153], v[128:129], v[152:153] op_sel_hi:[1,0]
	v_pk_fma_f32 v[186:187], v[134:135], v[154:155], v[186:187] op_sel:[0,1,0] neg_lo:[1,0,0] neg_hi:[1,0,0]
	v_pk_fma_f32 v[72:73], v[72:73], v[150:151], v[152:153] neg_lo:[0,0,1] neg_hi:[0,0,1]
	ds_read_b128 v[150:153], v20 offset:49408
	v_pk_fma_f32 v[72:73], v[136:137], v[154:155], v[72:73] op_sel_hi:[1,0,1] neg_lo:[1,0,0] neg_hi:[1,0,0]
	s_waitcnt lgkmcnt(9)
	v_pk_fma_f32 v[186:187], v[130:131], v[156:157], v[186:187] op_sel:[0,1,0] neg_lo:[1,0,0] neg_hi:[1,0,0]
	v_pk_fma_f32 v[72:73], v[132:133], v[156:157], v[72:73] op_sel_hi:[1,0,1] neg_lo:[1,0,0] neg_hi:[1,0,0]
	ds_read_b128 v[154:157], v20 offset:49424
	v_pk_fma_f32 v[186:187], v[84:85], v[158:159], v[186:187] op_sel:[0,1,0] neg_lo:[1,0,0] neg_hi:[1,0,0]
	v_pk_fma_f32 v[72:73], v[122:123], v[158:159], v[72:73] op_sel_hi:[1,0,1] neg_lo:[1,0,0] neg_hi:[1,0,0]
	s_waitcnt lgkmcnt(9)
	v_pk_fma_f32 v[186:187], v[10:11], v[160:161], v[186:187] op_sel:[0,1,0] neg_lo:[1,0,0] neg_hi:[1,0,0]
	v_pk_fma_f32 v[72:73], v[14:15], v[160:161], v[72:73] op_sel_hi:[1,0,1] neg_lo:[1,0,0] neg_hi:[1,0,0]
	ds_read_b128 v[158:161], v20 offset:49440
	v_pk_fma_f32 v[186:187], v[6:7], v[162:163], v[186:187] op_sel:[0,1,0] neg_lo:[1,0,0] neg_hi:[1,0,0]
	v_pk_fma_f32 v[72:73], v[16:17], v[162:163], v[72:73] op_sel_hi:[1,0,1] neg_lo:[1,0,0] neg_hi:[1,0,0]
	s_waitcnt lgkmcnt(9)
	v_pk_fma_f32 v[186:187], v[12:13], v[166:167], v[186:187] op_sel:[0,1,0] neg_lo:[1,0,0] neg_hi:[1,0,0]
	v_pk_fma_f32 v[72:73], v[18:19], v[166:167], v[72:73] op_sel_hi:[1,0,1] neg_lo:[1,0,0] neg_hi:[1,0,0]
	v_pk_fma_f32 v[186:187], v[4:5], v[168:169], v[186:187] op_sel:[0,1,0] neg_lo:[1,0,0] neg_hi:[1,0,0]
	v_pk_fma_f32 v[72:73], v[8:9], v[168:169], v[72:73] op_sel_hi:[1,0,1] neg_lo:[1,0,0] neg_hi:[1,0,0]
	ds_read_b128 v[166:169], v20 offset:49456
	s_waitcnt lgkmcnt(9)
	v_pk_fma_f32 v[186:187], v[0:1], v[170:171], v[186:187] op_sel:[0,1,0] neg_lo:[1,0,0] neg_hi:[1,0,0]
	v_pk_fma_f32 v[72:73], v[2:3], v[170:171], v[72:73] op_sel_hi:[1,0,1] neg_lo:[1,0,0] neg_hi:[1,0,0]
	v_pk_fma_f32 v[186:187], v[28:29], v[172:173], v[186:187] op_sel:[0,1,0] neg_lo:[1,0,0] neg_hi:[1,0,0]
	v_pk_fma_f32 v[72:73], v[30:31], v[172:173], v[72:73] op_sel_hi:[1,0,1] neg_lo:[1,0,0] neg_hi:[1,0,0]
	ds_read_b128 v[170:173], v20 offset:49472
	s_waitcnt lgkmcnt(9)
	v_pk_fma_f32 v[186:187], v[34:35], v[174:175], v[186:187] op_sel:[0,1,0] neg_lo:[1,0,0] neg_hi:[1,0,0]
	v_pk_fma_f32 v[72:73], v[32:33], v[174:175], v[72:73] op_sel_hi:[1,0,1] neg_lo:[1,0,0] neg_hi:[1,0,0]
	v_pk_fma_f32 v[186:187], v[40:41], v[176:177], v[186:187] op_sel:[0,1,0] neg_lo:[1,0,0] neg_hi:[1,0,0]
	v_pk_fma_f32 v[72:73], v[36:37], v[176:177], v[72:73] op_sel_hi:[1,0,1] neg_lo:[1,0,0] neg_hi:[1,0,0]
	ds_read_b128 v[174:177], v20 offset:49488
	s_waitcnt lgkmcnt(9)
	v_pk_fma_f32 v[186:187], v[42:43], v[178:179], v[186:187] op_sel:[0,1,0] neg_lo:[1,0,0] neg_hi:[1,0,0]
	v_pk_fma_f32 v[72:73], v[38:39], v[178:179], v[72:73] op_sel_hi:[1,0,1] neg_lo:[1,0,0] neg_hi:[1,0,0]
	v_pk_fma_f32 v[186:187], v[46:47], v[180:181], v[186:187] op_sel:[0,1,0] neg_lo:[1,0,0] neg_hi:[1,0,0]
	v_pk_fma_f32 v[72:73], v[44:45], v[180:181], v[72:73] op_sel_hi:[1,0,1] neg_lo:[1,0,0] neg_hi:[1,0,0]
	ds_read_b128 v[178:181], v20 offset:49504
	s_waitcnt lgkmcnt(9)
	v_pk_fma_f32 v[186:187], v[50:51], v[182:183], v[186:187] op_sel:[0,1,0] neg_lo:[1,0,0] neg_hi:[1,0,0]
	v_pk_fma_f32 v[72:73], v[48:49], v[182:183], v[72:73] op_sel_hi:[1,0,1] neg_lo:[1,0,0] neg_hi:[1,0,0]
	v_pk_fma_f32 v[186:187], v[54:55], v[184:185], v[186:187] op_sel:[0,1,0] neg_lo:[1,0,0] neg_hi:[1,0,0]
	v_pk_fma_f32 v[72:73], v[52:53], v[184:185], v[72:73] op_sel_hi:[1,0,1] neg_lo:[1,0,0] neg_hi:[1,0,0]
	ds_read_b128 v[182:185], v20 offset:49520
	s_waitcnt lgkmcnt(9)
	v_pk_fma_f32 v[186:187], v[58:59], v[208:209], v[186:187] op_sel:[0,1,0] neg_lo:[1,0,0] neg_hi:[1,0,0]
	v_pk_fma_f32 v[72:73], v[56:57], v[208:209], v[72:73] op_sel_hi:[1,0,1] neg_lo:[1,0,0] neg_hi:[1,0,0]
	v_pk_fma_f32 v[186:187], v[62:63], v[210:211], v[186:187] op_sel:[0,1,0] neg_lo:[1,0,0] neg_hi:[1,0,0]
	v_pk_fma_f32 v[72:73], v[60:61], v[210:211], v[72:73] op_sel_hi:[1,0,1] neg_lo:[1,0,0] neg_hi:[1,0,0]
	ds_read_b128 v[208:211], v20 offset:49536
	s_waitcnt lgkmcnt(9)
	v_pk_fma_f32 v[186:187], v[66:67], v[212:213], v[186:187] op_sel:[0,1,0] neg_lo:[1,0,0] neg_hi:[1,0,0]
	v_pk_fma_f32 v[72:73], v[64:65], v[212:213], v[72:73] op_sel_hi:[1,0,1] neg_lo:[1,0,0] neg_hi:[1,0,0]
	v_pk_fma_f32 v[186:187], v[214:215], v[70:71], v[186:187] op_sel:[1,0,0] neg_lo:[1,0,0] neg_hi:[1,0,0]
	v_pk_fma_f32 v[72:73], v[68:69], v[214:215], v[72:73] op_sel_hi:[1,0,1] neg_lo:[1,0,0] neg_hi:[1,0,0]
	ds_read_b128 v[212:215], v20 offset:49552
	v_pk_add_f32 v[72:73], v[72:73], v[186:187]
	s_waitcnt lgkmcnt(9)
	v_pk_fma_f32 v[162:163], v[138:139], v[150:151], 0 op_sel:[0,1,0] op_sel_hi:[1,1,0] neg_lo:[1,0,0] neg_hi:[1,0,0]
	v_pk_fma_f32 v[252:253], v[128:129], v[150:151], v[74:75] op_sel_hi:[1,0,1] neg_lo:[1,0,0] neg_hi:[1,0,0]
	v_pk_fma_f32 v[162:163], v[134:135], v[152:153], v[162:163] op_sel:[0,1,0] neg_lo:[1,0,0] neg_hi:[1,0,0]
	v_pk_fma_f32 v[252:253], v[136:137], v[152:153], v[252:253] op_sel_hi:[1,0,1] neg_lo:[1,0,0] neg_hi:[1,0,0]
	s_waitcnt lgkmcnt(8)
	v_pk_fma_f32 v[162:163], v[130:131], v[154:155], v[162:163] op_sel:[0,1,0] neg_lo:[1,0,0] neg_hi:[1,0,0]
	ds_read_b128 v[150:153], v20 offset:49664
	v_pk_fma_f32 v[162:163], v[84:85], v[156:157], v[162:163] op_sel:[0,1,0] neg_lo:[1,0,0] neg_hi:[1,0,0]
	v_pk_fma_f32 v[252:253], v[132:133], v[154:155], v[252:253] op_sel_hi:[1,0,1] neg_lo:[1,0,0] neg_hi:[1,0,0]
	s_waitcnt lgkmcnt(8)
	v_pk_fma_f32 v[162:163], v[10:11], v[158:159], v[162:163] op_sel:[0,1,0] neg_lo:[1,0,0] neg_hi:[1,0,0]
	v_pk_fma_f32 v[252:253], v[122:123], v[156:157], v[252:253] op_sel_hi:[1,0,1] neg_lo:[1,0,0] neg_hi:[1,0,0]
	v_pk_fma_f32 v[162:163], v[6:7], v[160:161], v[162:163] op_sel:[0,1,0] neg_lo:[1,0,0] neg_hi:[1,0,0]
	ds_read_b128 v[154:157], v20 offset:49680
	s_waitcnt lgkmcnt(8)
	v_pk_fma_f32 v[162:163], v[12:13], v[166:167], v[162:163] op_sel:[0,1,0] neg_lo:[1,0,0] neg_hi:[1,0,0]
	v_pk_fma_f32 v[252:253], v[14:15], v[158:159], v[252:253] op_sel_hi:[1,0,1] neg_lo:[1,0,0] neg_hi:[1,0,0]
	v_pk_fma_f32 v[162:163], v[4:5], v[168:169], v[162:163] op_sel:[0,1,0] neg_lo:[1,0,0] neg_hi:[1,0,0]
	v_pk_fma_f32 v[252:253], v[16:17], v[160:161], v[252:253] op_sel_hi:[1,0,1] neg_lo:[1,0,0] neg_hi:[1,0,0]
	ds_read_b128 v[158:161], v20 offset:49696
	s_waitcnt lgkmcnt(8)
	v_pk_fma_f32 v[162:163], v[0:1], v[170:171], v[162:163] op_sel:[0,1,0] neg_lo:[1,0,0] neg_hi:[1,0,0]
	v_pk_fma_f32 v[252:253], v[18:19], v[166:167], v[252:253] op_sel_hi:[1,0,1] neg_lo:[1,0,0] neg_hi:[1,0,0]
	v_pk_fma_f32 v[162:163], v[28:29], v[172:173], v[162:163] op_sel:[0,1,0] neg_lo:[1,0,0] neg_hi:[1,0,0]
	v_pk_fma_f32 v[252:253], v[8:9], v[168:169], v[252:253] op_sel_hi:[1,0,1] neg_lo:[1,0,0] neg_hi:[1,0,0]
	ds_read_b128 v[166:169], v20 offset:49712
	s_waitcnt lgkmcnt(8)
	v_pk_fma_f32 v[162:163], v[34:35], v[174:175], v[162:163] op_sel:[0,1,0] neg_lo:[1,0,0] neg_hi:[1,0,0]
	v_pk_fma_f32 v[252:253], v[2:3], v[170:171], v[252:253] op_sel_hi:[1,0,1] neg_lo:[1,0,0] neg_hi:[1,0,0]
	v_pk_fma_f32 v[162:163], v[40:41], v[176:177], v[162:163] op_sel:[0,1,0] neg_lo:[1,0,0] neg_hi:[1,0,0]
	v_pk_fma_f32 v[252:253], v[30:31], v[172:173], v[252:253] op_sel_hi:[1,0,1] neg_lo:[1,0,0] neg_hi:[1,0,0]
	ds_read_b128 v[170:173], v20 offset:49728
	s_waitcnt lgkmcnt(8)
	v_pk_fma_f32 v[162:163], v[42:43], v[178:179], v[162:163] op_sel:[0,1,0] neg_lo:[1,0,0] neg_hi:[1,0,0]
	v_pk_fma_f32 v[252:253], v[32:33], v[174:175], v[252:253] op_sel_hi:[1,0,1] neg_lo:[1,0,0] neg_hi:[1,0,0]
	v_pk_fma_f32 v[162:163], v[46:47], v[180:181], v[162:163] op_sel:[0,1,0] neg_lo:[1,0,0] neg_hi:[1,0,0]
	v_pk_fma_f32 v[252:253], v[36:37], v[176:177], v[252:253] op_sel_hi:[1,0,1] neg_lo:[1,0,0] neg_hi:[1,0,0]
	ds_read_b128 v[174:177], v20 offset:49744
	s_waitcnt lgkmcnt(8)
	v_pk_fma_f32 v[162:163], v[50:51], v[182:183], v[162:163] op_sel:[0,1,0] neg_lo:[1,0,0] neg_hi:[1,0,0]
	v_pk_fma_f32 v[252:253], v[38:39], v[178:179], v[252:253] op_sel_hi:[1,0,1] neg_lo:[1,0,0] neg_hi:[1,0,0]
	v_pk_fma_f32 v[162:163], v[54:55], v[184:185], v[162:163] op_sel:[0,1,0] neg_lo:[1,0,0] neg_hi:[1,0,0]
	v_pk_fma_f32 v[252:253], v[44:45], v[180:181], v[252:253] op_sel_hi:[1,0,1] neg_lo:[1,0,0] neg_hi:[1,0,0]
	ds_read_b128 v[178:181], v20 offset:49760
	s_waitcnt lgkmcnt(8)
	v_pk_fma_f32 v[162:163], v[58:59], v[208:209], v[162:163] op_sel:[0,1,0] neg_lo:[1,0,0] neg_hi:[1,0,0]
	v_pk_fma_f32 v[252:253], v[48:49], v[182:183], v[252:253] op_sel_hi:[1,0,1] neg_lo:[1,0,0] neg_hi:[1,0,0]
	v_pk_fma_f32 v[162:163], v[62:63], v[210:211], v[162:163] op_sel:[0,1,0] neg_lo:[1,0,0] neg_hi:[1,0,0]
	v_pk_fma_f32 v[252:253], v[52:53], v[184:185], v[252:253] op_sel_hi:[1,0,1] neg_lo:[1,0,0] neg_hi:[1,0,0]
	ds_read_b128 v[182:185], v20 offset:49776
	s_waitcnt lgkmcnt(8)
	v_pk_fma_f32 v[162:163], v[66:67], v[212:213], v[162:163] op_sel:[0,1,0] neg_lo:[1,0,0] neg_hi:[1,0,0]
	v_pk_fma_f32 v[252:253], v[56:57], v[208:209], v[252:253] op_sel_hi:[1,0,1] neg_lo:[1,0,0] neg_hi:[1,0,0]
	v_pk_fma_f32 v[162:163], v[70:71], v[214:215], v[162:163] op_sel:[0,1,0] neg_lo:[1,0,0] neg_hi:[1,0,0]
	v_pk_fma_f32 v[252:253], v[60:61], v[210:211], v[252:253] op_sel_hi:[1,0,1] neg_lo:[1,0,0] neg_hi:[1,0,0]
	ds_read_b128 v[208:211], v20 offset:49792
	v_pk_fma_f32 v[162:163], v[74:75], v[216:217], v[162:163] op_sel:[0,1,0] neg_lo:[1,0,0] neg_hi:[1,0,0]
	v_pk_fma_f32 v[252:253], v[64:65], v[212:213], v[252:253] op_sel_hi:[1,0,1] neg_lo:[1,0,0] neg_hi:[1,0,0]
	v_pk_fma_f32 v[162:163], v[78:79], v[218:219], v[162:163] op_sel:[0,1,0] neg_lo:[1,0,0] neg_hi:[1,0,0]
	v_pk_fma_f32 v[252:253], v[68:69], v[214:215], v[252:253] op_sel_hi:[1,0,1] neg_lo:[1,0,0] neg_hi:[1,0,0]
	ds_read_b128 v[212:215], v20 offset:49808
	v_pk_fma_f32 v[252:253], v[216:217], v[72:73], v[252:253] op_sel_hi:[0,1,1] neg_lo:[1,0,0] neg_hi:[1,0,0]
	s_nop 0
	v_pk_fma_f32 v[252:253], v[76:77], v[218:219], v[252:253] op_sel_hi:[1,0,1] neg_lo:[1,0,0] neg_hi:[1,0,0]
	ds_read_b128 v[216:219], v20 offset:49824
	v_pk_add_f32 v[74:75], v[252:253], v[162:163]
	s_waitcnt lgkmcnt(10)
	v_pk_fma_f32 v[162:163], v[138:139], v[150:151], 0 op_sel:[0,1,0] op_sel_hi:[1,1,0] neg_lo:[1,0,0] neg_hi:[1,0,0]
	v_pk_fma_f32 v[150:151], v[128:129], v[150:151], v[76:77] op_sel_hi:[1,0,1] neg_lo:[1,0,0] neg_hi:[1,0,0]
	v_pk_fma_f32 v[162:163], v[134:135], v[152:153], v[162:163] op_sel:[0,1,0] neg_lo:[1,0,0] neg_hi:[1,0,0]
	v_pk_fma_f32 v[150:151], v[136:137], v[152:153], v[150:151] op_sel_hi:[1,0,1] neg_lo:[1,0,0] neg_hi:[1,0,0]
	s_waitcnt lgkmcnt(9)
	v_pk_fma_f32 v[162:163], v[130:131], v[154:155], v[162:163] op_sel:[0,1,0] neg_lo:[1,0,0] neg_hi:[1,0,0]
	v_pk_fma_f32 v[150:151], v[132:133], v[154:155], v[150:151] op_sel_hi:[1,0,1] neg_lo:[1,0,0] neg_hi:[1,0,0]
	v_pk_fma_f32 v[162:163], v[84:85], v[156:157], v[162:163] op_sel:[0,1,0] neg_lo:[1,0,0] neg_hi:[1,0,0]
	v_pk_fma_f32 v[150:151], v[122:123], v[156:157], v[150:151] op_sel_hi:[1,0,1] neg_lo:[1,0,0] neg_hi:[1,0,0]
	ds_read_b128 v[154:157], v20 offset:49936
	s_waitcnt lgkmcnt(9)
	v_pk_fma_f32 v[162:163], v[10:11], v[158:159], v[162:163] op_sel:[0,1,0] neg_lo:[1,0,0] neg_hi:[1,0,0]
	v_pk_fma_f32 v[150:151], v[14:15], v[158:159], v[150:151] op_sel_hi:[1,0,1] neg_lo:[1,0,0] neg_hi:[1,0,0]
	v_pk_fma_f32 v[162:163], v[6:7], v[160:161], v[162:163] op_sel:[0,1,0] neg_lo:[1,0,0] neg_hi:[1,0,0]
	v_pk_fma_f32 v[150:151], v[16:17], v[160:161], v[150:151] op_sel_hi:[1,0,1] neg_lo:[1,0,0] neg_hi:[1,0,0]
	ds_read_b128 v[158:161], v20 offset:49952
	s_waitcnt lgkmcnt(9)
	v_pk_fma_f32 v[162:163], v[12:13], v[166:167], v[162:163] op_sel:[0,1,0] neg_lo:[1,0,0] neg_hi:[1,0,0]
	v_pk_fma_f32 v[150:151], v[18:19], v[166:167], v[150:151] op_sel_hi:[1,0,1] neg_lo:[1,0,0] neg_hi:[1,0,0]
	v_pk_fma_f32 v[162:163], v[4:5], v[168:169], v[162:163] op_sel:[0,1,0] neg_lo:[1,0,0] neg_hi:[1,0,0]
	v_pk_fma_f32 v[150:151], v[8:9], v[168:169], v[150:151] op_sel_hi:[1,0,1] neg_lo:[1,0,0] neg_hi:[1,0,0]
	ds_read_b128 v[166:169], v20 offset:49968
	s_waitcnt lgkmcnt(9)
	v_pk_fma_f32 v[162:163], v[0:1], v[170:171], v[162:163] op_sel:[0,1,0] neg_lo:[1,0,0] neg_hi:[1,0,0]
	v_pk_fma_f32 v[150:151], v[2:3], v[170:171], v[150:151] op_sel_hi:[1,0,1] neg_lo:[1,0,0] neg_hi:[1,0,0]
	v_pk_fma_f32 v[162:163], v[28:29], v[172:173], v[162:163] op_sel:[0,1,0] neg_lo:[1,0,0] neg_hi:[1,0,0]
	v_pk_fma_f32 v[150:151], v[30:31], v[172:173], v[150:151] op_sel_hi:[1,0,1] neg_lo:[1,0,0] neg_hi:[1,0,0]
	ds_read_b128 v[170:173], v20 offset:49984
	s_waitcnt lgkmcnt(9)
	v_pk_fma_f32 v[162:163], v[34:35], v[174:175], v[162:163] op_sel:[0,1,0] neg_lo:[1,0,0] neg_hi:[1,0,0]
	v_pk_fma_f32 v[150:151], v[32:33], v[174:175], v[150:151] op_sel_hi:[1,0,1] neg_lo:[1,0,0] neg_hi:[1,0,0]
	v_pk_fma_f32 v[162:163], v[40:41], v[176:177], v[162:163] op_sel:[0,1,0] neg_lo:[1,0,0] neg_hi:[1,0,0]
	v_pk_fma_f32 v[150:151], v[36:37], v[176:177], v[150:151] op_sel_hi:[1,0,1] neg_lo:[1,0,0] neg_hi:[1,0,0]
	ds_read_b128 v[174:177], v20 offset:50000
	s_waitcnt lgkmcnt(9)
	v_pk_fma_f32 v[162:163], v[42:43], v[178:179], v[162:163] op_sel:[0,1,0] neg_lo:[1,0,0] neg_hi:[1,0,0]
	v_pk_fma_f32 v[150:151], v[38:39], v[178:179], v[150:151] op_sel_hi:[1,0,1] neg_lo:[1,0,0] neg_hi:[1,0,0]
	v_pk_fma_f32 v[162:163], v[46:47], v[180:181], v[162:163] op_sel:[0,1,0] neg_lo:[1,0,0] neg_hi:[1,0,0]
	v_pk_fma_f32 v[150:151], v[44:45], v[180:181], v[150:151] op_sel_hi:[1,0,1] neg_lo:[1,0,0] neg_hi:[1,0,0]
	ds_read_b128 v[178:181], v20 offset:50016
	s_waitcnt lgkmcnt(9)
	v_pk_fma_f32 v[162:163], v[50:51], v[182:183], v[162:163] op_sel:[0,1,0] neg_lo:[1,0,0] neg_hi:[1,0,0]
	v_pk_fma_f32 v[150:151], v[48:49], v[182:183], v[150:151] op_sel_hi:[1,0,1] neg_lo:[1,0,0] neg_hi:[1,0,0]
	v_pk_fma_f32 v[162:163], v[54:55], v[184:185], v[162:163] op_sel:[0,1,0] neg_lo:[1,0,0] neg_hi:[1,0,0]
	v_pk_fma_f32 v[150:151], v[52:53], v[184:185], v[150:151] op_sel_hi:[1,0,1] neg_lo:[1,0,0] neg_hi:[1,0,0]
	ds_read_b128 v[182:185], v20 offset:50032
	s_waitcnt lgkmcnt(9)
	v_pk_fma_f32 v[162:163], v[58:59], v[208:209], v[162:163] op_sel:[0,1,0] neg_lo:[1,0,0] neg_hi:[1,0,0]
	v_pk_fma_f32 v[150:151], v[56:57], v[208:209], v[150:151] op_sel_hi:[1,0,1] neg_lo:[1,0,0] neg_hi:[1,0,0]
	v_pk_fma_f32 v[162:163], v[62:63], v[210:211], v[162:163] op_sel:[0,1,0] neg_lo:[1,0,0] neg_hi:[1,0,0]
	v_pk_fma_f32 v[150:151], v[60:61], v[210:211], v[150:151] op_sel_hi:[1,0,1] neg_lo:[1,0,0] neg_hi:[1,0,0]
	ds_read_b128 v[208:211], v20 offset:50048
	s_waitcnt lgkmcnt(9)
	v_pk_fma_f32 v[162:163], v[66:67], v[212:213], v[162:163] op_sel:[0,1,0] neg_lo:[1,0,0] neg_hi:[1,0,0]
	v_pk_fma_f32 v[150:151], v[64:65], v[212:213], v[150:151] op_sel_hi:[1,0,1] neg_lo:[1,0,0] neg_hi:[1,0,0]
	v_pk_fma_f32 v[162:163], v[70:71], v[214:215], v[162:163] op_sel:[0,1,0] neg_lo:[1,0,0] neg_hi:[1,0,0]
	v_pk_fma_f32 v[150:151], v[68:69], v[214:215], v[150:151] op_sel_hi:[1,0,1] neg_lo:[1,0,0] neg_hi:[1,0,0]
	ds_read_b128 v[212:215], v20 offset:50064
	s_waitcnt lgkmcnt(9)
	v_pk_fma_f32 v[162:163], v[216:217], v[74:75], v[162:163] op_sel:[1,0,0] neg_lo:[1,0,0] neg_hi:[1,0,0]
	v_pk_fma_f32 v[150:151], v[72:73], v[216:217], v[150:151] op_sel_hi:[1,0,1] neg_lo:[1,0,0] neg_hi:[1,0,0]
	v_pk_fma_f32 v[162:163], v[78:79], v[218:219], v[162:163] op_sel:[0,1,0] neg_lo:[1,0,0] neg_hi:[1,0,0]
	v_pk_fma_f32 v[76:77], v[76:77], v[218:219], v[150:151] op_sel_hi:[1,0,1] neg_lo:[1,0,0] neg_hi:[1,0,0]
	ds_read_b128 v[150:153], v20 offset:49920
	ds_read_b128 v[216:219], v20 offset:50080
	v_pk_add_f32 v[76:77], v[76:77], v[162:163]
	s_waitcnt lgkmcnt(1)
	v_pk_fma_f32 v[162:163], v[138:139], v[150:151], 0 op_sel:[0,1,0] op_sel_hi:[1,1,0] neg_lo:[1,0,0] neg_hi:[1,0,0]
	v_pk_fma_f32 v[252:253], v[128:129], v[150:151], v[78:79] op_sel_hi:[1,0,1] neg_lo:[1,0,0] neg_hi:[1,0,0]
	v_pk_fma_f32 v[162:163], v[134:135], v[152:153], v[162:163] op_sel:[0,1,0] neg_lo:[1,0,0] neg_hi:[1,0,0]
	v_pk_fma_f32 v[252:253], v[136:137], v[152:153], v[252:253] op_sel_hi:[1,0,1] neg_lo:[1,0,0] neg_hi:[1,0,0]
	v_pk_fma_f32 v[162:163], v[130:131], v[154:155], v[162:163] op_sel:[0,1,0] neg_lo:[1,0,0] neg_hi:[1,0,0]
	ds_read_b128 v[150:153], v20 offset:50176
	v_pk_fma_f32 v[162:163], v[84:85], v[156:157], v[162:163] op_sel:[0,1,0] neg_lo:[1,0,0] neg_hi:[1,0,0]
	v_pk_fma_f32 v[252:253], v[132:133], v[154:155], v[252:253] op_sel_hi:[1,0,1] neg_lo:[1,0,0] neg_hi:[1,0,0]
	v_pk_fma_f32 v[162:163], v[10:11], v[158:159], v[162:163] op_sel:[0,1,0] neg_lo:[1,0,0] neg_hi:[1,0,0]
	v_pk_fma_f32 v[252:253], v[122:123], v[156:157], v[252:253] op_sel_hi:[1,0,1] neg_lo:[1,0,0] neg_hi:[1,0,0]
	v_pk_fma_f32 v[162:163], v[6:7], v[160:161], v[162:163] op_sel:[0,1,0] neg_lo:[1,0,0] neg_hi:[1,0,0]
	ds_read_b128 v[154:157], v20 offset:50192
	v_pk_fma_f32 v[162:163], v[12:13], v[166:167], v[162:163] op_sel:[0,1,0] neg_lo:[1,0,0] neg_hi:[1,0,0]
	v_pk_fma_f32 v[252:253], v[14:15], v[158:159], v[252:253] op_sel_hi:[1,0,1] neg_lo:[1,0,0] neg_hi:[1,0,0]
	v_pk_fma_f32 v[162:163], v[4:5], v[168:169], v[162:163] op_sel:[0,1,0] neg_lo:[1,0,0] neg_hi:[1,0,0]
	v_pk_fma_f32 v[252:253], v[16:17], v[160:161], v[252:253] op_sel_hi:[1,0,1] neg_lo:[1,0,0] neg_hi:[1,0,0]
	ds_read_b128 v[158:161], v20 offset:50208
	v_pk_fma_f32 v[162:163], v[0:1], v[170:171], v[162:163] op_sel:[0,1,0] neg_lo:[1,0,0] neg_hi:[1,0,0]
	v_pk_fma_f32 v[252:253], v[18:19], v[166:167], v[252:253] op_sel_hi:[1,0,1] neg_lo:[1,0,0] neg_hi:[1,0,0]
	v_pk_fma_f32 v[162:163], v[28:29], v[172:173], v[162:163] op_sel:[0,1,0] neg_lo:[1,0,0] neg_hi:[1,0,0]
	v_pk_fma_f32 v[252:253], v[8:9], v[168:169], v[252:253] op_sel_hi:[1,0,1] neg_lo:[1,0,0] neg_hi:[1,0,0]
	ds_read_b128 v[166:169], v20 offset:50224
	v_pk_fma_f32 v[162:163], v[34:35], v[174:175], v[162:163] op_sel:[0,1,0] neg_lo:[1,0,0] neg_hi:[1,0,0]
	v_pk_fma_f32 v[252:253], v[2:3], v[170:171], v[252:253] op_sel_hi:[1,0,1] neg_lo:[1,0,0] neg_hi:[1,0,0]
	v_pk_fma_f32 v[162:163], v[40:41], v[176:177], v[162:163] op_sel:[0,1,0] neg_lo:[1,0,0] neg_hi:[1,0,0]
	v_pk_fma_f32 v[252:253], v[30:31], v[172:173], v[252:253] op_sel_hi:[1,0,1] neg_lo:[1,0,0] neg_hi:[1,0,0]
	ds_read_b128 v[170:173], v20 offset:50240
	v_pk_fma_f32 v[162:163], v[42:43], v[178:179], v[162:163] op_sel:[0,1,0] neg_lo:[1,0,0] neg_hi:[1,0,0]
	v_pk_fma_f32 v[252:253], v[32:33], v[174:175], v[252:253] op_sel_hi:[1,0,1] neg_lo:[1,0,0] neg_hi:[1,0,0]
	v_pk_fma_f32 v[162:163], v[46:47], v[180:181], v[162:163] op_sel:[0,1,0] neg_lo:[1,0,0] neg_hi:[1,0,0]
	v_pk_fma_f32 v[252:253], v[36:37], v[176:177], v[252:253] op_sel_hi:[1,0,1] neg_lo:[1,0,0] neg_hi:[1,0,0]
	ds_read_b128 v[174:177], v20 offset:50256
	v_pk_fma_f32 v[162:163], v[50:51], v[182:183], v[162:163] op_sel:[0,1,0] neg_lo:[1,0,0] neg_hi:[1,0,0]
	v_pk_fma_f32 v[252:253], v[38:39], v[178:179], v[252:253] op_sel_hi:[1,0,1] neg_lo:[1,0,0] neg_hi:[1,0,0]
	v_pk_fma_f32 v[162:163], v[54:55], v[184:185], v[162:163] op_sel:[0,1,0] neg_lo:[1,0,0] neg_hi:[1,0,0]
	v_pk_fma_f32 v[252:253], v[44:45], v[180:181], v[252:253] op_sel_hi:[1,0,1] neg_lo:[1,0,0] neg_hi:[1,0,0]
	ds_read_b128 v[178:181], v20 offset:50272
	v_pk_fma_f32 v[162:163], v[58:59], v[208:209], v[162:163] op_sel:[0,1,0] neg_lo:[1,0,0] neg_hi:[1,0,0]
	v_pk_fma_f32 v[252:253], v[48:49], v[182:183], v[252:253] op_sel_hi:[1,0,1] neg_lo:[1,0,0] neg_hi:[1,0,0]
	v_pk_fma_f32 v[162:163], v[62:63], v[210:211], v[162:163] op_sel:[0,1,0] neg_lo:[1,0,0] neg_hi:[1,0,0]
	v_pk_fma_f32 v[252:253], v[52:53], v[184:185], v[252:253] op_sel_hi:[1,0,1] neg_lo:[1,0,0] neg_hi:[1,0,0]
	ds_read_b128 v[182:185], v20 offset:50288
	v_pk_fma_f32 v[162:163], v[66:67], v[212:213], v[162:163] op_sel:[0,1,0] neg_lo:[1,0,0] neg_hi:[1,0,0]
	v_pk_fma_f32 v[252:253], v[56:57], v[208:209], v[252:253] op_sel_hi:[1,0,1] neg_lo:[1,0,0] neg_hi:[1,0,0]
	v_pk_fma_f32 v[162:163], v[70:71], v[214:215], v[162:163] op_sel:[0,1,0] neg_lo:[1,0,0] neg_hi:[1,0,0]
	v_pk_fma_f32 v[252:253], v[60:61], v[210:211], v[252:253] op_sel_hi:[1,0,1] neg_lo:[1,0,0] neg_hi:[1,0,0]
	ds_read_b128 v[208:211], v20 offset:50304
	s_waitcnt lgkmcnt(9)
	v_pk_fma_f32 v[162:163], v[74:75], v[216:217], v[162:163] op_sel:[0,1,0] neg_lo:[1,0,0] neg_hi:[1,0,0]
	v_pk_fma_f32 v[252:253], v[64:65], v[212:213], v[252:253] op_sel_hi:[1,0,1] neg_lo:[1,0,0] neg_hi:[1,0,0]
	v_pk_fma_f32 v[162:163], v[78:79], v[218:219], v[162:163] op_sel:[0,1,0] neg_lo:[1,0,0] neg_hi:[1,0,0]
	v_pk_fma_f32 v[252:253], v[68:69], v[214:215], v[252:253] op_sel_hi:[1,0,1] neg_lo:[1,0,0] neg_hi:[1,0,0]
	ds_read_b128 v[212:215], v20 offset:50320
	v_pk_fma_f32 v[252:253], v[72:73], v[216:217], v[252:253] op_sel_hi:[1,0,1] neg_lo:[1,0,0] neg_hi:[1,0,0]
	s_nop 0
	v_pk_fma_f32 v[252:253], v[218:219], v[76:77], v[252:253] op_sel_hi:[0,1,1] neg_lo:[1,0,0] neg_hi:[1,0,0]
	ds_read_b128 v[216:219], v20 offset:50336
	v_pk_add_f32 v[78:79], v[252:253], v[162:163]
	s_waitcnt lgkmcnt(10)
	v_pk_fma_f32 v[162:163], v[138:139], v[150:151], 0 op_sel:[0,1,0] op_sel_hi:[1,1,0] neg_lo:[1,0,0] neg_hi:[1,0,0]
	v_pk_mul_f32 v[150:151], v[128:129], v[150:151] op_sel_hi:[1,0]
	v_pk_fma_f32 v[162:163], v[134:135], v[152:153], v[162:163] op_sel:[0,1,0] neg_lo:[1,0,0] neg_hi:[1,0,0]
	v_pk_fma_f32 v[80:81], v[80:81], v[146:147], v[150:151] neg_lo:[0,0,1] neg_hi:[0,0,1]
	s_waitcnt lgkmcnt(9)
	v_pk_fma_f32 v[162:163], v[130:131], v[154:155], v[162:163] op_sel:[0,1,0] neg_lo:[1,0,0] neg_hi:[1,0,0]
	v_pk_fma_f32 v[80:81], v[136:137], v[152:153], v[80:81] op_sel_hi:[1,0,1] neg_lo:[1,0,0] neg_hi:[1,0,0]
	ds_read_b128 v[150:153], v20 offset:50432
	v_pk_fma_f32 v[80:81], v[132:133], v[154:155], v[80:81] op_sel_hi:[1,0,1] neg_lo:[1,0,0] neg_hi:[1,0,0]
	v_pk_fma_f32 v[162:163], v[84:85], v[156:157], v[162:163] op_sel:[0,1,0] neg_lo:[1,0,0] neg_hi:[1,0,0]
	v_pk_fma_f32 v[80:81], v[122:123], v[156:157], v[80:81] op_sel_hi:[1,0,1] neg_lo:[1,0,0] neg_hi:[1,0,0]
	ds_read_b128 v[154:157], v20 offset:50448
	s_waitcnt lgkmcnt(10)
	v_pk_fma_f32 v[162:163], v[10:11], v[158:159], v[162:163] op_sel:[0,1,0] neg_lo:[1,0,0] neg_hi:[1,0,0]
	v_pk_fma_f32 v[80:81], v[14:15], v[158:159], v[80:81] op_sel_hi:[1,0,1] neg_lo:[1,0,0] neg_hi:[1,0,0]
	v_pk_fma_f32 v[162:163], v[6:7], v[160:161], v[162:163] op_sel:[0,1,0] neg_lo:[1,0,0] neg_hi:[1,0,0]
	v_pk_fma_f32 v[80:81], v[16:17], v[160:161], v[80:81] op_sel_hi:[1,0,1] neg_lo:[1,0,0] neg_hi:[1,0,0]
	ds_read_b128 v[158:161], v20 offset:50464
	s_waitcnt lgkmcnt(10)
	v_pk_fma_f32 v[162:163], v[12:13], v[166:167], v[162:163] op_sel:[0,1,0] neg_lo:[1,0,0] neg_hi:[1,0,0]
	v_pk_fma_f32 v[80:81], v[18:19], v[166:167], v[80:81] op_sel_hi:[1,0,1] neg_lo:[1,0,0] neg_hi:[1,0,0]
	v_pk_fma_f32 v[162:163], v[4:5], v[168:169], v[162:163] op_sel:[0,1,0] neg_lo:[1,0,0] neg_hi:[1,0,0]
	v_pk_fma_f32 v[80:81], v[8:9], v[168:169], v[80:81] op_sel_hi:[1,0,1] neg_lo:[1,0,0] neg_hi:[1,0,0]
	ds_read_b128 v[166:169], v20 offset:50480
	s_waitcnt lgkmcnt(10)
	v_pk_fma_f32 v[162:163], v[0:1], v[170:171], v[162:163] op_sel:[0,1,0] neg_lo:[1,0,0] neg_hi:[1,0,0]
	v_pk_fma_f32 v[80:81], v[2:3], v[170:171], v[80:81] op_sel_hi:[1,0,1] neg_lo:[1,0,0] neg_hi:[1,0,0]
	v_pk_fma_f32 v[162:163], v[28:29], v[172:173], v[162:163] op_sel:[0,1,0] neg_lo:[1,0,0] neg_hi:[1,0,0]
	v_pk_fma_f32 v[80:81], v[30:31], v[172:173], v[80:81] op_sel_hi:[1,0,1] neg_lo:[1,0,0] neg_hi:[1,0,0]
	ds_read_b128 v[170:173], v20 offset:50496
	s_waitcnt lgkmcnt(10)
	v_pk_fma_f32 v[162:163], v[34:35], v[174:175], v[162:163] op_sel:[0,1,0] neg_lo:[1,0,0] neg_hi:[1,0,0]
	v_pk_fma_f32 v[80:81], v[32:33], v[174:175], v[80:81] op_sel_hi:[1,0,1] neg_lo:[1,0,0] neg_hi:[1,0,0]
	v_pk_fma_f32 v[162:163], v[40:41], v[176:177], v[162:163] op_sel:[0,1,0] neg_lo:[1,0,0] neg_hi:[1,0,0]
	v_pk_fma_f32 v[80:81], v[36:37], v[176:177], v[80:81] op_sel_hi:[1,0,1] neg_lo:[1,0,0] neg_hi:[1,0,0]
	ds_read_b128 v[174:177], v20 offset:50512
	s_waitcnt lgkmcnt(10)
	v_pk_fma_f32 v[162:163], v[42:43], v[178:179], v[162:163] op_sel:[0,1,0] neg_lo:[1,0,0] neg_hi:[1,0,0]
	v_pk_fma_f32 v[80:81], v[38:39], v[178:179], v[80:81] op_sel_hi:[1,0,1] neg_lo:[1,0,0] neg_hi:[1,0,0]
	v_pk_fma_f32 v[162:163], v[46:47], v[180:181], v[162:163] op_sel:[0,1,0] neg_lo:[1,0,0] neg_hi:[1,0,0]
	v_pk_fma_f32 v[80:81], v[44:45], v[180:181], v[80:81] op_sel_hi:[1,0,1] neg_lo:[1,0,0] neg_hi:[1,0,0]
	ds_read_b128 v[178:181], v20 offset:50528
	s_waitcnt lgkmcnt(10)
	v_pk_fma_f32 v[162:163], v[50:51], v[182:183], v[162:163] op_sel:[0,1,0] neg_lo:[1,0,0] neg_hi:[1,0,0]
	v_pk_fma_f32 v[80:81], v[48:49], v[182:183], v[80:81] op_sel_hi:[1,0,1] neg_lo:[1,0,0] neg_hi:[1,0,0]
	v_pk_fma_f32 v[162:163], v[54:55], v[184:185], v[162:163] op_sel:[0,1,0] neg_lo:[1,0,0] neg_hi:[1,0,0]
	v_pk_fma_f32 v[80:81], v[52:53], v[184:185], v[80:81] op_sel_hi:[1,0,1] neg_lo:[1,0,0] neg_hi:[1,0,0]
	ds_read_b128 v[182:185], v20 offset:50544
	s_waitcnt lgkmcnt(10)
	v_pk_fma_f32 v[162:163], v[58:59], v[208:209], v[162:163] op_sel:[0,1,0] neg_lo:[1,0,0] neg_hi:[1,0,0]
	v_pk_fma_f32 v[80:81], v[56:57], v[208:209], v[80:81] op_sel_hi:[1,0,1] neg_lo:[1,0,0] neg_hi:[1,0,0]
	v_pk_fma_f32 v[162:163], v[62:63], v[210:211], v[162:163] op_sel:[0,1,0] neg_lo:[1,0,0] neg_hi:[1,0,0]
	v_pk_fma_f32 v[80:81], v[60:61], v[210:211], v[80:81] op_sel_hi:[1,0,1] neg_lo:[1,0,0] neg_hi:[1,0,0]
	ds_read_b128 v[208:211], v20 offset:50560
	s_waitcnt lgkmcnt(10)
	v_pk_fma_f32 v[162:163], v[66:67], v[212:213], v[162:163] op_sel:[0,1,0] neg_lo:[1,0,0] neg_hi:[1,0,0]
	v_pk_fma_f32 v[80:81], v[64:65], v[212:213], v[80:81] op_sel_hi:[1,0,1] neg_lo:[1,0,0] neg_hi:[1,0,0]
	v_pk_fma_f32 v[162:163], v[70:71], v[214:215], v[162:163] op_sel:[0,1,0] neg_lo:[1,0,0] neg_hi:[1,0,0]
	v_pk_fma_f32 v[80:81], v[68:69], v[214:215], v[80:81] op_sel_hi:[1,0,1] neg_lo:[1,0,0] neg_hi:[1,0,0]
	ds_read_b128 v[212:215], v20 offset:50576
	s_waitcnt lgkmcnt(10)
	v_pk_fma_f32 v[162:163], v[74:75], v[216:217], v[162:163] op_sel:[0,1,0] neg_lo:[1,0,0] neg_hi:[1,0,0]
	v_pk_fma_f32 v[80:81], v[72:73], v[216:217], v[80:81] op_sel_hi:[1,0,1] neg_lo:[1,0,0] neg_hi:[1,0,0]
	v_pk_fma_f32 v[162:163], v[218:219], v[78:79], v[162:163] op_sel:[1,0,0] neg_lo:[1,0,0] neg_hi:[1,0,0]
	v_pk_fma_f32 v[80:81], v[76:77], v[218:219], v[80:81] op_sel_hi:[1,0,1] neg_lo:[1,0,0] neg_hi:[1,0,0]
	ds_read_b128 v[216:219], v20 offset:50592
	v_pk_add_f32 v[80:81], v[80:81], v[162:163]
	s_waitcnt lgkmcnt(10)
	v_pk_fma_f32 v[146:147], v[138:139], v[150:151], 0 op_sel:[0,1,0] op_sel_hi:[1,1,0] neg_lo:[1,0,0] neg_hi:[1,0,0]
	v_pk_fma_f32 v[252:253], v[128:129], v[150:151], v[82:83] op_sel_hi:[1,0,1] neg_lo:[1,0,0] neg_hi:[1,0,0]
	v_pk_fma_f32 v[146:147], v[134:135], v[152:153], v[146:147] op_sel:[0,1,0] neg_lo:[1,0,0] neg_hi:[1,0,0]
	v_pk_fma_f32 v[252:253], v[136:137], v[152:153], v[252:253] op_sel_hi:[1,0,1] neg_lo:[1,0,0] neg_hi:[1,0,0]
	s_waitcnt lgkmcnt(9)
	v_pk_fma_f32 v[146:147], v[130:131], v[154:155], v[146:147] op_sel:[0,1,0] neg_lo:[1,0,0] neg_hi:[1,0,0]
	ds_read_b128 v[150:153], v20 offset:50688
	v_pk_fma_f32 v[146:147], v[84:85], v[156:157], v[146:147] op_sel:[0,1,0] neg_lo:[1,0,0] neg_hi:[1,0,0]
	v_pk_fma_f32 v[252:253], v[132:133], v[154:155], v[252:253] op_sel_hi:[1,0,1] neg_lo:[1,0,0] neg_hi:[1,0,0]
	s_waitcnt lgkmcnt(9)
	v_pk_fma_f32 v[146:147], v[10:11], v[158:159], v[146:147] op_sel:[0,1,0] neg_lo:[1,0,0] neg_hi:[1,0,0]
	v_pk_fma_f32 v[252:253], v[122:123], v[156:157], v[252:253] op_sel_hi:[1,0,1] neg_lo:[1,0,0] neg_hi:[1,0,0]
	v_pk_fma_f32 v[146:147], v[6:7], v[160:161], v[146:147] op_sel:[0,1,0] neg_lo:[1,0,0] neg_hi:[1,0,0]
	ds_read_b128 v[154:157], v20 offset:50704
	s_waitcnt lgkmcnt(9)
	v_pk_fma_f32 v[146:147], v[12:13], v[166:167], v[146:147] op_sel:[0,1,0] neg_lo:[1,0,0] neg_hi:[1,0,0]
	v_pk_fma_f32 v[252:253], v[14:15], v[158:159], v[252:253] op_sel_hi:[1,0,1] neg_lo:[1,0,0] neg_hi:[1,0,0]
	v_pk_fma_f32 v[146:147], v[4:5], v[168:169], v[146:147] op_sel:[0,1,0] neg_lo:[1,0,0] neg_hi:[1,0,0]
	v_pk_fma_f32 v[252:253], v[16:17], v[160:161], v[252:253] op_sel_hi:[1,0,1] neg_lo:[1,0,0] neg_hi:[1,0,0]
	s_waitcnt lgkmcnt(8)
	v_pk_fma_f32 v[146:147], v[0:1], v[170:171], v[146:147] op_sel:[0,1,0] neg_lo:[1,0,0] neg_hi:[1,0,0]
	ds_read_b128 v[158:161], v20 offset:50720
	v_pk_fma_f32 v[146:147], v[28:29], v[172:173], v[146:147] op_sel:[0,1,0] neg_lo:[1,0,0] neg_hi:[1,0,0]
	v_pk_fma_f32 v[252:253], v[18:19], v[166:167], v[252:253] op_sel_hi:[1,0,1] neg_lo:[1,0,0] neg_hi:[1,0,0]
	s_waitcnt lgkmcnt(8)
	v_pk_fma_f32 v[146:147], v[34:35], v[174:175], v[146:147] op_sel:[0,1,0] neg_lo:[1,0,0] neg_hi:[1,0,0]
	v_pk_fma_f32 v[252:253], v[8:9], v[168:169], v[252:253] op_sel_hi:[1,0,1] neg_lo:[1,0,0] neg_hi:[1,0,0]
	ds_read_b128 v[166:169], v20 offset:50736
	v_pk_fma_f32 v[146:147], v[40:41], v[176:177], v[146:147] op_sel:[0,1,0] neg_lo:[1,0,0] neg_hi:[1,0,0]
	v_pk_fma_f32 v[252:253], v[2:3], v[170:171], v[252:253] op_sel_hi:[1,0,1] neg_lo:[1,0,0] neg_hi:[1,0,0]
	s_waitcnt lgkmcnt(8)
	v_pk_fma_f32 v[146:147], v[42:43], v[178:179], v[146:147] op_sel:[0,1,0] neg_lo:[1,0,0] neg_hi:[1,0,0]
	v_pk_fma_f32 v[252:253], v[30:31], v[172:173], v[252:253] op_sel_hi:[1,0,1] neg_lo:[1,0,0] neg_hi:[1,0,0]
	ds_read_b128 v[170:173], v20 offset:50752
	v_pk_fma_f32 v[146:147], v[46:47], v[180:181], v[146:147] op_sel:[0,1,0] neg_lo:[1,0,0] neg_hi:[1,0,0]
	v_pk_fma_f32 v[252:253], v[32:33], v[174:175], v[252:253] op_sel_hi:[1,0,1] neg_lo:[1,0,0] neg_hi:[1,0,0]
	s_waitcnt lgkmcnt(8)
	v_pk_fma_f32 v[146:147], v[50:51], v[182:183], v[146:147] op_sel:[0,1,0] neg_lo:[1,0,0] neg_hi:[1,0,0]
	v_pk_fma_f32 v[252:253], v[36:37], v[176:177], v[252:253] op_sel_hi:[1,0,1] neg_lo:[1,0,0] neg_hi:[1,0,0]
	ds_read_b128 v[174:177], v20 offset:50768
	v_pk_fma_f32 v[146:147], v[54:55], v[184:185], v[146:147] op_sel:[0,1,0] neg_lo:[1,0,0] neg_hi:[1,0,0]
	v_pk_fma_f32 v[252:253], v[38:39], v[178:179], v[252:253] op_sel_hi:[1,0,1] neg_lo:[1,0,0] neg_hi:[1,0,0]
	s_waitcnt lgkmcnt(8)
	v_pk_fma_f32 v[146:147], v[58:59], v[208:209], v[146:147] op_sel:[0,1,0] neg_lo:[1,0,0] neg_hi:[1,0,0]
	v_pk_fma_f32 v[252:253], v[44:45], v[180:181], v[252:253] op_sel_hi:[1,0,1] neg_lo:[1,0,0] neg_hi:[1,0,0]
	ds_read_b128 v[178:181], v20 offset:50784
	v_pk_fma_f32 v[146:147], v[62:63], v[210:211], v[146:147] op_sel:[0,1,0] neg_lo:[1,0,0] neg_hi:[1,0,0]
	v_pk_fma_f32 v[252:253], v[48:49], v[182:183], v[252:253] op_sel_hi:[1,0,1] neg_lo:[1,0,0] neg_hi:[1,0,0]
	s_waitcnt lgkmcnt(8)
	v_pk_fma_f32 v[146:147], v[66:67], v[212:213], v[146:147] op_sel:[0,1,0] neg_lo:[1,0,0] neg_hi:[1,0,0]
	v_pk_fma_f32 v[252:253], v[52:53], v[184:185], v[252:253] op_sel_hi:[1,0,1] neg_lo:[1,0,0] neg_hi:[1,0,0]
	ds_read_b128 v[182:185], v20 offset:50800
	v_pk_fma_f32 v[146:147], v[70:71], v[214:215], v[146:147] op_sel:[0,1,0] neg_lo:[1,0,0] neg_hi:[1,0,0]
	v_pk_fma_f32 v[252:253], v[56:57], v[208:209], v[252:253] op_sel_hi:[1,0,1] neg_lo:[1,0,0] neg_hi:[1,0,0]
	s_waitcnt lgkmcnt(8)
	v_pk_fma_f32 v[146:147], v[74:75], v[216:217], v[146:147] op_sel:[0,1,0] neg_lo:[1,0,0] neg_hi:[1,0,0]
	v_pk_fma_f32 v[252:253], v[60:61], v[210:211], v[252:253] op_sel_hi:[1,0,1] neg_lo:[1,0,0] neg_hi:[1,0,0]
	ds_read_b128 v[208:211], v20 offset:50816
	v_pk_fma_f32 v[146:147], v[78:79], v[218:219], v[146:147] op_sel:[0,1,0] neg_lo:[1,0,0] neg_hi:[1,0,0]
	v_pk_fma_f32 v[252:253], v[64:65], v[212:213], v[252:253] op_sel_hi:[1,0,1] neg_lo:[1,0,0] neg_hi:[1,0,0]
	v_pk_fma_f32 v[146:147], v[82:83], v[220:221], v[146:147] op_sel:[0,1,0] neg_lo:[1,0,0] neg_hi:[1,0,0]
	v_pk_fma_f32 v[252:253], v[68:69], v[214:215], v[252:253] op_sel_hi:[1,0,1] neg_lo:[1,0,0] neg_hi:[1,0,0]
	ds_read_b128 v[212:215], v20 offset:50832
	v_pk_fma_f32 v[146:147], v[88:89], v[222:223], v[146:147] op_sel:[0,1,0] neg_lo:[1,0,0] neg_hi:[1,0,0]
	v_pk_fma_f32 v[252:253], v[72:73], v[216:217], v[252:253] op_sel_hi:[1,0,1] neg_lo:[1,0,0] neg_hi:[1,0,0]
	s_nop 0
	v_pk_fma_f32 v[252:253], v[76:77], v[218:219], v[252:253] op_sel_hi:[1,0,1] neg_lo:[1,0,0] neg_hi:[1,0,0]
	ds_read_b128 v[216:219], v20 offset:50848
	v_pk_fma_f32 v[252:253], v[220:221], v[80:81], v[252:253] op_sel_hi:[0,1,1] neg_lo:[1,0,0] neg_hi:[1,0,0]
	s_nop 0
	v_pk_fma_f32 v[252:253], v[86:87], v[222:223], v[252:253] op_sel_hi:[1,0,1] neg_lo:[1,0,0] neg_hi:[1,0,0]
	ds_read_b128 v[220:223], v20 offset:50864
	v_pk_add_f32 v[82:83], v[252:253], v[146:147]
	s_waitcnt lgkmcnt(11)
	v_pk_fma_f32 v[146:147], v[138:139], v[150:151], 0 op_sel:[0,1,0] op_sel_hi:[1,1,0] neg_lo:[1,0,0] neg_hi:[1,0,0]
	v_pk_fma_f32 v[150:151], v[128:129], v[150:151], v[86:87] op_sel_hi:[1,0,1] neg_lo:[1,0,0] neg_hi:[1,0,0]
	v_pk_fma_f32 v[146:147], v[134:135], v[152:153], v[146:147] op_sel:[0,1,0] neg_lo:[1,0,0] neg_hi:[1,0,0]
	v_pk_fma_f32 v[150:151], v[136:137], v[152:153], v[150:151] op_sel_hi:[1,0,1] neg_lo:[1,0,0] neg_hi:[1,0,0]
	s_waitcnt lgkmcnt(10)
	v_pk_fma_f32 v[146:147], v[130:131], v[154:155], v[146:147] op_sel:[0,1,0] neg_lo:[1,0,0] neg_hi:[1,0,0]
	v_pk_fma_f32 v[150:151], v[132:133], v[154:155], v[150:151] op_sel_hi:[1,0,1] neg_lo:[1,0,0] neg_hi:[1,0,0]
	v_pk_fma_f32 v[146:147], v[84:85], v[156:157], v[146:147] op_sel:[0,1,0] neg_lo:[1,0,0] neg_hi:[1,0,0]
	v_pk_fma_f32 v[150:151], v[122:123], v[156:157], v[150:151] op_sel_hi:[1,0,1] neg_lo:[1,0,0] neg_hi:[1,0,0]
	ds_read_b128 v[154:157], v20 offset:50960
	s_waitcnt lgkmcnt(10)
	v_pk_fma_f32 v[146:147], v[10:11], v[158:159], v[146:147] op_sel:[0,1,0] neg_lo:[1,0,0] neg_hi:[1,0,0]
	v_pk_fma_f32 v[150:151], v[14:15], v[158:159], v[150:151] op_sel_hi:[1,0,1] neg_lo:[1,0,0] neg_hi:[1,0,0]
	v_pk_fma_f32 v[146:147], v[6:7], v[160:161], v[146:147] op_sel:[0,1,0] neg_lo:[1,0,0] neg_hi:[1,0,0]
	v_pk_fma_f32 v[150:151], v[16:17], v[160:161], v[150:151] op_sel_hi:[1,0,1] neg_lo:[1,0,0] neg_hi:[1,0,0]
	ds_read_b128 v[158:161], v20 offset:50976
	s_waitcnt lgkmcnt(10)
	v_pk_fma_f32 v[146:147], v[12:13], v[166:167], v[146:147] op_sel:[0,1,0] neg_lo:[1,0,0] neg_hi:[1,0,0]
	v_pk_fma_f32 v[150:151], v[18:19], v[166:167], v[150:151] op_sel_hi:[1,0,1] neg_lo:[1,0,0] neg_hi:[1,0,0]
	v_pk_fma_f32 v[146:147], v[4:5], v[168:169], v[146:147] op_sel:[0,1,0] neg_lo:[1,0,0] neg_hi:[1,0,0]
	v_pk_fma_f32 v[150:151], v[8:9], v[168:169], v[150:151] op_sel_hi:[1,0,1] neg_lo:[1,0,0] neg_hi:[1,0,0]
	ds_read_b128 v[166:169], v20 offset:50992
	s_waitcnt lgkmcnt(10)
	v_pk_fma_f32 v[146:147], v[0:1], v[170:171], v[146:147] op_sel:[0,1,0] neg_lo:[1,0,0] neg_hi:[1,0,0]
	v_pk_fma_f32 v[150:151], v[2:3], v[170:171], v[150:151] op_sel_hi:[1,0,1] neg_lo:[1,0,0] neg_hi:[1,0,0]
	v_pk_fma_f32 v[146:147], v[28:29], v[172:173], v[146:147] op_sel:[0,1,0] neg_lo:[1,0,0] neg_hi:[1,0,0]
	v_pk_fma_f32 v[150:151], v[30:31], v[172:173], v[150:151] op_sel_hi:[1,0,1] neg_lo:[1,0,0] neg_hi:[1,0,0]
	ds_read_b128 v[170:173], v20 offset:51008
	s_waitcnt lgkmcnt(10)
	v_pk_fma_f32 v[146:147], v[34:35], v[174:175], v[146:147] op_sel:[0,1,0] neg_lo:[1,0,0] neg_hi:[1,0,0]
	v_pk_fma_f32 v[150:151], v[32:33], v[174:175], v[150:151] op_sel_hi:[1,0,1] neg_lo:[1,0,0] neg_hi:[1,0,0]
	v_pk_fma_f32 v[146:147], v[40:41], v[176:177], v[146:147] op_sel:[0,1,0] neg_lo:[1,0,0] neg_hi:[1,0,0]
	v_pk_fma_f32 v[150:151], v[36:37], v[176:177], v[150:151] op_sel_hi:[1,0,1] neg_lo:[1,0,0] neg_hi:[1,0,0]
	ds_read_b128 v[174:177], v20 offset:51024
	s_waitcnt lgkmcnt(10)
	v_pk_fma_f32 v[146:147], v[42:43], v[178:179], v[146:147] op_sel:[0,1,0] neg_lo:[1,0,0] neg_hi:[1,0,0]
	v_pk_fma_f32 v[150:151], v[38:39], v[178:179], v[150:151] op_sel_hi:[1,0,1] neg_lo:[1,0,0] neg_hi:[1,0,0]
	v_pk_fma_f32 v[146:147], v[46:47], v[180:181], v[146:147] op_sel:[0,1,0] neg_lo:[1,0,0] neg_hi:[1,0,0]
	v_pk_fma_f32 v[150:151], v[44:45], v[180:181], v[150:151] op_sel_hi:[1,0,1] neg_lo:[1,0,0] neg_hi:[1,0,0]
	ds_read_b128 v[178:181], v20 offset:51040
	s_waitcnt lgkmcnt(10)
	v_pk_fma_f32 v[146:147], v[50:51], v[182:183], v[146:147] op_sel:[0,1,0] neg_lo:[1,0,0] neg_hi:[1,0,0]
	v_pk_fma_f32 v[150:151], v[48:49], v[182:183], v[150:151] op_sel_hi:[1,0,1] neg_lo:[1,0,0] neg_hi:[1,0,0]
	v_pk_fma_f32 v[146:147], v[54:55], v[184:185], v[146:147] op_sel:[0,1,0] neg_lo:[1,0,0] neg_hi:[1,0,0]
	v_pk_fma_f32 v[150:151], v[52:53], v[184:185], v[150:151] op_sel_hi:[1,0,1] neg_lo:[1,0,0] neg_hi:[1,0,0]
	ds_read_b128 v[182:185], v20 offset:51056
	s_waitcnt lgkmcnt(10)
	v_pk_fma_f32 v[146:147], v[58:59], v[208:209], v[146:147] op_sel:[0,1,0] neg_lo:[1,0,0] neg_hi:[1,0,0]
	v_pk_fma_f32 v[150:151], v[56:57], v[208:209], v[150:151] op_sel_hi:[1,0,1] neg_lo:[1,0,0] neg_hi:[1,0,0]
	v_pk_fma_f32 v[146:147], v[62:63], v[210:211], v[146:147] op_sel:[0,1,0] neg_lo:[1,0,0] neg_hi:[1,0,0]
	v_pk_fma_f32 v[150:151], v[60:61], v[210:211], v[150:151] op_sel_hi:[1,0,1] neg_lo:[1,0,0] neg_hi:[1,0,0]
	ds_read_b128 v[208:211], v20 offset:51072
	s_waitcnt lgkmcnt(10)
	v_pk_fma_f32 v[146:147], v[66:67], v[212:213], v[146:147] op_sel:[0,1,0] neg_lo:[1,0,0] neg_hi:[1,0,0]
	v_pk_fma_f32 v[150:151], v[64:65], v[212:213], v[150:151] op_sel_hi:[1,0,1] neg_lo:[1,0,0] neg_hi:[1,0,0]
	v_pk_fma_f32 v[146:147], v[70:71], v[214:215], v[146:147] op_sel:[0,1,0] neg_lo:[1,0,0] neg_hi:[1,0,0]
	v_pk_fma_f32 v[150:151], v[68:69], v[214:215], v[150:151] op_sel_hi:[1,0,1] neg_lo:[1,0,0] neg_hi:[1,0,0]
	ds_read_b128 v[212:215], v20 offset:51088
	s_waitcnt lgkmcnt(10)
	v_pk_fma_f32 v[146:147], v[74:75], v[216:217], v[146:147] op_sel:[0,1,0] neg_lo:[1,0,0] neg_hi:[1,0,0]
	v_pk_fma_f32 v[150:151], v[72:73], v[216:217], v[150:151] op_sel_hi:[1,0,1] neg_lo:[1,0,0] neg_hi:[1,0,0]
	v_pk_fma_f32 v[146:147], v[78:79], v[218:219], v[146:147] op_sel:[0,1,0] neg_lo:[1,0,0] neg_hi:[1,0,0]
	v_pk_fma_f32 v[150:151], v[76:77], v[218:219], v[150:151] op_sel_hi:[1,0,1] neg_lo:[1,0,0] neg_hi:[1,0,0]
	ds_read_b128 v[216:219], v20 offset:51104
	s_waitcnt lgkmcnt(10)
	v_pk_fma_f32 v[146:147], v[220:221], v[82:83], v[146:147] op_sel:[1,0,0] neg_lo:[1,0,0] neg_hi:[1,0,0]
	v_pk_fma_f32 v[150:151], v[80:81], v[220:221], v[150:151] op_sel_hi:[1,0,1] neg_lo:[1,0,0] neg_hi:[1,0,0]
	v_pk_fma_f32 v[146:147], v[88:89], v[222:223], v[146:147] op_sel:[0,1,0] neg_lo:[1,0,0] neg_hi:[1,0,0]
	v_pk_fma_f32 v[86:87], v[86:87], v[222:223], v[150:151] op_sel_hi:[1,0,1] neg_lo:[1,0,0] neg_hi:[1,0,0]
	ds_read_b128 v[150:153], v20 offset:50944
	ds_read_b128 v[220:223], v20 offset:51120
	v_pk_add_f32 v[86:87], v[86:87], v[146:147]
	s_waitcnt lgkmcnt(1)
	v_pk_fma_f32 v[146:147], v[138:139], v[150:151], 0 op_sel:[0,1,0] op_sel_hi:[1,1,0] neg_lo:[1,0,0] neg_hi:[1,0,0]
	v_pk_fma_f32 v[252:253], v[128:129], v[150:151], v[88:89] op_sel_hi:[1,0,1] neg_lo:[1,0,0] neg_hi:[1,0,0]
	v_pk_fma_f32 v[146:147], v[134:135], v[152:153], v[146:147] op_sel:[0,1,0] neg_lo:[1,0,0] neg_hi:[1,0,0]
	v_pk_fma_f32 v[252:253], v[136:137], v[152:153], v[252:253] op_sel_hi:[1,0,1] neg_lo:[1,0,0] neg_hi:[1,0,0]
	v_pk_fma_f32 v[146:147], v[130:131], v[154:155], v[146:147] op_sel:[0,1,0] neg_lo:[1,0,0] neg_hi:[1,0,0]
	ds_read_b128 v[150:153], v20 offset:51200
	v_pk_fma_f32 v[146:147], v[84:85], v[156:157], v[146:147] op_sel:[0,1,0] neg_lo:[1,0,0] neg_hi:[1,0,0]
	v_pk_fma_f32 v[252:253], v[132:133], v[154:155], v[252:253] op_sel_hi:[1,0,1] neg_lo:[1,0,0] neg_hi:[1,0,0]
	v_pk_fma_f32 v[146:147], v[10:11], v[158:159], v[146:147] op_sel:[0,1,0] neg_lo:[1,0,0] neg_hi:[1,0,0]
	v_pk_fma_f32 v[252:253], v[122:123], v[156:157], v[252:253] op_sel_hi:[1,0,1] neg_lo:[1,0,0] neg_hi:[1,0,0]
	v_pk_fma_f32 v[146:147], v[6:7], v[160:161], v[146:147] op_sel:[0,1,0] neg_lo:[1,0,0] neg_hi:[1,0,0]
	ds_read_b128 v[154:157], v20 offset:51216
	v_pk_fma_f32 v[146:147], v[12:13], v[166:167], v[146:147] op_sel:[0,1,0] neg_lo:[1,0,0] neg_hi:[1,0,0]
	v_pk_fma_f32 v[252:253], v[14:15], v[158:159], v[252:253] op_sel_hi:[1,0,1] neg_lo:[1,0,0] neg_hi:[1,0,0]
	v_pk_fma_f32 v[146:147], v[4:5], v[168:169], v[146:147] op_sel:[0,1,0] neg_lo:[1,0,0] neg_hi:[1,0,0]
	v_pk_fma_f32 v[252:253], v[16:17], v[160:161], v[252:253] op_sel_hi:[1,0,1] neg_lo:[1,0,0] neg_hi:[1,0,0]
	v_pk_fma_f32 v[146:147], v[0:1], v[170:171], v[146:147] op_sel:[0,1,0] neg_lo:[1,0,0] neg_hi:[1,0,0]
	ds_read_b128 v[158:161], v20 offset:51232
	v_pk_fma_f32 v[146:147], v[28:29], v[172:173], v[146:147] op_sel:[0,1,0] neg_lo:[1,0,0] neg_hi:[1,0,0]
	v_pk_fma_f32 v[252:253], v[18:19], v[166:167], v[252:253] op_sel_hi:[1,0,1] neg_lo:[1,0,0] neg_hi:[1,0,0]
	v_pk_fma_f32 v[146:147], v[34:35], v[174:175], v[146:147] op_sel:[0,1,0] neg_lo:[1,0,0] neg_hi:[1,0,0]
	v_pk_fma_f32 v[252:253], v[8:9], v[168:169], v[252:253] op_sel_hi:[1,0,1] neg_lo:[1,0,0] neg_hi:[1,0,0]
	v_pk_fma_f32 v[146:147], v[40:41], v[176:177], v[146:147] op_sel:[0,1,0] neg_lo:[1,0,0] neg_hi:[1,0,0]
	ds_read_b128 v[166:169], v20 offset:51248
	v_pk_fma_f32 v[146:147], v[42:43], v[178:179], v[146:147] op_sel:[0,1,0] neg_lo:[1,0,0] neg_hi:[1,0,0]
	v_pk_fma_f32 v[252:253], v[2:3], v[170:171], v[252:253] op_sel_hi:[1,0,1] neg_lo:[1,0,0] neg_hi:[1,0,0]
	v_pk_fma_f32 v[146:147], v[46:47], v[180:181], v[146:147] op_sel:[0,1,0] neg_lo:[1,0,0] neg_hi:[1,0,0]
	v_pk_fma_f32 v[252:253], v[30:31], v[172:173], v[252:253] op_sel_hi:[1,0,1] neg_lo:[1,0,0] neg_hi:[1,0,0]
	ds_read_b128 v[170:173], v20 offset:51264
	v_pk_fma_f32 v[146:147], v[50:51], v[182:183], v[146:147] op_sel:[0,1,0] neg_lo:[1,0,0] neg_hi:[1,0,0]
	v_pk_fma_f32 v[252:253], v[32:33], v[174:175], v[252:253] op_sel_hi:[1,0,1] neg_lo:[1,0,0] neg_hi:[1,0,0]
	v_pk_fma_f32 v[146:147], v[54:55], v[184:185], v[146:147] op_sel:[0,1,0] neg_lo:[1,0,0] neg_hi:[1,0,0]
	v_pk_fma_f32 v[252:253], v[36:37], v[176:177], v[252:253] op_sel_hi:[1,0,1] neg_lo:[1,0,0] neg_hi:[1,0,0]
	ds_read_b128 v[174:177], v20 offset:51280
	v_pk_fma_f32 v[146:147], v[58:59], v[208:209], v[146:147] op_sel:[0,1,0] neg_lo:[1,0,0] neg_hi:[1,0,0]
	v_pk_fma_f32 v[252:253], v[38:39], v[178:179], v[252:253] op_sel_hi:[1,0,1] neg_lo:[1,0,0] neg_hi:[1,0,0]
	v_pk_fma_f32 v[146:147], v[62:63], v[210:211], v[146:147] op_sel:[0,1,0] neg_lo:[1,0,0] neg_hi:[1,0,0]
	v_pk_fma_f32 v[252:253], v[44:45], v[180:181], v[252:253] op_sel_hi:[1,0,1] neg_lo:[1,0,0] neg_hi:[1,0,0]
	ds_read_b128 v[178:181], v20 offset:51296
	v_pk_fma_f32 v[146:147], v[66:67], v[212:213], v[146:147] op_sel:[0,1,0] neg_lo:[1,0,0] neg_hi:[1,0,0]
	v_pk_fma_f32 v[252:253], v[48:49], v[182:183], v[252:253] op_sel_hi:[1,0,1] neg_lo:[1,0,0] neg_hi:[1,0,0]
	v_pk_fma_f32 v[146:147], v[70:71], v[214:215], v[146:147] op_sel:[0,1,0] neg_lo:[1,0,0] neg_hi:[1,0,0]
	v_pk_fma_f32 v[252:253], v[52:53], v[184:185], v[252:253] op_sel_hi:[1,0,1] neg_lo:[1,0,0] neg_hi:[1,0,0]
	ds_read_b128 v[182:185], v20 offset:51312
	v_pk_fma_f32 v[146:147], v[74:75], v[216:217], v[146:147] op_sel:[0,1,0] neg_lo:[1,0,0] neg_hi:[1,0,0]
	v_pk_fma_f32 v[252:253], v[56:57], v[208:209], v[252:253] op_sel_hi:[1,0,1] neg_lo:[1,0,0] neg_hi:[1,0,0]
	v_pk_fma_f32 v[146:147], v[78:79], v[218:219], v[146:147] op_sel:[0,1,0] neg_lo:[1,0,0] neg_hi:[1,0,0]
	v_pk_fma_f32 v[252:253], v[60:61], v[210:211], v[252:253] op_sel_hi:[1,0,1] neg_lo:[1,0,0] neg_hi:[1,0,0]
	ds_read_b128 v[208:211], v20 offset:51328
	s_waitcnt lgkmcnt(9)
	v_pk_fma_f32 v[146:147], v[82:83], v[220:221], v[146:147] op_sel:[0,1,0] neg_lo:[1,0,0] neg_hi:[1,0,0]
	v_pk_fma_f32 v[252:253], v[64:65], v[212:213], v[252:253] op_sel_hi:[1,0,1] neg_lo:[1,0,0] neg_hi:[1,0,0]
	v_pk_fma_f32 v[146:147], v[88:89], v[222:223], v[146:147] op_sel:[0,1,0] neg_lo:[1,0,0] neg_hi:[1,0,0]
	v_pk_fma_f32 v[252:253], v[68:69], v[214:215], v[252:253] op_sel_hi:[1,0,1] neg_lo:[1,0,0] neg_hi:[1,0,0]
	ds_read_b128 v[212:215], v20 offset:51344
	v_pk_fma_f32 v[252:253], v[72:73], v[216:217], v[252:253] op_sel_hi:[1,0,1] neg_lo:[1,0,0] neg_hi:[1,0,0]
	s_nop 0
	v_pk_fma_f32 v[252:253], v[76:77], v[218:219], v[252:253] op_sel_hi:[1,0,1] neg_lo:[1,0,0] neg_hi:[1,0,0]
	ds_read_b128 v[216:219], v20 offset:51360
	v_pk_fma_f32 v[252:253], v[80:81], v[220:221], v[252:253] op_sel_hi:[1,0,1] neg_lo:[1,0,0] neg_hi:[1,0,0]
	s_nop 0
	v_pk_fma_f32 v[252:253], v[222:223], v[86:87], v[252:253] op_sel_hi:[0,1,1] neg_lo:[1,0,0] neg_hi:[1,0,0]
	ds_read_b128 v[220:223], v20 offset:51376
	v_pk_add_f32 v[88:89], v[252:253], v[146:147]
	s_waitcnt lgkmcnt(11)
	v_pk_fma_f32 v[146:147], v[138:139], v[150:151], 0 op_sel:[0,1,0] op_sel_hi:[1,1,0] neg_lo:[1,0,0] neg_hi:[1,0,0]
	v_pk_mul_f32 v[150:151], v[128:129], v[150:151] op_sel_hi:[1,0]
	v_pk_fma_f32 v[146:147], v[134:135], v[152:153], v[146:147] op_sel:[0,1,0] neg_lo:[1,0,0] neg_hi:[1,0,0]
	v_pk_fma_f32 v[90:91], v[90:91], v[112:113], v[150:151] neg_lo:[0,0,1] neg_hi:[0,0,1]
	s_waitcnt lgkmcnt(10)
	v_pk_fma_f32 v[146:147], v[130:131], v[154:155], v[146:147] op_sel:[0,1,0] neg_lo:[1,0,0] neg_hi:[1,0,0]
	v_pk_fma_f32 v[90:91], v[136:137], v[152:153], v[90:91] op_sel_hi:[1,0,1] neg_lo:[1,0,0] neg_hi:[1,0,0]
	ds_read_b128 v[150:153], v20 offset:51456
	v_pk_fma_f32 v[90:91], v[132:133], v[154:155], v[90:91] op_sel_hi:[1,0,1] neg_lo:[1,0,0] neg_hi:[1,0,0]
	v_pk_fma_f32 v[146:147], v[84:85], v[156:157], v[146:147] op_sel:[0,1,0] neg_lo:[1,0,0] neg_hi:[1,0,0]
	v_pk_fma_f32 v[90:91], v[122:123], v[156:157], v[90:91] op_sel_hi:[1,0,1] neg_lo:[1,0,0] neg_hi:[1,0,0]
	ds_read_b128 v[154:157], v20 offset:51472
	s_waitcnt lgkmcnt(11)
	v_pk_fma_f32 v[146:147], v[10:11], v[158:159], v[146:147] op_sel:[0,1,0] neg_lo:[1,0,0] neg_hi:[1,0,0]
	v_pk_fma_f32 v[90:91], v[14:15], v[158:159], v[90:91] op_sel_hi:[1,0,1] neg_lo:[1,0,0] neg_hi:[1,0,0]
	v_pk_fma_f32 v[146:147], v[6:7], v[160:161], v[146:147] op_sel:[0,1,0] neg_lo:[1,0,0] neg_hi:[1,0,0]
	v_pk_fma_f32 v[90:91], v[16:17], v[160:161], v[90:91] op_sel_hi:[1,0,1] neg_lo:[1,0,0] neg_hi:[1,0,0]
	ds_read_b128 v[158:161], v20 offset:51488
	s_waitcnt lgkmcnt(11)
	v_pk_fma_f32 v[146:147], v[12:13], v[166:167], v[146:147] op_sel:[0,1,0] neg_lo:[1,0,0] neg_hi:[1,0,0]
	v_pk_fma_f32 v[90:91], v[18:19], v[166:167], v[90:91] op_sel_hi:[1,0,1] neg_lo:[1,0,0] neg_hi:[1,0,0]
	v_pk_fma_f32 v[146:147], v[4:5], v[168:169], v[146:147] op_sel:[0,1,0] neg_lo:[1,0,0] neg_hi:[1,0,0]
	v_pk_fma_f32 v[90:91], v[8:9], v[168:169], v[90:91] op_sel_hi:[1,0,1] neg_lo:[1,0,0] neg_hi:[1,0,0]
	ds_read_b128 v[166:169], v20 offset:51504
	s_waitcnt lgkmcnt(11)
	v_pk_fma_f32 v[146:147], v[0:1], v[170:171], v[146:147] op_sel:[0,1,0] neg_lo:[1,0,0] neg_hi:[1,0,0]
	v_pk_fma_f32 v[90:91], v[2:3], v[170:171], v[90:91] op_sel_hi:[1,0,1] neg_lo:[1,0,0] neg_hi:[1,0,0]
	v_pk_fma_f32 v[146:147], v[28:29], v[172:173], v[146:147] op_sel:[0,1,0] neg_lo:[1,0,0] neg_hi:[1,0,0]
	v_pk_fma_f32 v[90:91], v[30:31], v[172:173], v[90:91] op_sel_hi:[1,0,1] neg_lo:[1,0,0] neg_hi:[1,0,0]
	ds_read_b128 v[170:173], v20 offset:51520
	s_waitcnt lgkmcnt(11)
	v_pk_fma_f32 v[146:147], v[34:35], v[174:175], v[146:147] op_sel:[0,1,0] neg_lo:[1,0,0] neg_hi:[1,0,0]
	v_pk_fma_f32 v[90:91], v[32:33], v[174:175], v[90:91] op_sel_hi:[1,0,1] neg_lo:[1,0,0] neg_hi:[1,0,0]
	v_pk_fma_f32 v[146:147], v[40:41], v[176:177], v[146:147] op_sel:[0,1,0] neg_lo:[1,0,0] neg_hi:[1,0,0]
	v_pk_fma_f32 v[90:91], v[36:37], v[176:177], v[90:91] op_sel_hi:[1,0,1] neg_lo:[1,0,0] neg_hi:[1,0,0]
	ds_read_b128 v[174:177], v20 offset:51536
	s_waitcnt lgkmcnt(11)
	v_pk_fma_f32 v[146:147], v[42:43], v[178:179], v[146:147] op_sel:[0,1,0] neg_lo:[1,0,0] neg_hi:[1,0,0]
	v_pk_fma_f32 v[90:91], v[38:39], v[178:179], v[90:91] op_sel_hi:[1,0,1] neg_lo:[1,0,0] neg_hi:[1,0,0]
	v_pk_fma_f32 v[146:147], v[46:47], v[180:181], v[146:147] op_sel:[0,1,0] neg_lo:[1,0,0] neg_hi:[1,0,0]
	v_pk_fma_f32 v[90:91], v[44:45], v[180:181], v[90:91] op_sel_hi:[1,0,1] neg_lo:[1,0,0] neg_hi:[1,0,0]
	ds_read_b128 v[178:181], v20 offset:51552
	s_waitcnt lgkmcnt(11)
	v_pk_fma_f32 v[146:147], v[50:51], v[182:183], v[146:147] op_sel:[0,1,0] neg_lo:[1,0,0] neg_hi:[1,0,0]
	v_pk_fma_f32 v[90:91], v[48:49], v[182:183], v[90:91] op_sel_hi:[1,0,1] neg_lo:[1,0,0] neg_hi:[1,0,0]
	v_pk_fma_f32 v[146:147], v[54:55], v[184:185], v[146:147] op_sel:[0,1,0] neg_lo:[1,0,0] neg_hi:[1,0,0]
	v_pk_fma_f32 v[90:91], v[52:53], v[184:185], v[90:91] op_sel_hi:[1,0,1] neg_lo:[1,0,0] neg_hi:[1,0,0]
	ds_read_b128 v[182:185], v20 offset:51568
	s_waitcnt lgkmcnt(11)
	v_pk_fma_f32 v[146:147], v[58:59], v[208:209], v[146:147] op_sel:[0,1,0] neg_lo:[1,0,0] neg_hi:[1,0,0]
	v_pk_fma_f32 v[90:91], v[56:57], v[208:209], v[90:91] op_sel_hi:[1,0,1] neg_lo:[1,0,0] neg_hi:[1,0,0]
	v_pk_fma_f32 v[146:147], v[62:63], v[210:211], v[146:147] op_sel:[0,1,0] neg_lo:[1,0,0] neg_hi:[1,0,0]
	v_pk_fma_f32 v[90:91], v[60:61], v[210:211], v[90:91] op_sel_hi:[1,0,1] neg_lo:[1,0,0] neg_hi:[1,0,0]
	ds_read_b128 v[208:211], v20 offset:51584
	s_waitcnt lgkmcnt(11)
	v_pk_fma_f32 v[146:147], v[66:67], v[212:213], v[146:147] op_sel:[0,1,0] neg_lo:[1,0,0] neg_hi:[1,0,0]
	v_pk_fma_f32 v[90:91], v[64:65], v[212:213], v[90:91] op_sel_hi:[1,0,1] neg_lo:[1,0,0] neg_hi:[1,0,0]
	v_pk_fma_f32 v[146:147], v[70:71], v[214:215], v[146:147] op_sel:[0,1,0] neg_lo:[1,0,0] neg_hi:[1,0,0]
	v_pk_fma_f32 v[90:91], v[68:69], v[214:215], v[90:91] op_sel_hi:[1,0,1] neg_lo:[1,0,0] neg_hi:[1,0,0]
	ds_read_b128 v[212:215], v20 offset:51600
	s_waitcnt lgkmcnt(11)
	v_pk_fma_f32 v[146:147], v[74:75], v[216:217], v[146:147] op_sel:[0,1,0] neg_lo:[1,0,0] neg_hi:[1,0,0]
	v_pk_fma_f32 v[90:91], v[72:73], v[216:217], v[90:91] op_sel_hi:[1,0,1] neg_lo:[1,0,0] neg_hi:[1,0,0]
	v_pk_fma_f32 v[146:147], v[78:79], v[218:219], v[146:147] op_sel:[0,1,0] neg_lo:[1,0,0] neg_hi:[1,0,0]
	v_pk_fma_f32 v[90:91], v[76:77], v[218:219], v[90:91] op_sel_hi:[1,0,1] neg_lo:[1,0,0] neg_hi:[1,0,0]
	ds_read_b128 v[216:219], v20 offset:51616
	s_waitcnt lgkmcnt(11)
	v_pk_fma_f32 v[146:147], v[82:83], v[220:221], v[146:147] op_sel:[0,1,0] neg_lo:[1,0,0] neg_hi:[1,0,0]
	v_pk_fma_f32 v[90:91], v[80:81], v[220:221], v[90:91] op_sel_hi:[1,0,1] neg_lo:[1,0,0] neg_hi:[1,0,0]
	v_pk_fma_f32 v[146:147], v[222:223], v[88:89], v[146:147] op_sel:[1,0,0] neg_lo:[1,0,0] neg_hi:[1,0,0]
	v_pk_fma_f32 v[90:91], v[86:87], v[222:223], v[90:91] op_sel_hi:[1,0,1] neg_lo:[1,0,0] neg_hi:[1,0,0]
	ds_read_b128 v[220:223], v20 offset:51632
	v_pk_add_f32 v[90:91], v[90:91], v[146:147]
	s_waitcnt lgkmcnt(11)
	v_pk_fma_f32 v[112:113], v[138:139], v[150:151], 0 op_sel:[0,1,0] op_sel_hi:[1,1,0] neg_lo:[1,0,0] neg_hi:[1,0,0]
	v_pk_fma_f32 v[252:253], v[128:129], v[150:151], v[92:93] op_sel_hi:[1,0,1] neg_lo:[1,0,0] neg_hi:[1,0,0]
	v_pk_fma_f32 v[112:113], v[134:135], v[152:153], v[112:113] op_sel:[0,1,0] neg_lo:[1,0,0] neg_hi:[1,0,0]
	v_pk_fma_f32 v[252:253], v[136:137], v[152:153], v[252:253] op_sel_hi:[1,0,1] neg_lo:[1,0,0] neg_hi:[1,0,0]
	s_waitcnt lgkmcnt(10)
	v_pk_fma_f32 v[112:113], v[130:131], v[154:155], v[112:113] op_sel:[0,1,0] neg_lo:[1,0,0] neg_hi:[1,0,0]
	ds_read_b128 v[150:153], v20 offset:51712
	v_pk_fma_f32 v[112:113], v[84:85], v[156:157], v[112:113] op_sel:[0,1,0] neg_lo:[1,0,0] neg_hi:[1,0,0]
	v_pk_fma_f32 v[252:253], v[132:133], v[154:155], v[252:253] op_sel_hi:[1,0,1] neg_lo:[1,0,0] neg_hi:[1,0,0]
	s_waitcnt lgkmcnt(10)
	v_pk_fma_f32 v[112:113], v[10:11], v[158:159], v[112:113] op_sel:[0,1,0] neg_lo:[1,0,0] neg_hi:[1,0,0]
	v_pk_fma_f32 v[252:253], v[122:123], v[156:157], v[252:253] op_sel_hi:[1,0,1] neg_lo:[1,0,0] neg_hi:[1,0,0]
	v_pk_fma_f32 v[112:113], v[6:7], v[160:161], v[112:113] op_sel:[0,1,0] neg_lo:[1,0,0] neg_hi:[1,0,0]
	ds_read_b128 v[154:157], v20 offset:51728
	s_waitcnt lgkmcnt(10)
	v_pk_fma_f32 v[112:113], v[12:13], v[166:167], v[112:113] op_sel:[0,1,0] neg_lo:[1,0,0] neg_hi:[1,0,0]
	v_pk_fma_f32 v[252:253], v[14:15], v[158:159], v[252:253] op_sel_hi:[1,0,1] neg_lo:[1,0,0] neg_hi:[1,0,0]
	v_pk_fma_f32 v[112:113], v[4:5], v[168:169], v[112:113] op_sel:[0,1,0] neg_lo:[1,0,0] neg_hi:[1,0,0]
	v_pk_fma_f32 v[252:253], v[16:17], v[160:161], v[252:253] op_sel_hi:[1,0,1] neg_lo:[1,0,0] neg_hi:[1,0,0]
	s_waitcnt lgkmcnt(9)
	v_pk_fma_f32 v[112:113], v[0:1], v[170:171], v[112:113] op_sel:[0,1,0] neg_lo:[1,0,0] neg_hi:[1,0,0]
	ds_read_b128 v[158:161], v20 offset:51744
	v_pk_fma_f32 v[112:113], v[28:29], v[172:173], v[112:113] op_sel:[0,1,0] neg_lo:[1,0,0] neg_hi:[1,0,0]
	v_pk_fma_f32 v[252:253], v[18:19], v[166:167], v[252:253] op_sel_hi:[1,0,1] neg_lo:[1,0,0] neg_hi:[1,0,0]
	s_waitcnt lgkmcnt(9)
	v_pk_fma_f32 v[112:113], v[34:35], v[174:175], v[112:113] op_sel:[0,1,0] neg_lo:[1,0,0] neg_hi:[1,0,0]
	v_pk_fma_f32 v[252:253], v[8:9], v[168:169], v[252:253] op_sel_hi:[1,0,1] neg_lo:[1,0,0] neg_hi:[1,0,0]
	v_pk_fma_f32 v[112:113], v[40:41], v[176:177], v[112:113] op_sel:[0,1,0] neg_lo:[1,0,0] neg_hi:[1,0,0]
	ds_read_b128 v[166:169], v20 offset:51760
	s_waitcnt lgkmcnt(9)
	v_pk_fma_f32 v[112:113], v[42:43], v[178:179], v[112:113] op_sel:[0,1,0] neg_lo:[1,0,0] neg_hi:[1,0,0]
	v_pk_fma_f32 v[252:253], v[2:3], v[170:171], v[252:253] op_sel_hi:[1,0,1] neg_lo:[1,0,0] neg_hi:[1,0,0]
	v_pk_fma_f32 v[112:113], v[46:47], v[180:181], v[112:113] op_sel:[0,1,0] neg_lo:[1,0,0] neg_hi:[1,0,0]
	v_pk_fma_f32 v[252:253], v[30:31], v[172:173], v[252:253] op_sel_hi:[1,0,1] neg_lo:[1,0,0] neg_hi:[1,0,0]
	s_waitcnt lgkmcnt(8)
	v_pk_fma_f32 v[112:113], v[50:51], v[182:183], v[112:113] op_sel:[0,1,0] neg_lo:[1,0,0] neg_hi:[1,0,0]
	ds_read_b128 v[170:173], v20 offset:51776
	v_pk_fma_f32 v[112:113], v[54:55], v[184:185], v[112:113] op_sel:[0,1,0] neg_lo:[1,0,0] neg_hi:[1,0,0]
	v_pk_fma_f32 v[252:253], v[32:33], v[174:175], v[252:253] op_sel_hi:[1,0,1] neg_lo:[1,0,0] neg_hi:[1,0,0]
	s_waitcnt lgkmcnt(8)
	v_pk_fma_f32 v[112:113], v[58:59], v[208:209], v[112:113] op_sel:[0,1,0] neg_lo:[1,0,0] neg_hi:[1,0,0]
	v_pk_fma_f32 v[252:253], v[36:37], v[176:177], v[252:253] op_sel_hi:[1,0,1] neg_lo:[1,0,0] neg_hi:[1,0,0]
	ds_read_b128 v[174:177], v20 offset:51792
	v_pk_fma_f32 v[112:113], v[62:63], v[210:211], v[112:113] op_sel:[0,1,0] neg_lo:[1,0,0] neg_hi:[1,0,0]
	v_pk_fma_f32 v[252:253], v[38:39], v[178:179], v[252:253] op_sel_hi:[1,0,1] neg_lo:[1,0,0] neg_hi:[1,0,0]
	s_waitcnt lgkmcnt(8)
	v_pk_fma_f32 v[112:113], v[66:67], v[212:213], v[112:113] op_sel:[0,1,0] neg_lo:[1,0,0] neg_hi:[1,0,0]
	v_pk_fma_f32 v[252:253], v[44:45], v[180:181], v[252:253] op_sel_hi:[1,0,1] neg_lo:[1,0,0] neg_hi:[1,0,0]
	ds_read_b128 v[178:181], v20 offset:51808
	v_pk_fma_f32 v[112:113], v[70:71], v[214:215], v[112:113] op_sel:[0,1,0] neg_lo:[1,0,0] neg_hi:[1,0,0]
	v_pk_fma_f32 v[252:253], v[48:49], v[182:183], v[252:253] op_sel_hi:[1,0,1] neg_lo:[1,0,0] neg_hi:[1,0,0]
	s_waitcnt lgkmcnt(8)
	v_pk_fma_f32 v[112:113], v[74:75], v[216:217], v[112:113] op_sel:[0,1,0] neg_lo:[1,0,0] neg_hi:[1,0,0]
	v_pk_fma_f32 v[252:253], v[52:53], v[184:185], v[252:253] op_sel_hi:[1,0,1] neg_lo:[1,0,0] neg_hi:[1,0,0]
	ds_read_b128 v[182:185], v20 offset:51824
	v_pk_fma_f32 v[112:113], v[78:79], v[218:219], v[112:113] op_sel:[0,1,0] neg_lo:[1,0,0] neg_hi:[1,0,0]
	v_pk_fma_f32 v[252:253], v[56:57], v[208:209], v[252:253] op_sel_hi:[1,0,1] neg_lo:[1,0,0] neg_hi:[1,0,0]
	s_waitcnt lgkmcnt(8)
	v_pk_fma_f32 v[112:113], v[82:83], v[220:221], v[112:113] op_sel:[0,1,0] neg_lo:[1,0,0] neg_hi:[1,0,0]
	v_pk_fma_f32 v[252:253], v[60:61], v[210:211], v[252:253] op_sel_hi:[1,0,1] neg_lo:[1,0,0] neg_hi:[1,0,0]
	ds_read_b128 v[208:211], v20 offset:51840
	v_pk_fma_f32 v[112:113], v[88:89], v[222:223], v[112:113] op_sel:[0,1,0] neg_lo:[1,0,0] neg_hi:[1,0,0]
	v_pk_fma_f32 v[252:253], v[64:65], v[212:213], v[252:253] op_sel_hi:[1,0,1] neg_lo:[1,0,0] neg_hi:[1,0,0]
	v_pk_fma_f32 v[112:113], v[92:93], v[224:225], v[112:113] op_sel:[0,1,0] neg_lo:[1,0,0] neg_hi:[1,0,0]
	v_pk_fma_f32 v[252:253], v[68:69], v[214:215], v[252:253] op_sel_hi:[1,0,1] neg_lo:[1,0,0] neg_hi:[1,0,0]
	ds_read_b128 v[212:215], v20 offset:51856
	v_pk_fma_f32 v[112:113], v[96:97], v[226:227], v[112:113] op_sel:[0,1,0] neg_lo:[1,0,0] neg_hi:[1,0,0]
	v_pk_fma_f32 v[252:253], v[72:73], v[216:217], v[252:253] op_sel_hi:[1,0,1] neg_lo:[1,0,0] neg_hi:[1,0,0]
	s_waitcnt lgkmcnt(9)
	v_pk_fma_f32 v[146:147], v[128:129], v[150:151], v[94:95] op_sel_hi:[1,0,1] neg_lo:[1,0,0] neg_hi:[1,0,0]
	v_pk_fma_f32 v[252:253], v[76:77], v[218:219], v[252:253] op_sel_hi:[1,0,1] neg_lo:[1,0,0] neg_hi:[1,0,0]
	ds_read_b128 v[216:219], v20 offset:51872
	v_pk_fma_f32 v[252:253], v[80:81], v[220:221], v[252:253] op_sel_hi:[1,0,1] neg_lo:[1,0,0] neg_hi:[1,0,0]
	v_pk_fma_f32 v[146:147], v[136:137], v[152:153], v[146:147] op_sel_hi:[1,0,1] neg_lo:[1,0,0] neg_hi:[1,0,0]
	v_pk_fma_f32 v[252:253], v[86:87], v[222:223], v[252:253] op_sel_hi:[1,0,1] neg_lo:[1,0,0] neg_hi:[1,0,0]
	ds_read_b128 v[220:223], v20 offset:51888
	v_pk_fma_f32 v[252:253], v[224:225], v[90:91], v[252:253] op_sel_hi:[0,1,1] neg_lo:[1,0,0] neg_hi:[1,0,0]
	s_waitcnt lgkmcnt(10)
	v_pk_fma_f32 v[146:147], v[132:133], v[154:155], v[146:147] op_sel_hi:[1,0,1] neg_lo:[1,0,0] neg_hi:[1,0,0]
	v_pk_fma_f32 v[252:253], v[94:95], v[226:227], v[252:253] op_sel_hi:[1,0,1] neg_lo:[1,0,0] neg_hi:[1,0,0]
	ds_read_b128 v[224:227], v20 offset:51904
	v_pk_add_f32 v[92:93], v[252:253], v[112:113]
	v_pk_fma_f32 v[112:113], v[138:139], v[150:151], 0 op_sel:[0,1,0] op_sel_hi:[1,1,0] neg_lo:[1,0,0] neg_hi:[1,0,0]
	v_pk_fma_f32 v[146:147], v[122:123], v[156:157], v[146:147] op_sel_hi:[1,0,1] neg_lo:[1,0,0] neg_hi:[1,0,0]
	v_pk_fma_f32 v[112:113], v[134:135], v[152:153], v[112:113] op_sel:[0,1,0] neg_lo:[1,0,0] neg_hi:[1,0,0]
	ds_read_b128 v[150:153], v20 offset:51968
	v_pk_fma_f32 v[112:113], v[130:131], v[154:155], v[112:113] op_sel:[0,1,0] neg_lo:[1,0,0] neg_hi:[1,0,0]
	s_waitcnt lgkmcnt(11)
	v_pk_fma_f32 v[146:147], v[14:15], v[158:159], v[146:147] op_sel_hi:[1,0,1] neg_lo:[1,0,0] neg_hi:[1,0,0]
	v_pk_fma_f32 v[112:113], v[84:85], v[156:157], v[112:113] op_sel:[0,1,0] neg_lo:[1,0,0] neg_hi:[1,0,0]
	ds_read_b128 v[154:157], v20 offset:51984
	v_pk_fma_f32 v[112:113], v[10:11], v[158:159], v[112:113] op_sel:[0,1,0] neg_lo:[1,0,0] neg_hi:[1,0,0]
	v_pk_fma_f32 v[146:147], v[16:17], v[160:161], v[146:147] op_sel_hi:[1,0,1] neg_lo:[1,0,0] neg_hi:[1,0,0]
	v_pk_fma_f32 v[112:113], v[6:7], v[160:161], v[112:113] op_sel:[0,1,0] neg_lo:[1,0,0] neg_hi:[1,0,0]
	ds_read_b128 v[158:161], v20 offset:52000
	s_waitcnt lgkmcnt(12)
	v_pk_fma_f32 v[112:113], v[12:13], v[166:167], v[112:113] op_sel:[0,1,0] neg_lo:[1,0,0] neg_hi:[1,0,0]
	v_pk_fma_f32 v[146:147], v[18:19], v[166:167], v[146:147] op_sel_hi:[1,0,1] neg_lo:[1,0,0] neg_hi:[1,0,0]
	v_pk_fma_f32 v[112:113], v[4:5], v[168:169], v[112:113] op_sel:[0,1,0] neg_lo:[1,0,0] neg_hi:[1,0,0]
	v_pk_fma_f32 v[146:147], v[8:9], v[168:169], v[146:147] op_sel_hi:[1,0,1] neg_lo:[1,0,0] neg_hi:[1,0,0]
	s_waitcnt lgkmcnt(11)
	v_pk_fma_f32 v[112:113], v[0:1], v[170:171], v[112:113] op_sel:[0,1,0] neg_lo:[1,0,0] neg_hi:[1,0,0]
	ds_read_b128 v[166:169], v20 offset:52016
	v_pk_fma_f32 v[112:113], v[28:29], v[172:173], v[112:113] op_sel:[0,1,0] neg_lo:[1,0,0] neg_hi:[1,0,0]
	v_pk_fma_f32 v[146:147], v[2:3], v[170:171], v[146:147] op_sel_hi:[1,0,1] neg_lo:[1,0,0] neg_hi:[1,0,0]
	s_waitcnt lgkmcnt(11)
	v_pk_fma_f32 v[112:113], v[34:35], v[174:175], v[112:113] op_sel:[0,1,0] neg_lo:[1,0,0] neg_hi:[1,0,0]
	v_pk_fma_f32 v[146:147], v[30:31], v[172:173], v[146:147] op_sel_hi:[1,0,1] neg_lo:[1,0,0] neg_hi:[1,0,0]
	v_pk_fma_f32 v[112:113], v[40:41], v[176:177], v[112:113] op_sel:[0,1,0] neg_lo:[1,0,0] neg_hi:[1,0,0]
	ds_read_b128 v[170:173], v20 offset:52032
	s_waitcnt lgkmcnt(11)
	v_pk_fma_f32 v[112:113], v[42:43], v[178:179], v[112:113] op_sel:[0,1,0] neg_lo:[1,0,0] neg_hi:[1,0,0]
	v_pk_fma_f32 v[146:147], v[32:33], v[174:175], v[146:147] op_sel_hi:[1,0,1] neg_lo:[1,0,0] neg_hi:[1,0,0]
	v_pk_fma_f32 v[112:113], v[46:47], v[180:181], v[112:113] op_sel:[0,1,0] neg_lo:[1,0,0] neg_hi:[1,0,0]
	v_pk_fma_f32 v[146:147], v[36:37], v[176:177], v[146:147] op_sel_hi:[1,0,1] neg_lo:[1,0,0] neg_hi:[1,0,0]
	s_waitcnt lgkmcnt(10)
	v_pk_fma_f32 v[112:113], v[50:51], v[182:183], v[112:113] op_sel:[0,1,0] neg_lo:[1,0,0] neg_hi:[1,0,0]
	ds_read_b128 v[174:177], v20 offset:52048
	v_pk_fma_f32 v[112:113], v[54:55], v[184:185], v[112:113] op_sel:[0,1,0] neg_lo:[1,0,0] neg_hi:[1,0,0]
	v_pk_fma_f32 v[146:147], v[38:39], v[178:179], v[146:147] op_sel_hi:[1,0,1] neg_lo:[1,0,0] neg_hi:[1,0,0]
	s_waitcnt lgkmcnt(10)
	v_pk_fma_f32 v[112:113], v[58:59], v[208:209], v[112:113] op_sel:[0,1,0] neg_lo:[1,0,0] neg_hi:[1,0,0]
	v_pk_fma_f32 v[146:147], v[44:45], v[180:181], v[146:147] op_sel_hi:[1,0,1] neg_lo:[1,0,0] neg_hi:[1,0,0]
	ds_read_b128 v[178:181], v20 offset:52064
	v_pk_fma_f32 v[112:113], v[62:63], v[210:211], v[112:113] op_sel:[0,1,0] neg_lo:[1,0,0] neg_hi:[1,0,0]
	v_pk_fma_f32 v[146:147], v[48:49], v[182:183], v[146:147] op_sel_hi:[1,0,1] neg_lo:[1,0,0] neg_hi:[1,0,0]
	s_waitcnt lgkmcnt(10)
	v_pk_fma_f32 v[112:113], v[66:67], v[212:213], v[112:113] op_sel:[0,1,0] neg_lo:[1,0,0] neg_hi:[1,0,0]
	v_pk_fma_f32 v[146:147], v[52:53], v[184:185], v[146:147] op_sel_hi:[1,0,1] neg_lo:[1,0,0] neg_hi:[1,0,0]
	ds_read_b128 v[182:185], v20 offset:52080
	v_pk_fma_f32 v[112:113], v[70:71], v[214:215], v[112:113] op_sel:[0,1,0] neg_lo:[1,0,0] neg_hi:[1,0,0]
	v_pk_fma_f32 v[146:147], v[56:57], v[208:209], v[146:147] op_sel_hi:[1,0,1] neg_lo:[1,0,0] neg_hi:[1,0,0]
	s_waitcnt lgkmcnt(10)
	v_pk_fma_f32 v[112:113], v[74:75], v[216:217], v[112:113] op_sel:[0,1,0] neg_lo:[1,0,0] neg_hi:[1,0,0]
	v_pk_fma_f32 v[146:147], v[60:61], v[210:211], v[146:147] op_sel_hi:[1,0,1] neg_lo:[1,0,0] neg_hi:[1,0,0]
	ds_read_b128 v[208:211], v20 offset:52096
	v_pk_fma_f32 v[112:113], v[78:79], v[218:219], v[112:113] op_sel:[0,1,0] neg_lo:[1,0,0] neg_hi:[1,0,0]
	v_pk_fma_f32 v[146:147], v[64:65], v[212:213], v[146:147] op_sel_hi:[1,0,1] neg_lo:[1,0,0] neg_hi:[1,0,0]
	s_waitcnt lgkmcnt(10)
	v_pk_fma_f32 v[112:113], v[82:83], v[220:221], v[112:113] op_sel:[0,1,0] neg_lo:[1,0,0] neg_hi:[1,0,0]
	v_pk_fma_f32 v[146:147], v[68:69], v[214:215], v[146:147] op_sel_hi:[1,0,1] neg_lo:[1,0,0] neg_hi:[1,0,0]
	ds_read_b128 v[212:215], v20 offset:52112
	v_pk_fma_f32 v[112:113], v[88:89], v[222:223], v[112:113] op_sel:[0,1,0] neg_lo:[1,0,0] neg_hi:[1,0,0]
	v_pk_fma_f32 v[146:147], v[72:73], v[216:217], v[146:147] op_sel_hi:[1,0,1] neg_lo:[1,0,0] neg_hi:[1,0,0]
	s_waitcnt lgkmcnt(10)
	v_pk_fma_f32 v[112:113], v[224:225], v[92:93], v[112:113] op_sel:[1,0,0] neg_lo:[1,0,0] neg_hi:[1,0,0]
	v_pk_fma_f32 v[146:147], v[76:77], v[218:219], v[146:147] op_sel_hi:[1,0,1] neg_lo:[1,0,0] neg_hi:[1,0,0]
	ds_read_b128 v[216:219], v20 offset:52128
	v_pk_fma_f32 v[112:113], v[96:97], v[226:227], v[112:113] op_sel:[0,1,0] neg_lo:[1,0,0] neg_hi:[1,0,0]
	v_pk_fma_f32 v[146:147], v[80:81], v[220:221], v[146:147] op_sel_hi:[1,0,1] neg_lo:[1,0,0] neg_hi:[1,0,0]
	s_waitcnt lgkmcnt(10)
	v_pk_fma_f32 v[252:253], v[128:129], v[150:151], v[96:97] op_sel_hi:[1,0,1] neg_lo:[1,0,0] neg_hi:[1,0,0]
	v_pk_fma_f32 v[146:147], v[86:87], v[222:223], v[146:147] op_sel_hi:[1,0,1] neg_lo:[1,0,0] neg_hi:[1,0,0]
	ds_read_b128 v[220:223], v20 offset:52144
	v_pk_fma_f32 v[146:147], v[90:91], v[224:225], v[146:147] op_sel_hi:[1,0,1] neg_lo:[1,0,0] neg_hi:[1,0,0]
	v_pk_fma_f32 v[252:253], v[136:137], v[152:153], v[252:253] op_sel_hi:[1,0,1] neg_lo:[1,0,0] neg_hi:[1,0,0]
	v_pk_fma_f32 v[94:95], v[94:95], v[226:227], v[146:147] op_sel_hi:[1,0,1] neg_lo:[1,0,0] neg_hi:[1,0,0]
	ds_read_b128 v[224:227], v20 offset:52160
	v_pk_add_f32 v[94:95], v[94:95], v[112:113]
	v_pk_fma_f32 v[112:113], v[138:139], v[150:151], 0 op_sel:[0,1,0] op_sel_hi:[1,1,0] neg_lo:[1,0,0] neg_hi:[1,0,0]
	s_waitcnt lgkmcnt(11)
	v_pk_fma_f32 v[252:253], v[132:133], v[154:155], v[252:253] op_sel_hi:[1,0,1] neg_lo:[1,0,0] neg_hi:[1,0,0]
	v_pk_fma_f32 v[112:113], v[134:135], v[152:153], v[112:113] op_sel:[0,1,0] neg_lo:[1,0,0] neg_hi:[1,0,0]
	ds_read_b128 v[150:153], v20 offset:52224
	v_pk_fma_f32 v[112:113], v[130:131], v[154:155], v[112:113] op_sel:[0,1,0] neg_lo:[1,0,0] neg_hi:[1,0,0]
	v_pk_fma_f32 v[252:253], v[122:123], v[156:157], v[252:253] op_sel_hi:[1,0,1] neg_lo:[1,0,0] neg_hi:[1,0,0]
	v_pk_fma_f32 v[112:113], v[84:85], v[156:157], v[112:113] op_sel:[0,1,0] neg_lo:[1,0,0] neg_hi:[1,0,0]
	ds_read_b128 v[154:157], v20 offset:52240
	s_waitcnt lgkmcnt(12)
	v_pk_fma_f32 v[112:113], v[10:11], v[158:159], v[112:113] op_sel:[0,1,0] neg_lo:[1,0,0] neg_hi:[1,0,0]
	v_pk_fma_f32 v[252:253], v[14:15], v[158:159], v[252:253] op_sel_hi:[1,0,1] neg_lo:[1,0,0] neg_hi:[1,0,0]
	v_pk_fma_f32 v[112:113], v[6:7], v[160:161], v[112:113] op_sel:[0,1,0] neg_lo:[1,0,0] neg_hi:[1,0,0]
	v_pk_fma_f32 v[252:253], v[16:17], v[160:161], v[252:253] op_sel_hi:[1,0,1] neg_lo:[1,0,0] neg_hi:[1,0,0]
	s_waitcnt lgkmcnt(11)
	v_pk_fma_f32 v[112:113], v[12:13], v[166:167], v[112:113] op_sel:[0,1,0] neg_lo:[1,0,0] neg_hi:[1,0,0]
	ds_read_b128 v[158:161], v20 offset:52256
	v_pk_fma_f32 v[112:113], v[4:5], v[168:169], v[112:113] op_sel:[0,1,0] neg_lo:[1,0,0] neg_hi:[1,0,0]
	v_pk_fma_f32 v[252:253], v[18:19], v[166:167], v[252:253] op_sel_hi:[1,0,1] neg_lo:[1,0,0] neg_hi:[1,0,0]
	s_waitcnt lgkmcnt(11)
	v_pk_fma_f32 v[112:113], v[0:1], v[170:171], v[112:113] op_sel:[0,1,0] neg_lo:[1,0,0] neg_hi:[1,0,0]
	v_pk_fma_f32 v[252:253], v[8:9], v[168:169], v[252:253] op_sel_hi:[1,0,1] neg_lo:[1,0,0] neg_hi:[1,0,0]
	v_pk_fma_f32 v[112:113], v[28:29], v[172:173], v[112:113] op_sel:[0,1,0] neg_lo:[1,0,0] neg_hi:[1,0,0]
	ds_read_b128 v[166:169], v20 offset:52272
	s_waitcnt lgkmcnt(11)
	v_pk_fma_f32 v[112:113], v[34:35], v[174:175], v[112:113] op_sel:[0,1,0] neg_lo:[1,0,0] neg_hi:[1,0,0]
	v_pk_fma_f32 v[252:253], v[2:3], v[170:171], v[252:253] op_sel_hi:[1,0,1] neg_lo:[1,0,0] neg_hi:[1,0,0]
	v_pk_fma_f32 v[112:113], v[40:41], v[176:177], v[112:113] op_sel:[0,1,0] neg_lo:[1,0,0] neg_hi:[1,0,0]
	v_pk_fma_f32 v[252:253], v[30:31], v[172:173], v[252:253] op_sel_hi:[1,0,1] neg_lo:[1,0,0] neg_hi:[1,0,0]
	s_waitcnt lgkmcnt(10)
	v_pk_fma_f32 v[112:113], v[42:43], v[178:179], v[112:113] op_sel:[0,1,0] neg_lo:[1,0,0] neg_hi:[1,0,0]
	ds_read_b128 v[170:173], v20 offset:52288
	v_pk_fma_f32 v[112:113], v[46:47], v[180:181], v[112:113] op_sel:[0,1,0] neg_lo:[1,0,0] neg_hi:[1,0,0]
	v_pk_fma_f32 v[252:253], v[32:33], v[174:175], v[252:253] op_sel_hi:[1,0,1] neg_lo:[1,0,0] neg_hi:[1,0,0]
	s_waitcnt lgkmcnt(10)
	v_pk_fma_f32 v[112:113], v[50:51], v[182:183], v[112:113] op_sel:[0,1,0] neg_lo:[1,0,0] neg_hi:[1,0,0]
	v_pk_fma_f32 v[252:253], v[36:37], v[176:177], v[252:253] op_sel_hi:[1,0,1] neg_lo:[1,0,0] neg_hi:[1,0,0]
	v_pk_fma_f32 v[112:113], v[54:55], v[184:185], v[112:113] op_sel:[0,1,0] neg_lo:[1,0,0] neg_hi:[1,0,0]
	ds_read_b128 v[174:177], v20 offset:52304
	s_waitcnt lgkmcnt(10)
	v_pk_fma_f32 v[112:113], v[58:59], v[208:209], v[112:113] op_sel:[0,1,0] neg_lo:[1,0,0] neg_hi:[1,0,0]
	v_pk_fma_f32 v[252:253], v[38:39], v[178:179], v[252:253] op_sel_hi:[1,0,1] neg_lo:[1,0,0] neg_hi:[1,0,0]
	v_pk_fma_f32 v[112:113], v[62:63], v[210:211], v[112:113] op_sel:[0,1,0] neg_lo:[1,0,0] neg_hi:[1,0,0]
	v_pk_fma_f32 v[252:253], v[44:45], v[180:181], v[252:253] op_sel_hi:[1,0,1] neg_lo:[1,0,0] neg_hi:[1,0,0]
	ds_read_b128 v[178:181], v20 offset:52320
	s_waitcnt lgkmcnt(10)
	v_pk_fma_f32 v[112:113], v[66:67], v[212:213], v[112:113] op_sel:[0,1,0] neg_lo:[1,0,0] neg_hi:[1,0,0]
	v_pk_fma_f32 v[252:253], v[48:49], v[182:183], v[252:253] op_sel_hi:[1,0,1] neg_lo:[1,0,0] neg_hi:[1,0,0]
	v_pk_fma_f32 v[112:113], v[70:71], v[214:215], v[112:113] op_sel:[0,1,0] neg_lo:[1,0,0] neg_hi:[1,0,0]
	v_pk_fma_f32 v[252:253], v[52:53], v[184:185], v[252:253] op_sel_hi:[1,0,1] neg_lo:[1,0,0] neg_hi:[1,0,0]
	ds_read_b128 v[182:185], v20 offset:52336
	s_waitcnt lgkmcnt(10)
	v_pk_fma_f32 v[112:113], v[74:75], v[216:217], v[112:113] op_sel:[0,1,0] neg_lo:[1,0,0] neg_hi:[1,0,0]
	v_pk_fma_f32 v[252:253], v[56:57], v[208:209], v[252:253] op_sel_hi:[1,0,1] neg_lo:[1,0,0] neg_hi:[1,0,0]
	v_pk_fma_f32 v[112:113], v[78:79], v[218:219], v[112:113] op_sel:[0,1,0] neg_lo:[1,0,0] neg_hi:[1,0,0]
	v_pk_fma_f32 v[252:253], v[60:61], v[210:211], v[252:253] op_sel_hi:[1,0,1] neg_lo:[1,0,0] neg_hi:[1,0,0]
	ds_read_b128 v[208:211], v20 offset:52352
	s_waitcnt lgkmcnt(10)
	v_pk_fma_f32 v[112:113], v[82:83], v[220:221], v[112:113] op_sel:[0,1,0] neg_lo:[1,0,0] neg_hi:[1,0,0]
	v_pk_fma_f32 v[252:253], v[64:65], v[212:213], v[252:253] op_sel_hi:[1,0,1] neg_lo:[1,0,0] neg_hi:[1,0,0]
	v_pk_fma_f32 v[112:113], v[88:89], v[222:223], v[112:113] op_sel:[0,1,0] neg_lo:[1,0,0] neg_hi:[1,0,0]
	v_pk_fma_f32 v[252:253], v[68:69], v[214:215], v[252:253] op_sel_hi:[1,0,1] neg_lo:[1,0,0] neg_hi:[1,0,0]
	ds_read_b128 v[212:215], v20 offset:52368
	s_waitcnt lgkmcnt(10)
	v_pk_fma_f32 v[112:113], v[92:93], v[224:225], v[112:113] op_sel:[0,1,0] neg_lo:[1,0,0] neg_hi:[1,0,0]
	v_pk_fma_f32 v[252:253], v[72:73], v[216:217], v[252:253] op_sel_hi:[1,0,1] neg_lo:[1,0,0] neg_hi:[1,0,0]
	v_pk_fma_f32 v[112:113], v[96:97], v[226:227], v[112:113] op_sel:[0,1,0] neg_lo:[1,0,0] neg_hi:[1,0,0]
	v_pk_fma_f32 v[252:253], v[76:77], v[218:219], v[252:253] op_sel_hi:[1,0,1] neg_lo:[1,0,0] neg_hi:[1,0,0]
	ds_read_b128 v[216:219], v20 offset:52384
	v_pk_fma_f32 v[252:253], v[80:81], v[220:221], v[252:253] op_sel_hi:[1,0,1] neg_lo:[1,0,0] neg_hi:[1,0,0]
	s_waitcnt lgkmcnt(10)
	v_pk_mul_f32 v[146:147], v[128:129], v[150:151] op_sel_hi:[1,0]
	v_pk_fma_f32 v[252:253], v[86:87], v[222:223], v[252:253] op_sel_hi:[1,0,1] neg_lo:[1,0,0] neg_hi:[1,0,0]
	ds_read_b128 v[220:223], v20 offset:52400
	v_pk_fma_f32 v[252:253], v[90:91], v[224:225], v[252:253] op_sel_hi:[1,0,1] neg_lo:[1,0,0] neg_hi:[1,0,0]
	v_pk_fma_f32 v[98:99], v[98:99], v[110:111], v[146:147] neg_lo:[0,0,1] neg_hi:[0,0,1]
	v_pk_fma_f32 v[252:253], v[226:227], v[94:95], v[252:253] op_sel_hi:[0,1,1] neg_lo:[1,0,0] neg_hi:[1,0,0]
	ds_read_b128 v[224:227], v20 offset:52416
	v_pk_add_f32 v[96:97], v[252:253], v[112:113]
	v_pk_fma_f32 v[112:113], v[138:139], v[150:151], 0 op_sel:[0,1,0] op_sel_hi:[1,1,0] neg_lo:[1,0,0] neg_hi:[1,0,0]
	v_pk_fma_f32 v[98:99], v[136:137], v[152:153], v[98:99] op_sel_hi:[1,0,1] neg_lo:[1,0,0] neg_hi:[1,0,0]
	v_pk_fma_f32 v[112:113], v[134:135], v[152:153], v[112:113] op_sel:[0,1,0] neg_lo:[1,0,0] neg_hi:[1,0,0]
	ds_read_b128 v[150:153], v20 offset:52496
	s_waitcnt lgkmcnt(12)
	v_pk_fma_f32 v[112:113], v[130:131], v[154:155], v[112:113] op_sel:[0,1,0] neg_lo:[1,0,0] neg_hi:[1,0,0]
	v_pk_fma_f32 v[98:99], v[132:133], v[154:155], v[98:99] op_sel_hi:[1,0,1] neg_lo:[1,0,0] neg_hi:[1,0,0]
	v_pk_fma_f32 v[112:113], v[84:85], v[156:157], v[112:113] op_sel:[0,1,0] neg_lo:[1,0,0] neg_hi:[1,0,0]
	v_pk_fma_f32 v[98:99], v[122:123], v[156:157], v[98:99] op_sel_hi:[1,0,1] neg_lo:[1,0,0] neg_hi:[1,0,0]
	s_waitcnt lgkmcnt(11)
	v_pk_fma_f32 v[112:113], v[10:11], v[158:159], v[112:113] op_sel:[0,1,0] neg_lo:[1,0,0] neg_hi:[1,0,0]
	ds_read_b128 v[154:157], v20 offset:52512
	v_pk_fma_f32 v[112:113], v[6:7], v[160:161], v[112:113] op_sel:[0,1,0] neg_lo:[1,0,0] neg_hi:[1,0,0]
	v_pk_fma_f32 v[98:99], v[14:15], v[158:159], v[98:99] op_sel_hi:[1,0,1] neg_lo:[1,0,0] neg_hi:[1,0,0]
	s_waitcnt lgkmcnt(11)
	v_pk_fma_f32 v[112:113], v[12:13], v[166:167], v[112:113] op_sel:[0,1,0] neg_lo:[1,0,0] neg_hi:[1,0,0]
	v_pk_fma_f32 v[98:99], v[16:17], v[160:161], v[98:99] op_sel_hi:[1,0,1] neg_lo:[1,0,0] neg_hi:[1,0,0]
	v_pk_fma_f32 v[112:113], v[4:5], v[168:169], v[112:113] op_sel:[0,1,0] neg_lo:[1,0,0] neg_hi:[1,0,0]
	ds_read_b128 v[158:161], v20 offset:52528
	s_waitcnt lgkmcnt(11)
	v_pk_fma_f32 v[112:113], v[0:1], v[170:171], v[112:113] op_sel:[0,1,0] neg_lo:[1,0,0] neg_hi:[1,0,0]
	v_pk_fma_f32 v[98:99], v[18:19], v[166:167], v[98:99] op_sel_hi:[1,0,1] neg_lo:[1,0,0] neg_hi:[1,0,0]
	v_pk_fma_f32 v[112:113], v[28:29], v[172:173], v[112:113] op_sel:[0,1,0] neg_lo:[1,0,0] neg_hi:[1,0,0]
	v_pk_fma_f32 v[98:99], v[8:9], v[168:169], v[98:99] op_sel_hi:[1,0,1] neg_lo:[1,0,0] neg_hi:[1,0,0]
	s_waitcnt lgkmcnt(10)
	v_pk_fma_f32 v[112:113], v[34:35], v[174:175], v[112:113] op_sel:[0,1,0] neg_lo:[1,0,0] neg_hi:[1,0,0]
	ds_read_b128 v[166:169], v20 offset:52544
	v_pk_fma_f32 v[112:113], v[40:41], v[176:177], v[112:113] op_sel:[0,1,0] neg_lo:[1,0,0] neg_hi:[1,0,0]
	v_pk_fma_f32 v[98:99], v[2:3], v[170:171], v[98:99] op_sel_hi:[1,0,1] neg_lo:[1,0,0] neg_hi:[1,0,0]
	s_waitcnt lgkmcnt(10)
	v_pk_fma_f32 v[112:113], v[42:43], v[178:179], v[112:113] op_sel:[0,1,0] neg_lo:[1,0,0] neg_hi:[1,0,0]
	v_pk_fma_f32 v[98:99], v[30:31], v[172:173], v[98:99] op_sel_hi:[1,0,1] neg_lo:[1,0,0] neg_hi:[1,0,0]
	v_pk_fma_f32 v[112:113], v[46:47], v[180:181], v[112:113] op_sel:[0,1,0] neg_lo:[1,0,0] neg_hi:[1,0,0]
	ds_read_b128 v[170:173], v20 offset:52560
	s_waitcnt lgkmcnt(10)
	v_pk_fma_f32 v[112:113], v[50:51], v[182:183], v[112:113] op_sel:[0,1,0] neg_lo:[1,0,0] neg_hi:[1,0,0]
	v_pk_fma_f32 v[98:99], v[32:33], v[174:175], v[98:99] op_sel_hi:[1,0,1] neg_lo:[1,0,0] neg_hi:[1,0,0]
	v_pk_fma_f32 v[112:113], v[54:55], v[184:185], v[112:113] op_sel:[0,1,0] neg_lo:[1,0,0] neg_hi:[1,0,0]
	v_pk_fma_f32 v[98:99], v[36:37], v[176:177], v[98:99] op_sel_hi:[1,0,1] neg_lo:[1,0,0] neg_hi:[1,0,0]
	s_waitcnt lgkmcnt(9)
	v_pk_fma_f32 v[112:113], v[58:59], v[208:209], v[112:113] op_sel:[0,1,0] neg_lo:[1,0,0] neg_hi:[1,0,0]
	ds_read_b128 v[174:177], v20 offset:52576
	v_pk_fma_f32 v[112:113], v[62:63], v[210:211], v[112:113] op_sel:[0,1,0] neg_lo:[1,0,0] neg_hi:[1,0,0]
	v_pk_fma_f32 v[98:99], v[38:39], v[178:179], v[98:99] op_sel_hi:[1,0,1] neg_lo:[1,0,0] neg_hi:[1,0,0]
	s_waitcnt lgkmcnt(9)
	v_pk_fma_f32 v[112:113], v[66:67], v[212:213], v[112:113] op_sel:[0,1,0] neg_lo:[1,0,0] neg_hi:[1,0,0]
	v_pk_fma_f32 v[98:99], v[44:45], v[180:181], v[98:99] op_sel_hi:[1,0,1] neg_lo:[1,0,0] neg_hi:[1,0,0]
	ds_read_b128 v[178:181], v20 offset:52592
	v_pk_fma_f32 v[112:113], v[70:71], v[214:215], v[112:113] op_sel:[0,1,0] neg_lo:[1,0,0] neg_hi:[1,0,0]
	v_pk_fma_f32 v[98:99], v[48:49], v[182:183], v[98:99] op_sel_hi:[1,0,1] neg_lo:[1,0,0] neg_hi:[1,0,0]
	s_waitcnt lgkmcnt(9)
	v_pk_fma_f32 v[112:113], v[74:75], v[216:217], v[112:113] op_sel:[0,1,0] neg_lo:[1,0,0] neg_hi:[1,0,0]
	v_pk_fma_f32 v[98:99], v[52:53], v[184:185], v[98:99] op_sel_hi:[1,0,1] neg_lo:[1,0,0] neg_hi:[1,0,0]
	ds_read_b128 v[182:185], v20 offset:52608
	v_pk_fma_f32 v[112:113], v[78:79], v[218:219], v[112:113] op_sel:[0,1,0] neg_lo:[1,0,0] neg_hi:[1,0,0]
	v_pk_fma_f32 v[98:99], v[56:57], v[208:209], v[98:99] op_sel_hi:[1,0,1] neg_lo:[1,0,0] neg_hi:[1,0,0]
	s_waitcnt lgkmcnt(9)
	v_pk_fma_f32 v[112:113], v[82:83], v[220:221], v[112:113] op_sel:[0,1,0] neg_lo:[1,0,0] neg_hi:[1,0,0]
	v_pk_fma_f32 v[98:99], v[60:61], v[210:211], v[98:99] op_sel_hi:[1,0,1] neg_lo:[1,0,0] neg_hi:[1,0,0]
	ds_read_b128 v[208:211], v20 offset:52624
	v_pk_fma_f32 v[112:113], v[88:89], v[222:223], v[112:113] op_sel:[0,1,0] neg_lo:[1,0,0] neg_hi:[1,0,0]
	v_pk_fma_f32 v[98:99], v[64:65], v[212:213], v[98:99] op_sel_hi:[1,0,1] neg_lo:[1,0,0] neg_hi:[1,0,0]
	s_waitcnt lgkmcnt(9)
	v_pk_fma_f32 v[112:113], v[92:93], v[224:225], v[112:113] op_sel:[0,1,0] neg_lo:[1,0,0] neg_hi:[1,0,0]
	v_pk_fma_f32 v[98:99], v[68:69], v[214:215], v[98:99] op_sel_hi:[1,0,1] neg_lo:[1,0,0] neg_hi:[1,0,0]
	ds_read_b128 v[212:215], v20 offset:52640
	v_pk_fma_f32 v[112:113], v[226:227], v[96:97], v[112:113] op_sel:[1,0,0] neg_lo:[1,0,0] neg_hi:[1,0,0]
	v_pk_fma_f32 v[98:99], v[72:73], v[216:217], v[98:99] op_sel_hi:[1,0,1] neg_lo:[1,0,0] neg_hi:[1,0,0]
	s_nop 0
	v_pk_fma_f32 v[98:99], v[76:77], v[218:219], v[98:99] op_sel_hi:[1,0,1] neg_lo:[1,0,0] neg_hi:[1,0,0]
	ds_read_b128 v[216:219], v20 offset:52656
	v_pk_fma_f32 v[98:99], v[80:81], v[220:221], v[98:99] op_sel_hi:[1,0,1] neg_lo:[1,0,0] neg_hi:[1,0,0]
	s_nop 0
	v_pk_fma_f32 v[98:99], v[86:87], v[222:223], v[98:99] op_sel_hi:[1,0,1] neg_lo:[1,0,0] neg_hi:[1,0,0]
	ds_read_b128 v[220:223], v20 offset:52672
	v_pk_fma_f32 v[98:99], v[90:91], v[224:225], v[98:99] op_sel_hi:[1,0,1] neg_lo:[1,0,0] neg_hi:[1,0,0]
	s_nop 0
	v_pk_fma_f32 v[98:99], v[94:95], v[226:227], v[98:99] op_sel_hi:[1,0,1] neg_lo:[1,0,0] neg_hi:[1,0,0]
	ds_read_b128 v[224:227], v20 offset:52688
	v_pk_add_f32 v[98:99], v[98:99], v[112:113]
	ds_read_b128 v[110:113], v20 offset:52480
	s_waitcnt lgkmcnt(0)
	v_pk_fma_f32 v[146:147], v[138:139], v[110:111], 0 op_sel:[0,1,0] op_sel_hi:[1,1,0] neg_lo:[1,0,0] neg_hi:[1,0,0]
	v_pk_fma_f32 v[252:253], v[128:129], v[110:111], v[100:101] op_sel_hi:[1,0,1] neg_lo:[1,0,0] neg_hi:[1,0,0]
	v_pk_fma_f32 v[146:147], v[134:135], v[112:113], v[146:147] op_sel:[0,1,0] neg_lo:[1,0,0] neg_hi:[1,0,0]
	v_pk_fma_f32 v[252:253], v[136:137], v[112:113], v[252:253] op_sel_hi:[1,0,1] neg_lo:[1,0,0] neg_hi:[1,0,0]
	v_pk_fma_f32 v[146:147], v[130:131], v[150:151], v[146:147] op_sel:[0,1,0] neg_lo:[1,0,0] neg_hi:[1,0,0]
	ds_read_b128 v[110:113], v20 offset:52736
	v_pk_fma_f32 v[146:147], v[84:85], v[152:153], v[146:147] op_sel:[0,1,0] neg_lo:[1,0,0] neg_hi:[1,0,0]
	v_pk_fma_f32 v[252:253], v[132:133], v[150:151], v[252:253] op_sel_hi:[1,0,1] neg_lo:[1,0,0] neg_hi:[1,0,0]
	v_pk_fma_f32 v[146:147], v[10:11], v[154:155], v[146:147] op_sel:[0,1,0] neg_lo:[1,0,0] neg_hi:[1,0,0]
	v_pk_fma_f32 v[252:253], v[122:123], v[152:153], v[252:253] op_sel_hi:[1,0,1] neg_lo:[1,0,0] neg_hi:[1,0,0]
	v_pk_fma_f32 v[146:147], v[6:7], v[156:157], v[146:147] op_sel:[0,1,0] neg_lo:[1,0,0] neg_hi:[1,0,0]
	ds_read_b128 v[150:153], v20 offset:52752
	v_pk_fma_f32 v[146:147], v[12:13], v[158:159], v[146:147] op_sel:[0,1,0] neg_lo:[1,0,0] neg_hi:[1,0,0]
	v_pk_fma_f32 v[252:253], v[14:15], v[154:155], v[252:253] op_sel_hi:[1,0,1] neg_lo:[1,0,0] neg_hi:[1,0,0]
	v_pk_fma_f32 v[146:147], v[4:5], v[160:161], v[146:147] op_sel:[0,1,0] neg_lo:[1,0,0] neg_hi:[1,0,0]
	v_pk_fma_f32 v[252:253], v[16:17], v[156:157], v[252:253] op_sel_hi:[1,0,1] neg_lo:[1,0,0] neg_hi:[1,0,0]
	v_pk_fma_f32 v[146:147], v[0:1], v[166:167], v[146:147] op_sel:[0,1,0] neg_lo:[1,0,0] neg_hi:[1,0,0]
	ds_read_b128 v[154:157], v20 offset:52768
	v_pk_fma_f32 v[146:147], v[28:29], v[168:169], v[146:147] op_sel:[0,1,0] neg_lo:[1,0,0] neg_hi:[1,0,0]
	v_pk_fma_f32 v[252:253], v[18:19], v[158:159], v[252:253] op_sel_hi:[1,0,1] neg_lo:[1,0,0] neg_hi:[1,0,0]
	v_pk_fma_f32 v[146:147], v[34:35], v[170:171], v[146:147] op_sel:[0,1,0] neg_lo:[1,0,0] neg_hi:[1,0,0]
	v_pk_fma_f32 v[252:253], v[8:9], v[160:161], v[252:253] op_sel_hi:[1,0,1] neg_lo:[1,0,0] neg_hi:[1,0,0]
	v_pk_fma_f32 v[146:147], v[40:41], v[172:173], v[146:147] op_sel:[0,1,0] neg_lo:[1,0,0] neg_hi:[1,0,0]
	ds_read_b128 v[158:161], v20 offset:52784
	v_pk_fma_f32 v[146:147], v[42:43], v[174:175], v[146:147] op_sel:[0,1,0] neg_lo:[1,0,0] neg_hi:[1,0,0]
	v_pk_fma_f32 v[252:253], v[2:3], v[166:167], v[252:253] op_sel_hi:[1,0,1] neg_lo:[1,0,0] neg_hi:[1,0,0]
	v_pk_fma_f32 v[146:147], v[46:47], v[176:177], v[146:147] op_sel:[0,1,0] neg_lo:[1,0,0] neg_hi:[1,0,0]
	v_pk_fma_f32 v[252:253], v[30:31], v[168:169], v[252:253] op_sel_hi:[1,0,1] neg_lo:[1,0,0] neg_hi:[1,0,0]
	v_pk_fma_f32 v[146:147], v[50:51], v[178:179], v[146:147] op_sel:[0,1,0] neg_lo:[1,0,0] neg_hi:[1,0,0]
	ds_read_b128 v[166:169], v20 offset:52800
	v_pk_fma_f32 v[146:147], v[54:55], v[180:181], v[146:147] op_sel:[0,1,0] neg_lo:[1,0,0] neg_hi:[1,0,0]
	v_pk_fma_f32 v[252:253], v[32:33], v[170:171], v[252:253] op_sel_hi:[1,0,1] neg_lo:[1,0,0] neg_hi:[1,0,0]
	v_pk_fma_f32 v[146:147], v[58:59], v[182:183], v[146:147] op_sel:[0,1,0] neg_lo:[1,0,0] neg_hi:[1,0,0]
	v_pk_fma_f32 v[252:253], v[36:37], v[172:173], v[252:253] op_sel_hi:[1,0,1] neg_lo:[1,0,0] neg_hi:[1,0,0]
	v_pk_fma_f32 v[146:147], v[62:63], v[184:185], v[146:147] op_sel:[0,1,0] neg_lo:[1,0,0] neg_hi:[1,0,0]
	ds_read_b128 v[170:173], v20 offset:52816
	v_pk_fma_f32 v[146:147], v[66:67], v[208:209], v[146:147] op_sel:[0,1,0] neg_lo:[1,0,0] neg_hi:[1,0,0]
	v_pk_fma_f32 v[252:253], v[38:39], v[174:175], v[252:253] op_sel_hi:[1,0,1] neg_lo:[1,0,0] neg_hi:[1,0,0]
	v_pk_fma_f32 v[146:147], v[70:71], v[210:211], v[146:147] op_sel:[0,1,0] neg_lo:[1,0,0] neg_hi:[1,0,0]
	v_pk_fma_f32 v[252:253], v[44:45], v[176:177], v[252:253] op_sel_hi:[1,0,1] neg_lo:[1,0,0] neg_hi:[1,0,0]
	ds_read_b128 v[174:177], v20 offset:52832
	v_pk_fma_f32 v[146:147], v[74:75], v[212:213], v[146:147] op_sel:[0,1,0] neg_lo:[1,0,0] neg_hi:[1,0,0]
	v_pk_fma_f32 v[252:253], v[48:49], v[178:179], v[252:253] op_sel_hi:[1,0,1] neg_lo:[1,0,0] neg_hi:[1,0,0]
	v_pk_fma_f32 v[146:147], v[78:79], v[214:215], v[146:147] op_sel:[0,1,0] neg_lo:[1,0,0] neg_hi:[1,0,0]
	v_pk_fma_f32 v[252:253], v[52:53], v[180:181], v[252:253] op_sel_hi:[1,0,1] neg_lo:[1,0,0] neg_hi:[1,0,0]
	ds_read_b128 v[178:181], v20 offset:52848
	v_pk_fma_f32 v[146:147], v[82:83], v[216:217], v[146:147] op_sel:[0,1,0] neg_lo:[1,0,0] neg_hi:[1,0,0]
	v_pk_fma_f32 v[252:253], v[56:57], v[182:183], v[252:253] op_sel_hi:[1,0,1] neg_lo:[1,0,0] neg_hi:[1,0,0]
	v_pk_fma_f32 v[146:147], v[88:89], v[218:219], v[146:147] op_sel:[0,1,0] neg_lo:[1,0,0] neg_hi:[1,0,0]
	v_pk_fma_f32 v[252:253], v[60:61], v[184:185], v[252:253] op_sel_hi:[1,0,1] neg_lo:[1,0,0] neg_hi:[1,0,0]
	ds_read_b128 v[182:185], v20 offset:52864
	v_pk_fma_f32 v[146:147], v[92:93], v[220:221], v[146:147] op_sel:[0,1,0] neg_lo:[1,0,0] neg_hi:[1,0,0]
	v_pk_fma_f32 v[252:253], v[64:65], v[208:209], v[252:253] op_sel_hi:[1,0,1] neg_lo:[1,0,0] neg_hi:[1,0,0]
	v_pk_fma_f32 v[146:147], v[96:97], v[222:223], v[146:147] op_sel:[0,1,0] neg_lo:[1,0,0] neg_hi:[1,0,0]
	v_pk_fma_f32 v[252:253], v[68:69], v[210:211], v[252:253] op_sel_hi:[1,0,1] neg_lo:[1,0,0] neg_hi:[1,0,0]
	ds_read_b128 v[208:211], v20 offset:52880
	v_pk_fma_f32 v[146:147], v[100:101], v[224:225], v[146:147] op_sel:[0,1,0] neg_lo:[1,0,0] neg_hi:[1,0,0]
	v_pk_fma_f32 v[252:253], v[72:73], v[212:213], v[252:253] op_sel_hi:[1,0,1] neg_lo:[1,0,0] neg_hi:[1,0,0]
	v_pk_fma_f32 v[146:147], v[104:105], v[226:227], v[146:147] op_sel:[0,1,0] neg_lo:[1,0,0] neg_hi:[1,0,0]
	v_pk_fma_f32 v[252:253], v[76:77], v[214:215], v[252:253] op_sel_hi:[1,0,1] neg_lo:[1,0,0] neg_hi:[1,0,0]
	ds_read_b128 v[212:215], v20 offset:52896
	v_pk_fma_f32 v[252:253], v[80:81], v[216:217], v[252:253] op_sel_hi:[1,0,1] neg_lo:[1,0,0] neg_hi:[1,0,0]
	s_nop 0
	v_pk_fma_f32 v[252:253], v[86:87], v[218:219], v[252:253] op_sel_hi:[1,0,1] neg_lo:[1,0,0] neg_hi:[1,0,0]
	ds_read_b128 v[216:219], v20 offset:52912
	v_pk_fma_f32 v[252:253], v[90:91], v[220:221], v[252:253] op_sel_hi:[1,0,1] neg_lo:[1,0,0] neg_hi:[1,0,0]
	s_nop 0
	v_pk_fma_f32 v[252:253], v[94:95], v[222:223], v[252:253] op_sel_hi:[1,0,1] neg_lo:[1,0,0] neg_hi:[1,0,0]
	ds_read_b128 v[220:223], v20 offset:52928
	v_pk_fma_f32 v[252:253], v[224:225], v[98:99], v[252:253] op_sel_hi:[0,1,1] neg_lo:[1,0,0] neg_hi:[1,0,0]
	s_nop 0
	v_pk_fma_f32 v[252:253], v[102:103], v[226:227], v[252:253] op_sel_hi:[1,0,1] neg_lo:[1,0,0] neg_hi:[1,0,0]
	ds_read_b128 v[224:227], v20 offset:52944
	v_pk_add_f32 v[100:101], v[252:253], v[146:147]
	s_waitcnt lgkmcnt(13)
	v_pk_fma_f32 v[146:147], v[138:139], v[110:111], 0 op_sel:[0,1,0] op_sel_hi:[1,1,0] neg_lo:[1,0,0] neg_hi:[1,0,0]
	v_pk_fma_f32 v[110:111], v[128:129], v[110:111], v[102:103] op_sel_hi:[1,0,1] neg_lo:[1,0,0] neg_hi:[1,0,0]
	v_pk_fma_f32 v[146:147], v[134:135], v[112:113], v[146:147] op_sel:[0,1,0] neg_lo:[1,0,0] neg_hi:[1,0,0]
	v_pk_fma_f32 v[110:111], v[136:137], v[112:113], v[110:111] op_sel_hi:[1,0,1] neg_lo:[1,0,0] neg_hi:[1,0,0]
	s_waitcnt lgkmcnt(12)
	v_pk_fma_f32 v[146:147], v[130:131], v[150:151], v[146:147] op_sel:[0,1,0] neg_lo:[1,0,0] neg_hi:[1,0,0]
	v_pk_fma_f32 v[110:111], v[132:133], v[150:151], v[110:111] op_sel_hi:[1,0,1] neg_lo:[1,0,0] neg_hi:[1,0,0]
	v_pk_fma_f32 v[146:147], v[84:85], v[152:153], v[146:147] op_sel:[0,1,0] neg_lo:[1,0,0] neg_hi:[1,0,0]
	v_pk_fma_f32 v[110:111], v[122:123], v[152:153], v[110:111] op_sel_hi:[1,0,1] neg_lo:[1,0,0] neg_hi:[1,0,0]
	ds_read_b128 v[150:153], v20 offset:53008
	s_waitcnt lgkmcnt(12)
	v_pk_fma_f32 v[146:147], v[10:11], v[154:155], v[146:147] op_sel:[0,1,0] neg_lo:[1,0,0] neg_hi:[1,0,0]
	v_pk_fma_f32 v[110:111], v[14:15], v[154:155], v[110:111] op_sel_hi:[1,0,1] neg_lo:[1,0,0] neg_hi:[1,0,0]
	v_pk_fma_f32 v[146:147], v[6:7], v[156:157], v[146:147] op_sel:[0,1,0] neg_lo:[1,0,0] neg_hi:[1,0,0]
	v_pk_fma_f32 v[110:111], v[16:17], v[156:157], v[110:111] op_sel_hi:[1,0,1] neg_lo:[1,0,0] neg_hi:[1,0,0]
	ds_read_b128 v[154:157], v20 offset:53024
	s_waitcnt lgkmcnt(12)
	v_pk_fma_f32 v[146:147], v[12:13], v[158:159], v[146:147] op_sel:[0,1,0] neg_lo:[1,0,0] neg_hi:[1,0,0]
	v_pk_fma_f32 v[110:111], v[18:19], v[158:159], v[110:111] op_sel_hi:[1,0,1] neg_lo:[1,0,0] neg_hi:[1,0,0]
	v_pk_fma_f32 v[146:147], v[4:5], v[160:161], v[146:147] op_sel:[0,1,0] neg_lo:[1,0,0] neg_hi:[1,0,0]
	v_pk_fma_f32 v[110:111], v[8:9], v[160:161], v[110:111] op_sel_hi:[1,0,1] neg_lo:[1,0,0] neg_hi:[1,0,0]
	ds_read_b128 v[158:161], v20 offset:53040
	s_waitcnt lgkmcnt(12)
	v_pk_fma_f32 v[146:147], v[0:1], v[166:167], v[146:147] op_sel:[0,1,0] neg_lo:[1,0,0] neg_hi:[1,0,0]
	v_pk_fma_f32 v[110:111], v[2:3], v[166:167], v[110:111] op_sel_hi:[1,0,1] neg_lo:[1,0,0] neg_hi:[1,0,0]
	v_pk_fma_f32 v[146:147], v[28:29], v[168:169], v[146:147] op_sel:[0,1,0] neg_lo:[1,0,0] neg_hi:[1,0,0]
	v_pk_fma_f32 v[110:111], v[30:31], v[168:169], v[110:111] op_sel_hi:[1,0,1] neg_lo:[1,0,0] neg_hi:[1,0,0]
	ds_read_b128 v[166:169], v20 offset:53056
	s_waitcnt lgkmcnt(12)
	v_pk_fma_f32 v[146:147], v[34:35], v[170:171], v[146:147] op_sel:[0,1,0] neg_lo:[1,0,0] neg_hi:[1,0,0]
	v_pk_fma_f32 v[110:111], v[32:33], v[170:171], v[110:111] op_sel_hi:[1,0,1] neg_lo:[1,0,0] neg_hi:[1,0,0]
	v_pk_fma_f32 v[146:147], v[40:41], v[172:173], v[146:147] op_sel:[0,1,0] neg_lo:[1,0,0] neg_hi:[1,0,0]
	v_pk_fma_f32 v[110:111], v[36:37], v[172:173], v[110:111] op_sel_hi:[1,0,1] neg_lo:[1,0,0] neg_hi:[1,0,0]
	ds_read_b128 v[170:173], v20 offset:53072
	s_waitcnt lgkmcnt(12)
	v_pk_fma_f32 v[146:147], v[42:43], v[174:175], v[146:147] op_sel:[0,1,0] neg_lo:[1,0,0] neg_hi:[1,0,0]
	v_pk_fma_f32 v[110:111], v[38:39], v[174:175], v[110:111] op_sel_hi:[1,0,1] neg_lo:[1,0,0] neg_hi:[1,0,0]
	v_pk_fma_f32 v[146:147], v[46:47], v[176:177], v[146:147] op_sel:[0,1,0] neg_lo:[1,0,0] neg_hi:[1,0,0]
	v_pk_fma_f32 v[110:111], v[44:45], v[176:177], v[110:111] op_sel_hi:[1,0,1] neg_lo:[1,0,0] neg_hi:[1,0,0]
	ds_read_b128 v[174:177], v20 offset:53088
	s_waitcnt lgkmcnt(12)
	v_pk_fma_f32 v[146:147], v[50:51], v[178:179], v[146:147] op_sel:[0,1,0] neg_lo:[1,0,0] neg_hi:[1,0,0]
	v_pk_fma_f32 v[110:111], v[48:49], v[178:179], v[110:111] op_sel_hi:[1,0,1] neg_lo:[1,0,0] neg_hi:[1,0,0]
	v_pk_fma_f32 v[146:147], v[54:55], v[180:181], v[146:147] op_sel:[0,1,0] neg_lo:[1,0,0] neg_hi:[1,0,0]
	v_pk_fma_f32 v[110:111], v[52:53], v[180:181], v[110:111] op_sel_hi:[1,0,1] neg_lo:[1,0,0] neg_hi:[1,0,0]
	ds_read_b128 v[178:181], v20 offset:53104
	s_waitcnt lgkmcnt(12)
	v_pk_fma_f32 v[146:147], v[58:59], v[182:183], v[146:147] op_sel:[0,1,0] neg_lo:[1,0,0] neg_hi:[1,0,0]
	v_pk_fma_f32 v[110:111], v[56:57], v[182:183], v[110:111] op_sel_hi:[1,0,1] neg_lo:[1,0,0] neg_hi:[1,0,0]
	v_pk_fma_f32 v[146:147], v[62:63], v[184:185], v[146:147] op_sel:[0,1,0] neg_lo:[1,0,0] neg_hi:[1,0,0]
	v_pk_fma_f32 v[110:111], v[60:61], v[184:185], v[110:111] op_sel_hi:[1,0,1] neg_lo:[1,0,0] neg_hi:[1,0,0]
	ds_read_b128 v[182:185], v20 offset:53120
	s_waitcnt lgkmcnt(12)
	v_pk_fma_f32 v[146:147], v[66:67], v[208:209], v[146:147] op_sel:[0,1,0] neg_lo:[1,0,0] neg_hi:[1,0,0]
	v_pk_fma_f32 v[110:111], v[64:65], v[208:209], v[110:111] op_sel_hi:[1,0,1] neg_lo:[1,0,0] neg_hi:[1,0,0]
	v_pk_fma_f32 v[146:147], v[70:71], v[210:211], v[146:147] op_sel:[0,1,0] neg_lo:[1,0,0] neg_hi:[1,0,0]
	v_pk_fma_f32 v[110:111], v[68:69], v[210:211], v[110:111] op_sel_hi:[1,0,1] neg_lo:[1,0,0] neg_hi:[1,0,0]
	ds_read_b128 v[208:211], v20 offset:53136
	s_waitcnt lgkmcnt(12)
	v_pk_fma_f32 v[146:147], v[74:75], v[212:213], v[146:147] op_sel:[0,1,0] neg_lo:[1,0,0] neg_hi:[1,0,0]
	v_pk_fma_f32 v[110:111], v[72:73], v[212:213], v[110:111] op_sel_hi:[1,0,1] neg_lo:[1,0,0] neg_hi:[1,0,0]
	v_pk_fma_f32 v[146:147], v[78:79], v[214:215], v[146:147] op_sel:[0,1,0] neg_lo:[1,0,0] neg_hi:[1,0,0]
	v_pk_fma_f32 v[110:111], v[76:77], v[214:215], v[110:111] op_sel_hi:[1,0,1] neg_lo:[1,0,0] neg_hi:[1,0,0]
	ds_read_b128 v[212:215], v20 offset:53152
	s_waitcnt lgkmcnt(12)
	v_pk_fma_f32 v[146:147], v[82:83], v[216:217], v[146:147] op_sel:[0,1,0] neg_lo:[1,0,0] neg_hi:[1,0,0]
	v_pk_fma_f32 v[110:111], v[80:81], v[216:217], v[110:111] op_sel_hi:[1,0,1] neg_lo:[1,0,0] neg_hi:[1,0,0]
	v_pk_fma_f32 v[146:147], v[88:89], v[218:219], v[146:147] op_sel:[0,1,0] neg_lo:[1,0,0] neg_hi:[1,0,0]
	v_pk_fma_f32 v[110:111], v[86:87], v[218:219], v[110:111] op_sel_hi:[1,0,1] neg_lo:[1,0,0] neg_hi:[1,0,0]
	ds_read_b128 v[216:219], v20 offset:53168
	s_waitcnt lgkmcnt(12)
	v_pk_fma_f32 v[146:147], v[92:93], v[220:221], v[146:147] op_sel:[0,1,0] neg_lo:[1,0,0] neg_hi:[1,0,0]
	v_pk_fma_f32 v[110:111], v[90:91], v[220:221], v[110:111] op_sel_hi:[1,0,1] neg_lo:[1,0,0] neg_hi:[1,0,0]
	v_pk_fma_f32 v[146:147], v[96:97], v[222:223], v[146:147] op_sel:[0,1,0] neg_lo:[1,0,0] neg_hi:[1,0,0]
	v_pk_fma_f32 v[110:111], v[94:95], v[222:223], v[110:111] op_sel_hi:[1,0,1] neg_lo:[1,0,0] neg_hi:[1,0,0]
	ds_read_b128 v[220:223], v20 offset:53184
	s_waitcnt lgkmcnt(12)
	v_pk_fma_f32 v[146:147], v[224:225], v[100:101], v[146:147] op_sel:[1,0,0] neg_lo:[1,0,0] neg_hi:[1,0,0]
	v_pk_fma_f32 v[110:111], v[98:99], v[224:225], v[110:111] op_sel_hi:[1,0,1] neg_lo:[1,0,0] neg_hi:[1,0,0]
	v_pk_fma_f32 v[146:147], v[104:105], v[226:227], v[146:147] op_sel:[0,1,0] neg_lo:[1,0,0] neg_hi:[1,0,0]
	v_pk_fma_f32 v[102:103], v[102:103], v[226:227], v[110:111] op_sel_hi:[1,0,1] neg_lo:[1,0,0] neg_hi:[1,0,0]
	ds_read_b128 v[110:113], v20 offset:52992
	ds_read_b128 v[224:227], v20 offset:53200
	v_pk_add_f32 v[102:103], v[102:103], v[146:147]
	s_waitcnt lgkmcnt(1)
	v_pk_fma_f32 v[146:147], v[138:139], v[110:111], 0 op_sel:[0,1,0] op_sel_hi:[1,1,0] neg_lo:[1,0,0] neg_hi:[1,0,0]
	v_pk_fma_f32 v[252:253], v[128:129], v[110:111], v[104:105] op_sel_hi:[1,0,1] neg_lo:[1,0,0] neg_hi:[1,0,0]
	v_pk_fma_f32 v[146:147], v[134:135], v[112:113], v[146:147] op_sel:[0,1,0] neg_lo:[1,0,0] neg_hi:[1,0,0]
	v_pk_fma_f32 v[252:253], v[136:137], v[112:113], v[252:253] op_sel_hi:[1,0,1] neg_lo:[1,0,0] neg_hi:[1,0,0]
	v_pk_fma_f32 v[146:147], v[130:131], v[150:151], v[146:147] op_sel:[0,1,0] neg_lo:[1,0,0] neg_hi:[1,0,0]
	ds_read_b128 v[110:113], v20 offset:53248
	v_pk_fma_f32 v[146:147], v[84:85], v[152:153], v[146:147] op_sel:[0,1,0] neg_lo:[1,0,0] neg_hi:[1,0,0]
	v_pk_fma_f32 v[252:253], v[132:133], v[150:151], v[252:253] op_sel_hi:[1,0,1] neg_lo:[1,0,0] neg_hi:[1,0,0]
	v_pk_fma_f32 v[146:147], v[10:11], v[154:155], v[146:147] op_sel:[0,1,0] neg_lo:[1,0,0] neg_hi:[1,0,0]
	v_pk_fma_f32 v[252:253], v[122:123], v[152:153], v[252:253] op_sel_hi:[1,0,1] neg_lo:[1,0,0] neg_hi:[1,0,0]
	v_pk_fma_f32 v[146:147], v[6:7], v[156:157], v[146:147] op_sel:[0,1,0] neg_lo:[1,0,0] neg_hi:[1,0,0]
	ds_read_b128 v[150:153], v20 offset:53264
	v_pk_fma_f32 v[146:147], v[12:13], v[158:159], v[146:147] op_sel:[0,1,0] neg_lo:[1,0,0] neg_hi:[1,0,0]
	v_pk_fma_f32 v[252:253], v[14:15], v[154:155], v[252:253] op_sel_hi:[1,0,1] neg_lo:[1,0,0] neg_hi:[1,0,0]
	v_pk_fma_f32 v[146:147], v[4:5], v[160:161], v[146:147] op_sel:[0,1,0] neg_lo:[1,0,0] neg_hi:[1,0,0]
	v_pk_fma_f32 v[252:253], v[16:17], v[156:157], v[252:253] op_sel_hi:[1,0,1] neg_lo:[1,0,0] neg_hi:[1,0,0]
	v_pk_fma_f32 v[146:147], v[0:1], v[166:167], v[146:147] op_sel:[0,1,0] neg_lo:[1,0,0] neg_hi:[1,0,0]
	ds_read_b128 v[154:157], v20 offset:53280
	v_pk_fma_f32 v[146:147], v[28:29], v[168:169], v[146:147] op_sel:[0,1,0] neg_lo:[1,0,0] neg_hi:[1,0,0]
	v_pk_fma_f32 v[252:253], v[18:19], v[158:159], v[252:253] op_sel_hi:[1,0,1] neg_lo:[1,0,0] neg_hi:[1,0,0]
	v_pk_fma_f32 v[146:147], v[34:35], v[170:171], v[146:147] op_sel:[0,1,0] neg_lo:[1,0,0] neg_hi:[1,0,0]
	v_pk_fma_f32 v[252:253], v[8:9], v[160:161], v[252:253] op_sel_hi:[1,0,1] neg_lo:[1,0,0] neg_hi:[1,0,0]
	v_pk_fma_f32 v[146:147], v[40:41], v[172:173], v[146:147] op_sel:[0,1,0] neg_lo:[1,0,0] neg_hi:[1,0,0]
	ds_read_b128 v[158:161], v20 offset:53296
	v_pk_fma_f32 v[146:147], v[42:43], v[174:175], v[146:147] op_sel:[0,1,0] neg_lo:[1,0,0] neg_hi:[1,0,0]
	v_pk_fma_f32 v[252:253], v[2:3], v[166:167], v[252:253] op_sel_hi:[1,0,1] neg_lo:[1,0,0] neg_hi:[1,0,0]
	v_pk_fma_f32 v[146:147], v[46:47], v[176:177], v[146:147] op_sel:[0,1,0] neg_lo:[1,0,0] neg_hi:[1,0,0]
	v_pk_fma_f32 v[252:253], v[30:31], v[168:169], v[252:253] op_sel_hi:[1,0,1] neg_lo:[1,0,0] neg_hi:[1,0,0]
	v_pk_fma_f32 v[146:147], v[50:51], v[178:179], v[146:147] op_sel:[0,1,0] neg_lo:[1,0,0] neg_hi:[1,0,0]
	ds_read_b128 v[166:169], v20 offset:53312
	v_pk_fma_f32 v[146:147], v[54:55], v[180:181], v[146:147] op_sel:[0,1,0] neg_lo:[1,0,0] neg_hi:[1,0,0]
	v_pk_fma_f32 v[252:253], v[32:33], v[170:171], v[252:253] op_sel_hi:[1,0,1] neg_lo:[1,0,0] neg_hi:[1,0,0]
	v_pk_fma_f32 v[146:147], v[58:59], v[182:183], v[146:147] op_sel:[0,1,0] neg_lo:[1,0,0] neg_hi:[1,0,0]
	v_pk_fma_f32 v[252:253], v[36:37], v[172:173], v[252:253] op_sel_hi:[1,0,1] neg_lo:[1,0,0] neg_hi:[1,0,0]
	v_pk_fma_f32 v[146:147], v[62:63], v[184:185], v[146:147] op_sel:[0,1,0] neg_lo:[1,0,0] neg_hi:[1,0,0]
	ds_read_b128 v[170:173], v20 offset:53328
	v_pk_fma_f32 v[146:147], v[66:67], v[208:209], v[146:147] op_sel:[0,1,0] neg_lo:[1,0,0] neg_hi:[1,0,0]
	v_pk_fma_f32 v[252:253], v[38:39], v[174:175], v[252:253] op_sel_hi:[1,0,1] neg_lo:[1,0,0] neg_hi:[1,0,0]
	v_pk_fma_f32 v[146:147], v[70:71], v[210:211], v[146:147] op_sel:[0,1,0] neg_lo:[1,0,0] neg_hi:[1,0,0]
	v_pk_fma_f32 v[252:253], v[44:45], v[176:177], v[252:253] op_sel_hi:[1,0,1] neg_lo:[1,0,0] neg_hi:[1,0,0]
	ds_read_b128 v[174:177], v20 offset:53344
	v_pk_fma_f32 v[146:147], v[74:75], v[212:213], v[146:147] op_sel:[0,1,0] neg_lo:[1,0,0] neg_hi:[1,0,0]
	v_pk_fma_f32 v[252:253], v[48:49], v[178:179], v[252:253] op_sel_hi:[1,0,1] neg_lo:[1,0,0] neg_hi:[1,0,0]
	v_pk_fma_f32 v[146:147], v[78:79], v[214:215], v[146:147] op_sel:[0,1,0] neg_lo:[1,0,0] neg_hi:[1,0,0]
	v_pk_fma_f32 v[252:253], v[52:53], v[180:181], v[252:253] op_sel_hi:[1,0,1] neg_lo:[1,0,0] neg_hi:[1,0,0]
	ds_read_b128 v[178:181], v20 offset:53360
	v_pk_fma_f32 v[146:147], v[82:83], v[216:217], v[146:147] op_sel:[0,1,0] neg_lo:[1,0,0] neg_hi:[1,0,0]
	v_pk_fma_f32 v[252:253], v[56:57], v[182:183], v[252:253] op_sel_hi:[1,0,1] neg_lo:[1,0,0] neg_hi:[1,0,0]
	v_pk_fma_f32 v[146:147], v[88:89], v[218:219], v[146:147] op_sel:[0,1,0] neg_lo:[1,0,0] neg_hi:[1,0,0]
	v_pk_fma_f32 v[252:253], v[60:61], v[184:185], v[252:253] op_sel_hi:[1,0,1] neg_lo:[1,0,0] neg_hi:[1,0,0]
	ds_read_b128 v[182:185], v20 offset:53376
	v_pk_fma_f32 v[146:147], v[92:93], v[220:221], v[146:147] op_sel:[0,1,0] neg_lo:[1,0,0] neg_hi:[1,0,0]
	v_pk_fma_f32 v[252:253], v[64:65], v[208:209], v[252:253] op_sel_hi:[1,0,1] neg_lo:[1,0,0] neg_hi:[1,0,0]
	v_pk_fma_f32 v[146:147], v[96:97], v[222:223], v[146:147] op_sel:[0,1,0] neg_lo:[1,0,0] neg_hi:[1,0,0]
	v_pk_fma_f32 v[252:253], v[68:69], v[210:211], v[252:253] op_sel_hi:[1,0,1] neg_lo:[1,0,0] neg_hi:[1,0,0]
	ds_read_b128 v[208:211], v20 offset:53392
	s_waitcnt lgkmcnt(10)
	v_pk_fma_f32 v[146:147], v[100:101], v[224:225], v[146:147] op_sel:[0,1,0] neg_lo:[1,0,0] neg_hi:[1,0,0]
	v_pk_fma_f32 v[252:253], v[72:73], v[212:213], v[252:253] op_sel_hi:[1,0,1] neg_lo:[1,0,0] neg_hi:[1,0,0]
	v_pk_fma_f32 v[146:147], v[104:105], v[226:227], v[146:147] op_sel:[0,1,0] neg_lo:[1,0,0] neg_hi:[1,0,0]
	v_pk_fma_f32 v[252:253], v[76:77], v[214:215], v[252:253] op_sel_hi:[1,0,1] neg_lo:[1,0,0] neg_hi:[1,0,0]
	ds_read_b128 v[212:215], v20 offset:53408
	v_pk_fma_f32 v[252:253], v[80:81], v[216:217], v[252:253] op_sel_hi:[1,0,1] neg_lo:[1,0,0] neg_hi:[1,0,0]
	s_nop 0
	v_pk_fma_f32 v[252:253], v[86:87], v[218:219], v[252:253] op_sel_hi:[1,0,1] neg_lo:[1,0,0] neg_hi:[1,0,0]
	ds_read_b128 v[216:219], v20 offset:53424
	v_pk_fma_f32 v[252:253], v[90:91], v[220:221], v[252:253] op_sel_hi:[1,0,1] neg_lo:[1,0,0] neg_hi:[1,0,0]
	s_nop 0
	v_pk_fma_f32 v[252:253], v[94:95], v[222:223], v[252:253] op_sel_hi:[1,0,1] neg_lo:[1,0,0] neg_hi:[1,0,0]
	ds_read_b128 v[220:223], v20 offset:53440
	v_pk_fma_f32 v[252:253], v[98:99], v[224:225], v[252:253] op_sel_hi:[1,0,1] neg_lo:[1,0,0] neg_hi:[1,0,0]
	s_nop 0
	v_pk_fma_f32 v[252:253], v[226:227], v[102:103], v[252:253] op_sel_hi:[0,1,1] neg_lo:[1,0,0] neg_hi:[1,0,0]
	ds_read_b128 v[224:227], v20 offset:53456
	v_pk_add_f32 v[104:105], v[252:253], v[146:147]
	s_waitcnt lgkmcnt(13)
	v_pk_fma_f32 v[146:147], v[138:139], v[110:111], 0 op_sel:[0,1,0] op_sel_hi:[1,1,0] neg_lo:[1,0,0] neg_hi:[1,0,0]
	v_pk_mul_f32 v[110:111], v[128:129], v[110:111] op_sel_hi:[1,0]
	v_pk_fma_f32 v[146:147], v[134:135], v[112:113], v[146:147] op_sel:[0,1,0] neg_lo:[1,0,0] neg_hi:[1,0,0]
	v_pk_fma_f32 v[106:107], v[106:107], v[108:109], v[110:111] neg_lo:[0,0,1] neg_hi:[0,0,1]
	ds_read_b128 v[108:111], v20 offset:53504
	v_pk_fma_f32 v[106:107], v[136:137], v[112:113], v[106:107] op_sel_hi:[1,0,1] neg_lo:[1,0,0] neg_hi:[1,0,0]
	s_waitcnt lgkmcnt(13)
	v_pk_fma_f32 v[146:147], v[130:131], v[150:151], v[146:147] op_sel:[0,1,0] neg_lo:[1,0,0] neg_hi:[1,0,0]
	v_pk_fma_f32 v[106:107], v[132:133], v[150:151], v[106:107] op_sel_hi:[1,0,1] neg_lo:[1,0,0] neg_hi:[1,0,0]
	v_pk_fma_f32 v[146:147], v[84:85], v[152:153], v[146:147] op_sel:[0,1,0] neg_lo:[1,0,0] neg_hi:[1,0,0]
	v_pk_fma_f32 v[106:107], v[122:123], v[152:153], v[106:107] op_sel_hi:[1,0,1] neg_lo:[1,0,0] neg_hi:[1,0,0]
	ds_read_b128 v[150:153], v20 offset:53520
	s_waitcnt lgkmcnt(13)
	v_pk_fma_f32 v[146:147], v[10:11], v[154:155], v[146:147] op_sel:[0,1,0] neg_lo:[1,0,0] neg_hi:[1,0,0]
	v_pk_fma_f32 v[106:107], v[14:15], v[154:155], v[106:107] op_sel_hi:[1,0,1] neg_lo:[1,0,0] neg_hi:[1,0,0]
	v_pk_fma_f32 v[146:147], v[6:7], v[156:157], v[146:147] op_sel:[0,1,0] neg_lo:[1,0,0] neg_hi:[1,0,0]
	v_pk_fma_f32 v[106:107], v[16:17], v[156:157], v[106:107] op_sel_hi:[1,0,1] neg_lo:[1,0,0] neg_hi:[1,0,0]
	ds_read_b128 v[154:157], v20 offset:53536
	s_waitcnt lgkmcnt(13)
	v_pk_fma_f32 v[146:147], v[12:13], v[158:159], v[146:147] op_sel:[0,1,0] neg_lo:[1,0,0] neg_hi:[1,0,0]
	v_pk_fma_f32 v[106:107], v[18:19], v[158:159], v[106:107] op_sel_hi:[1,0,1] neg_lo:[1,0,0] neg_hi:[1,0,0]
	v_pk_fma_f32 v[146:147], v[4:5], v[160:161], v[146:147] op_sel:[0,1,0] neg_lo:[1,0,0] neg_hi:[1,0,0]
	v_pk_fma_f32 v[106:107], v[8:9], v[160:161], v[106:107] op_sel_hi:[1,0,1] neg_lo:[1,0,0] neg_hi:[1,0,0]
	ds_read_b128 v[158:161], v20 offset:53552
	s_waitcnt lgkmcnt(13)
	v_pk_fma_f32 v[146:147], v[0:1], v[166:167], v[146:147] op_sel:[0,1,0] neg_lo:[1,0,0] neg_hi:[1,0,0]
	v_pk_fma_f32 v[106:107], v[2:3], v[166:167], v[106:107] op_sel_hi:[1,0,1] neg_lo:[1,0,0] neg_hi:[1,0,0]
	v_pk_fma_f32 v[146:147], v[28:29], v[168:169], v[146:147] op_sel:[0,1,0] neg_lo:[1,0,0] neg_hi:[1,0,0]
	v_pk_fma_f32 v[106:107], v[30:31], v[168:169], v[106:107] op_sel_hi:[1,0,1] neg_lo:[1,0,0] neg_hi:[1,0,0]
	ds_read_b128 v[166:169], v20 offset:53568
	s_waitcnt lgkmcnt(13)
	v_pk_fma_f32 v[146:147], v[34:35], v[170:171], v[146:147] op_sel:[0,1,0] neg_lo:[1,0,0] neg_hi:[1,0,0]
	v_pk_fma_f32 v[106:107], v[32:33], v[170:171], v[106:107] op_sel_hi:[1,0,1] neg_lo:[1,0,0] neg_hi:[1,0,0]
	v_pk_fma_f32 v[146:147], v[40:41], v[172:173], v[146:147] op_sel:[0,1,0] neg_lo:[1,0,0] neg_hi:[1,0,0]
	v_pk_fma_f32 v[106:107], v[36:37], v[172:173], v[106:107] op_sel_hi:[1,0,1] neg_lo:[1,0,0] neg_hi:[1,0,0]
	ds_read_b128 v[170:173], v20 offset:53584
	s_waitcnt lgkmcnt(13)
	v_pk_fma_f32 v[146:147], v[42:43], v[174:175], v[146:147] op_sel:[0,1,0] neg_lo:[1,0,0] neg_hi:[1,0,0]
	v_pk_fma_f32 v[106:107], v[38:39], v[174:175], v[106:107] op_sel_hi:[1,0,1] neg_lo:[1,0,0] neg_hi:[1,0,0]
	v_pk_fma_f32 v[146:147], v[46:47], v[176:177], v[146:147] op_sel:[0,1,0] neg_lo:[1,0,0] neg_hi:[1,0,0]
	v_pk_fma_f32 v[106:107], v[44:45], v[176:177], v[106:107] op_sel_hi:[1,0,1] neg_lo:[1,0,0] neg_hi:[1,0,0]
	ds_read_b128 v[174:177], v20 offset:53600
	s_waitcnt lgkmcnt(13)
	v_pk_fma_f32 v[146:147], v[50:51], v[178:179], v[146:147] op_sel:[0,1,0] neg_lo:[1,0,0] neg_hi:[1,0,0]
	v_pk_fma_f32 v[106:107], v[48:49], v[178:179], v[106:107] op_sel_hi:[1,0,1] neg_lo:[1,0,0] neg_hi:[1,0,0]
	v_pk_fma_f32 v[146:147], v[54:55], v[180:181], v[146:147] op_sel:[0,1,0] neg_lo:[1,0,0] neg_hi:[1,0,0]
	v_pk_fma_f32 v[106:107], v[52:53], v[180:181], v[106:107] op_sel_hi:[1,0,1] neg_lo:[1,0,0] neg_hi:[1,0,0]
	ds_read_b128 v[178:181], v20 offset:53616
	s_waitcnt lgkmcnt(13)
	v_pk_fma_f32 v[146:147], v[58:59], v[182:183], v[146:147] op_sel:[0,1,0] neg_lo:[1,0,0] neg_hi:[1,0,0]
	v_pk_fma_f32 v[106:107], v[56:57], v[182:183], v[106:107] op_sel_hi:[1,0,1] neg_lo:[1,0,0] neg_hi:[1,0,0]
	v_pk_fma_f32 v[146:147], v[62:63], v[184:185], v[146:147] op_sel:[0,1,0] neg_lo:[1,0,0] neg_hi:[1,0,0]
	v_pk_fma_f32 v[106:107], v[60:61], v[184:185], v[106:107] op_sel_hi:[1,0,1] neg_lo:[1,0,0] neg_hi:[1,0,0]
	ds_read_b128 v[182:185], v20 offset:53632
	s_waitcnt lgkmcnt(13)
	v_pk_fma_f32 v[146:147], v[66:67], v[208:209], v[146:147] op_sel:[0,1,0] neg_lo:[1,0,0] neg_hi:[1,0,0]
	v_pk_fma_f32 v[106:107], v[64:65], v[208:209], v[106:107] op_sel_hi:[1,0,1] neg_lo:[1,0,0] neg_hi:[1,0,0]
	v_pk_fma_f32 v[146:147], v[70:71], v[210:211], v[146:147] op_sel:[0,1,0] neg_lo:[1,0,0] neg_hi:[1,0,0]
	v_pk_fma_f32 v[106:107], v[68:69], v[210:211], v[106:107] op_sel_hi:[1,0,1] neg_lo:[1,0,0] neg_hi:[1,0,0]
	ds_read_b128 v[208:211], v20 offset:53648
	s_waitcnt lgkmcnt(13)
	v_pk_fma_f32 v[146:147], v[74:75], v[212:213], v[146:147] op_sel:[0,1,0] neg_lo:[1,0,0] neg_hi:[1,0,0]
	v_pk_fma_f32 v[106:107], v[72:73], v[212:213], v[106:107] op_sel_hi:[1,0,1] neg_lo:[1,0,0] neg_hi:[1,0,0]
	v_pk_fma_f32 v[146:147], v[78:79], v[214:215], v[146:147] op_sel:[0,1,0] neg_lo:[1,0,0] neg_hi:[1,0,0]
	v_pk_fma_f32 v[106:107], v[76:77], v[214:215], v[106:107] op_sel_hi:[1,0,1] neg_lo:[1,0,0] neg_hi:[1,0,0]
	ds_read_b128 v[212:215], v20 offset:53664
	s_waitcnt lgkmcnt(13)
	v_pk_fma_f32 v[146:147], v[82:83], v[216:217], v[146:147] op_sel:[0,1,0] neg_lo:[1,0,0] neg_hi:[1,0,0]
	v_pk_fma_f32 v[106:107], v[80:81], v[216:217], v[106:107] op_sel_hi:[1,0,1] neg_lo:[1,0,0] neg_hi:[1,0,0]
	v_pk_fma_f32 v[146:147], v[88:89], v[218:219], v[146:147] op_sel:[0,1,0] neg_lo:[1,0,0] neg_hi:[1,0,0]
	v_pk_fma_f32 v[106:107], v[86:87], v[218:219], v[106:107] op_sel_hi:[1,0,1] neg_lo:[1,0,0] neg_hi:[1,0,0]
	ds_read_b128 v[216:219], v20 offset:53680
	s_waitcnt lgkmcnt(13)
	v_pk_fma_f32 v[146:147], v[92:93], v[220:221], v[146:147] op_sel:[0,1,0] neg_lo:[1,0,0] neg_hi:[1,0,0]
	v_pk_fma_f32 v[106:107], v[90:91], v[220:221], v[106:107] op_sel_hi:[1,0,1] neg_lo:[1,0,0] neg_hi:[1,0,0]
	v_pk_fma_f32 v[146:147], v[96:97], v[222:223], v[146:147] op_sel:[0,1,0] neg_lo:[1,0,0] neg_hi:[1,0,0]
	v_pk_fma_f32 v[106:107], v[94:95], v[222:223], v[106:107] op_sel_hi:[1,0,1] neg_lo:[1,0,0] neg_hi:[1,0,0]
	ds_read_b128 v[220:223], v20 offset:53696
	s_waitcnt lgkmcnt(13)
	v_pk_fma_f32 v[146:147], v[100:101], v[224:225], v[146:147] op_sel:[0,1,0] neg_lo:[1,0,0] neg_hi:[1,0,0]
	v_pk_fma_f32 v[106:107], v[98:99], v[224:225], v[106:107] op_sel_hi:[1,0,1] neg_lo:[1,0,0] neg_hi:[1,0,0]
	v_pk_fma_f32 v[146:147], v[226:227], v[104:105], v[146:147] op_sel:[1,0,0] neg_lo:[1,0,0] neg_hi:[1,0,0]
	v_pk_fma_f32 v[106:107], v[102:103], v[226:227], v[106:107] op_sel_hi:[1,0,1] neg_lo:[1,0,0] neg_hi:[1,0,0]
	ds_read_b128 v[224:227], v20 offset:53712
	v_pk_add_f32 v[106:107], v[106:107], v[146:147]
	s_waitcnt lgkmcnt(13)
	v_pk_fma_f32 v[112:113], v[138:139], v[108:109], 0 op_sel:[0,1,0] op_sel_hi:[1,1,0] neg_lo:[1,0,0] neg_hi:[1,0,0]
	v_pk_fma_f32 v[108:109], v[128:129], v[108:109], v[148:149] op_sel_hi:[1,0,1] neg_lo:[1,0,0] neg_hi:[1,0,0]
	v_pk_fma_f32 v[112:113], v[134:135], v[110:111], v[112:113] op_sel:[0,1,0] neg_lo:[1,0,0] neg_hi:[1,0,0]
	v_pk_fma_f32 v[108:109], v[136:137], v[110:111], v[108:109] op_sel_hi:[1,0,1] neg_lo:[1,0,0] neg_hi:[1,0,0]
	s_waitcnt lgkmcnt(12)
	v_pk_fma_f32 v[112:113], v[130:131], v[150:151], v[112:113] op_sel:[0,1,0] neg_lo:[1,0,0] neg_hi:[1,0,0]
	v_pk_fma_f32 v[108:109], v[132:133], v[150:151], v[108:109] op_sel_hi:[1,0,1] neg_lo:[1,0,0] neg_hi:[1,0,0]
	v_pk_fma_f32 v[112:113], v[84:85], v[152:153], v[112:113] op_sel:[0,1,0] neg_lo:[1,0,0] neg_hi:[1,0,0]
	v_pk_fma_f32 v[108:109], v[122:123], v[152:153], v[108:109] op_sel_hi:[1,0,1] neg_lo:[1,0,0] neg_hi:[1,0,0]
	s_waitcnt lgkmcnt(11)
	v_pk_fma_f32 v[112:113], v[10:11], v[154:155], v[112:113] op_sel:[0,1,0] neg_lo:[1,0,0] neg_hi:[1,0,0]
	ds_read_b128 v[150:153], v20 offset:53792
	v_pk_fma_f32 v[108:109], v[14:15], v[154:155], v[108:109] op_sel_hi:[1,0,1] neg_lo:[1,0,0] neg_hi:[1,0,0]
	v_pk_fma_f32 v[112:113], v[6:7], v[156:157], v[112:113] op_sel:[0,1,0] neg_lo:[1,0,0] neg_hi:[1,0,0]
	v_pk_fma_f32 v[108:109], v[16:17], v[156:157], v[108:109] op_sel_hi:[1,0,1] neg_lo:[1,0,0] neg_hi:[1,0,0]
	ds_read_b128 v[154:157], v20 offset:53808
	s_waitcnt lgkmcnt(12)
	v_pk_fma_f32 v[112:113], v[12:13], v[158:159], v[112:113] op_sel:[0,1,0] neg_lo:[1,0,0] neg_hi:[1,0,0]
	v_pk_fma_f32 v[108:109], v[18:19], v[158:159], v[108:109] op_sel_hi:[1,0,1] neg_lo:[1,0,0] neg_hi:[1,0,0]
	v_pk_fma_f32 v[112:113], v[4:5], v[160:161], v[112:113] op_sel:[0,1,0] neg_lo:[1,0,0] neg_hi:[1,0,0]
	v_pk_fma_f32 v[108:109], v[8:9], v[160:161], v[108:109] op_sel_hi:[1,0,1] neg_lo:[1,0,0] neg_hi:[1,0,0]
	ds_read_b128 v[158:161], v20 offset:53824
	s_waitcnt lgkmcnt(12)
	v_pk_fma_f32 v[112:113], v[0:1], v[166:167], v[112:113] op_sel:[0,1,0] neg_lo:[1,0,0] neg_hi:[1,0,0]
	v_pk_fma_f32 v[108:109], v[2:3], v[166:167], v[108:109] op_sel_hi:[1,0,1] neg_lo:[1,0,0] neg_hi:[1,0,0]
	v_pk_fma_f32 v[112:113], v[28:29], v[168:169], v[112:113] op_sel:[0,1,0] neg_lo:[1,0,0] neg_hi:[1,0,0]
	v_pk_fma_f32 v[108:109], v[30:31], v[168:169], v[108:109] op_sel_hi:[1,0,1] neg_lo:[1,0,0] neg_hi:[1,0,0]
	ds_read_b128 v[166:169], v20 offset:53840
	s_waitcnt lgkmcnt(12)
	v_pk_fma_f32 v[112:113], v[34:35], v[170:171], v[112:113] op_sel:[0,1,0] neg_lo:[1,0,0] neg_hi:[1,0,0]
	v_pk_fma_f32 v[108:109], v[32:33], v[170:171], v[108:109] op_sel_hi:[1,0,1] neg_lo:[1,0,0] neg_hi:[1,0,0]
	v_pk_fma_f32 v[112:113], v[40:41], v[172:173], v[112:113] op_sel:[0,1,0] neg_lo:[1,0,0] neg_hi:[1,0,0]
	v_pk_fma_f32 v[108:109], v[36:37], v[172:173], v[108:109] op_sel_hi:[1,0,1] neg_lo:[1,0,0] neg_hi:[1,0,0]
	ds_read_b128 v[170:173], v20 offset:53856
	s_waitcnt lgkmcnt(12)
	v_pk_fma_f32 v[112:113], v[42:43], v[174:175], v[112:113] op_sel:[0,1,0] neg_lo:[1,0,0] neg_hi:[1,0,0]
	v_pk_fma_f32 v[108:109], v[38:39], v[174:175], v[108:109] op_sel_hi:[1,0,1] neg_lo:[1,0,0] neg_hi:[1,0,0]
	v_pk_fma_f32 v[112:113], v[46:47], v[176:177], v[112:113] op_sel:[0,1,0] neg_lo:[1,0,0] neg_hi:[1,0,0]
	v_pk_fma_f32 v[108:109], v[44:45], v[176:177], v[108:109] op_sel_hi:[1,0,1] neg_lo:[1,0,0] neg_hi:[1,0,0]
	ds_read_b128 v[174:177], v20 offset:53872
	s_waitcnt lgkmcnt(12)
	v_pk_fma_f32 v[112:113], v[50:51], v[178:179], v[112:113] op_sel:[0,1,0] neg_lo:[1,0,0] neg_hi:[1,0,0]
	v_pk_fma_f32 v[108:109], v[48:49], v[178:179], v[108:109] op_sel_hi:[1,0,1] neg_lo:[1,0,0] neg_hi:[1,0,0]
	v_pk_fma_f32 v[112:113], v[54:55], v[180:181], v[112:113] op_sel:[0,1,0] neg_lo:[1,0,0] neg_hi:[1,0,0]
	v_pk_fma_f32 v[108:109], v[52:53], v[180:181], v[108:109] op_sel_hi:[1,0,1] neg_lo:[1,0,0] neg_hi:[1,0,0]
	ds_read_b128 v[178:181], v20 offset:53888
	s_waitcnt lgkmcnt(12)
	v_pk_fma_f32 v[112:113], v[58:59], v[182:183], v[112:113] op_sel:[0,1,0] neg_lo:[1,0,0] neg_hi:[1,0,0]
	v_pk_fma_f32 v[108:109], v[56:57], v[182:183], v[108:109] op_sel_hi:[1,0,1] neg_lo:[1,0,0] neg_hi:[1,0,0]
	v_pk_fma_f32 v[112:113], v[62:63], v[184:185], v[112:113] op_sel:[0,1,0] neg_lo:[1,0,0] neg_hi:[1,0,0]
	v_pk_fma_f32 v[108:109], v[60:61], v[184:185], v[108:109] op_sel_hi:[1,0,1] neg_lo:[1,0,0] neg_hi:[1,0,0]
	ds_read_b128 v[182:185], v20 offset:53904
	s_waitcnt lgkmcnt(12)
	v_pk_fma_f32 v[112:113], v[66:67], v[208:209], v[112:113] op_sel:[0,1,0] neg_lo:[1,0,0] neg_hi:[1,0,0]
	v_pk_fma_f32 v[108:109], v[64:65], v[208:209], v[108:109] op_sel_hi:[1,0,1] neg_lo:[1,0,0] neg_hi:[1,0,0]
	v_pk_fma_f32 v[112:113], v[70:71], v[210:211], v[112:113] op_sel:[0,1,0] neg_lo:[1,0,0] neg_hi:[1,0,0]
	v_pk_fma_f32 v[108:109], v[68:69], v[210:211], v[108:109] op_sel_hi:[1,0,1] neg_lo:[1,0,0] neg_hi:[1,0,0]
	ds_read_b128 v[208:211], v20 offset:53920
	s_waitcnt lgkmcnt(12)
	v_pk_fma_f32 v[112:113], v[74:75], v[212:213], v[112:113] op_sel:[0,1,0] neg_lo:[1,0,0] neg_hi:[1,0,0]
	v_pk_fma_f32 v[108:109], v[72:73], v[212:213], v[108:109] op_sel_hi:[1,0,1] neg_lo:[1,0,0] neg_hi:[1,0,0]
	v_pk_fma_f32 v[112:113], v[78:79], v[214:215], v[112:113] op_sel:[0,1,0] neg_lo:[1,0,0] neg_hi:[1,0,0]
	v_pk_fma_f32 v[108:109], v[76:77], v[214:215], v[108:109] op_sel_hi:[1,0,1] neg_lo:[1,0,0] neg_hi:[1,0,0]
	ds_read_b128 v[212:215], v20 offset:53936
	s_waitcnt lgkmcnt(12)
	v_pk_fma_f32 v[112:113], v[82:83], v[216:217], v[112:113] op_sel:[0,1,0] neg_lo:[1,0,0] neg_hi:[1,0,0]
	v_pk_fma_f32 v[108:109], v[80:81], v[216:217], v[108:109] op_sel_hi:[1,0,1] neg_lo:[1,0,0] neg_hi:[1,0,0]
	v_pk_fma_f32 v[112:113], v[88:89], v[218:219], v[112:113] op_sel:[0,1,0] neg_lo:[1,0,0] neg_hi:[1,0,0]
	v_pk_fma_f32 v[108:109], v[86:87], v[218:219], v[108:109] op_sel_hi:[1,0,1] neg_lo:[1,0,0] neg_hi:[1,0,0]
	ds_read_b128 v[216:219], v20 offset:53952
	s_waitcnt lgkmcnt(12)
	v_pk_fma_f32 v[112:113], v[92:93], v[220:221], v[112:113] op_sel:[0,1,0] neg_lo:[1,0,0] neg_hi:[1,0,0]
	v_pk_fma_f32 v[108:109], v[90:91], v[220:221], v[108:109] op_sel_hi:[1,0,1] neg_lo:[1,0,0] neg_hi:[1,0,0]
	v_pk_fma_f32 v[112:113], v[96:97], v[222:223], v[112:113] op_sel:[0,1,0] neg_lo:[1,0,0] neg_hi:[1,0,0]
	v_pk_fma_f32 v[108:109], v[94:95], v[222:223], v[108:109] op_sel_hi:[1,0,1] neg_lo:[1,0,0] neg_hi:[1,0,0]
	ds_read_b128 v[220:223], v20 offset:53968
	s_waitcnt lgkmcnt(12)
	v_pk_fma_f32 v[112:113], v[100:101], v[224:225], v[112:113] op_sel:[0,1,0] neg_lo:[1,0,0] neg_hi:[1,0,0]
	v_pk_fma_f32 v[108:109], v[98:99], v[224:225], v[108:109] op_sel_hi:[1,0,1] neg_lo:[1,0,0] neg_hi:[1,0,0]
	v_pk_fma_f32 v[112:113], v[104:105], v[226:227], v[112:113] op_sel:[0,1,0] neg_lo:[1,0,0] neg_hi:[1,0,0]
	v_pk_fma_f32 v[108:109], v[102:103], v[226:227], v[108:109] op_sel_hi:[1,0,1] neg_lo:[1,0,0] neg_hi:[1,0,0]
	ds_read_b128 v[224:227], v20 offset:53984
	v_pk_fma_f32 v[112:113], v[148:149], v[228:229], v[112:113] op_sel:[0,1,0] neg_lo:[1,0,0] neg_hi:[1,0,0]
	ds_read_b128 v[146:149], v20 offset:53776
	v_pk_fma_f32 v[108:109], v[228:229], v[106:107], v[108:109] op_sel_hi:[0,1,1] neg_lo:[1,0,0] neg_hi:[1,0,0]
	v_pk_fma_f32 v[112:113], v[142:143], v[230:231], v[112:113] op_sel:[0,1,0] neg_lo:[1,0,0] neg_hi:[1,0,0]
	v_pk_fma_f32 v[108:109], v[144:145], v[230:231], v[108:109] op_sel_hi:[1,0,1] neg_lo:[1,0,0] neg_hi:[1,0,0]
	s_nop 0
	v_pk_add_f32 v[108:109], v[108:109], v[112:113]
	ds_read_b128 v[110:113], v20 offset:53760
	s_waitcnt lgkmcnt(0)
	v_pk_fma_f32 v[162:163], v[138:139], v[110:111], 0 op_sel:[0,1,0] op_sel_hi:[1,1,0] neg_lo:[1,0,0] neg_hi:[1,0,0]
	v_pk_fma_f32 v[110:111], v[128:129], v[110:111], v[144:145] op_sel_hi:[1,0,1] neg_lo:[1,0,0] neg_hi:[1,0,0]
	v_pk_fma_f32 v[162:163], v[134:135], v[112:113], v[162:163] op_sel:[0,1,0] neg_lo:[1,0,0] neg_hi:[1,0,0]
	v_pk_fma_f32 v[110:111], v[136:137], v[112:113], v[110:111] op_sel_hi:[1,0,1] neg_lo:[1,0,0] neg_hi:[1,0,0]
	v_pk_fma_f32 v[162:163], v[130:131], v[146:147], v[162:163] op_sel:[0,1,0] neg_lo:[1,0,0] neg_hi:[1,0,0]
	v_pk_fma_f32 v[110:111], v[132:133], v[146:147], v[110:111] op_sel_hi:[1,0,1] neg_lo:[1,0,0] neg_hi:[1,0,0]
	v_pk_fma_f32 v[162:163], v[84:85], v[148:149], v[162:163] op_sel:[0,1,0] neg_lo:[1,0,0] neg_hi:[1,0,0]
	v_pk_fma_f32 v[110:111], v[122:123], v[148:149], v[110:111] op_sel_hi:[1,0,1] neg_lo:[1,0,0] neg_hi:[1,0,0]
	v_pk_fma_f32 v[162:163], v[10:11], v[150:151], v[162:163] op_sel:[0,1,0] neg_lo:[1,0,0] neg_hi:[1,0,0]
	v_pk_fma_f32 v[110:111], v[14:15], v[150:151], v[110:111] op_sel_hi:[1,0,1] neg_lo:[1,0,0] neg_hi:[1,0,0]
	ds_read_b128 v[148:151], v20 offset:54032
	v_pk_fma_f32 v[162:163], v[6:7], v[152:153], v[162:163] op_sel:[0,1,0] neg_lo:[1,0,0] neg_hi:[1,0,0]
	v_pk_fma_f32 v[110:111], v[16:17], v[152:153], v[110:111] op_sel_hi:[1,0,1] neg_lo:[1,0,0] neg_hi:[1,0,0]
	v_pk_fma_f32 v[162:163], v[12:13], v[154:155], v[162:163] op_sel:[0,1,0] neg_lo:[1,0,0] neg_hi:[1,0,0]
	v_pk_fma_f32 v[110:111], v[18:19], v[154:155], v[110:111] op_sel_hi:[1,0,1] neg_lo:[1,0,0] neg_hi:[1,0,0]
	ds_read_b128 v[152:155], v20 offset:54048
	v_pk_fma_f32 v[162:163], v[4:5], v[156:157], v[162:163] op_sel:[0,1,0] neg_lo:[1,0,0] neg_hi:[1,0,0]
	v_pk_fma_f32 v[110:111], v[8:9], v[156:157], v[110:111] op_sel_hi:[1,0,1] neg_lo:[1,0,0] neg_hi:[1,0,0]
	v_pk_fma_f32 v[162:163], v[0:1], v[158:159], v[162:163] op_sel:[0,1,0] neg_lo:[1,0,0] neg_hi:[1,0,0]
	v_pk_fma_f32 v[110:111], v[2:3], v[158:159], v[110:111] op_sel_hi:[1,0,1] neg_lo:[1,0,0] neg_hi:[1,0,0]
	ds_read_b128 v[156:159], v20 offset:54064
	v_pk_fma_f32 v[162:163], v[28:29], v[160:161], v[162:163] op_sel:[0,1,0] neg_lo:[1,0,0] neg_hi:[1,0,0]
	v_pk_fma_f32 v[110:111], v[30:31], v[160:161], v[110:111] op_sel_hi:[1,0,1] neg_lo:[1,0,0] neg_hi:[1,0,0]
	v_pk_fma_f32 v[162:163], v[34:35], v[166:167], v[162:163] op_sel:[0,1,0] neg_lo:[1,0,0] neg_hi:[1,0,0]
	v_pk_fma_f32 v[110:111], v[32:33], v[166:167], v[110:111] op_sel_hi:[1,0,1] neg_lo:[1,0,0] neg_hi:[1,0,0]
	v_pk_fma_f32 v[162:163], v[40:41], v[168:169], v[162:163] op_sel:[0,1,0] neg_lo:[1,0,0] neg_hi:[1,0,0]
	v_pk_fma_f32 v[110:111], v[36:37], v[168:169], v[110:111] op_sel_hi:[1,0,1] neg_lo:[1,0,0] neg_hi:[1,0,0]
	ds_read_b128 v[166:169], v20 offset:54096
	v_pk_fma_f32 v[162:163], v[42:43], v[170:171], v[162:163] op_sel:[0,1,0] neg_lo:[1,0,0] neg_hi:[1,0,0]
	v_pk_fma_f32 v[110:111], v[38:39], v[170:171], v[110:111] op_sel_hi:[1,0,1] neg_lo:[1,0,0] neg_hi:[1,0,0]
	v_pk_fma_f32 v[162:163], v[46:47], v[172:173], v[162:163] op_sel:[0,1,0] neg_lo:[1,0,0] neg_hi:[1,0,0]
	v_pk_fma_f32 v[110:111], v[44:45], v[172:173], v[110:111] op_sel_hi:[1,0,1] neg_lo:[1,0,0] neg_hi:[1,0,0]
	ds_read_b128 v[170:173], v20 offset:54112
	v_pk_fma_f32 v[162:163], v[50:51], v[174:175], v[162:163] op_sel:[0,1,0] neg_lo:[1,0,0] neg_hi:[1,0,0]
	v_pk_fma_f32 v[110:111], v[48:49], v[174:175], v[110:111] op_sel_hi:[1,0,1] neg_lo:[1,0,0] neg_hi:[1,0,0]
	v_pk_fma_f32 v[162:163], v[54:55], v[176:177], v[162:163] op_sel:[0,1,0] neg_lo:[1,0,0] neg_hi:[1,0,0]
	v_pk_fma_f32 v[110:111], v[52:53], v[176:177], v[110:111] op_sel_hi:[1,0,1] neg_lo:[1,0,0] neg_hi:[1,0,0]
	ds_read_b128 v[174:177], v20 offset:54128
	v_pk_fma_f32 v[162:163], v[58:59], v[178:179], v[162:163] op_sel:[0,1,0] neg_lo:[1,0,0] neg_hi:[1,0,0]
	v_pk_fma_f32 v[110:111], v[56:57], v[178:179], v[110:111] op_sel_hi:[1,0,1] neg_lo:[1,0,0] neg_hi:[1,0,0]
	v_pk_fma_f32 v[162:163], v[62:63], v[180:181], v[162:163] op_sel:[0,1,0] neg_lo:[1,0,0] neg_hi:[1,0,0]
	v_pk_fma_f32 v[110:111], v[60:61], v[180:181], v[110:111] op_sel_hi:[1,0,1] neg_lo:[1,0,0] neg_hi:[1,0,0]
	ds_read_b128 v[178:181], v20 offset:54144
	v_pk_fma_f32 v[162:163], v[66:67], v[182:183], v[162:163] op_sel:[0,1,0] neg_lo:[1,0,0] neg_hi:[1,0,0]
	v_pk_fma_f32 v[110:111], v[64:65], v[182:183], v[110:111] op_sel_hi:[1,0,1] neg_lo:[1,0,0] neg_hi:[1,0,0]
	v_pk_fma_f32 v[162:163], v[70:71], v[184:185], v[162:163] op_sel:[0,1,0] neg_lo:[1,0,0] neg_hi:[1,0,0]
	v_pk_fma_f32 v[110:111], v[68:69], v[184:185], v[110:111] op_sel_hi:[1,0,1] neg_lo:[1,0,0] neg_hi:[1,0,0]
	ds_read_b128 v[182:185], v20 offset:54160
	v_pk_fma_f32 v[162:163], v[74:75], v[208:209], v[162:163] op_sel:[0,1,0] neg_lo:[1,0,0] neg_hi:[1,0,0]
	v_pk_fma_f32 v[110:111], v[72:73], v[208:209], v[110:111] op_sel_hi:[1,0,1] neg_lo:[1,0,0] neg_hi:[1,0,0]
	v_pk_fma_f32 v[162:163], v[78:79], v[210:211], v[162:163] op_sel:[0,1,0] neg_lo:[1,0,0] neg_hi:[1,0,0]
	v_pk_fma_f32 v[110:111], v[76:77], v[210:211], v[110:111] op_sel_hi:[1,0,1] neg_lo:[1,0,0] neg_hi:[1,0,0]
	ds_read_b128 v[208:211], v20 offset:54176
	v_pk_fma_f32 v[162:163], v[82:83], v[212:213], v[162:163] op_sel:[0,1,0] neg_lo:[1,0,0] neg_hi:[1,0,0]
	v_pk_fma_f32 v[110:111], v[80:81], v[212:213], v[110:111] op_sel_hi:[1,0,1] neg_lo:[1,0,0] neg_hi:[1,0,0]
	v_pk_fma_f32 v[162:163], v[88:89], v[214:215], v[162:163] op_sel:[0,1,0] neg_lo:[1,0,0] neg_hi:[1,0,0]
	v_pk_fma_f32 v[110:111], v[86:87], v[214:215], v[110:111] op_sel_hi:[1,0,1] neg_lo:[1,0,0] neg_hi:[1,0,0]
	ds_read_b128 v[212:215], v20 offset:54192
	v_pk_fma_f32 v[162:163], v[92:93], v[216:217], v[162:163] op_sel:[0,1,0] neg_lo:[1,0,0] neg_hi:[1,0,0]
	v_pk_fma_f32 v[110:111], v[90:91], v[216:217], v[110:111] op_sel_hi:[1,0,1] neg_lo:[1,0,0] neg_hi:[1,0,0]
	v_pk_fma_f32 v[162:163], v[96:97], v[218:219], v[162:163] op_sel:[0,1,0] neg_lo:[1,0,0] neg_hi:[1,0,0]
	v_pk_fma_f32 v[110:111], v[94:95], v[218:219], v[110:111] op_sel_hi:[1,0,1] neg_lo:[1,0,0] neg_hi:[1,0,0]
	ds_read_b128 v[216:219], v20 offset:54208
	v_pk_fma_f32 v[162:163], v[100:101], v[220:221], v[162:163] op_sel:[0,1,0] neg_lo:[1,0,0] neg_hi:[1,0,0]
	v_pk_fma_f32 v[110:111], v[98:99], v[220:221], v[110:111] op_sel_hi:[1,0,1] neg_lo:[1,0,0] neg_hi:[1,0,0]
	v_pk_fma_f32 v[162:163], v[104:105], v[222:223], v[162:163] op_sel:[0,1,0] neg_lo:[1,0,0] neg_hi:[1,0,0]
	v_pk_fma_f32 v[110:111], v[102:103], v[222:223], v[110:111] op_sel_hi:[1,0,1] neg_lo:[1,0,0] neg_hi:[1,0,0]
	ds_read_b128 v[220:223], v20 offset:54224
	v_pk_fma_f32 v[162:163], v[224:225], v[108:109], v[162:163] op_sel:[1,0,0] neg_lo:[1,0,0] neg_hi:[1,0,0]
	v_pk_fma_f32 v[110:111], v[106:107], v[224:225], v[110:111] op_sel_hi:[1,0,1] neg_lo:[1,0,0] neg_hi:[1,0,0]
	v_pk_fma_f32 v[162:163], v[142:143], v[226:227], v[162:163] op_sel:[0,1,0] neg_lo:[1,0,0] neg_hi:[1,0,0]
	v_pk_fma_f32 v[110:111], v[144:145], v[226:227], v[110:111] op_sel_hi:[1,0,1] neg_lo:[1,0,0] neg_hi:[1,0,0]
	ds_read_b128 v[144:147], v20 offset:54016
	ds_read_b128 v[224:227], v20 offset:54240
	v_pk_add_f32 v[110:111], v[110:111], v[162:163]
	ds_read_b128 v[160:163], v20 offset:54080
	s_waitcnt lgkmcnt(2)
	v_pk_fma_f32 v[112:113], v[138:139], v[144:145], 0 op_sel:[0,1,0] op_sel_hi:[1,1,0] neg_lo:[1,0,0] neg_hi:[1,0,0]
	v_pk_fma_f32 v[252:253], v[128:129], v[144:145], v[142:143] op_sel_hi:[1,0,1] neg_lo:[1,0,0] neg_hi:[1,0,0]
	v_pk_fma_f32 v[112:113], v[134:135], v[146:147], v[112:113] op_sel:[0,1,0] neg_lo:[1,0,0] neg_hi:[1,0,0]
	v_pk_fma_f32 v[252:253], v[136:137], v[146:147], v[252:253] op_sel_hi:[1,0,1] neg_lo:[1,0,0] neg_hi:[1,0,0]
	v_pk_fma_f32 v[112:113], v[130:131], v[148:149], v[112:113] op_sel:[0,1,0] neg_lo:[1,0,0] neg_hi:[1,0,0]
	v_pk_fma_f32 v[252:253], v[132:133], v[148:149], v[252:253] op_sel_hi:[1,0,1] neg_lo:[1,0,0] neg_hi:[1,0,0]
	v_pk_fma_f32 v[112:113], v[84:85], v[150:151], v[112:113] op_sel:[0,1,0] neg_lo:[1,0,0] neg_hi:[1,0,0]
	ds_read_b128 v[146:149], v20 offset:54288
	v_pk_fma_f32 v[112:113], v[10:11], v[152:153], v[112:113] op_sel:[0,1,0] neg_lo:[1,0,0] neg_hi:[1,0,0]
	v_pk_fma_f32 v[252:253], v[122:123], v[150:151], v[252:253] op_sel_hi:[1,0,1] neg_lo:[1,0,0] neg_hi:[1,0,0]
	v_pk_fma_f32 v[112:113], v[6:7], v[154:155], v[112:113] op_sel:[0,1,0] neg_lo:[1,0,0] neg_hi:[1,0,0]
	v_pk_fma_f32 v[252:253], v[14:15], v[152:153], v[252:253] op_sel_hi:[1,0,1] neg_lo:[1,0,0] neg_hi:[1,0,0]
	v_pk_fma_f32 v[112:113], v[12:13], v[156:157], v[112:113] op_sel:[0,1,0] neg_lo:[1,0,0] neg_hi:[1,0,0]
	ds_read_b128 v[150:153], v20 offset:54304
	v_pk_fma_f32 v[112:113], v[4:5], v[158:159], v[112:113] op_sel:[0,1,0] neg_lo:[1,0,0] neg_hi:[1,0,0]
	v_pk_fma_f32 v[252:253], v[16:17], v[154:155], v[252:253] op_sel_hi:[1,0,1] neg_lo:[1,0,0] neg_hi:[1,0,0]
	s_waitcnt lgkmcnt(2)
	v_pk_fma_f32 v[112:113], v[0:1], v[160:161], v[112:113] op_sel:[0,1,0] neg_lo:[1,0,0] neg_hi:[1,0,0]
	v_pk_fma_f32 v[252:253], v[18:19], v[156:157], v[252:253] op_sel_hi:[1,0,1] neg_lo:[1,0,0] neg_hi:[1,0,0]
	v_pk_fma_f32 v[112:113], v[28:29], v[162:163], v[112:113] op_sel:[0,1,0] neg_lo:[1,0,0] neg_hi:[1,0,0]
	ds_read_b128 v[154:157], v20 offset:54320
	v_pk_fma_f32 v[112:113], v[34:35], v[166:167], v[112:113] op_sel:[0,1,0] neg_lo:[1,0,0] neg_hi:[1,0,0]
	v_pk_fma_f32 v[252:253], v[8:9], v[158:159], v[252:253] op_sel_hi:[1,0,1] neg_lo:[1,0,0] neg_hi:[1,0,0]
	v_pk_fma_f32 v[112:113], v[40:41], v[168:169], v[112:113] op_sel:[0,1,0] neg_lo:[1,0,0] neg_hi:[1,0,0]
	v_pk_fma_f32 v[252:253], v[2:3], v[160:161], v[252:253] op_sel_hi:[1,0,1] neg_lo:[1,0,0] neg_hi:[1,0,0]
	v_pk_fma_f32 v[112:113], v[42:43], v[170:171], v[112:113] op_sel:[0,1,0] neg_lo:[1,0,0] neg_hi:[1,0,0]
	ds_read_b128 v[158:161], v20 offset:54336
	v_pk_fma_f32 v[112:113], v[46:47], v[172:173], v[112:113] op_sel:[0,1,0] neg_lo:[1,0,0] neg_hi:[1,0,0]
	v_pk_fma_f32 v[252:253], v[30:31], v[162:163], v[252:253] op_sel_hi:[1,0,1] neg_lo:[1,0,0] neg_hi:[1,0,0]
	v_pk_fma_f32 v[112:113], v[50:51], v[174:175], v[112:113] op_sel:[0,1,0] neg_lo:[1,0,0] neg_hi:[1,0,0]
	v_pk_fma_f32 v[252:253], v[32:33], v[166:167], v[252:253] op_sel_hi:[1,0,1] neg_lo:[1,0,0] neg_hi:[1,0,0]
	v_pk_fma_f32 v[112:113], v[54:55], v[176:177], v[112:113] op_sel:[0,1,0] neg_lo:[1,0,0] neg_hi:[1,0,0]
	v_pk_fma_f32 v[252:253], v[36:37], v[168:169], v[252:253] op_sel_hi:[1,0,1] neg_lo:[1,0,0] neg_hi:[1,0,0]
	v_pk_fma_f32 v[112:113], v[58:59], v[178:179], v[112:113] op_sel:[0,1,0] neg_lo:[1,0,0] neg_hi:[1,0,0]
	ds_read_b128 v[166:169], v20 offset:54352
	v_pk_fma_f32 v[112:113], v[62:63], v[180:181], v[112:113] op_sel:[0,1,0] neg_lo:[1,0,0] neg_hi:[1,0,0]
	v_pk_fma_f32 v[252:253], v[38:39], v[170:171], v[252:253] op_sel_hi:[1,0,1] neg_lo:[1,0,0] neg_hi:[1,0,0]
	v_pk_fma_f32 v[112:113], v[66:67], v[182:183], v[112:113] op_sel:[0,1,0] neg_lo:[1,0,0] neg_hi:[1,0,0]
	v_pk_fma_f32 v[252:253], v[44:45], v[172:173], v[252:253] op_sel_hi:[1,0,1] neg_lo:[1,0,0] neg_hi:[1,0,0]
	v_pk_fma_f32 v[112:113], v[70:71], v[184:185], v[112:113] op_sel:[0,1,0] neg_lo:[1,0,0] neg_hi:[1,0,0]
	ds_read_b128 v[170:173], v20 offset:54368
	v_pk_fma_f32 v[112:113], v[74:75], v[208:209], v[112:113] op_sel:[0,1,0] neg_lo:[1,0,0] neg_hi:[1,0,0]
	v_pk_fma_f32 v[252:253], v[48:49], v[174:175], v[252:253] op_sel_hi:[1,0,1] neg_lo:[1,0,0] neg_hi:[1,0,0]
	v_pk_fma_f32 v[112:113], v[78:79], v[210:211], v[112:113] op_sel:[0,1,0] neg_lo:[1,0,0] neg_hi:[1,0,0]
	v_pk_fma_f32 v[252:253], v[52:53], v[176:177], v[252:253] op_sel_hi:[1,0,1] neg_lo:[1,0,0] neg_hi:[1,0,0]
	v_pk_fma_f32 v[112:113], v[82:83], v[212:213], v[112:113] op_sel:[0,1,0] neg_lo:[1,0,0] neg_hi:[1,0,0]
	ds_read_b128 v[174:177], v20 offset:54384
	v_pk_fma_f32 v[112:113], v[88:89], v[214:215], v[112:113] op_sel:[0,1,0] neg_lo:[1,0,0] neg_hi:[1,0,0]
	v_pk_fma_f32 v[252:253], v[56:57], v[178:179], v[252:253] op_sel_hi:[1,0,1] neg_lo:[1,0,0] neg_hi:[1,0,0]
	v_pk_fma_f32 v[112:113], v[92:93], v[216:217], v[112:113] op_sel:[0,1,0] neg_lo:[1,0,0] neg_hi:[1,0,0]
	v_pk_fma_f32 v[252:253], v[60:61], v[180:181], v[252:253] op_sel_hi:[1,0,1] neg_lo:[1,0,0] neg_hi:[1,0,0]
	ds_read_b128 v[178:181], v20 offset:54400
	v_pk_fma_f32 v[112:113], v[96:97], v[218:219], v[112:113] op_sel:[0,1,0] neg_lo:[1,0,0] neg_hi:[1,0,0]
	v_pk_fma_f32 v[252:253], v[64:65], v[182:183], v[252:253] op_sel_hi:[1,0,1] neg_lo:[1,0,0] neg_hi:[1,0,0]
	v_pk_fma_f32 v[112:113], v[100:101], v[220:221], v[112:113] op_sel:[0,1,0] neg_lo:[1,0,0] neg_hi:[1,0,0]
	v_pk_fma_f32 v[252:253], v[68:69], v[184:185], v[252:253] op_sel_hi:[1,0,1] neg_lo:[1,0,0] neg_hi:[1,0,0]
	ds_read_b128 v[182:185], v20 offset:54416
	v_pk_fma_f32 v[112:113], v[104:105], v[222:223], v[112:113] op_sel:[0,1,0] neg_lo:[1,0,0] neg_hi:[1,0,0]
	v_pk_fma_f32 v[252:253], v[72:73], v[208:209], v[252:253] op_sel_hi:[1,0,1] neg_lo:[1,0,0] neg_hi:[1,0,0]
	v_pk_fma_f32 v[112:113], v[108:109], v[224:225], v[112:113] op_sel:[0,1,0] neg_lo:[1,0,0] neg_hi:[1,0,0]
	v_pk_fma_f32 v[252:253], v[76:77], v[210:211], v[252:253] op_sel_hi:[1,0,1] neg_lo:[1,0,0] neg_hi:[1,0,0]
	ds_read_b128 v[208:211], v20 offset:54432
	v_pk_fma_f32 v[112:113], v[142:143], v[226:227], v[112:113] op_sel:[0,1,0] neg_lo:[1,0,0] neg_hi:[1,0,0]
	ds_read_b128 v[142:145], v20 offset:54272
	v_pk_fma_f32 v[252:253], v[80:81], v[212:213], v[252:253] op_sel_hi:[1,0,1] neg_lo:[1,0,0] neg_hi:[1,0,0]
	s_waitcnt lgkmcnt(0)
	v_pk_fma_f32 v[162:163], v[138:139], v[142:143], 0 op_sel:[0,1,0] op_sel_hi:[1,1,0] neg_lo:[1,0,0] neg_hi:[1,0,0]
	v_pk_fma_f32 v[252:253], v[86:87], v[214:215], v[252:253] op_sel_hi:[1,0,1] neg_lo:[1,0,0] neg_hi:[1,0,0]
	ds_read_b128 v[212:215], v20 offset:54448
	v_pk_fma_f32 v[252:253], v[90:91], v[216:217], v[252:253] op_sel_hi:[1,0,1] neg_lo:[1,0,0] neg_hi:[1,0,0]
	v_pk_mul_f32 v[142:143], v[128:129], v[142:143] op_sel_hi:[1,0]
	v_pk_fma_f32 v[252:253], v[94:95], v[218:219], v[252:253] op_sel_hi:[1,0,1] neg_lo:[1,0,0] neg_hi:[1,0,0]
	ds_read_b128 v[216:219], v20 offset:54464
	v_pk_fma_f32 v[252:253], v[98:99], v[220:221], v[252:253] op_sel_hi:[1,0,1] neg_lo:[1,0,0] neg_hi:[1,0,0]
	v_pk_fma_f32 v[114:115], v[114:115], v[140:141], v[142:143] neg_lo:[0,0,1] neg_hi:[0,0,1]
	v_pk_fma_f32 v[252:253], v[102:103], v[222:223], v[252:253] op_sel_hi:[1,0,1] neg_lo:[1,0,0] neg_hi:[1,0,0]
	ds_read_b128 v[220:223], v20 offset:54480
	v_pk_fma_f32 v[252:253], v[106:107], v[224:225], v[252:253] op_sel_hi:[1,0,1] neg_lo:[1,0,0] neg_hi:[1,0,0]
	v_pk_fma_f32 v[162:163], v[134:135], v[144:145], v[162:163] op_sel:[0,1,0] neg_lo:[1,0,0] neg_hi:[1,0,0]
	v_pk_fma_f32 v[252:253], v[226:227], v[110:111], v[252:253] op_sel_hi:[0,1,1] neg_lo:[1,0,0] neg_hi:[1,0,0]
	ds_read_b128 v[224:227], v20 offset:54496
	v_pk_add_f32 v[112:113], v[252:253], v[112:113]
	v_pk_fma_f32 v[114:115], v[136:137], v[144:145], v[114:115] op_sel_hi:[1,0,1] neg_lo:[1,0,0] neg_hi:[1,0,0]
	v_pk_fma_f32 v[162:163], v[130:131], v[146:147], v[162:163] op_sel:[0,1,0] neg_lo:[1,0,0] neg_hi:[1,0,0]
	v_pk_fma_f32 v[114:115], v[132:133], v[146:147], v[114:115] op_sel_hi:[1,0,1] neg_lo:[1,0,0] neg_hi:[1,0,0]
	v_pk_fma_f32 v[162:163], v[84:85], v[148:149], v[162:163] op_sel:[0,1,0] neg_lo:[1,0,0] neg_hi:[1,0,0]
	v_pk_fma_f32 v[114:115], v[122:123], v[148:149], v[114:115] op_sel_hi:[1,0,1] neg_lo:[1,0,0] neg_hi:[1,0,0]
	ds_read_b128 v[140:143], v20 offset:54528
	v_pk_fma_f32 v[162:163], v[10:11], v[150:151], v[162:163] op_sel:[0,1,0] neg_lo:[1,0,0] neg_hi:[1,0,0]
	ds_read_b128 v[144:147], v20 offset:54544
	v_pk_fma_f32 v[114:115], v[14:15], v[150:151], v[114:115] op_sel_hi:[1,0,1] neg_lo:[1,0,0] neg_hi:[1,0,0]
	ds_read_b128 v[148:151], v20 offset:54560
	v_pk_fma_f32 v[162:163], v[6:7], v[152:153], v[162:163] op_sel:[0,1,0] neg_lo:[1,0,0] neg_hi:[1,0,0]
	v_pk_fma_f32 v[114:115], v[16:17], v[152:153], v[114:115] op_sel_hi:[1,0,1] neg_lo:[1,0,0] neg_hi:[1,0,0]
	v_pk_fma_f32 v[162:163], v[12:13], v[154:155], v[162:163] op_sel:[0,1,0] neg_lo:[1,0,0] neg_hi:[1,0,0]
	v_pk_fma_f32 v[114:115], v[18:19], v[154:155], v[114:115] op_sel_hi:[1,0,1] neg_lo:[1,0,0] neg_hi:[1,0,0]
	ds_read_b128 v[152:155], v20 offset:54576
	v_pk_fma_f32 v[162:163], v[4:5], v[156:157], v[162:163] op_sel:[0,1,0] neg_lo:[1,0,0] neg_hi:[1,0,0]
	v_pk_fma_f32 v[114:115], v[8:9], v[156:157], v[114:115] op_sel_hi:[1,0,1] neg_lo:[1,0,0] neg_hi:[1,0,0]
	v_pk_fma_f32 v[162:163], v[0:1], v[158:159], v[162:163] op_sel:[0,1,0] neg_lo:[1,0,0] neg_hi:[1,0,0]
	v_pk_fma_f32 v[114:115], v[2:3], v[158:159], v[114:115] op_sel_hi:[1,0,1] neg_lo:[1,0,0] neg_hi:[1,0,0]
	ds_read_b128 v[156:159], v20 offset:54592
	v_pk_fma_f32 v[162:163], v[28:29], v[160:161], v[162:163] op_sel:[0,1,0] neg_lo:[1,0,0] neg_hi:[1,0,0]
	v_pk_fma_f32 v[114:115], v[30:31], v[160:161], v[114:115] op_sel_hi:[1,0,1] neg_lo:[1,0,0] neg_hi:[1,0,0]
	v_pk_fma_f32 v[162:163], v[34:35], v[166:167], v[162:163] op_sel:[0,1,0] neg_lo:[1,0,0] neg_hi:[1,0,0]
	v_pk_fma_f32 v[114:115], v[32:33], v[166:167], v[114:115] op_sel_hi:[1,0,1] neg_lo:[1,0,0] neg_hi:[1,0,0]
	v_pk_fma_f32 v[162:163], v[40:41], v[168:169], v[162:163] op_sel:[0,1,0] neg_lo:[1,0,0] neg_hi:[1,0,0]
	v_pk_fma_f32 v[114:115], v[36:37], v[168:169], v[114:115] op_sel_hi:[1,0,1] neg_lo:[1,0,0] neg_hi:[1,0,0]
	ds_read_b128 v[166:169], v20 offset:54624
	v_pk_fma_f32 v[162:163], v[42:43], v[170:171], v[162:163] op_sel:[0,1,0] neg_lo:[1,0,0] neg_hi:[1,0,0]
	v_pk_fma_f32 v[114:115], v[38:39], v[170:171], v[114:115] op_sel_hi:[1,0,1] neg_lo:[1,0,0] neg_hi:[1,0,0]
	v_pk_fma_f32 v[162:163], v[46:47], v[172:173], v[162:163] op_sel:[0,1,0] neg_lo:[1,0,0] neg_hi:[1,0,0]
	v_pk_fma_f32 v[114:115], v[44:45], v[172:173], v[114:115] op_sel_hi:[1,0,1] neg_lo:[1,0,0] neg_hi:[1,0,0]
	ds_read_b128 v[170:173], v20 offset:54640
	v_pk_fma_f32 v[162:163], v[50:51], v[174:175], v[162:163] op_sel:[0,1,0] neg_lo:[1,0,0] neg_hi:[1,0,0]
	v_pk_fma_f32 v[114:115], v[48:49], v[174:175], v[114:115] op_sel_hi:[1,0,1] neg_lo:[1,0,0] neg_hi:[1,0,0]
	v_pk_fma_f32 v[162:163], v[54:55], v[176:177], v[162:163] op_sel:[0,1,0] neg_lo:[1,0,0] neg_hi:[1,0,0]
	v_pk_fma_f32 v[114:115], v[52:53], v[176:177], v[114:115] op_sel_hi:[1,0,1] neg_lo:[1,0,0] neg_hi:[1,0,0]
	ds_read_b128 v[174:177], v20 offset:54656
	v_pk_fma_f32 v[162:163], v[58:59], v[178:179], v[162:163] op_sel:[0,1,0] neg_lo:[1,0,0] neg_hi:[1,0,0]
	v_pk_fma_f32 v[114:115], v[56:57], v[178:179], v[114:115] op_sel_hi:[1,0,1] neg_lo:[1,0,0] neg_hi:[1,0,0]
	v_pk_fma_f32 v[162:163], v[62:63], v[180:181], v[162:163] op_sel:[0,1,0] neg_lo:[1,0,0] neg_hi:[1,0,0]
	v_pk_fma_f32 v[114:115], v[60:61], v[180:181], v[114:115] op_sel_hi:[1,0,1] neg_lo:[1,0,0] neg_hi:[1,0,0]
	ds_read_b128 v[178:181], v20 offset:54672
	v_pk_fma_f32 v[162:163], v[66:67], v[182:183], v[162:163] op_sel:[0,1,0] neg_lo:[1,0,0] neg_hi:[1,0,0]
	v_pk_fma_f32 v[114:115], v[64:65], v[182:183], v[114:115] op_sel_hi:[1,0,1] neg_lo:[1,0,0] neg_hi:[1,0,0]
	v_pk_fma_f32 v[162:163], v[70:71], v[184:185], v[162:163] op_sel:[0,1,0] neg_lo:[1,0,0] neg_hi:[1,0,0]
	v_pk_fma_f32 v[114:115], v[68:69], v[184:185], v[114:115] op_sel_hi:[1,0,1] neg_lo:[1,0,0] neg_hi:[1,0,0]
	ds_read_b128 v[182:185], v20 offset:54688
	v_pk_fma_f32 v[162:163], v[74:75], v[208:209], v[162:163] op_sel:[0,1,0] neg_lo:[1,0,0] neg_hi:[1,0,0]
	v_pk_fma_f32 v[114:115], v[72:73], v[208:209], v[114:115] op_sel_hi:[1,0,1] neg_lo:[1,0,0] neg_hi:[1,0,0]
	v_pk_fma_f32 v[162:163], v[78:79], v[210:211], v[162:163] op_sel:[0,1,0] neg_lo:[1,0,0] neg_hi:[1,0,0]
	v_pk_fma_f32 v[114:115], v[76:77], v[210:211], v[114:115] op_sel_hi:[1,0,1] neg_lo:[1,0,0] neg_hi:[1,0,0]
	ds_read_b128 v[208:211], v20 offset:54704
	s_waitcnt lgkmcnt(14)
	v_pk_fma_f32 v[162:163], v[82:83], v[212:213], v[162:163] op_sel:[0,1,0] neg_lo:[1,0,0] neg_hi:[1,0,0]
	v_pk_fma_f32 v[114:115], v[80:81], v[212:213], v[114:115] op_sel_hi:[1,0,1] neg_lo:[1,0,0] neg_hi:[1,0,0]
	v_pk_fma_f32 v[162:163], v[88:89], v[214:215], v[162:163] op_sel:[0,1,0] neg_lo:[1,0,0] neg_hi:[1,0,0]
	v_pk_fma_f32 v[114:115], v[86:87], v[214:215], v[114:115] op_sel_hi:[1,0,1] neg_lo:[1,0,0] neg_hi:[1,0,0]
	ds_read_b128 v[212:215], v20 offset:54720
	s_waitcnt lgkmcnt(14)
	v_pk_fma_f32 v[162:163], v[92:93], v[216:217], v[162:163] op_sel:[0,1,0] neg_lo:[1,0,0] neg_hi:[1,0,0]
	v_pk_fma_f32 v[114:115], v[90:91], v[216:217], v[114:115] op_sel_hi:[1,0,1] neg_lo:[1,0,0] neg_hi:[1,0,0]
	v_pk_fma_f32 v[162:163], v[96:97], v[218:219], v[162:163] op_sel:[0,1,0] neg_lo:[1,0,0] neg_hi:[1,0,0]
	v_pk_fma_f32 v[114:115], v[94:95], v[218:219], v[114:115] op_sel_hi:[1,0,1] neg_lo:[1,0,0] neg_hi:[1,0,0]
	ds_read_b128 v[216:219], v20 offset:54736
	s_waitcnt lgkmcnt(14)
	v_pk_fma_f32 v[162:163], v[100:101], v[220:221], v[162:163] op_sel:[0,1,0] neg_lo:[1,0,0] neg_hi:[1,0,0]
	v_pk_fma_f32 v[114:115], v[98:99], v[220:221], v[114:115] op_sel_hi:[1,0,1] neg_lo:[1,0,0] neg_hi:[1,0,0]
	v_pk_fma_f32 v[162:163], v[104:105], v[222:223], v[162:163] op_sel:[0,1,0] neg_lo:[1,0,0] neg_hi:[1,0,0]
	v_pk_fma_f32 v[114:115], v[102:103], v[222:223], v[114:115] op_sel_hi:[1,0,1] neg_lo:[1,0,0] neg_hi:[1,0,0]
	ds_read_b128 v[220:223], v20 offset:54752
	s_waitcnt lgkmcnt(14)
	v_pk_fma_f32 v[162:163], v[108:109], v[224:225], v[162:163] op_sel:[0,1,0] neg_lo:[1,0,0] neg_hi:[1,0,0]
	v_pk_fma_f32 v[114:115], v[106:107], v[224:225], v[114:115] op_sel_hi:[1,0,1] neg_lo:[1,0,0] neg_hi:[1,0,0]
	v_pk_fma_f32 v[162:163], v[226:227], v[112:113], v[162:163] op_sel:[1,0,0] neg_lo:[1,0,0] neg_hi:[1,0,0]
	v_pk_fma_f32 v[114:115], v[110:111], v[226:227], v[114:115] op_sel_hi:[1,0,1] neg_lo:[1,0,0] neg_hi:[1,0,0]
	ds_read_b128 v[224:227], v20 offset:54768
	v_pk_add_f32 v[114:115], v[114:115], v[162:163]
	s_waitcnt lgkmcnt(14)
	v_pk_fma_f32 v[186:187], v[138:139], v[140:141], 0 op_sel:[0,1,0] op_sel_hi:[1,1,0] neg_lo:[1,0,0] neg_hi:[1,0,0]
	ds_read_b128 v[160:163], v20 offset:54608
	v_pk_fma_f32 v[186:187], v[134:135], v[142:143], v[186:187] op_sel:[0,1,0] neg_lo:[1,0,0] neg_hi:[1,0,0]
	v_pk_fma_f32 v[252:253], v[128:129], v[140:141], v[116:117] op_sel_hi:[1,0,1] neg_lo:[1,0,0] neg_hi:[1,0,0]
	s_waitcnt lgkmcnt(14)
	v_pk_fma_f32 v[186:187], v[130:131], v[144:145], v[186:187] op_sel:[0,1,0] neg_lo:[1,0,0] neg_hi:[1,0,0]
	v_pk_fma_f32 v[252:253], v[136:137], v[142:143], v[252:253] op_sel_hi:[1,0,1] neg_lo:[1,0,0] neg_hi:[1,0,0]
	v_pk_fma_f32 v[186:187], v[84:85], v[146:147], v[186:187] op_sel:[0,1,0] neg_lo:[1,0,0] neg_hi:[1,0,0]
	ds_read_b128 v[140:143], v20 offset:54784
	s_waitcnt lgkmcnt(14)
	v_pk_fma_f32 v[186:187], v[10:11], v[148:149], v[186:187] op_sel:[0,1,0] neg_lo:[1,0,0] neg_hi:[1,0,0]
	v_pk_fma_f32 v[252:253], v[132:133], v[144:145], v[252:253] op_sel_hi:[1,0,1] neg_lo:[1,0,0] neg_hi:[1,0,0]
	v_pk_fma_f32 v[186:187], v[6:7], v[150:151], v[186:187] op_sel:[0,1,0] neg_lo:[1,0,0] neg_hi:[1,0,0]
	v_pk_fma_f32 v[252:253], v[122:123], v[146:147], v[252:253] op_sel_hi:[1,0,1] neg_lo:[1,0,0] neg_hi:[1,0,0]
	s_waitcnt lgkmcnt(13)
	v_pk_fma_f32 v[186:187], v[12:13], v[152:153], v[186:187] op_sel:[0,1,0] neg_lo:[1,0,0] neg_hi:[1,0,0]
	ds_read_b128 v[144:147], v20 offset:54800
	v_pk_fma_f32 v[186:187], v[4:5], v[154:155], v[186:187] op_sel:[0,1,0] neg_lo:[1,0,0] neg_hi:[1,0,0]
	v_pk_fma_f32 v[252:253], v[14:15], v[148:149], v[252:253] op_sel_hi:[1,0,1] neg_lo:[1,0,0] neg_hi:[1,0,0]
	s_waitcnt lgkmcnt(13)
	v_pk_fma_f32 v[186:187], v[0:1], v[156:157], v[186:187] op_sel:[0,1,0] neg_lo:[1,0,0] neg_hi:[1,0,0]
	v_pk_fma_f32 v[252:253], v[16:17], v[150:151], v[252:253] op_sel_hi:[1,0,1] neg_lo:[1,0,0] neg_hi:[1,0,0]
	v_pk_fma_f32 v[186:187], v[28:29], v[158:159], v[186:187] op_sel:[0,1,0] neg_lo:[1,0,0] neg_hi:[1,0,0]
	ds_read_b128 v[148:151], v20 offset:54816
	s_waitcnt lgkmcnt(3)
	v_pk_fma_f32 v[186:187], v[34:35], v[160:161], v[186:187] op_sel:[0,1,0] neg_lo:[1,0,0] neg_hi:[1,0,0]
	v_pk_fma_f32 v[252:253], v[18:19], v[152:153], v[252:253] op_sel_hi:[1,0,1] neg_lo:[1,0,0] neg_hi:[1,0,0]
	v_pk_fma_f32 v[186:187], v[40:41], v[162:163], v[186:187] op_sel:[0,1,0] neg_lo:[1,0,0] neg_hi:[1,0,0]
	v_pk_fma_f32 v[252:253], v[8:9], v[154:155], v[252:253] op_sel_hi:[1,0,1] neg_lo:[1,0,0] neg_hi:[1,0,0]
	v_pk_fma_f32 v[186:187], v[42:43], v[166:167], v[186:187] op_sel:[0,1,0] neg_lo:[1,0,0] neg_hi:[1,0,0]
	ds_read_b128 v[152:155], v20 offset:54832
	v_pk_fma_f32 v[186:187], v[46:47], v[168:169], v[186:187] op_sel:[0,1,0] neg_lo:[1,0,0] neg_hi:[1,0,0]
	v_pk_fma_f32 v[252:253], v[2:3], v[156:157], v[252:253] op_sel_hi:[1,0,1] neg_lo:[1,0,0] neg_hi:[1,0,0]
	v_pk_fma_f32 v[186:187], v[50:51], v[170:171], v[186:187] op_sel:[0,1,0] neg_lo:[1,0,0] neg_hi:[1,0,0]
	v_pk_fma_f32 v[252:253], v[30:31], v[158:159], v[252:253] op_sel_hi:[1,0,1] neg_lo:[1,0,0] neg_hi:[1,0,0]
	v_pk_fma_f32 v[186:187], v[54:55], v[172:173], v[186:187] op_sel:[0,1,0] neg_lo:[1,0,0] neg_hi:[1,0,0]
	ds_read_b128 v[156:159], v20 offset:54848
	v_pk_fma_f32 v[186:187], v[58:59], v[174:175], v[186:187] op_sel:[0,1,0] neg_lo:[1,0,0] neg_hi:[1,0,0]
	v_pk_fma_f32 v[252:253], v[32:33], v[160:161], v[252:253] op_sel_hi:[1,0,1] neg_lo:[1,0,0] neg_hi:[1,0,0]
	v_pk_fma_f32 v[186:187], v[62:63], v[176:177], v[186:187] op_sel:[0,1,0] neg_lo:[1,0,0] neg_hi:[1,0,0]
	v_pk_fma_f32 v[252:253], v[36:37], v[162:163], v[252:253] op_sel_hi:[1,0,1] neg_lo:[1,0,0] neg_hi:[1,0,0]
	v_pk_fma_f32 v[186:187], v[66:67], v[178:179], v[186:187] op_sel:[0,1,0] neg_lo:[1,0,0] neg_hi:[1,0,0]
	ds_read_b128 v[160:163], v20 offset:54864
	v_pk_fma_f32 v[186:187], v[70:71], v[180:181], v[186:187] op_sel:[0,1,0] neg_lo:[1,0,0] neg_hi:[1,0,0]
	v_pk_fma_f32 v[252:253], v[38:39], v[166:167], v[252:253] op_sel_hi:[1,0,1] neg_lo:[1,0,0] neg_hi:[1,0,0]
	v_pk_fma_f32 v[186:187], v[74:75], v[182:183], v[186:187] op_sel:[0,1,0] neg_lo:[1,0,0] neg_hi:[1,0,0]
	v_pk_fma_f32 v[252:253], v[44:45], v[168:169], v[252:253] op_sel_hi:[1,0,1] neg_lo:[1,0,0] neg_hi:[1,0,0]
	v_pk_fma_f32 v[186:187], v[78:79], v[184:185], v[186:187] op_sel:[0,1,0] neg_lo:[1,0,0] neg_hi:[1,0,0]
	ds_read_b128 v[166:169], v20 offset:54880
	v_pk_fma_f32 v[186:187], v[82:83], v[208:209], v[186:187] op_sel:[0,1,0] neg_lo:[1,0,0] neg_hi:[1,0,0]
	v_pk_fma_f32 v[252:253], v[48:49], v[170:171], v[252:253] op_sel_hi:[1,0,1] neg_lo:[1,0,0] neg_hi:[1,0,0]
	v_pk_fma_f32 v[186:187], v[88:89], v[210:211], v[186:187] op_sel:[0,1,0] neg_lo:[1,0,0] neg_hi:[1,0,0]
	v_pk_fma_f32 v[252:253], v[52:53], v[172:173], v[252:253] op_sel_hi:[1,0,1] neg_lo:[1,0,0] neg_hi:[1,0,0]
	v_pk_fma_f32 v[186:187], v[92:93], v[212:213], v[186:187] op_sel:[0,1,0] neg_lo:[1,0,0] neg_hi:[1,0,0]
	ds_read_b128 v[170:173], v20 offset:54896
	v_pk_fma_f32 v[186:187], v[96:97], v[214:215], v[186:187] op_sel:[0,1,0] neg_lo:[1,0,0] neg_hi:[1,0,0]
	v_pk_fma_f32 v[252:253], v[56:57], v[174:175], v[252:253] op_sel_hi:[1,0,1] neg_lo:[1,0,0] neg_hi:[1,0,0]
	v_pk_fma_f32 v[186:187], v[100:101], v[216:217], v[186:187] op_sel:[0,1,0] neg_lo:[1,0,0] neg_hi:[1,0,0]
	v_pk_fma_f32 v[252:253], v[60:61], v[176:177], v[252:253] op_sel_hi:[1,0,1] neg_lo:[1,0,0] neg_hi:[1,0,0]
	ds_read_b128 v[174:177], v20 offset:54912
	v_pk_fma_f32 v[186:187], v[104:105], v[218:219], v[186:187] op_sel:[0,1,0] neg_lo:[1,0,0] neg_hi:[1,0,0]
	v_pk_fma_f32 v[252:253], v[64:65], v[178:179], v[252:253] op_sel_hi:[1,0,1] neg_lo:[1,0,0] neg_hi:[1,0,0]
	v_pk_fma_f32 v[186:187], v[108:109], v[220:221], v[186:187] op_sel:[0,1,0] neg_lo:[1,0,0] neg_hi:[1,0,0]
	v_pk_fma_f32 v[252:253], v[68:69], v[180:181], v[252:253] op_sel_hi:[1,0,1] neg_lo:[1,0,0] neg_hi:[1,0,0]
	ds_read_b128 v[178:181], v20 offset:54928
	v_pk_fma_f32 v[186:187], v[112:113], v[222:223], v[186:187] op_sel:[0,1,0] neg_lo:[1,0,0] neg_hi:[1,0,0]
	v_pk_fma_f32 v[252:253], v[72:73], v[182:183], v[252:253] op_sel_hi:[1,0,1] neg_lo:[1,0,0] neg_hi:[1,0,0]
	v_pk_fma_f32 v[186:187], v[116:117], v[224:225], v[186:187] op_sel:[0,1,0] neg_lo:[1,0,0] neg_hi:[1,0,0]
	v_pk_fma_f32 v[252:253], v[76:77], v[184:185], v[252:253] op_sel_hi:[1,0,1] neg_lo:[1,0,0] neg_hi:[1,0,0]
	ds_read_b128 v[182:185], v20 offset:54944
	v_pk_fma_f32 v[186:187], v[120:121], v[226:227], v[186:187] op_sel:[0,1,0] neg_lo:[1,0,0] neg_hi:[1,0,0]
	v_pk_fma_f32 v[252:253], v[80:81], v[208:209], v[252:253] op_sel_hi:[1,0,1] neg_lo:[1,0,0] neg_hi:[1,0,0]
	s_nop 0
	v_pk_fma_f32 v[252:253], v[86:87], v[210:211], v[252:253] op_sel_hi:[1,0,1] neg_lo:[1,0,0] neg_hi:[1,0,0]
	ds_read_b128 v[208:211], v20 offset:54960
	v_pk_fma_f32 v[252:253], v[90:91], v[212:213], v[252:253] op_sel_hi:[1,0,1] neg_lo:[1,0,0] neg_hi:[1,0,0]
	s_nop 0
	v_pk_fma_f32 v[252:253], v[94:95], v[214:215], v[252:253] op_sel_hi:[1,0,1] neg_lo:[1,0,0] neg_hi:[1,0,0]
	ds_read_b128 v[212:215], v20 offset:54976
	v_pk_fma_f32 v[252:253], v[98:99], v[216:217], v[252:253] op_sel_hi:[1,0,1] neg_lo:[1,0,0] neg_hi:[1,0,0]
	s_nop 0
	v_pk_fma_f32 v[252:253], v[102:103], v[218:219], v[252:253] op_sel_hi:[1,0,1] neg_lo:[1,0,0] neg_hi:[1,0,0]
	ds_read_b128 v[216:219], v20 offset:54992
	v_pk_fma_f32 v[252:253], v[106:107], v[220:221], v[252:253] op_sel_hi:[1,0,1] neg_lo:[1,0,0] neg_hi:[1,0,0]
	s_nop 0
	v_pk_fma_f32 v[252:253], v[110:111], v[222:223], v[252:253] op_sel_hi:[1,0,1] neg_lo:[1,0,0] neg_hi:[1,0,0]
	ds_read_b128 v[220:223], v20 offset:55008
	v_pk_fma_f32 v[252:253], v[224:225], v[114:115], v[252:253] op_sel_hi:[0,1,1] neg_lo:[1,0,0] neg_hi:[1,0,0]
	s_nop 0
	v_pk_fma_f32 v[252:253], v[118:119], v[226:227], v[252:253] op_sel_hi:[1,0,1] neg_lo:[1,0,0] neg_hi:[1,0,0]
	s_nop 0
	v_pk_add_f32 v[116:117], v[252:253], v[186:187]
	s_waitcnt lgkmcnt(14)
	v_pk_fma_f32 v[186:187], v[138:139], v[140:141], 0 op_sel:[0,1,0] op_sel_hi:[1,1,0] neg_lo:[1,0,0] neg_hi:[1,0,0]
	ds_read_b128 v[224:227], v20 offset:55024
	v_pk_fma_f32 v[140:141], v[128:129], v[140:141], v[118:119] op_sel_hi:[1,0,1] neg_lo:[1,0,0] neg_hi:[1,0,0]
	v_pk_fma_f32 v[186:187], v[134:135], v[142:143], v[186:187] op_sel:[0,1,0] neg_lo:[1,0,0] neg_hi:[1,0,0]
	v_pk_fma_f32 v[140:141], v[136:137], v[142:143], v[140:141] op_sel_hi:[1,0,1] neg_lo:[1,0,0] neg_hi:[1,0,0]
	s_waitcnt lgkmcnt(14)
	v_pk_fma_f32 v[186:187], v[130:131], v[144:145], v[186:187] op_sel:[0,1,0] neg_lo:[1,0,0] neg_hi:[1,0,0]
	v_pk_fma_f32 v[140:141], v[132:133], v[144:145], v[140:141] op_sel_hi:[1,0,1] neg_lo:[1,0,0] neg_hi:[1,0,0]
	v_pk_fma_f32 v[186:187], v[84:85], v[146:147], v[186:187] op_sel:[0,1,0] neg_lo:[1,0,0] neg_hi:[1,0,0]
	v_pk_fma_f32 v[140:141], v[122:123], v[146:147], v[140:141] op_sel_hi:[1,0,1] neg_lo:[1,0,0] neg_hi:[1,0,0]
	s_waitcnt lgkmcnt(13)
	v_pk_fma_f32 v[186:187], v[10:11], v[148:149], v[186:187] op_sel:[0,1,0] neg_lo:[1,0,0] neg_hi:[1,0,0]
	v_pk_fma_f32 v[140:141], v[14:15], v[148:149], v[140:141] op_sel_hi:[1,0,1] neg_lo:[1,0,0] neg_hi:[1,0,0]
	v_pk_fma_f32 v[186:187], v[6:7], v[150:151], v[186:187] op_sel:[0,1,0] neg_lo:[1,0,0] neg_hi:[1,0,0]
	v_pk_fma_f32 v[140:141], v[16:17], v[150:151], v[140:141] op_sel_hi:[1,0,1] neg_lo:[1,0,0] neg_hi:[1,0,0]
	ds_read_b128 v[144:147], v20 offset:55056
	ds_read_b128 v[148:151], v20 offset:55072
	s_waitcnt lgkmcnt(14)
	v_pk_fma_f32 v[186:187], v[12:13], v[152:153], v[186:187] op_sel:[0,1,0] neg_lo:[1,0,0] neg_hi:[1,0,0]
	v_pk_fma_f32 v[140:141], v[18:19], v[152:153], v[140:141] op_sel_hi:[1,0,1] neg_lo:[1,0,0] neg_hi:[1,0,0]
	v_pk_fma_f32 v[186:187], v[4:5], v[154:155], v[186:187] op_sel:[0,1,0] neg_lo:[1,0,0] neg_hi:[1,0,0]
	v_pk_fma_f32 v[140:141], v[8:9], v[154:155], v[140:141] op_sel_hi:[1,0,1] neg_lo:[1,0,0] neg_hi:[1,0,0]
	ds_read_b128 v[152:155], v20 offset:55088
	s_waitcnt lgkmcnt(14)
	v_pk_fma_f32 v[186:187], v[0:1], v[156:157], v[186:187] op_sel:[0,1,0] neg_lo:[1,0,0] neg_hi:[1,0,0]
	v_pk_fma_f32 v[140:141], v[2:3], v[156:157], v[140:141] op_sel_hi:[1,0,1] neg_lo:[1,0,0] neg_hi:[1,0,0]
	v_pk_fma_f32 v[186:187], v[28:29], v[158:159], v[186:187] op_sel:[0,1,0] neg_lo:[1,0,0] neg_hi:[1,0,0]
	v_pk_fma_f32 v[140:141], v[30:31], v[158:159], v[140:141] op_sel_hi:[1,0,1] neg_lo:[1,0,0] neg_hi:[1,0,0]
	ds_read_b128 v[156:159], v20 offset:55104
	s_waitcnt lgkmcnt(14)
	v_pk_fma_f32 v[186:187], v[34:35], v[160:161], v[186:187] op_sel:[0,1,0] neg_lo:[1,0,0] neg_hi:[1,0,0]
	v_pk_fma_f32 v[140:141], v[32:33], v[160:161], v[140:141] op_sel_hi:[1,0,1] neg_lo:[1,0,0] neg_hi:[1,0,0]
	v_pk_fma_f32 v[186:187], v[40:41], v[162:163], v[186:187] op_sel:[0,1,0] neg_lo:[1,0,0] neg_hi:[1,0,0]
	v_pk_fma_f32 v[140:141], v[36:37], v[162:163], v[140:141] op_sel_hi:[1,0,1] neg_lo:[1,0,0] neg_hi:[1,0,0]
	ds_read_b128 v[160:163], v20 offset:55120
	s_waitcnt lgkmcnt(14)
	v_pk_fma_f32 v[186:187], v[42:43], v[166:167], v[186:187] op_sel:[0,1,0] neg_lo:[1,0,0] neg_hi:[1,0,0]
	v_pk_fma_f32 v[140:141], v[38:39], v[166:167], v[140:141] op_sel_hi:[1,0,1] neg_lo:[1,0,0] neg_hi:[1,0,0]
	v_pk_fma_f32 v[186:187], v[46:47], v[168:169], v[186:187] op_sel:[0,1,0] neg_lo:[1,0,0] neg_hi:[1,0,0]
	v_pk_fma_f32 v[140:141], v[44:45], v[168:169], v[140:141] op_sel_hi:[1,0,1] neg_lo:[1,0,0] neg_hi:[1,0,0]
	ds_read_b128 v[166:169], v20 offset:55136
	s_waitcnt lgkmcnt(14)
	v_pk_fma_f32 v[186:187], v[50:51], v[170:171], v[186:187] op_sel:[0,1,0] neg_lo:[1,0,0] neg_hi:[1,0,0]
	v_pk_fma_f32 v[140:141], v[48:49], v[170:171], v[140:141] op_sel_hi:[1,0,1] neg_lo:[1,0,0] neg_hi:[1,0,0]
	v_pk_fma_f32 v[186:187], v[54:55], v[172:173], v[186:187] op_sel:[0,1,0] neg_lo:[1,0,0] neg_hi:[1,0,0]
	v_pk_fma_f32 v[140:141], v[52:53], v[172:173], v[140:141] op_sel_hi:[1,0,1] neg_lo:[1,0,0] neg_hi:[1,0,0]
	ds_read_b128 v[170:173], v20 offset:55152
	s_waitcnt lgkmcnt(14)
	v_pk_fma_f32 v[186:187], v[58:59], v[174:175], v[186:187] op_sel:[0,1,0] neg_lo:[1,0,0] neg_hi:[1,0,0]
	v_pk_fma_f32 v[140:141], v[56:57], v[174:175], v[140:141] op_sel_hi:[1,0,1] neg_lo:[1,0,0] neg_hi:[1,0,0]
	v_pk_fma_f32 v[186:187], v[62:63], v[176:177], v[186:187] op_sel:[0,1,0] neg_lo:[1,0,0] neg_hi:[1,0,0]
	v_pk_fma_f32 v[140:141], v[60:61], v[176:177], v[140:141] op_sel_hi:[1,0,1] neg_lo:[1,0,0] neg_hi:[1,0,0]
	ds_read_b128 v[174:177], v20 offset:55168
	s_waitcnt lgkmcnt(14)
	v_pk_fma_f32 v[186:187], v[66:67], v[178:179], v[186:187] op_sel:[0,1,0] neg_lo:[1,0,0] neg_hi:[1,0,0]
	v_pk_fma_f32 v[140:141], v[64:65], v[178:179], v[140:141] op_sel_hi:[1,0,1] neg_lo:[1,0,0] neg_hi:[1,0,0]
	v_pk_fma_f32 v[186:187], v[70:71], v[180:181], v[186:187] op_sel:[0,1,0] neg_lo:[1,0,0] neg_hi:[1,0,0]
	v_pk_fma_f32 v[140:141], v[68:69], v[180:181], v[140:141] op_sel_hi:[1,0,1] neg_lo:[1,0,0] neg_hi:[1,0,0]
	ds_read_b128 v[178:181], v20 offset:55184
	s_waitcnt lgkmcnt(14)
	v_pk_fma_f32 v[186:187], v[74:75], v[182:183], v[186:187] op_sel:[0,1,0] neg_lo:[1,0,0] neg_hi:[1,0,0]
	v_pk_fma_f32 v[140:141], v[72:73], v[182:183], v[140:141] op_sel_hi:[1,0,1] neg_lo:[1,0,0] neg_hi:[1,0,0]
	v_pk_fma_f32 v[186:187], v[78:79], v[184:185], v[186:187] op_sel:[0,1,0] neg_lo:[1,0,0] neg_hi:[1,0,0]
	v_pk_fma_f32 v[140:141], v[76:77], v[184:185], v[140:141] op_sel_hi:[1,0,1] neg_lo:[1,0,0] neg_hi:[1,0,0]
	ds_read_b128 v[182:185], v20 offset:55200
	s_waitcnt lgkmcnt(14)
	v_pk_fma_f32 v[186:187], v[82:83], v[208:209], v[186:187] op_sel:[0,1,0] neg_lo:[1,0,0] neg_hi:[1,0,0]
	v_pk_fma_f32 v[140:141], v[80:81], v[208:209], v[140:141] op_sel_hi:[1,0,1] neg_lo:[1,0,0] neg_hi:[1,0,0]
	v_pk_fma_f32 v[186:187], v[88:89], v[210:211], v[186:187] op_sel:[0,1,0] neg_lo:[1,0,0] neg_hi:[1,0,0]
	v_pk_fma_f32 v[140:141], v[86:87], v[210:211], v[140:141] op_sel_hi:[1,0,1] neg_lo:[1,0,0] neg_hi:[1,0,0]
	ds_read_b128 v[208:211], v20 offset:55216
	s_waitcnt lgkmcnt(14)
	v_pk_fma_f32 v[186:187], v[92:93], v[212:213], v[186:187] op_sel:[0,1,0] neg_lo:[1,0,0] neg_hi:[1,0,0]
	v_pk_fma_f32 v[140:141], v[90:91], v[212:213], v[140:141] op_sel_hi:[1,0,1] neg_lo:[1,0,0] neg_hi:[1,0,0]
	v_pk_fma_f32 v[186:187], v[96:97], v[214:215], v[186:187] op_sel:[0,1,0] neg_lo:[1,0,0] neg_hi:[1,0,0]
	v_pk_fma_f32 v[140:141], v[94:95], v[214:215], v[140:141] op_sel_hi:[1,0,1] neg_lo:[1,0,0] neg_hi:[1,0,0]
	ds_read_b128 v[212:215], v20 offset:55232
	s_waitcnt lgkmcnt(14)
	v_pk_fma_f32 v[186:187], v[100:101], v[216:217], v[186:187] op_sel:[0,1,0] neg_lo:[1,0,0] neg_hi:[1,0,0]
	v_pk_fma_f32 v[140:141], v[98:99], v[216:217], v[140:141] op_sel_hi:[1,0,1] neg_lo:[1,0,0] neg_hi:[1,0,0]
	v_pk_fma_f32 v[186:187], v[104:105], v[218:219], v[186:187] op_sel:[0,1,0] neg_lo:[1,0,0] neg_hi:[1,0,0]
	v_pk_fma_f32 v[140:141], v[102:103], v[218:219], v[140:141] op_sel_hi:[1,0,1] neg_lo:[1,0,0] neg_hi:[1,0,0]
	ds_read_b128 v[216:219], v20 offset:55248
	s_waitcnt lgkmcnt(14)
	v_pk_fma_f32 v[186:187], v[108:109], v[220:221], v[186:187] op_sel:[0,1,0] neg_lo:[1,0,0] neg_hi:[1,0,0]
	v_pk_fma_f32 v[140:141], v[106:107], v[220:221], v[140:141] op_sel_hi:[1,0,1] neg_lo:[1,0,0] neg_hi:[1,0,0]
	v_pk_fma_f32 v[186:187], v[112:113], v[222:223], v[186:187] op_sel:[0,1,0] neg_lo:[1,0,0] neg_hi:[1,0,0]
	v_pk_fma_f32 v[140:141], v[110:111], v[222:223], v[140:141] op_sel_hi:[1,0,1] neg_lo:[1,0,0] neg_hi:[1,0,0]
	ds_read_b128 v[220:223], v20 offset:55264
	s_waitcnt lgkmcnt(14)
	v_pk_fma_f32 v[186:187], v[224:225], v[116:117], v[186:187] op_sel:[1,0,0] neg_lo:[1,0,0] neg_hi:[1,0,0]
	v_pk_fma_f32 v[140:141], v[114:115], v[224:225], v[140:141] op_sel_hi:[1,0,1] neg_lo:[1,0,0] neg_hi:[1,0,0]
	v_pk_fma_f32 v[186:187], v[120:121], v[226:227], v[186:187] op_sel:[0,1,0] neg_lo:[1,0,0] neg_hi:[1,0,0]
	v_pk_fma_f32 v[118:119], v[118:119], v[226:227], v[140:141] op_sel_hi:[1,0,1] neg_lo:[1,0,0] neg_hi:[1,0,0]
	ds_read_b128 v[140:143], v20 offset:55040
	v_pk_add_f32 v[118:119], v[118:119], v[186:187]
	s_waitcnt lgkmcnt(0)
	v_pk_fma_f32 v[186:187], v[138:139], v[140:141], 0 op_sel:[0,1,0] op_sel_hi:[1,1,0] neg_lo:[1,0,0] neg_hi:[1,0,0]
	ds_read_b128 v[224:227], v20 offset:55280
	v_pk_fma_f32 v[186:187], v[134:135], v[142:143], v[186:187] op_sel:[0,1,0] neg_lo:[1,0,0] neg_hi:[1,0,0]
	s_nop 0
	v_pk_fma_f32 v[186:187], v[130:131], v[144:145], v[186:187] op_sel:[0,1,0] neg_lo:[1,0,0] neg_hi:[1,0,0]
	s_nop 0
	v_pk_fma_f32 v[186:187], v[84:85], v[146:147], v[186:187] op_sel:[0,1,0] neg_lo:[1,0,0] neg_hi:[1,0,0]
	s_nop 0
	v_pk_fma_f32 v[186:187], v[10:11], v[148:149], v[186:187] op_sel:[0,1,0] neg_lo:[1,0,0] neg_hi:[1,0,0]
	s_nop 0
	v_pk_fma_f32 v[186:187], v[6:7], v[150:151], v[186:187] op_sel:[0,1,0] neg_lo:[1,0,0] neg_hi:[1,0,0]
	s_nop 0
	v_pk_fma_f32 v[186:187], v[12:13], v[152:153], v[186:187] op_sel:[0,1,0] neg_lo:[1,0,0] neg_hi:[1,0,0]
	s_nop 0
	v_pk_fma_f32 v[186:187], v[4:5], v[154:155], v[186:187] op_sel:[0,1,0] neg_lo:[1,0,0] neg_hi:[1,0,0]
	s_nop 0
	v_pk_fma_f32 v[186:187], v[0:1], v[156:157], v[186:187] op_sel:[0,1,0] neg_lo:[1,0,0] neg_hi:[1,0,0]
	s_nop 0
	v_pk_fma_f32 v[186:187], v[28:29], v[158:159], v[186:187] op_sel:[0,1,0] neg_lo:[1,0,0] neg_hi:[1,0,0]
	s_nop 0
	v_pk_fma_f32 v[186:187], v[34:35], v[160:161], v[186:187] op_sel:[0,1,0] neg_lo:[1,0,0] neg_hi:[1,0,0]
	s_nop 0
	v_pk_fma_f32 v[186:187], v[40:41], v[162:163], v[186:187] op_sel:[0,1,0] neg_lo:[1,0,0] neg_hi:[1,0,0]
	s_nop 0
	v_pk_fma_f32 v[186:187], v[42:43], v[166:167], v[186:187] op_sel:[0,1,0] neg_lo:[1,0,0] neg_hi:[1,0,0]
	s_nop 0
	v_pk_fma_f32 v[186:187], v[46:47], v[168:169], v[186:187] op_sel:[0,1,0] neg_lo:[1,0,0] neg_hi:[1,0,0]
	s_nop 0
	v_pk_fma_f32 v[186:187], v[50:51], v[170:171], v[186:187] op_sel:[0,1,0] neg_lo:[1,0,0] neg_hi:[1,0,0]
	s_nop 0
	v_pk_fma_f32 v[186:187], v[54:55], v[172:173], v[186:187] op_sel:[0,1,0] neg_lo:[1,0,0] neg_hi:[1,0,0]
	s_nop 0
	v_pk_fma_f32 v[186:187], v[58:59], v[174:175], v[186:187] op_sel:[0,1,0] neg_lo:[1,0,0] neg_hi:[1,0,0]
	s_nop 0
	v_pk_fma_f32 v[186:187], v[62:63], v[176:177], v[186:187] op_sel:[0,1,0] neg_lo:[1,0,0] neg_hi:[1,0,0]
	s_nop 0
	v_pk_fma_f32 v[186:187], v[66:67], v[178:179], v[186:187] op_sel:[0,1,0] neg_lo:[1,0,0] neg_hi:[1,0,0]
	s_nop 0
	v_pk_fma_f32 v[186:187], v[70:71], v[180:181], v[186:187] op_sel:[0,1,0] neg_lo:[1,0,0] neg_hi:[1,0,0]
	s_nop 0
	v_pk_fma_f32 v[186:187], v[74:75], v[182:183], v[186:187] op_sel:[0,1,0] neg_lo:[1,0,0] neg_hi:[1,0,0]
	s_nop 0
	v_pk_fma_f32 v[186:187], v[78:79], v[184:185], v[186:187] op_sel:[0,1,0] neg_lo:[1,0,0] neg_hi:[1,0,0]
	s_nop 0
	v_pk_fma_f32 v[186:187], v[82:83], v[208:209], v[186:187] op_sel:[0,1,0] neg_lo:[1,0,0] neg_hi:[1,0,0]
	s_nop 0
	v_pk_fma_f32 v[186:187], v[88:89], v[210:211], v[186:187] op_sel:[0,1,0] neg_lo:[1,0,0] neg_hi:[1,0,0]
	s_nop 0
	v_pk_fma_f32 v[186:187], v[92:93], v[212:213], v[186:187] op_sel:[0,1,0] neg_lo:[1,0,0] neg_hi:[1,0,0]
	s_nop 0
	v_pk_fma_f32 v[186:187], v[96:97], v[214:215], v[186:187] op_sel:[0,1,0] neg_lo:[1,0,0] neg_hi:[1,0,0]
	s_nop 0
	v_pk_fma_f32 v[186:187], v[100:101], v[216:217], v[186:187] op_sel:[0,1,0] neg_lo:[1,0,0] neg_hi:[1,0,0]
	s_nop 0
	v_pk_fma_f32 v[186:187], v[104:105], v[218:219], v[186:187] op_sel:[0,1,0] neg_lo:[1,0,0] neg_hi:[1,0,0]
	s_nop 0
	v_pk_fma_f32 v[186:187], v[108:109], v[220:221], v[186:187] op_sel:[0,1,0] neg_lo:[1,0,0] neg_hi:[1,0,0]
	s_nop 0
	v_pk_fma_f32 v[186:187], v[112:113], v[222:223], v[186:187] op_sel:[0,1,0] neg_lo:[1,0,0] neg_hi:[1,0,0]
	s_nop 0
	s_waitcnt lgkmcnt(0)
	v_pk_fma_f32 v[186:187], v[116:117], v[224:225], v[186:187] op_sel:[0,1,0] neg_lo:[1,0,0] neg_hi:[1,0,0]
	s_nop 0
	v_pk_fma_f32 v[186:187], v[120:121], v[226:227], v[186:187] op_sel:[0,1,0] neg_lo:[1,0,0] neg_hi:[1,0,0]
	s_waitcnt lgkmcnt(0)
	v_lshlrev_b32_e32 v20, 1, v127
	v_lshl_add_u64 v[124:125], v[124:125], 0, v[20:21]
	v_mov_b32_e32 v127, v21
	v_pk_fma_f32 v[120:121], v[128:129], v[140:141], v[120:121] op_sel_hi:[1,0,1] neg_lo:[1,0,0] neg_hi:[1,0,0]
	v_lshl_add_u64 v[140:141], v[124:125], 0, v[126:127]
	v_lshlrev_b64 v[124:125], 13, v[22:23]
	v_lshl_add_u64 v[124:125], s[20:21], 0, v[124:125]
	v_lshl_add_u64 v[124:125], v[124:125], 0, v[20:21]
	v_lshl_add_u64 v[124:125], v[124:125], 0, v[126:127]
	s_nop 0
	v_and_b32_e32 v236, 1, v164
	v_mov_b32_e32 v237, 0x5040100
	v_mov_b32_e32 v238, 0x3020706
	v_cmp_eq_u32_e32 vcc, 1, v236
	v_mov_b32_e32 v239, 0x5ffe
	v_mov_b32_e32 v240, 0x1ffe
	v_cndmask_b32_e32 v236, v237, v238, vcc
	v_cndmask_b32_e32 v239, 0, v239, vcc
	v_cndmask_b32_e32 v240, 0, v240, vcc
	v_add_co_u32_e32 v232, vcc, v239, v140
	s_nop 1
	v_addc_co_u32_e32 v233, vcc, 0, v141, vcc
	v_add_co_u32_e32 v234, vcc, v240, v124
	s_nop 1
	v_addc_co_u32_e32 v235, vcc, 0, v125, vcc
	v_cvt_pk_bf16_f32 v241, v128, v138
	v_add_co_u32_e32 v244, vcc, 0x2000, v232
	s_nop 0
	v_mov_b32_dpp v242, v241 quad_perm:[1,0,3,2] row_mask:0xf bank_mask:0xf
	v_addc_co_u32_e32 v245, vcc, 0, v233, vcc
	v_perm_b32 v242, v242, v241, v236
	global_store_dword v[244:245], v242, off
	s_nop 0
	v_cvt_pk_bf16_f32 v248, v129, v139
	v_add_co_u32_e32 v246, vcc, 0x0, v234
	s_nop 0
	v_mov_b32_dpp v249, v248 quad_perm:[1,0,3,2] row_mask:0xf bank_mask:0xf
	v_addc_co_u32_e32 v247, vcc, 0, v235, vcc
	v_perm_b32 v249, v249, v248, v236
	global_store_dword v[246:247], v249, off
	s_nop 0
	s_movk_i32 s0, 0x4000
	v_pk_fma_f32 v[120:121], v[136:137], v[142:143], v[120:121] op_sel_hi:[1,0,1] neg_lo:[1,0,0] neg_hi:[1,0,0]
	s_nop 0
	s_nop 0
	v_cvt_pk_bf16_f32 v241, v136, v134
	v_add_co_u32_e32 v244, vcc, 0xe000, v232
	s_nop 0
	v_mov_b32_dpp v242, v241 quad_perm:[1,0,3,2] row_mask:0xf bank_mask:0xf
	v_addc_co_u32_e32 v245, vcc, 0, v233, vcc
	v_perm_b32 v242, v242, v241, v236
	global_store_dword v[244:245], v242, off
	s_nop 0
	v_cvt_pk_bf16_f32 v248, v137, v135
	v_add_co_u32_e32 v246, vcc, 0x4000, v234
	s_nop 0
	v_mov_b32_dpp v249, v248 quad_perm:[1,0,3,2] row_mask:0xf bank_mask:0xf
	v_addc_co_u32_e32 v247, vcc, 0, v235, vcc
	v_perm_b32 v249, v249, v248, v236
	global_store_dword v[246:247], v249, off
	s_nop 0
	s_nop 0
	s_nop 0
	v_cvt_pk_bf16_f32 v241, v132, v130
	v_add_co_u32_e32 v244, vcc, 0x1a000, v232
	s_nop 0
	v_mov_b32_dpp v242, v241 quad_perm:[1,0,3,2] row_mask:0xf bank_mask:0xf
	v_addc_co_u32_e32 v245, vcc, 0, v233, vcc
	v_perm_b32 v242, v242, v241, v236
	global_store_dword v[244:245], v242, off
	s_mov_b32 s0, 0xa000
	v_pk_fma_f32 v[120:121], v[132:133], v[144:145], v[120:121] op_sel_hi:[1,0,1] neg_lo:[1,0,0] neg_hi:[1,0,0]
	s_nop 0
	v_cvt_pk_bf16_f32 v248, v133, v131
	v_add_co_u32_e32 v246, vcc, 0x8000, v234
	s_nop 0
	v_mov_b32_dpp v249, v248 quad_perm:[1,0,3,2] row_mask:0xf bank_mask:0xf
	v_addc_co_u32_e32 v247, vcc, 0, v235, vcc
	v_perm_b32 v249, v249, v248, v236
	global_store_dword v[246:247], v249, off
	v_pk_fma_f32 v[120:121], v[122:123], v[146:147], v[120:121] op_sel_hi:[1,0,1] neg_lo:[1,0,0] neg_hi:[1,0,0]
	s_nop 0
	s_nop 0
	v_cvt_pk_bf16_f32 v241, v122, v84
	v_add_co_u32_e32 v244, vcc, 0x26000, v232
	s_nop 0
	v_mov_b32_dpp v242, v241 quad_perm:[1,0,3,2] row_mask:0xf bank_mask:0xf
	v_addc_co_u32_e32 v245, vcc, 0, v233, vcc
	v_perm_b32 v242, v242, v241, v236
	global_store_dword v[244:245], v242, off
	v_cvt_pk_bf16_f32 v248, v123, v85
	v_add_co_u32_e32 v246, vcc, 0xc000, v234
	s_nop 0
	v_mov_b32_dpp v249, v248 quad_perm:[1,0,3,2] row_mask:0xf bank_mask:0xf
	v_addc_co_u32_e32 v247, vcc, 0, v235, vcc
	v_perm_b32 v249, v249, v248, v236
	global_store_dword v[246:247], v249, off
	v_pk_fma_f32 v[120:121], v[14:15], v[148:149], v[120:121] op_sel_hi:[1,0,1] neg_lo:[1,0,0] neg_hi:[1,0,0]
	s_mov_b32 s0, 0x10000
	s_nop 0
	v_pk_fma_f32 v[120:121], v[16:17], v[150:151], v[120:121] op_sel_hi:[1,0,1] neg_lo:[1,0,0] neg_hi:[1,0,0]
	s_nop 0
	v_cvt_pk_bf16_f32 v241, v14, v10
	v_add_co_u32_e32 v244, vcc, 0x32000, v232
	s_nop 0
	v_mov_b32_dpp v242, v241 quad_perm:[1,0,3,2] row_mask:0xf bank_mask:0xf
	v_addc_co_u32_e32 v245, vcc, 0, v233, vcc
	v_perm_b32 v242, v242, v241, v236
	global_store_dword v[244:245], v242, off
	s_mov_b32 s0, 0x12000
	s_nop 0
	v_cvt_pk_bf16_f32 v248, v15, v11
	v_add_co_u32_e32 v246, vcc, 0x10000, v234
	s_nop 0
	v_mov_b32_dpp v249, v248 quad_perm:[1,0,3,2] row_mask:0xf bank_mask:0xf
	v_addc_co_u32_e32 v247, vcc, 0, v235, vcc
	v_perm_b32 v249, v249, v248, v236
	global_store_dword v[246:247], v249, off
	s_nop 0
	s_nop 0
	v_pk_fma_f32 v[120:121], v[18:19], v[152:153], v[120:121] op_sel_hi:[1,0,1] neg_lo:[1,0,0] neg_hi:[1,0,0]
	s_nop 0
	v_cvt_pk_bf16_f32 v241, v16, v6
	v_add_co_u32_e32 v244, vcc, 0x3e000, v232
	s_nop 0
	v_mov_b32_dpp v242, v241 quad_perm:[1,0,3,2] row_mask:0xf bank_mask:0xf
	v_addc_co_u32_e32 v245, vcc, 0, v233, vcc
	v_perm_b32 v242, v242, v241, v236
	global_store_dword v[244:245], v242, off
	s_mov_b32 s0, 0x16000
	v_pk_fma_f32 v[120:121], v[8:9], v[154:155], v[120:121] op_sel_hi:[1,0,1] neg_lo:[1,0,0] neg_hi:[1,0,0]
	s_nop 0
	v_cvt_pk_bf16_f32 v248, v17, v7
	v_add_co_u32_e32 v246, vcc, 0x14000, v234
	s_nop 0
	v_mov_b32_dpp v249, v248 quad_perm:[1,0,3,2] row_mask:0xf bank_mask:0xf
	v_addc_co_u32_e32 v247, vcc, 0, v235, vcc
	v_perm_b32 v249, v249, v248, v236
	global_store_dword v[246:247], v249, off
	s_nop 0
	s_mov_b32 s0, 0x18000
	s_nop 0
	s_nop 0
	v_cvt_pk_bf16_f32 v241, v18, v12
	v_add_co_u32_e32 v244, vcc, 0x4a000, v232
	s_nop 0
	v_mov_b32_dpp v242, v241 quad_perm:[1,0,3,2] row_mask:0xf bank_mask:0xf
	v_addc_co_u32_e32 v245, vcc, 0, v233, vcc
	v_perm_b32 v242, v242, v241, v236
	global_store_dword v[244:245], v242, off
	s_nop 0
	v_cvt_pk_bf16_f32 v248, v19, v13
	v_add_co_u32_e32 v246, vcc, 0x18000, v234
	s_nop 0
	v_mov_b32_dpp v249, v248 quad_perm:[1,0,3,2] row_mask:0xf bank_mask:0xf
	v_addc_co_u32_e32 v247, vcc, 0, v235, vcc
	v_perm_b32 v249, v249, v248, v236
	global_store_dword v[246:247], v249, off
	v_pk_fma_f32 v[120:121], v[2:3], v[156:157], v[120:121] op_sel_hi:[1,0,1] neg_lo:[1,0,0] neg_hi:[1,0,0]
	s_nop 0
	s_mov_b32 s0, 0x1c000
	s_nop 0
	s_nop 0
	v_cvt_pk_bf16_f32 v241, v8, v4
	v_add_co_u32_e32 v244, vcc, 0x56000, v232
	s_nop 0
	v_mov_b32_dpp v242, v241 quad_perm:[1,0,3,2] row_mask:0xf bank_mask:0xf
	v_addc_co_u32_e32 v245, vcc, 0, v233, vcc
	v_perm_b32 v242, v242, v241, v236
	global_store_dword v[244:245], v242, off
	s_nop 0
	v_cvt_pk_bf16_f32 v248, v9, v5
	v_add_co_u32_e32 v246, vcc, 0x1c000, v234
	s_nop 0
	v_mov_b32_dpp v249, v248 quad_perm:[1,0,3,2] row_mask:0xf bank_mask:0xf
	v_addc_co_u32_e32 v247, vcc, 0, v235, vcc
	v_perm_b32 v249, v249, v248, v236
	global_store_dword v[246:247], v249, off
	s_nop 0
	s_nop 0
	v_pk_fma_f32 v[120:121], v[30:31], v[158:159], v[120:121] op_sel_hi:[1,0,1] neg_lo:[1,0,0] neg_hi:[1,0,0]
	s_nop 0
	v_cvt_pk_bf16_f32 v241, v2, v0
	v_add_co_u32_e32 v244, vcc, 0x62000, v232
	s_nop 0
	v_mov_b32_dpp v242, v241 quad_perm:[1,0,3,2] row_mask:0xf bank_mask:0xf
	v_addc_co_u32_e32 v245, vcc, 0, v233, vcc
	v_perm_b32 v242, v242, v241, v236
	global_store_dword v[244:245], v242, off
	s_mov_b32 s0, 0x22000
	v_pk_fma_f32 v[120:121], v[32:33], v[160:161], v[120:121] op_sel_hi:[1,0,1] neg_lo:[1,0,0] neg_hi:[1,0,0]
	s_nop 0
	v_cvt_pk_bf16_f32 v248, v3, v1
	v_add_co_u32_e32 v246, vcc, 0x20000, v234
	s_nop 0
	v_mov_b32_dpp v249, v248 quad_perm:[1,0,3,2] row_mask:0xf bank_mask:0xf
	v_addc_co_u32_e32 v247, vcc, 0, v235, vcc
	v_perm_b32 v249, v249, v248, v236
	global_store_dword v[246:247], v249, off
	s_nop 0
	s_nop 0
	s_nop 0
	v_cvt_pk_bf16_f32 v241, v30, v28
	v_add_co_u32_e32 v244, vcc, 0x6e000, v232
	s_nop 0
	v_mov_b32_dpp v242, v241 quad_perm:[1,0,3,2] row_mask:0xf bank_mask:0xf
	v_addc_co_u32_e32 v245, vcc, 0, v233, vcc
	v_perm_b32 v242, v242, v241, v236
	global_store_dword v[244:245], v242, off
	s_nop 0
	v_cvt_pk_bf16_f32 v248, v31, v29
	v_add_co_u32_e32 v246, vcc, 0x24000, v234
	s_nop 0
	v_mov_b32_dpp v249, v248 quad_perm:[1,0,3,2] row_mask:0xf bank_mask:0xf
	v_addc_co_u32_e32 v247, vcc, 0, v235, vcc
	v_perm_b32 v249, v249, v248, v236
	global_store_dword v[246:247], v249, off
	s_nop 0
	s_mov_b32 s0, 0x28000
	v_pk_fma_f32 v[120:121], v[36:37], v[162:163], v[120:121] op_sel_hi:[1,0,1] neg_lo:[1,0,0] neg_hi:[1,0,0]
	s_nop 0
	s_mov_b32 s0, 0x80000
	v_pk_fma_f32 v[120:121], v[38:39], v[166:167], v[120:121] op_sel_hi:[1,0,1] neg_lo:[1,0,0] neg_hi:[1,0,0]
	s_nop 0
	v_cvt_pk_bf16_f32 v241, v32, v34
	v_add_co_u32_e32 v244, vcc, 0x7a000, v232
	s_nop 0
	v_mov_b32_dpp v242, v241 quad_perm:[1,0,3,2] row_mask:0xf bank_mask:0xf
	v_addc_co_u32_e32 v245, vcc, 0, v233, vcc
	v_perm_b32 v242, v242, v241, v236
	global_store_dword v[244:245], v242, off
	s_nop 0
	v_cvt_pk_bf16_f32 v248, v33, v35
	v_add_co_u32_e32 v246, vcc, 0x28000, v234
	s_nop 0
	v_mov_b32_dpp v249, v248 quad_perm:[1,0,3,2] row_mask:0xf bank_mask:0xf
	v_addc_co_u32_e32 v247, vcc, 0, v235, vcc
	v_perm_b32 v249, v249, v248, v236
	global_store_dword v[246:247], v249, off
	s_mov_b32 s0, 0x86000
	v_pk_fma_f32 v[120:121], v[44:45], v[168:169], v[120:121] op_sel_hi:[1,0,1] neg_lo:[1,0,0] neg_hi:[1,0,0]
	s_nop 0
	s_nop 0
	s_mov_b32 s0, 0x8c000
	v_pk_fma_f32 v[120:121], v[48:49], v[170:171], v[120:121] op_sel_hi:[1,0,1] neg_lo:[1,0,0] neg_hi:[1,0,0]
	s_nop 0
	v_cvt_pk_bf16_f32 v241, v36, v40
	v_add_co_u32_e32 v244, vcc, 0x86000, v232
	s_nop 0
	v_mov_b32_dpp v242, v241 quad_perm:[1,0,3,2] row_mask:0xf bank_mask:0xf
	v_addc_co_u32_e32 v245, vcc, 0, v233, vcc
	v_perm_b32 v242, v242, v241, v236
	global_store_dword v[244:245], v242, off
	s_mov_b32 s0, 0x2e000
	v_pk_fma_f32 v[120:121], v[52:53], v[172:173], v[120:121] op_sel_hi:[1,0,1] neg_lo:[1,0,0] neg_hi:[1,0,0]
	s_nop 0
	v_cvt_pk_bf16_f32 v248, v37, v41
	v_add_co_u32_e32 v246, vcc, 0x2c000, v234
	s_nop 0
	v_mov_b32_dpp v249, v248 quad_perm:[1,0,3,2] row_mask:0xf bank_mask:0xf
	v_addc_co_u32_e32 v247, vcc, 0, v235, vcc
	v_perm_b32 v249, v249, v248, v236
	global_store_dword v[246:247], v249, off
	s_mov_b32 s0, 0x92000
	v_pk_fma_f32 v[120:121], v[56:57], v[174:175], v[120:121] op_sel_hi:[1,0,1] neg_lo:[1,0,0] neg_hi:[1,0,0]
	s_nop 0
	s_nop 0
	s_mov_b32 s0, 0x98000
	v_pk_fma_f32 v[120:121], v[60:61], v[176:177], v[120:121] op_sel_hi:[1,0,1] neg_lo:[1,0,0] neg_hi:[1,0,0]
	s_nop 0
	v_cvt_pk_bf16_f32 v241, v38, v42
	v_add_co_u32_e32 v244, vcc, 0x92000, v232
	s_nop 0
	v_mov_b32_dpp v242, v241 quad_perm:[1,0,3,2] row_mask:0xf bank_mask:0xf
	v_addc_co_u32_e32 v245, vcc, 0, v233, vcc
	v_perm_b32 v242, v242, v241, v236
	global_store_dword v[244:245], v242, off
	s_nop 0
	v_cvt_pk_bf16_f32 v248, v39, v43
	v_add_co_u32_e32 v246, vcc, 0x30000, v234
	s_nop 0
	v_mov_b32_dpp v249, v248 quad_perm:[1,0,3,2] row_mask:0xf bank_mask:0xf
	v_addc_co_u32_e32 v247, vcc, 0, v235, vcc
	v_perm_b32 v249, v249, v248, v236
	global_store_dword v[246:247], v249, off
	s_mov_b32 s0, 0x9e000
	v_pk_fma_f32 v[120:121], v[64:65], v[178:179], v[120:121] op_sel_hi:[1,0,1] neg_lo:[1,0,0] neg_hi:[1,0,0]
	s_nop 0
	s_mov_b32 s0, 0x34000
	v_pk_fma_f32 v[120:121], v[68:69], v[180:181], v[120:121] op_sel_hi:[1,0,1] neg_lo:[1,0,0] neg_hi:[1,0,0]
	s_nop 0
	s_mov_b32 s0, 0xa4000
	v_pk_fma_f32 v[120:121], v[72:73], v[182:183], v[120:121] op_sel_hi:[1,0,1] neg_lo:[1,0,0] neg_hi:[1,0,0]
	s_nop 0
	v_cvt_pk_bf16_f32 v241, v44, v46
	v_add_co_u32_e32 v244, vcc, 0x9e000, v232
	s_nop 0
	v_mov_b32_dpp v242, v241 quad_perm:[1,0,3,2] row_mask:0xf bank_mask:0xf
	v_addc_co_u32_e32 v245, vcc, 0, v233, vcc
	v_perm_b32 v242, v242, v241, v236
	global_store_dword v[244:245], v242, off
	s_nop 0
	v_cvt_pk_bf16_f32 v248, v45, v47
	v_add_co_u32_e32 v246, vcc, 0x34000, v234
	s_nop 0
	v_mov_b32_dpp v249, v248 quad_perm:[1,0,3,2] row_mask:0xf bank_mask:0xf
	v_addc_co_u32_e32 v247, vcc, 0, v235, vcc
	v_perm_b32 v249, v249, v248, v236
	global_store_dword v[246:247], v249, off
	s_mov_b32 s0, 0xaa000
	v_pk_fma_f32 v[120:121], v[76:77], v[184:185], v[120:121] op_sel_hi:[1,0,1] neg_lo:[1,0,0] neg_hi:[1,0,0]
	s_nop 0
	s_nop 0
	s_mov_b32 s0, 0xb0000
	v_pk_fma_f32 v[120:121], v[80:81], v[208:209], v[120:121] op_sel_hi:[1,0,1] neg_lo:[1,0,0] neg_hi:[1,0,0]
	s_nop 0
	v_cvt_pk_bf16_f32 v241, v48, v50
	v_add_co_u32_e32 v244, vcc, 0xaa000, v232
	s_nop 0
	v_mov_b32_dpp v242, v241 quad_perm:[1,0,3,2] row_mask:0xf bank_mask:0xf
	v_addc_co_u32_e32 v245, vcc, 0, v233, vcc
	v_perm_b32 v242, v242, v241, v236
	global_store_dword v[244:245], v242, off
	s_mov_b32 s0, 0x3a000
	v_pk_fma_f32 v[120:121], v[86:87], v[210:211], v[120:121] op_sel_hi:[1,0,1] neg_lo:[1,0,0] neg_hi:[1,0,0]
	s_nop 0
	v_cvt_pk_bf16_f32 v248, v49, v51
	v_add_co_u32_e32 v246, vcc, 0x38000, v234
	s_nop 0
	v_mov_b32_dpp v249, v248 quad_perm:[1,0,3,2] row_mask:0xf bank_mask:0xf
	v_addc_co_u32_e32 v247, vcc, 0, v235, vcc
	v_perm_b32 v249, v249, v248, v236
	global_store_dword v[246:247], v249, off
	s_mov_b32 s0, 0xb6000
	v_pk_fma_f32 v[120:121], v[90:91], v[212:213], v[120:121] op_sel_hi:[1,0,1] neg_lo:[1,0,0] neg_hi:[1,0,0]
	s_nop 0
	s_nop 0
	s_mov_b32 s0, 0xbc000
	v_pk_fma_f32 v[120:121], v[94:95], v[214:215], v[120:121] op_sel_hi:[1,0,1] neg_lo:[1,0,0] neg_hi:[1,0,0]
	s_nop 0
	v_cvt_pk_bf16_f32 v241, v52, v54
	v_add_co_u32_e32 v244, vcc, 0xb6000, v232
	s_nop 0
	v_mov_b32_dpp v242, v241 quad_perm:[1,0,3,2] row_mask:0xf bank_mask:0xf
	v_addc_co_u32_e32 v245, vcc, 0, v233, vcc
	v_perm_b32 v242, v242, v241, v236
	global_store_dword v[244:245], v242, off
	s_nop 0
	v_cvt_pk_bf16_f32 v248, v53, v55
	v_add_co_u32_e32 v246, vcc, 0x3c000, v234
	s_nop 0
	v_mov_b32_dpp v249, v248 quad_perm:[1,0,3,2] row_mask:0xf bank_mask:0xf
	v_addc_co_u32_e32 v247, vcc, 0, v235, vcc
	v_perm_b32 v249, v249, v248, v236
	global_store_dword v[246:247], v249, off
	s_mov_b32 s0, 0xc2000
	v_pk_fma_f32 v[120:121], v[98:99], v[216:217], v[120:121] op_sel_hi:[1,0,1] neg_lo:[1,0,0] neg_hi:[1,0,0]
	s_nop 0
	s_mov_b32 s0, 0x40000
	v_pk_fma_f32 v[120:121], v[102:103], v[218:219], v[120:121] op_sel_hi:[1,0,1] neg_lo:[1,0,0] neg_hi:[1,0,0]
	s_nop 0
	s_mov_b32 s0, 0xc8000
	v_pk_fma_f32 v[120:121], v[106:107], v[220:221], v[120:121] op_sel_hi:[1,0,1] neg_lo:[1,0,0] neg_hi:[1,0,0]
	s_nop 0
	v_cvt_pk_bf16_f32 v241, v56, v58
	v_add_co_u32_e32 v244, vcc, 0xc2000, v232
	s_nop 0
	v_mov_b32_dpp v242, v241 quad_perm:[1,0,3,2] row_mask:0xf bank_mask:0xf
	v_addc_co_u32_e32 v245, vcc, 0, v233, vcc
	v_perm_b32 v242, v242, v241, v236
	global_store_dword v[244:245], v242, off
	s_nop 0
	v_cvt_pk_bf16_f32 v248, v57, v59
	v_add_co_u32_e32 v246, vcc, 0x40000, v234
	s_nop 0
	v_mov_b32_dpp v249, v248 quad_perm:[1,0,3,2] row_mask:0xf bank_mask:0xf
	v_addc_co_u32_e32 v247, vcc, 0, v235, vcc
	v_perm_b32 v249, v249, v248, v236
	global_store_dword v[246:247], v249, off
	s_mov_b32 s0, 0xce000
	v_pk_fma_f32 v[120:121], v[110:111], v[222:223], v[120:121] op_sel_hi:[1,0,1] neg_lo:[1,0,0] neg_hi:[1,0,0]
	s_nop 0
	s_nop 0
	s_mov_b32 s0, 0xd4000
	v_pk_fma_f32 v[120:121], v[114:115], v[224:225], v[120:121] op_sel_hi:[1,0,1] neg_lo:[1,0,0] neg_hi:[1,0,0]
	s_nop 0
	v_cvt_pk_bf16_f32 v241, v60, v62
	v_add_co_u32_e32 v244, vcc, 0xce000, v232
	s_nop 0
	v_mov_b32_dpp v242, v241 quad_perm:[1,0,3,2] row_mask:0xf bank_mask:0xf
	v_addc_co_u32_e32 v245, vcc, 0, v233, vcc
	v_perm_b32 v242, v242, v241, v236
	global_store_dword v[244:245], v242, off
	s_mov_b32 s0, 0x46000
	v_pk_fma_f32 v[120:121], v[226:227], v[118:119], v[120:121] op_sel_hi:[0,1,1] neg_lo:[1,0,0] neg_hi:[1,0,0]
	s_nop 0
	v_cvt_pk_bf16_f32 v248, v61, v63
	v_add_co_u32_e32 v246, vcc, 0x44000, v234
	s_nop 0
	v_mov_b32_dpp v249, v248 quad_perm:[1,0,3,2] row_mask:0xf bank_mask:0xf
	v_addc_co_u32_e32 v247, vcc, 0, v235, vcc
	v_perm_b32 v249, v249, v248, v236
	global_store_dword v[246:247], v249, off
	s_mov_b32 s0, 0xda000
	v_pk_add_f32 v[120:121], v[120:121], v[186:187]
	s_nop 0
	s_nop 0
	s_mov_b32 s0, 0xe0000
	v_add_u32_e32 v8, v196, v26
	s_nop 0
	v_cvt_pk_bf16_f32 v241, v64, v66
	v_add_co_u32_e32 v244, vcc, 0xda000, v232
	s_nop 0
	v_mov_b32_dpp v242, v241 quad_perm:[1,0,3,2] row_mask:0xf bank_mask:0xf
	v_addc_co_u32_e32 v245, vcc, 0, v233, vcc
	v_perm_b32 v242, v242, v241, v236
	global_store_dword v[244:245], v242, off
	s_nop 0
	v_cvt_pk_bf16_f32 v248, v65, v67
	v_add_co_u32_e32 v246, vcc, 0x48000, v234
	s_nop 0
	v_mov_b32_dpp v249, v248 quad_perm:[1,0,3,2] row_mask:0xf bank_mask:0xf
	v_addc_co_u32_e32 v247, vcc, 0, v235, vcc
	v_perm_b32 v249, v249, v248, v236
	global_store_dword v[246:247], v249, off
	s_mov_b32 s0, 0xe6000
	v_or_b32_e32 v6, v22, v24
	s_nop 0
	s_mov_b32 s0, 0x4c000
	v_mul_lo_u32 v10, v23, s29
	s_nop 0
	s_mov_b32 s0, 0xec000
	v_lshlrev_b32_e32 v20, 1, v27
	s_nop 0
	v_cvt_pk_bf16_f32 v241, v68, v70
	v_add_co_u32_e32 v244, vcc, 0xe6000, v232
	s_nop 0
	v_mov_b32_dpp v242, v241 quad_perm:[1,0,3,2] row_mask:0xf bank_mask:0xf
	v_addc_co_u32_e32 v245, vcc, 0, v233, vcc
	v_perm_b32 v242, v242, v241, v236
	global_store_dword v[244:245], v242, off
	s_nop 0
	v_cvt_pk_bf16_f32 v248, v69, v71
	v_add_co_u32_e32 v246, vcc, 0x4c000, v234
	s_nop 0
	v_mov_b32_dpp v249, v248 quad_perm:[1,0,3,2] row_mask:0xf bank_mask:0xf
	v_addc_co_u32_e32 v247, vcc, 0, v235, vcc
	v_perm_b32 v249, v249, v248, v236
	global_store_dword v[246:247], v249, off
	s_mov_b32 s0, 0xf2000
	v_mov_b32_e32 v27, v21
	s_nop 0
	s_nop 0
	s_mov_b32 s0, 0xf8000
	s_nop 1
	v_cvt_pk_bf16_f32 v241, v72, v74
	v_add_co_u32_e32 v244, vcc, 0xf2000, v232
	s_nop 0
	v_mov_b32_dpp v242, v241 quad_perm:[1,0,3,2] row_mask:0xf bank_mask:0xf
	v_addc_co_u32_e32 v245, vcc, 0, v233, vcc
	v_perm_b32 v242, v242, v241, v236
	global_store_dword v[244:245], v242, off
	s_mov_b32 s0, 0x52000
	s_nop 1
	v_cvt_pk_bf16_f32 v248, v73, v75
	v_add_co_u32_e32 v246, vcc, 0x50000, v234
	s_nop 0
	v_mov_b32_dpp v249, v248 quad_perm:[1,0,3,2] row_mask:0xf bank_mask:0xf
	v_addc_co_u32_e32 v247, vcc, 0, v235, vcc
	v_perm_b32 v249, v249, v248, v236
	global_store_dword v[246:247], v249, off
	s_mov_b32 s0, 0xfe000
	s_nop 1
	s_nop 0
	s_mov_b32 s0, 0x104000
	s_nop 1
	v_cvt_pk_bf16_f32 v241, v76, v78
	v_add_co_u32_e32 v244, vcc, 0xfe000, v232
	s_nop 0
	v_mov_b32_dpp v242, v241 quad_perm:[1,0,3,2] row_mask:0xf bank_mask:0xf
	v_addc_co_u32_e32 v245, vcc, 0, v233, vcc
	v_perm_b32 v242, v242, v241, v236
	global_store_dword v[244:245], v242, off
	s_nop 0
	v_cvt_pk_bf16_f32 v248, v77, v79
	v_add_co_u32_e32 v246, vcc, 0x54000, v234
	s_nop 0
	v_mov_b32_dpp v249, v248 quad_perm:[1,0,3,2] row_mask:0xf bank_mask:0xf
	v_addc_co_u32_e32 v247, vcc, 0, v235, vcc
	v_perm_b32 v249, v249, v248, v236
	global_store_dword v[246:247], v249, off
	s_mov_b32 s0, 0x10a000
	s_nop 1
	s_mov_b32 s0, 0x58000
	s_nop 1
	s_mov_b32 s0, 0x110000
	s_nop 1
	v_cvt_pk_bf16_f32 v241, v80, v82
	v_add_co_u32_e32 v244, vcc, 0x10a000, v232
	s_nop 0
	v_mov_b32_dpp v242, v241 quad_perm:[1,0,3,2] row_mask:0xf bank_mask:0xf
	v_addc_co_u32_e32 v245, vcc, 0, v233, vcc
	v_perm_b32 v242, v242, v241, v236
	global_store_dword v[244:245], v242, off
	s_nop 0
	v_cvt_pk_bf16_f32 v248, v81, v83
	v_add_co_u32_e32 v246, vcc, 0x58000, v234
	s_nop 0
	v_mov_b32_dpp v249, v248 quad_perm:[1,0,3,2] row_mask:0xf bank_mask:0xf
	v_addc_co_u32_e32 v247, vcc, 0, v235, vcc
	v_perm_b32 v249, v249, v248, v236
	global_store_dword v[246:247], v249, off
	s_mov_b32 s0, 0x116000
	s_nop 1
	s_nop 0
	s_mov_b32 s0, 0x11c000
	s_nop 1
	v_cvt_pk_bf16_f32 v241, v86, v88
	v_add_co_u32_e32 v244, vcc, 0x116000, v232
	s_nop 0
	v_mov_b32_dpp v242, v241 quad_perm:[1,0,3,2] row_mask:0xf bank_mask:0xf
	v_addc_co_u32_e32 v245, vcc, 0, v233, vcc
	v_perm_b32 v242, v242, v241, v236
	global_store_dword v[244:245], v242, off
	s_mov_b32 s0, 0x5e000
	s_nop 1
	v_cvt_pk_bf16_f32 v248, v87, v89
	v_add_co_u32_e32 v246, vcc, 0x5c000, v234
	s_nop 0
	v_mov_b32_dpp v249, v248 quad_perm:[1,0,3,2] row_mask:0xf bank_mask:0xf
	v_addc_co_u32_e32 v247, vcc, 0, v235, vcc
	v_perm_b32 v249, v249, v248, v236
	global_store_dword v[246:247], v249, off
	s_mov_b32 s0, 0x122000
	s_nop 1
	s_nop 0
	s_mov_b32 s0, 0x128000
	s_nop 1
	v_cvt_pk_bf16_f32 v241, v90, v92
	v_add_co_u32_e32 v244, vcc, 0x122000, v232
	s_nop 0
	v_mov_b32_dpp v242, v241 quad_perm:[1,0,3,2] row_mask:0xf bank_mask:0xf
	v_addc_co_u32_e32 v245, vcc, 0, v233, vcc
	v_perm_b32 v242, v242, v241, v236
	global_store_dword v[244:245], v242, off
	s_nop 0
	v_cvt_pk_bf16_f32 v248, v91, v93
	v_add_co_u32_e32 v246, vcc, 0x60000, v234
	s_nop 0
	v_mov_b32_dpp v249, v248 quad_perm:[1,0,3,2] row_mask:0xf bank_mask:0xf
	v_addc_co_u32_e32 v247, vcc, 0, v235, vcc
	v_perm_b32 v249, v249, v248, v236
	global_store_dword v[246:247], v249, off
	s_mov_b32 s0, 0x12e000
	s_nop 1
	s_mov_b32 s0, 0x64000
	s_nop 1
	s_mov_b32 s0, 0x134000
	s_nop 1
	v_cvt_pk_bf16_f32 v241, v94, v96
	v_add_co_u32_e32 v244, vcc, 0x12e000, v232
	s_nop 0
	v_mov_b32_dpp v242, v241 quad_perm:[1,0,3,2] row_mask:0xf bank_mask:0xf
	v_addc_co_u32_e32 v245, vcc, 0, v233, vcc
	v_perm_b32 v242, v242, v241, v236
	global_store_dword v[244:245], v242, off
	s_nop 0
	v_cvt_pk_bf16_f32 v248, v95, v97
	v_add_co_u32_e32 v246, vcc, 0x64000, v234
	s_nop 0
	v_mov_b32_dpp v249, v248 quad_perm:[1,0,3,2] row_mask:0xf bank_mask:0xf
	v_addc_co_u32_e32 v247, vcc, 0, v235, vcc
	v_perm_b32 v249, v249, v248, v236
	global_store_dword v[246:247], v249, off
	s_mov_b32 s0, 0x13a000
	s_nop 1
	s_nop 0
	s_mov_b32 s0, 0x140000
	s_nop 1
	v_cvt_pk_bf16_f32 v241, v98, v100
	v_add_co_u32_e32 v244, vcc, 0x13a000, v232
	s_nop 0
	v_mov_b32_dpp v242, v241 quad_perm:[1,0,3,2] row_mask:0xf bank_mask:0xf
	v_addc_co_u32_e32 v245, vcc, 0, v233, vcc
	v_perm_b32 v242, v242, v241, v236
	global_store_dword v[244:245], v242, off
	s_mov_b32 s0, 0x6a000
	s_nop 1
	v_cvt_pk_bf16_f32 v248, v99, v101
	v_add_co_u32_e32 v246, vcc, 0x68000, v234
	s_nop 0
	v_mov_b32_dpp v249, v248 quad_perm:[1,0,3,2] row_mask:0xf bank_mask:0xf
	v_addc_co_u32_e32 v247, vcc, 0, v235, vcc
	v_perm_b32 v249, v249, v248, v236
	global_store_dword v[246:247], v249, off
	s_mov_b32 s0, 0x146000
	s_nop 1
	s_nop 0
	s_mov_b32 s0, 0x14c000
	s_nop 1
	v_cvt_pk_bf16_f32 v241, v102, v104
	v_add_co_u32_e32 v244, vcc, 0x146000, v232
	s_nop 0
	v_mov_b32_dpp v242, v241 quad_perm:[1,0,3,2] row_mask:0xf bank_mask:0xf
	v_addc_co_u32_e32 v245, vcc, 0, v233, vcc
	v_perm_b32 v242, v242, v241, v236
	global_store_dword v[244:245], v242, off
	s_nop 0
	v_cvt_pk_bf16_f32 v248, v103, v105
	v_add_co_u32_e32 v246, vcc, 0x6c000, v234
	s_nop 0
	v_mov_b32_dpp v249, v248 quad_perm:[1,0,3,2] row_mask:0xf bank_mask:0xf
	v_addc_co_u32_e32 v247, vcc, 0, v235, vcc
	v_perm_b32 v249, v249, v248, v236
	global_store_dword v[246:247], v249, off
	s_mov_b32 s0, 0x152000
	s_nop 1
	s_mov_b32 s0, 0x70000
	s_nop 1
	s_mov_b32 s0, 0x158000
	s_nop 1
	v_cvt_pk_bf16_f32 v241, v106, v108
	v_add_co_u32_e32 v244, vcc, 0x152000, v232
	s_nop 0
	v_mov_b32_dpp v242, v241 quad_perm:[1,0,3,2] row_mask:0xf bank_mask:0xf
	v_addc_co_u32_e32 v245, vcc, 0, v233, vcc
	v_perm_b32 v242, v242, v241, v236
	global_store_dword v[244:245], v242, off
	s_nop 0
	v_cvt_pk_bf16_f32 v248, v107, v109
	v_add_co_u32_e32 v246, vcc, 0x70000, v234
	s_nop 0
	v_mov_b32_dpp v249, v248 quad_perm:[1,0,3,2] row_mask:0xf bank_mask:0xf
	v_addc_co_u32_e32 v247, vcc, 0, v235, vcc
	v_perm_b32 v249, v249, v248, v236
	global_store_dword v[246:247], v249, off
	s_mov_b32 s0, 0x15e000
	s_nop 1
	s_nop 0
	s_mov_b32 s0, 0x164000
	s_nop 1
	v_cvt_pk_bf16_f32 v241, v110, v112
	v_add_co_u32_e32 v244, vcc, 0x15e000, v232
	s_nop 0
	v_mov_b32_dpp v242, v241 quad_perm:[1,0,3,2] row_mask:0xf bank_mask:0xf
	v_addc_co_u32_e32 v245, vcc, 0, v233, vcc
	v_perm_b32 v242, v242, v241, v236
	global_store_dword v[244:245], v242, off
	s_mov_b32 s0, 0x76000
	s_nop 1
	v_cvt_pk_bf16_f32 v248, v111, v113
	v_add_co_u32_e32 v246, vcc, 0x74000, v234
	s_nop 0
	v_mov_b32_dpp v249, v248 quad_perm:[1,0,3,2] row_mask:0xf bank_mask:0xf
	v_addc_co_u32_e32 v247, vcc, 0, v235, vcc
	v_perm_b32 v249, v249, v248, v236
	global_store_dword v[246:247], v249, off
	s_mov_b32 s0, 0x16a000
	s_nop 1
	s_nop 0
	s_mov_b32 s0, 0x170000
	s_nop 1
	v_cvt_pk_bf16_f32 v241, v114, v116
	v_add_co_u32_e32 v244, vcc, 0x16a000, v232
	s_nop 0
	v_mov_b32_dpp v242, v241 quad_perm:[1,0,3,2] row_mask:0xf bank_mask:0xf
	v_addc_co_u32_e32 v245, vcc, 0, v233, vcc
	v_perm_b32 v242, v242, v241, v236
	global_store_dword v[244:245], v242, off
	s_nop 0
	v_cvt_pk_bf16_f32 v248, v115, v117
	v_add_co_u32_e32 v246, vcc, 0x78000, v234
	s_nop 0
	v_mov_b32_dpp v249, v248 quad_perm:[1,0,3,2] row_mask:0xf bank_mask:0xf
	v_addc_co_u32_e32 v247, vcc, 0, v235, vcc
	v_perm_b32 v249, v249, v248, v236
	global_store_dword v[246:247], v249, off
	s_mov_b32 s0, 0x176000
	s_nop 1
	s_mov_b32 s0, 0x7c000
	s_nop 1
	s_mov_b32 s0, 0x17c000
	s_nop 1
	v_cvt_pk_bf16_f32 v241, v118, v120
	v_add_co_u32_e32 v244, vcc, 0x176000, v232
	s_nop 0
	v_mov_b32_dpp v242, v241 quad_perm:[1,0,3,2] row_mask:0xf bank_mask:0xf
	v_addc_co_u32_e32 v245, vcc, 0, v233, vcc
	v_perm_b32 v242, v242, v241, v236
	global_store_dword v[244:245], v242, off
	s_nop 0
	v_cvt_pk_bf16_f32 v248, v119, v121
	v_add_co_u32_e32 v246, vcc, 0x7c000, v234
	s_nop 0
	v_mov_b32_dpp v249, v248 quad_perm:[1,0,3,2] row_mask:0xf bank_mask:0xf
	v_addc_co_u32_e32 v247, vcc, 0, v235, vcc
	v_perm_b32 v249, v249, v248, v236
	global_store_dword v[246:247], v249, off
	v_and_b32_e32 v0, 56, v195
	v_mul_u32_u24_e32 v9, 0x110, v0
	v_add_u32_e32 v0, v8, v201
	ds_read_b128 v[2:5], v0 offset:4096
	v_mov_b64_e32 v[0:1], s[68:69]
	v_mad_u64_u32 v[6:7], s[0:1], v6, s29, v[0:1]
	v_add_u32_e32 v7, v10, v7
	v_lshl_add_u64 v[6:7], v[6:7], 0, v[20:21]
	v_lshl_add_u64 v[6:7], v[6:7], 0, v[26:27]
	s_waitcnt lgkmcnt(0)
	global_store_dwordx4 v[6:7], v[2:5], off
	v_add_co_u32_e32 v6, vcc, s27, v6
	s_nop 0
	v_lshrrev_b32_e32 v2, 2, v194
	v_and_b32_e32 v2, 62, v2
	v_add3_u32 v2, v196, v2, v9
	ds_read_u16 v3, v2 offset:21504
	ds_read_u16 v4, v2 offset:21776
	ds_read_u16 v5, v2 offset:22048
	ds_read_u16 v11, v2 offset:22320
	ds_read_u16 v12, v2 offset:22592
	ds_read_u16 v13, v2 offset:22864
	ds_read_u16 v14, v2 offset:23136
	ds_read_u16 v2, v2 offset:23408
	s_waitcnt lgkmcnt(7)
	v_lshlrev_b32_e32 v3, 16, v3
	s_waitcnt lgkmcnt(6)
	v_lshlrev_b32_e32 v4, 16, v4
	s_waitcnt lgkmcnt(5)
	v_lshlrev_b32_e32 v5, 16, v5
	s_waitcnt lgkmcnt(4)
	v_lshlrev_b32_e32 v11, 16, v11
	s_waitcnt lgkmcnt(3)
	v_lshlrev_b32_e32 v12, 16, v12
	s_waitcnt lgkmcnt(2)
	v_lshlrev_b32_e32 v13, 16, v13
	s_waitcnt lgkmcnt(1)
	v_lshlrev_b32_e32 v14, 16, v14
	s_waitcnt lgkmcnt(0)
	v_lshlrev_b32_e32 v15, 16, v2
	v_cvt_pk_bf16_f32 v2, v3, v4
	v_cvt_pk_bf16_f32 v3, v5, v11
	v_cvt_pk_bf16_f32 v4, v12, v13
	v_cvt_pk_bf16_f32 v5, v14, v15
	v_addc_co_u32_e32 v7, vcc, 0, v7, vcc
	global_store_dwordx4 v[6:7], v[2:5], off
	v_or_b32_e32 v6, v22, v198
	v_mad_u64_u32 v[6:7], s[0:1], v6, s29, v[0:1]
	v_add_u32_e32 v2, v8, v204
	ds_read_b128 v[2:5], v2 offset:4096
	v_add_u32_e32 v7, v10, v7
	v_lshl_add_u64 v[6:7], v[6:7], 0, v[20:21]
	v_lshl_add_u64 v[6:7], v[6:7], 0, v[26:27]
	s_waitcnt lgkmcnt(0)
	global_store_dwordx4 v[6:7], v[2:5], off
	v_add_co_u32_e32 v6, vcc, s27, v6
	s_nop 0
	v_lshrrev_b32_e32 v2, 2, v197
	v_and_b32_e32 v2, 0x7e, v2
	v_add3_u32 v2, v196, v2, v9
	ds_read_u16 v3, v2 offset:21504
	ds_read_u16 v4, v2 offset:21776
	ds_read_u16 v5, v2 offset:22048
	ds_read_u16 v11, v2 offset:22320
	ds_read_u16 v12, v2 offset:22592
	ds_read_u16 v13, v2 offset:22864
	ds_read_u16 v14, v2 offset:23136
	ds_read_u16 v2, v2 offset:23408
	s_waitcnt lgkmcnt(7)
	v_lshlrev_b32_e32 v3, 16, v3
	s_waitcnt lgkmcnt(6)
	v_lshlrev_b32_e32 v4, 16, v4
	s_waitcnt lgkmcnt(5)
	v_lshlrev_b32_e32 v5, 16, v5
	s_waitcnt lgkmcnt(4)
	v_lshlrev_b32_e32 v11, 16, v11
	s_waitcnt lgkmcnt(3)
	v_lshlrev_b32_e32 v12, 16, v12
	s_waitcnt lgkmcnt(2)
	v_lshlrev_b32_e32 v13, 16, v13
	s_waitcnt lgkmcnt(1)
	v_lshlrev_b32_e32 v14, 16, v14
	s_waitcnt lgkmcnt(0)
	v_lshlrev_b32_e32 v15, 16, v2
	v_cvt_pk_bf16_f32 v2, v3, v4
	v_cvt_pk_bf16_f32 v3, v5, v11
	v_cvt_pk_bf16_f32 v4, v12, v13
	v_cvt_pk_bf16_f32 v5, v14, v15
	v_addc_co_u32_e32 v7, vcc, 0, v7, vcc
	global_store_dwordx4 v[6:7], v[2:5], off
	v_or_b32_e32 v6, v22, v200
	v_mad_u64_u32 v[6:7], s[0:1], v6, s29, v[0:1]
	v_add_u32_e32 v2, v8, v205
	ds_read_b128 v[2:5], v2 offset:4096
	v_add_u32_e32 v7, v10, v7
	v_lshl_add_u64 v[6:7], v[6:7], 0, v[20:21]
	v_lshl_add_u64 v[6:7], v[6:7], 0, v[26:27]
	s_waitcnt lgkmcnt(0)
	global_store_dwordx4 v[6:7], v[2:5], off
	v_add_co_u32_e32 v6, vcc, s27, v6
	s_nop 0
	v_lshrrev_b32_e32 v2, 2, v199
	v_and_b32_e32 v2, 0xfe, v2
	v_add3_u32 v2, v196, v2, v9
	ds_read_u16 v3, v2 offset:21504
	ds_read_u16 v4, v2 offset:21776
	ds_read_u16 v5, v2 offset:22048
	ds_read_u16 v11, v2 offset:22320
	ds_read_u16 v12, v2 offset:22592
	ds_read_u16 v13, v2 offset:22864
	ds_read_u16 v14, v2 offset:23136
	ds_read_u16 v2, v2 offset:23408
	s_waitcnt lgkmcnt(7)
	v_lshlrev_b32_e32 v3, 16, v3
	s_waitcnt lgkmcnt(6)
	v_lshlrev_b32_e32 v4, 16, v4
	s_waitcnt lgkmcnt(5)
	v_lshlrev_b32_e32 v5, 16, v5
	s_waitcnt lgkmcnt(4)
	v_lshlrev_b32_e32 v11, 16, v11
	s_waitcnt lgkmcnt(3)
	v_lshlrev_b32_e32 v12, 16, v12
	s_waitcnt lgkmcnt(2)
	v_lshlrev_b32_e32 v13, 16, v13
	s_waitcnt lgkmcnt(1)
	v_lshlrev_b32_e32 v14, 16, v14
	s_waitcnt lgkmcnt(0)
	v_lshlrev_b32_e32 v15, 16, v2
	v_cvt_pk_bf16_f32 v2, v3, v4
	v_cvt_pk_bf16_f32 v3, v5, v11
	v_cvt_pk_bf16_f32 v4, v12, v13
	v_cvt_pk_bf16_f32 v5, v14, v15
	v_addc_co_u32_e32 v7, vcc, 0, v7, vcc
	global_store_dwordx4 v[6:7], v[2:5], off
	v_or_b32_e32 v6, v22, v203
	v_mad_u64_u32 v[0:1], s[0:1], v6, s29, v[0:1]
	v_add_u32_e32 v2, v8, v206
	ds_read_b128 v[2:5], v2 offset:4096
	v_add_u32_e32 v1, v10, v1
	v_lshl_add_u64 v[0:1], v[0:1], 0, v[20:21]
	v_lshl_add_u64 v[6:7], v[0:1], 0, v[26:27]
	v_lshrrev_b32_e32 v0, 2, v202
	v_and_b32_e32 v0, 0xfe, v0
	v_add3_u32 v0, v196, v0, v9
	s_waitcnt lgkmcnt(0)
	global_store_dwordx4 v[6:7], v[2:5], off
	ds_read_u16 v1, v0 offset:21504
	ds_read_u16 v2, v0 offset:21776
	ds_read_u16 v3, v0 offset:22048
	ds_read_u16 v4, v0 offset:22320
	ds_read_u16 v5, v0 offset:22592
	ds_read_u16 v8, v0 offset:22864
	ds_read_u16 v9, v0 offset:23136
	ds_read_u16 v0, v0 offset:23408
	s_waitcnt lgkmcnt(7)
	v_lshlrev_b32_e32 v1, 16, v1
	s_waitcnt lgkmcnt(6)
	v_lshlrev_b32_e32 v2, 16, v2
	s_waitcnt lgkmcnt(5)
	v_lshlrev_b32_e32 v3, 16, v3
	s_waitcnt lgkmcnt(4)
	v_lshlrev_b32_e32 v4, 16, v4
	s_waitcnt lgkmcnt(3)
	v_lshlrev_b32_e32 v5, 16, v5
	s_waitcnt lgkmcnt(2)
	v_lshlrev_b32_e32 v8, 16, v8
	s_waitcnt lgkmcnt(1)
	v_lshlrev_b32_e32 v9, 16, v9
	s_waitcnt lgkmcnt(0)
	v_lshlrev_b32_e32 v10, 16, v0
	v_cvt_pk_bf16_f32 v0, v1, v2
	v_cvt_pk_bf16_f32 v1, v3, v4
	v_add_co_u32_e32 v4, vcc, 0x1000, v6
	v_cvt_pk_bf16_f32 v2, v5, v8
	v_cvt_pk_bf16_f32 v3, v9, v10
	v_addc_co_u32_e32 v5, vcc, 0, v7, vcc
	global_store_dwordx4 v[4:5], v[0:3], off
	s_cbranch_scc1 .LBB0_325
